# baseline (speedup 1.0000x reference)
; template <class Epi, class Sched>
; __device__ __forceinline__ void gemm_phase(PG8_LAS unsigned char* lds, const Gemm g, const Sched& S, const Epi& E) {
;     const int tid = threadIdx.x, wid = __builtin_amdgcn_readfirstlane(tid >> 6), lane = tid & 63, wr = wid >> 2, wc = wid & 3, fr = lane & 15, fq = lane >> 4;
.LBB0_98:
	v_readfirstlane_b32 s98, v146
	s_nop 3
	s_cmp_ge_u32 s98, 4
	s_cbranch_scc0 .Lprio_0
	s_setprio 1

; #define PG8_STAGE(bufoff, gbase, voff) do { _Pragma("unroll") for (int _i = 0; _i < 2; ++_i) \
;         __builtin_amdgcn_global_load_lds((const unsigned*)((const char*)(gbase) + (voff)[_i]), (PG8_LAS unsigned*)(lds + (bufoff) + ldsw + _i * 8192), 16, 0, 0); } while (0)
; #define PG8_LDA(dst, b, h) do { _Pragma("unroll") for (int m = 0; m < 4; ++m) _Pragma("unroll") for (int k = 0; k < 2; ++k) dst[m][k] = *(const PG8_LAS bf16x8*)(lds + PG8_SA(b, h) + aoff + m * 2048 + k * 1024); } while (0)
; #define PG8_LDB(dst, b, h) do { _Pragma("unroll") for (int n = 0; n < 2; ++n) _Pragma("unroll") for (int k = 0; k < 2; ++k) dst[n][k] = *(const PG8_LAS bf16x8*)(lds + PG8_SB(b, h) + boff + n * 2048 + k * 1024); } while (0)
; #define PG8_MMA(ai, bj, At, Bt) do { __builtin_amdgcn_s_setprio(1); _Pragma("unroll") for (int m = 0; m < 4; ++m) _Pragma("unroll") for (int n = 0; n < 2; ++n) _Pragma("unroll") for (int k = 0; k < 2; ++k) \
;         acc[ai][bj][m][n] = __builtin_amdgcn_mfma_f32_16x16x32_bf16(Bt[n][k], At[m][k], acc[ai][bj][m][n], 0, 0, 0); __builtin_amdgcn_s_setprio(0); } while (0)
; #define PG8_WAIT_L(n) asm volatile("s_waitcnt lgkmcnt(" #n ")" ::: "memory")
; #define PG8_BAR __builtin_amdgcn_s_barrier()
; #define PG8_SCHED __builtin_amdgcn_sched_barrier(0)
; template <class Epi, class Sched>
; __device__ __forceinline__ void gemm_phase(PG8_LAS unsigned char* lds, const Gemm g, const Sched& S, const Epi& E) {
;     ...
;             PG8_LDB(B0, 0, 0); PG8_SCHED; PG8_LDA(At, 0, 0); PG8_STAGE(PG8_SA(1, 1), a1 + hstep, voffA);
;             PG8_WAIT_L(8); PG8_BAR; PG8_WAIT_L(0); PG8_MMA(0, 0, At, B0); PG8_BAR; PG8_SCHED;
;             PG8_LDB(B1, 0, 1); PG8_STAGE(PG8_SB(0, 0), b2, voffB);
;             PG8_BAR; PG8_WAIT_L(0); PG8_MMA(0, 1, At, B1); PG8_BAR;
;             PG8_LDA(At, 0, 1); PG8_STAGE(PG8_SA(0, 0), a2, voffA);
;             PG8_BAR; PG8_WAIT_L(0); PG8_MMA(1, 0, At, B0); PG8_BAR; PG8_SCHED;
.LBB0_115:
	ds_read_b128 v[136:139], v164
	ds_read_b128 v[168:171], v164 offset:1024
	ds_read_b128 v[172:175], v164 offset:2048
	ds_read_b128 v[176:179], v164 offset:3072
	s_add_u32 s22, s20, 0xfff80080
	s_addc_u32 s23, s21, -1
	s_cmp_eq_u32 s59, 28
	s_cselect_b32 s25, s13, s23
	s_cselect_b32 s24, s51, s22
	s_cselect_b32 s23, s11, s58
	s_cselect_b32 s22, s56, s57
	v_lshl_add_u64 v[212:213], s[20:21], 0, v[128:129]
	s_add_i32 m0, s19, 0xc000
	ds_read_b128 v[180:183], v165
	ds_read_b128 v[184:187], v165 offset:1024
	ds_read_b128 v[188:191], v165 offset:2048
	ds_read_b128 v[192:195], v165 offset:3072
	ds_read_b128 v[196:199], v165 offset:4096
	ds_read_b128 v[200:203], v165 offset:5120
	ds_read_b128 v[204:207], v165 offset:6144
	ds_read_b128 v[208:211], v165 offset:7168
	global_load_lds_dwordx4 v[212:213], off
	v_lshl_add_u64 v[212:213], s[20:21], 0, v[130:131]
	s_add_i32 m0, s19, 0xe000
	s_nop 0
	global_load_lds_dwordx4 v[212:213], off
	s_waitcnt lgkmcnt(8)
	s_barrier
	s_waitcnt lgkmcnt(0)
	s_waitcnt lgkmcnt(0)
	v_mfma_f32_16x16x32_bf16 v[124:127], v[136:139], v[180:183], v[124:127]
	v_mfma_f32_16x16x32_bf16 v[120:123], v[172:175], v[180:183], v[120:123]
	v_mfma_f32_16x16x32_bf16 v[108:111], v[136:139], v[188:191], v[108:111]
	v_mfma_f32_16x16x32_bf16 v[104:107], v[172:175], v[188:191], v[104:107]
	v_mfma_f32_16x16x32_bf16 v[92:95], v[136:139], v[196:199], v[92:95]
	v_mfma_f32_16x16x32_bf16 v[88:91], v[172:175], v[196:199], v[88:91]
	v_mfma_f32_16x16x32_bf16 v[76:79], v[136:139], v[204:207], v[76:79]
	v_mfma_f32_16x16x32_bf16 v[72:75], v[172:175], v[204:207], v[72:75]
	v_mfma_f32_16x16x32_bf16 v[124:127], v[168:171], v[184:187], v[124:127]
	v_mfma_f32_16x16x32_bf16 v[120:123], v[176:179], v[184:187], v[120:123]
	v_mfma_f32_16x16x32_bf16 v[108:111], v[168:171], v[192:195], v[108:111]
	v_mfma_f32_16x16x32_bf16 v[104:107], v[176:179], v[192:195], v[104:107]
	v_mfma_f32_16x16x32_bf16 v[92:95], v[168:171], v[200:203], v[92:95]
	v_mfma_f32_16x16x32_bf16 v[88:91], v[176:179], v[200:203], v[88:91]
	v_mfma_f32_16x16x32_bf16 v[76:79], v[168:171], v[208:211], v[76:79]
	v_mfma_f32_16x16x32_bf16 v[72:75], v[176:179], v[208:211], v[72:75]
	s_barrier
	s_add_i32 s30, s48, s27
	v_lshl_add_u64 v[228:229], s[22:23], 0, v[150:151]
	s_mov_b32 m0, s30
	ds_read_b128 v[212:215], v166
	ds_read_b128 v[216:219], v166 offset:1024
	ds_read_b128 v[220:223], v166 offset:2048
	ds_read_b128 v[224:227], v166 offset:3072
	global_load_lds_dwordx4 v[228:229], off
	v_lshl_add_u64 v[230:231], s[22:23], 0, v[154:155]
	s_add_i32 m0, s30, 0x2000
	s_nop 0
	global_load_lds_dwordx4 v[230:231], off
	s_barrier
	s_waitcnt lgkmcnt(0)
	s_waitcnt lgkmcnt(0)
	v_mfma_f32_16x16x32_bf16 v[116:119], v[212:215], v[180:183], v[116:119]
	v_mfma_f32_16x16x32_bf16 v[112:115], v[220:223], v[180:183], v[112:115]
	v_mfma_f32_16x16x32_bf16 v[100:103], v[212:215], v[188:191], v[100:103]
	v_mfma_f32_16x16x32_bf16 v[96:99], v[220:223], v[188:191], v[96:99]
	v_mfma_f32_16x16x32_bf16 v[84:87], v[212:215], v[196:199], v[84:87]
	v_mfma_f32_16x16x32_bf16 v[80:83], v[220:223], v[196:199], v[80:83]
	v_mfma_f32_16x16x32_bf16 v[68:71], v[212:215], v[204:207], v[68:71]
	v_mfma_f32_16x16x32_bf16 v[64:67], v[220:223], v[204:207], v[64:67]
	v_mfma_f32_16x16x32_bf16 v[116:119], v[216:219], v[184:187], v[116:119]
	v_mfma_f32_16x16x32_bf16 v[112:115], v[224:227], v[184:187], v[112:115]
	v_mfma_f32_16x16x32_bf16 v[100:103], v[216:219], v[192:195], v[100:103]
	v_mfma_f32_16x16x32_bf16 v[96:99], v[224:227], v[192:195], v[96:99]
	v_mfma_f32_16x16x32_bf16 v[84:87], v[216:219], v[200:203], v[84:87]
	v_mfma_f32_16x16x32_bf16 v[80:83], v[224:227], v[200:203], v[80:83]
	v_mfma_f32_16x16x32_bf16 v[68:71], v[216:219], v[208:211], v[68:71]
	v_mfma_f32_16x16x32_bf16 v[64:67], v[224:227], v[208:211], v[64:67]
	s_mov_b32 m0, s19
	v_lshl_add_u64 v[232:233], s[24:25], 0, v[148:149]
	s_barrier
	ds_read_b128 v[180:183], v165 offset:16384
	ds_read_b128 v[184:187], v165 offset:17408
	ds_read_b128 v[188:191], v165 offset:18432
	ds_read_b128 v[192:195], v165 offset:19456
	ds_read_b128 v[196:199], v165 offset:20480
	ds_read_b128 v[200:203], v165 offset:21504
	ds_read_b128 v[204:207], v165 offset:22528
	ds_read_b128 v[208:211], v165 offset:23552
	global_load_lds_dwordx4 v[232:233], off
	v_lshl_add_u64 v[234:235], s[24:25], 0, v[152:153]
	s_mov_b32 m0, s40
	s_nop 0
	global_load_lds_dwordx4 v[234:235], off
	s_barrier
	s_waitcnt lgkmcnt(0)
	s_waitcnt lgkmcnt(0)
	v_mfma_f32_16x16x32_bf16 v[60:63], v[136:139], v[180:183], v[60:63]
	v_mfma_f32_16x16x32_bf16 v[56:59], v[172:175], v[180:183], v[56:59]
	v_mfma_f32_16x16x32_bf16 v[44:47], v[136:139], v[188:191], v[44:47]
	v_mfma_f32_16x16x32_bf16 v[40:43], v[172:175], v[188:191], v[40:43]
	v_mfma_f32_16x16x32_bf16 v[28:31], v[136:139], v[196:199], v[28:31]
	v_mfma_f32_16x16x32_bf16 v[24:27], v[172:175], v[196:199], v[24:27]
	v_mfma_f32_16x16x32_bf16 v[12:15], v[136:139], v[204:207], v[12:15]
	v_mfma_f32_16x16x32_bf16 v[8:11], v[172:175], v[204:207], v[8:11]
	v_mfma_f32_16x16x32_bf16 v[60:63], v[168:171], v[184:187], v[60:63]
	v_mfma_f32_16x16x32_bf16 v[56:59], v[176:179], v[184:187], v[56:59]
	v_mfma_f32_16x16x32_bf16 v[44:47], v[168:171], v[192:195], v[44:47]
	v_mfma_f32_16x16x32_bf16 v[40:43], v[176:179], v[192:195], v[40:43]
	v_mfma_f32_16x16x32_bf16 v[28:31], v[168:171], v[200:203], v[28:31]
	v_mfma_f32_16x16x32_bf16 v[24:27], v[176:179], v[200:203], v[24:27]
	v_mfma_f32_16x16x32_bf16 v[12:15], v[168:171], v[208:211], v[12:15]
	v_mfma_f32_16x16x32_bf16 v[8:11], v[176:179], v[208:211], v[8:11]
	s_barrier
; #define PG8_STAGE(bufoff, gbase, voff) do { _Pragma("unroll") for (int _i = 0; _i < 2; ++_i) \
;         __builtin_amdgcn_global_load_lds((const unsigned*)((const char*)(gbase) + (voff)[_i]), (PG8_LAS unsigned*)(lds + (bufoff) + ldsw + _i * 8192), 16, 0, 0); } while (0)
; #define PG8_LDA(dst, b, h) do { _Pragma("unroll") for (int m = 0; m < 4; ++m) _Pragma("unroll") for (int k = 0; k < 2; ++k) dst[m][k] = *(const PG8_LAS bf16x8*)(lds + PG8_SA(b, h) + aoff + m * 2048 + k * 1024); } while (0)
; #define PG8_LDB(dst, b, h) do { _Pragma("unroll") for (int n = 0; n < 2; ++n) _Pragma("unroll") for (int k = 0; k < 2; ++k) dst[n][k] = *(const PG8_LAS bf16x8*)(lds + PG8_SB(b, h) + boff + n * 2048 + k * 1024); } while (0)
; #define PG8_MMA(ai, bj, At, Bt) do { __builtin_amdgcn_s_setprio(1); _Pragma("unroll") for (int m = 0; m < 4; ++m) _Pragma("unroll") for (int n = 0; n < 2; ++n) _Pragma("unroll") for (int k = 0; k < 2; ++k) \
;         acc[ai][bj][m][n] = __builtin_amdgcn_mfma_f32_16x16x32_bf16(Bt[n][k], At[m][k], acc[ai][bj][m][n], 0, 0, 0); __builtin_amdgcn_s_setprio(0); } while (0)
; #define PG8_WAIT_V(n) asm volatile("s_waitcnt vmcnt(" #n ")" ::: "memory")
; #define PG8_WAIT_L(n) asm volatile("s_waitcnt lgkmcnt(" #n ")" ::: "memory")
; #define PG8_BAR __builtin_amdgcn_s_barrier()
; #define PG8_SCHED __builtin_amdgcn_sched_barrier(0)
; template <class Epi, class Sched>
; __device__ __forceinline__ void gemm_phase(PG8_LAS unsigned char* lds, const Gemm g, const Sched& S, const Epi& E) {
;     ...
;             PG8_STAGE(PG8_SB(0, 1), b2 + hstep, voffB);
;             PG8_WAIT_V(6); PG8_BAR; PG8_MMA(1, 1, At, B1); PG8_BAR;
;             PG8_LDB(B0, 1, 0); PG8_SCHED; PG8_LDA(At, 1, 0); PG8_STAGE(PG8_SA(0, 1), a2 + hstep, voffA);
;             PG8_WAIT_L(8); PG8_BAR; PG8_WAIT_L(0); PG8_MMA(0, 0, At, B0); PG8_BAR; PG8_SCHED;
;             PG8_LDB(B1, 1, 1); PG8_STAGE(PG8_SB(1, 0), b3, voffB);
	s_add_u32 s60, s22, 0x80000
	s_addc_u32 s61, s23, 0
	s_add_i32 s30, s49, s27
	v_lshl_add_u64 v[136:137], s[60:61], 0, v[150:151]
	s_mov_b32 m0, s30
	s_nop 0
	global_load_lds_dwordx4 v[136:137], off
	v_lshl_add_u64 v[136:137], s[60:61], 0, v[154:155]
	s_add_i32 m0, s30, 0x2000
	s_nop 0
	global_load_lds_dwordx4 v[136:137], off
	s_waitcnt vmcnt(6)
	s_barrier
	v_mfma_f32_16x16x32_bf16 v[52:55], v[212:215], v[180:183], v[52:55]
	v_mfma_f32_16x16x32_bf16 v[48:51], v[220:223], v[180:183], v[48:51]
	v_mfma_f32_16x16x32_bf16 v[36:39], v[212:215], v[188:191], v[36:39]
	v_mfma_f32_16x16x32_bf16 v[32:35], v[220:223], v[188:191], v[32:35]
	v_mfma_f32_16x16x32_bf16 v[20:23], v[212:215], v[196:199], v[20:23]
	v_mfma_f32_16x16x32_bf16 v[16:19], v[220:223], v[196:199], v[16:19]
	v_mfma_f32_16x16x32_bf16 v[4:7], v[212:215], v[204:207], v[4:7]
	v_mfma_f32_16x16x32_bf16 v[0:3], v[220:223], v[204:207], v[0:3]
	v_mfma_f32_16x16x32_bf16 v[52:55], v[216:219], v[184:187], v[52:55]
	v_mfma_f32_16x16x32_bf16 v[48:51], v[224:227], v[184:187], v[48:51]
	v_mfma_f32_16x16x32_bf16 v[36:39], v[216:219], v[192:195], v[36:39]
	v_mfma_f32_16x16x32_bf16 v[32:35], v[224:227], v[192:195], v[32:35]
	v_mfma_f32_16x16x32_bf16 v[20:23], v[216:219], v[200:203], v[20:23]
	v_mfma_f32_16x16x32_bf16 v[16:19], v[224:227], v[200:203], v[16:19]
	v_mfma_f32_16x16x32_bf16 v[4:7], v[216:219], v[208:211], v[4:7]
	v_mfma_f32_16x16x32_bf16 v[0:3], v[224:227], v[208:211], v[0:3]
	s_add_i32 s30, 0, 0x18000
	v_add_u32_e32 v167, s30, v159
	s_barrier
	ds_read_b128 v[136:139], v167
	ds_read_b128 v[168:171], v167 offset:1024
	ds_read_b128 v[172:175], v167 offset:2048
	ds_read_b128 v[176:179], v167 offset:3072
	s_add_u32 s24, s24, 0x80000
	s_addc_u32 s25, s25, 0
	s_mov_b32 m0, s41
	v_lshl_add_u64 v[212:213], s[24:25], 0, v[148:149]
	ds_read_b128 v[180:183], v165 offset:32768
	ds_read_b128 v[184:187], v165 offset:33792
	ds_read_b128 v[188:191], v165 offset:34816
	ds_read_b128 v[192:195], v165 offset:35840
	ds_read_b128 v[196:199], v165 offset:36864
	ds_read_b128 v[200:203], v165 offset:37888
	ds_read_b128 v[204:207], v165 offset:38912
	ds_read_b128 v[208:211], v165 offset:39936
	global_load_lds_dwordx4 v[212:213], off
	v_lshl_add_u64 v[212:213], s[24:25], 0, v[152:153]
	s_mov_b32 m0, s42
	s_nop 0
	global_load_lds_dwordx4 v[212:213], off
	s_waitcnt lgkmcnt(8)
	s_barrier
	s_waitcnt lgkmcnt(0)
	s_waitcnt lgkmcnt(0)
	v_mfma_f32_16x16x32_bf16 v[124:127], v[136:139], v[180:183], v[124:127]
	v_mfma_f32_16x16x32_bf16 v[120:123], v[172:175], v[180:183], v[120:123]
	v_mfma_f32_16x16x32_bf16 v[108:111], v[136:139], v[188:191], v[108:111]
	v_mfma_f32_16x16x32_bf16 v[104:107], v[172:175], v[188:191], v[104:107]
	v_mfma_f32_16x16x32_bf16 v[92:95], v[136:139], v[196:199], v[92:95]
	v_mfma_f32_16x16x32_bf16 v[88:91], v[172:175], v[196:199], v[88:91]
	v_mfma_f32_16x16x32_bf16 v[76:79], v[136:139], v[204:207], v[76:79]
	v_mfma_f32_16x16x32_bf16 v[72:75], v[172:175], v[204:207], v[72:75]
	v_mfma_f32_16x16x32_bf16 v[124:127], v[168:171], v[184:187], v[124:127]
	v_mfma_f32_16x16x32_bf16 v[120:123], v[176:179], v[184:187], v[120:123]
	v_mfma_f32_16x16x32_bf16 v[108:111], v[168:171], v[192:195], v[108:111]
	v_mfma_f32_16x16x32_bf16 v[104:107], v[176:179], v[192:195], v[104:107]
	v_mfma_f32_16x16x32_bf16 v[92:95], v[168:171], v[200:203], v[92:95]
	v_mfma_f32_16x16x32_bf16 v[88:91], v[176:179], v[200:203], v[88:91]
	v_mfma_f32_16x16x32_bf16 v[76:79], v[168:171], v[208:211], v[76:79]
	v_mfma_f32_16x16x32_bf16 v[72:75], v[176:179], v[208:211], v[72:75]
	s_barrier
	s_add_i32 s24, 0, 0x1c000
	s_add_i32 s25, s30, s27
	v_add_u32_e32 v167, s24, v159
	v_lshl_add_u64 v[228:229], v[228:229], 0, s[8:9]
	s_mov_b32 m0, s25
	ds_read_b128 v[212:215], v167
	ds_read_b128 v[216:219], v167 offset:1024
	ds_read_b128 v[220:223], v167 offset:2048
	ds_read_b128 v[224:227], v167 offset:3072
	global_load_lds_dwordx4 v[228:229], off
	v_lshl_add_u64 v[228:229], v[230:231], 0, s[8:9]
	s_add_i32 m0, s25, 0x2000
	s_nop 0
	global_load_lds_dwordx4 v[228:229], off
	s_barrier
; #define PG8_STAGE(bufoff, gbase, voff) do { _Pragma("unroll") for (int _i = 0; _i < 2; ++_i) \
;         __builtin_amdgcn_global_load_lds((const unsigned*)((const char*)(gbase) + (voff)[_i]), (PG8_LAS unsigned*)(lds + (bufoff) + ldsw + _i * 8192), 16, 0, 0); } while (0)
; #define PG8_LDA(dst, b, h) do { _Pragma("unroll") for (int m = 0; m < 4; ++m) _Pragma("unroll") for (int k = 0; k < 2; ++k) dst[m][k] = *(const PG8_LAS bf16x8*)(lds + PG8_SA(b, h) + aoff + m * 2048 + k * 1024); } while (0)
; #define PG8_MMA(ai, bj, At, Bt) do { __builtin_amdgcn_s_setprio(1); _Pragma("unroll") for (int m = 0; m < 4; ++m) _Pragma("unroll") for (int n = 0; n < 2; ++n) _Pragma("unroll") for (int k = 0; k < 2; ++k) \
;         acc[ai][bj][m][n] = __builtin_amdgcn_mfma_f32_16x16x32_bf16(Bt[n][k], At[m][k], acc[ai][bj][m][n], 0, 0, 0); __builtin_amdgcn_s_setprio(0); } while (0)
; #define PG8_WAIT_V(n) asm volatile("s_waitcnt vmcnt(" #n ")" ::: "memory")
; #define PG8_WAIT_L(n) asm volatile("s_waitcnt lgkmcnt(" #n ")" ::: "memory")
; #define PG8_BAR __builtin_amdgcn_s_barrier()
; #define PG8_SCHED __builtin_amdgcn_sched_barrier(0)
; template <class Epi, class Sched>
; __device__ __forceinline__ void gemm_phase(PG8_LAS unsigned char* lds, const Gemm g, const Sched& S, const Epi& E) {
;     ...
;             PG8_BAR; PG8_WAIT_L(0); PG8_MMA(0, 1, At, B1); PG8_BAR;
;             PG8_LDA(At, 1, 1); PG8_STAGE(PG8_SA(1, 0), a3, voffA);
;             PG8_BAR; PG8_WAIT_L(0); PG8_MMA(1, 0, At, B0); PG8_BAR; PG8_SCHED;
;             PG8_STAGE(PG8_SB(1, 1), b3 + hstep, voffB);
;             PG8_WAIT_V(6); PG8_BAR; PG8_MMA(1, 1, At, B1); PG8_BAR;
;         }
;     __device__ __forceinline__ void operator()(AccRef acc, const Unit& u, int wr, int wc, int fr, int fq) const {
;         const int pi = u.pn / tpp; bf16_t* base = pi == 0 ? pl[0] : (pi == 1 ? pl[1] : (pi == 2 ? pl[2] : pl[3]));
	s_waitcnt lgkmcnt(0)
	s_waitcnt lgkmcnt(0)
	v_mfma_f32_16x16x32_bf16 v[116:119], v[212:215], v[180:183], v[116:119]
	v_mfma_f32_16x16x32_bf16 v[112:115], v[220:223], v[180:183], v[112:115]
	v_mfma_f32_16x16x32_bf16 v[100:103], v[212:215], v[188:191], v[100:103]
	v_mfma_f32_16x16x32_bf16 v[96:99], v[220:223], v[188:191], v[96:99]
	v_mfma_f32_16x16x32_bf16 v[84:87], v[212:215], v[196:199], v[84:87]
	v_mfma_f32_16x16x32_bf16 v[80:83], v[220:223], v[196:199], v[80:83]
	v_mfma_f32_16x16x32_bf16 v[68:71], v[212:215], v[204:207], v[68:71]
	v_mfma_f32_16x16x32_bf16 v[64:67], v[220:223], v[204:207], v[64:67]
	v_mfma_f32_16x16x32_bf16 v[116:119], v[216:219], v[184:187], v[116:119]
	v_mfma_f32_16x16x32_bf16 v[112:115], v[224:227], v[184:187], v[112:115]
	v_mfma_f32_16x16x32_bf16 v[100:103], v[216:219], v[192:195], v[100:103]
	v_mfma_f32_16x16x32_bf16 v[96:99], v[224:227], v[192:195], v[96:99]
	v_mfma_f32_16x16x32_bf16 v[84:87], v[216:219], v[200:203], v[84:87]
	v_mfma_f32_16x16x32_bf16 v[80:83], v[224:227], v[200:203], v[80:83]
	v_mfma_f32_16x16x32_bf16 v[68:71], v[216:219], v[208:211], v[68:71]
	v_mfma_f32_16x16x32_bf16 v[64:67], v[224:227], v[208:211], v[64:67]
	s_mov_b32 m0, s44
	v_lshl_add_u64 v[228:229], v[232:233], 0, s[8:9]
	s_barrier
	ds_read_b128 v[180:183], v165 offset:49152
	ds_read_b128 v[184:187], v165 offset:50176
	ds_read_b128 v[188:191], v165 offset:51200
	ds_read_b128 v[192:195], v165 offset:52224
	ds_read_b128 v[196:199], v165 offset:53248
	ds_read_b128 v[200:203], v165 offset:54272
	ds_read_b128 v[204:207], v165 offset:55296
	ds_read_b128 v[208:211], v165 offset:56320
	global_load_lds_dwordx4 v[228:229], off
	v_lshl_add_u64 v[228:229], v[234:235], 0, s[8:9]
	s_mov_b32 m0, s45
	s_nop 0
	global_load_lds_dwordx4 v[228:229], off
	s_barrier
	s_waitcnt lgkmcnt(0)
	s_waitcnt lgkmcnt(0)
	v_mfma_f32_16x16x32_bf16 v[60:63], v[136:139], v[180:183], v[60:63]
	v_mfma_f32_16x16x32_bf16 v[56:59], v[172:175], v[180:183], v[56:59]
	v_mfma_f32_16x16x32_bf16 v[44:47], v[136:139], v[188:191], v[44:47]
	v_mfma_f32_16x16x32_bf16 v[40:43], v[172:175], v[188:191], v[40:43]
	v_mfma_f32_16x16x32_bf16 v[28:31], v[136:139], v[196:199], v[28:31]
	v_mfma_f32_16x16x32_bf16 v[24:27], v[172:175], v[196:199], v[24:27]
	v_mfma_f32_16x16x32_bf16 v[12:15], v[136:139], v[204:207], v[12:15]
	v_mfma_f32_16x16x32_bf16 v[8:11], v[172:175], v[204:207], v[8:11]
	v_mfma_f32_16x16x32_bf16 v[60:63], v[168:171], v[184:187], v[60:63]
	v_mfma_f32_16x16x32_bf16 v[56:59], v[176:179], v[184:187], v[56:59]
	v_mfma_f32_16x16x32_bf16 v[44:47], v[168:171], v[192:195], v[44:47]
	v_mfma_f32_16x16x32_bf16 v[40:43], v[176:179], v[192:195], v[40:43]
	v_mfma_f32_16x16x32_bf16 v[28:31], v[168:171], v[200:203], v[28:31]
	v_mfma_f32_16x16x32_bf16 v[24:27], v[176:179], v[200:203], v[24:27]
	v_mfma_f32_16x16x32_bf16 v[12:15], v[168:171], v[208:211], v[12:15]
	v_mfma_f32_16x16x32_bf16 v[8:11], v[176:179], v[208:211], v[8:11]
	s_barrier
	s_add_u32 s22, s22, 0x80080
	s_addc_u32 s23, s23, 0
	s_add_i32 s24, s24, s27
	v_lshl_add_u64 v[136:137], s[22:23], 0, v[150:151]
	s_mov_b32 m0, s24
	s_nop 0
	global_load_lds_dwordx4 v[136:137], off
	v_lshl_add_u64 v[136:137], s[22:23], 0, v[154:155]
	s_add_i32 m0, s24, 0x2000
	s_nop 0
	global_load_lds_dwordx4 v[136:137], off
	s_waitcnt vmcnt(6)
	s_barrier
	v_mfma_f32_16x16x32_bf16 v[52:55], v[212:215], v[180:183], v[52:55]
	v_mfma_f32_16x16x32_bf16 v[48:51], v[220:223], v[180:183], v[48:51]
	v_mfma_f32_16x16x32_bf16 v[36:39], v[212:215], v[188:191], v[36:39]
	v_mfma_f32_16x16x32_bf16 v[32:35], v[220:223], v[188:191], v[32:35]
	v_mfma_f32_16x16x32_bf16 v[20:23], v[212:215], v[196:199], v[20:23]
	v_mfma_f32_16x16x32_bf16 v[16:19], v[220:223], v[196:199], v[16:19]
	v_mfma_f32_16x16x32_bf16 v[4:7], v[212:215], v[204:207], v[4:7]
	v_mfma_f32_16x16x32_bf16 v[0:3], v[220:223], v[204:207], v[0:3]
	v_mfma_f32_16x16x32_bf16 v[52:55], v[216:219], v[184:187], v[52:55]
	v_mfma_f32_16x16x32_bf16 v[48:51], v[224:227], v[184:187], v[48:51]
	v_mfma_f32_16x16x32_bf16 v[36:39], v[216:219], v[192:195], v[36:39]
	v_mfma_f32_16x16x32_bf16 v[32:35], v[224:227], v[192:195], v[32:35]
	v_mfma_f32_16x16x32_bf16 v[20:23], v[216:219], v[200:203], v[20:23]
	v_mfma_f32_16x16x32_bf16 v[16:19], v[224:227], v[200:203], v[16:19]
	v_mfma_f32_16x16x32_bf16 v[4:7], v[216:219], v[208:211], v[4:7]
	v_mfma_f32_16x16x32_bf16 v[0:3], v[224:227], v[208:211], v[0:3]
	s_add_i32 s59, s59, 2
	s_add_u32 s20, s20, 0x100
	s_addc_u32 s21, s21, 0
	s_add_u32 s57, s57, 0x100
	s_addc_u32 s58, s58, 0
	s_cmp_gt_u32 s59, 29
	s_barrier
	s_cbranch_scc0 .LBB0_115
	s_ashr_i32 s11, s50, 31
	s_lshr_b32 s11, s11, 30
	s_add_i32 s11, s50, s11
	s_ashr_i32 s13, s11, 2
	s_cmp_lt_i32 s13, 1
	s_cbranch_scc1 .LBB0_120
	s_cmp_gt_i32 s13, 1
	s_mov_b64 s[24:25], 0
	s_mov_b64 s[20:21], s[88:89]
	s_mov_b64 s[22:23], 0
	s_cbranch_scc0 .LBB0_121
	s_cmp_eq_u32 s13, 2
	s_mov_b64 s[22:23], -1
	s_cbranch_scc0 .LBB0_125
	s_mov_b64 s[22:23], 0
	s_mov_b64 s[20:21], s[0:1]
	s_and_b64 vcc, exec, s[24:25]
	s_cbranch_vccnz .LBB0_122
	s_branch .LBB0_123

; #define PG8_STAGE(bufoff, gbase, voff) do { _Pragma("unroll") for (int _i = 0; _i < 2; ++_i) \
;         __builtin_amdgcn_global_load_lds((const unsigned*)((const char*)(gbase) + (voff)[_i]), (PG8_LAS unsigned*)(lds + (bufoff) + ldsw + _i * 8192), 16, 0, 0); } while (0)
; #define PG8_LDA(dst, b, h) do { _Pragma("unroll") for (int m = 0; m < 4; ++m) _Pragma("unroll") for (int k = 0; k < 2; ++k) dst[m][k] = *(const PG8_LAS bf16x8*)(lds + PG8_SA(b, h) + aoff + m * 2048 + k * 1024); } while (0)
; #define PG8_LDB(dst, b, h) do { _Pragma("unroll") for (int n = 0; n < 2; ++n) _Pragma("unroll") for (int k = 0; k < 2; ++k) dst[n][k] = *(const PG8_LAS bf16x8*)(lds + PG8_SB(b, h) + boff + n * 2048 + k * 1024); } while (0)
; #define PG8_MMA(ai, bj, At, Bt) do { __builtin_amdgcn_s_setprio(1); _Pragma("unroll") for (int m = 0; m < 4; ++m) _Pragma("unroll") for (int n = 0; n < 2; ++n) _Pragma("unroll") for (int k = 0; k < 2; ++k) \
;         acc[ai][bj][m][n] = __builtin_amdgcn_mfma_f32_16x16x32_bf16(Bt[n][k], At[m][k], acc[ai][bj][m][n], 0, 0, 0); __builtin_amdgcn_s_setprio(0); } while (0)
; #define PG8_WAIT_L(n) asm volatile("s_waitcnt lgkmcnt(" #n ")" ::: "memory")
; #define PG8_BAR __builtin_amdgcn_s_barrier()
; #define PG8_SCHED __builtin_amdgcn_sched_barrier(0)
; template <class Epi, class Sched>
; __device__ __forceinline__ void gemm_phase(PG8_LAS unsigned char* lds, const Gemm g, const Sched& S, const Epi& E) {
;     ...
;             PG8_LDB(B0, 0, 0); PG8_SCHED; PG8_LDA(At, 0, 0); PG8_STAGE(PG8_SA(1, 1), a1 + hstep, voffA);
;             PG8_WAIT_L(8); PG8_BAR; PG8_WAIT_L(0); PG8_MMA(0, 0, At, B0); PG8_BAR; PG8_SCHED;
;             PG8_LDB(B1, 0, 1); PG8_STAGE(PG8_SB(0, 0), b2, voffB);
;             PG8_BAR; PG8_WAIT_L(0); PG8_MMA(0, 1, At, B1); PG8_BAR;
;             PG8_LDA(At, 0, 1); PG8_STAGE(PG8_SA(0, 0), a2, voffA);
;             PG8_BAR; PG8_WAIT_L(0); PG8_MMA(1, 0, At, B0); PG8_BAR; PG8_SCHED;
.LBB0_144:
	ds_read_b128 v[128:131], v145
	ds_read_b128 v[132:135], v145 offset:1024
	ds_read_b128 v[136:139], v145 offset:2048
	ds_read_b128 v[140:143], v145 offset:3072
	s_add_u32 s20, s18, 0xfff80080
	s_addc_u32 s21, s19, -1
	s_cmp_eq_u32 s59, 28
	s_cselect_b32 s23, s11, s21
	s_cselect_b32 s22, s51, s20
	s_cselect_b32 s21, s9, s58
	s_cselect_b32 s20, s56, s57
	v_lshl_add_u64 v[200:201], s[18:19], 0, v[156:157]
	s_add_i32 m0, s17, 0xc000
	ds_read_b128 v[164:167], v170
	ds_read_b128 v[172:175], v170 offset:1024
	ds_read_b128 v[176:179], v170 offset:2048
	ds_read_b128 v[180:183], v170 offset:3072
	ds_read_b128 v[184:187], v170 offset:4096
	ds_read_b128 v[188:191], v170 offset:5120
	ds_read_b128 v[192:195], v170 offset:6144
	ds_read_b128 v[196:199], v170 offset:7168
	global_load_lds_dwordx4 v[200:201], off
	v_lshl_add_u64 v[200:201], s[18:19], 0, v[158:159]
	s_add_i32 m0, s17, 0xe000
	s_nop 0
	global_load_lds_dwordx4 v[200:201], off
	s_waitcnt lgkmcnt(8)
	s_barrier
	s_waitcnt lgkmcnt(0)
	s_waitcnt lgkmcnt(0)
	v_mfma_f32_16x16x32_bf16 v[124:127], v[128:131], v[164:167], v[124:127]
	v_mfma_f32_16x16x32_bf16 v[120:123], v[136:139], v[164:167], v[120:123]
	v_mfma_f32_16x16x32_bf16 v[116:119], v[128:131], v[176:179], v[116:119]
	v_mfma_f32_16x16x32_bf16 v[112:115], v[136:139], v[176:179], v[112:115]
	v_mfma_f32_16x16x32_bf16 v[108:111], v[128:131], v[184:187], v[108:111]
	v_mfma_f32_16x16x32_bf16 v[100:103], v[136:139], v[184:187], v[100:103]
	v_mfma_f32_16x16x32_bf16 v[92:95], v[128:131], v[192:195], v[92:95]
	v_mfma_f32_16x16x32_bf16 v[80:83], v[136:139], v[192:195], v[80:83]
	v_mfma_f32_16x16x32_bf16 v[124:127], v[132:135], v[172:175], v[124:127]
	v_mfma_f32_16x16x32_bf16 v[120:123], v[140:143], v[172:175], v[120:123]
	v_mfma_f32_16x16x32_bf16 v[116:119], v[132:135], v[180:183], v[116:119]
	v_mfma_f32_16x16x32_bf16 v[112:115], v[140:143], v[180:183], v[112:115]
	v_mfma_f32_16x16x32_bf16 v[108:111], v[132:135], v[188:191], v[108:111]
	v_mfma_f32_16x16x32_bf16 v[100:103], v[140:143], v[188:191], v[100:103]
	v_mfma_f32_16x16x32_bf16 v[92:95], v[132:135], v[196:199], v[92:95]
	v_mfma_f32_16x16x32_bf16 v[80:83], v[140:143], v[196:199], v[80:83]
	s_barrier
	s_add_i32 s30, s48, s27
	v_lshl_add_u64 v[216:217], s[20:21], 0, v[150:151]
	s_mov_b32 m0, s30
	ds_read_b128 v[200:203], v171
	ds_read_b128 v[204:207], v171 offset:1024
	ds_read_b128 v[208:211], v171 offset:2048
	ds_read_b128 v[212:215], v171 offset:3072
	global_load_lds_dwordx4 v[216:217], off
	v_lshl_add_u64 v[218:219], s[20:21], 0, v[154:155]
	s_add_i32 m0, s30, 0x2000
	s_nop 0
	global_load_lds_dwordx4 v[218:219], off
	s_barrier
	s_waitcnt lgkmcnt(0)
	s_waitcnt lgkmcnt(0)
	v_mfma_f32_16x16x32_bf16 v[104:107], v[200:203], v[164:167], v[104:107]
	v_mfma_f32_16x16x32_bf16 v[96:99], v[208:211], v[164:167], v[96:99]
	v_mfma_f32_16x16x32_bf16 v[88:91], v[200:203], v[176:179], v[88:91]
	v_mfma_f32_16x16x32_bf16 v[84:87], v[208:211], v[176:179], v[84:87]
	v_mfma_f32_16x16x32_bf16 v[76:79], v[200:203], v[184:187], v[76:79]
	v_mfma_f32_16x16x32_bf16 v[72:75], v[208:211], v[184:187], v[72:75]
	v_mfma_f32_16x16x32_bf16 v[68:71], v[200:203], v[192:195], v[68:71]
	v_mfma_f32_16x16x32_bf16 v[64:67], v[208:211], v[192:195], v[64:67]
	v_mfma_f32_16x16x32_bf16 v[104:107], v[204:207], v[172:175], v[104:107]
	v_mfma_f32_16x16x32_bf16 v[96:99], v[212:215], v[172:175], v[96:99]
	v_mfma_f32_16x16x32_bf16 v[88:91], v[204:207], v[180:183], v[88:91]
	v_mfma_f32_16x16x32_bf16 v[84:87], v[212:215], v[180:183], v[84:87]
	v_mfma_f32_16x16x32_bf16 v[76:79], v[204:207], v[188:191], v[76:79]
	v_mfma_f32_16x16x32_bf16 v[72:75], v[212:215], v[188:191], v[72:75]
	v_mfma_f32_16x16x32_bf16 v[68:71], v[204:207], v[196:199], v[68:71]
	v_mfma_f32_16x16x32_bf16 v[64:67], v[212:215], v[196:199], v[64:67]
	s_mov_b32 m0, s17
	v_lshl_add_u64 v[220:221], s[22:23], 0, v[148:149]
	s_barrier
	ds_read_b128 v[164:167], v170 offset:16384
	ds_read_b128 v[172:175], v170 offset:17408
	ds_read_b128 v[176:179], v170 offset:18432
	ds_read_b128 v[180:183], v170 offset:19456
	ds_read_b128 v[184:187], v170 offset:20480
	ds_read_b128 v[188:191], v170 offset:21504
	ds_read_b128 v[192:195], v170 offset:22528
	ds_read_b128 v[196:199], v170 offset:23552
	global_load_lds_dwordx4 v[220:221], off
	v_lshl_add_u64 v[222:223], s[22:23], 0, v[152:153]
	s_mov_b32 m0, s40
	s_nop 0
	global_load_lds_dwordx4 v[222:223], off
	s_barrier
	s_waitcnt lgkmcnt(0)
	s_waitcnt lgkmcnt(0)
	v_mfma_f32_16x16x32_bf16 v[60:63], v[128:131], v[164:167], v[60:63]
	v_mfma_f32_16x16x32_bf16 v[56:59], v[136:139], v[164:167], v[56:59]
	v_mfma_f32_16x16x32_bf16 v[48:51], v[128:131], v[176:179], v[48:51]
	v_mfma_f32_16x16x32_bf16 v[40:43], v[136:139], v[176:179], v[40:43]
	v_mfma_f32_16x16x32_bf16 v[32:35], v[128:131], v[184:187], v[32:35]
	v_mfma_f32_16x16x32_bf16 v[24:27], v[136:139], v[184:187], v[24:27]
	v_mfma_f32_16x16x32_bf16 v[16:19], v[128:131], v[192:195], v[16:19]
	v_mfma_f32_16x16x32_bf16 v[8:11], v[136:139], v[192:195], v[8:11]
	v_mfma_f32_16x16x32_bf16 v[60:63], v[132:135], v[172:175], v[60:63]
	v_mfma_f32_16x16x32_bf16 v[56:59], v[140:143], v[172:175], v[56:59]
	v_mfma_f32_16x16x32_bf16 v[48:51], v[132:135], v[180:183], v[48:51]
	v_mfma_f32_16x16x32_bf16 v[40:43], v[140:143], v[180:183], v[40:43]
	v_mfma_f32_16x16x32_bf16 v[32:35], v[132:135], v[188:191], v[32:35]
	v_mfma_f32_16x16x32_bf16 v[24:27], v[140:143], v[188:191], v[24:27]
	v_mfma_f32_16x16x32_bf16 v[16:19], v[132:135], v[196:199], v[16:19]
	v_mfma_f32_16x16x32_bf16 v[8:11], v[140:143], v[196:199], v[8:11]
	s_barrier
; #define PG8_STAGE(bufoff, gbase, voff) do { _Pragma("unroll") for (int _i = 0; _i < 2; ++_i) \
;         __builtin_amdgcn_global_load_lds((const unsigned*)((const char*)(gbase) + (voff)[_i]), (PG8_LAS unsigned*)(lds + (bufoff) + ldsw + _i * 8192), 16, 0, 0); } while (0)
; #define PG8_LDA(dst, b, h) do { _Pragma("unroll") for (int m = 0; m < 4; ++m) _Pragma("unroll") for (int k = 0; k < 2; ++k) dst[m][k] = *(const PG8_LAS bf16x8*)(lds + PG8_SA(b, h) + aoff + m * 2048 + k * 1024); } while (0)
; #define PG8_LDB(dst, b, h) do { _Pragma("unroll") for (int n = 0; n < 2; ++n) _Pragma("unroll") for (int k = 0; k < 2; ++k) dst[n][k] = *(const PG8_LAS bf16x8*)(lds + PG8_SB(b, h) + boff + n * 2048 + k * 1024); } while (0)
; #define PG8_MMA(ai, bj, At, Bt) do { __builtin_amdgcn_s_setprio(1); _Pragma("unroll") for (int m = 0; m < 4; ++m) _Pragma("unroll") for (int n = 0; n < 2; ++n) _Pragma("unroll") for (int k = 0; k < 2; ++k) \
;         acc[ai][bj][m][n] = __builtin_amdgcn_mfma_f32_16x16x32_bf16(Bt[n][k], At[m][k], acc[ai][bj][m][n], 0, 0, 0); __builtin_amdgcn_s_setprio(0); } while (0)
; #define PG8_WAIT_V(n) asm volatile("s_waitcnt vmcnt(" #n ")" ::: "memory")
; #define PG8_WAIT_L(n) asm volatile("s_waitcnt lgkmcnt(" #n ")" ::: "memory")
; #define PG8_BAR __builtin_amdgcn_s_barrier()
; #define PG8_SCHED __builtin_amdgcn_sched_barrier(0)
; template <class Epi, class Sched>
; __device__ __forceinline__ void gemm_phase(PG8_LAS unsigned char* lds, const Gemm g, const Sched& S, const Epi& E) {
;     ...
;             PG8_STAGE(PG8_SB(0, 1), b2 + hstep, voffB);
;             PG8_WAIT_V(6); PG8_BAR; PG8_MMA(1, 1, At, B1); PG8_BAR;
;             PG8_LDB(B0, 1, 0); PG8_SCHED; PG8_LDA(At, 1, 0); PG8_STAGE(PG8_SA(0, 1), a2 + hstep, voffA);
;             PG8_WAIT_L(8); PG8_BAR; PG8_WAIT_L(0); PG8_MMA(0, 0, At, B0); PG8_BAR; PG8_SCHED;
;             PG8_LDB(B1, 1, 1); PG8_STAGE(PG8_SB(1, 0), b3, voffB);
;             PG8_BAR; PG8_WAIT_L(0); PG8_MMA(0, 1, At, B1); PG8_BAR;
;             PG8_LDA(At, 1, 1); PG8_STAGE(PG8_SA(1, 0), a3, voffA);
	s_add_u32 s60, s20, 0x80000
	s_addc_u32 s61, s21, 0
	s_add_i32 s30, s49, s27
	v_lshl_add_u64 v[128:129], s[60:61], 0, v[150:151]
	s_mov_b32 m0, s30
	s_nop 0
	global_load_lds_dwordx4 v[128:129], off
	v_lshl_add_u64 v[128:129], s[60:61], 0, v[154:155]
	s_add_i32 m0, s30, 0x2000
	s_nop 0
	global_load_lds_dwordx4 v[128:129], off
	s_waitcnt vmcnt(6)
	s_barrier
	v_mfma_f32_16x16x32_bf16 v[52:55], v[200:203], v[164:167], v[52:55]
	v_mfma_f32_16x16x32_bf16 v[44:47], v[208:211], v[164:167], v[44:47]
	v_mfma_f32_16x16x32_bf16 v[36:39], v[200:203], v[176:179], v[36:39]
	v_mfma_f32_16x16x32_bf16 v[28:31], v[208:211], v[176:179], v[28:31]
	v_mfma_f32_16x16x32_bf16 v[20:23], v[200:203], v[184:187], v[20:23]
	v_mfma_f32_16x16x32_bf16 v[12:15], v[208:211], v[184:187], v[12:15]
	v_mfma_f32_16x16x32_bf16 v[4:7], v[200:203], v[192:195], v[4:7]
	v_mfma_f32_16x16x32_bf16 v[0:3], v[208:211], v[192:195], v[0:3]
	v_mfma_f32_16x16x32_bf16 v[52:55], v[204:207], v[172:175], v[52:55]
	v_mfma_f32_16x16x32_bf16 v[44:47], v[212:215], v[172:175], v[44:47]
	v_mfma_f32_16x16x32_bf16 v[36:39], v[204:207], v[180:183], v[36:39]
	v_mfma_f32_16x16x32_bf16 v[28:31], v[212:215], v[180:183], v[28:31]
	v_mfma_f32_16x16x32_bf16 v[20:23], v[204:207], v[188:191], v[20:23]
	v_mfma_f32_16x16x32_bf16 v[12:15], v[212:215], v[188:191], v[12:15]
	v_mfma_f32_16x16x32_bf16 v[4:7], v[204:207], v[196:199], v[4:7]
	v_mfma_f32_16x16x32_bf16 v[0:3], v[212:215], v[196:199], v[0:3]
	s_add_i32 s30, 0, 0x18000
	v_add_u32_e32 v140, s30, v147
	s_barrier
	ds_read_b128 v[128:131], v140
	ds_read_b128 v[132:135], v140 offset:1024
	ds_read_b128 v[136:139], v140 offset:2048
	ds_read_b128 v[140:143], v140 offset:3072
	s_add_u32 s22, s22, 0x80000
	s_addc_u32 s23, s23, 0
	s_mov_b32 m0, s41
	v_lshl_add_u64 v[200:201], s[22:23], 0, v[148:149]
	ds_read_b128 v[164:167], v170 offset:32768
	ds_read_b128 v[172:175], v170 offset:33792
	ds_read_b128 v[176:179], v170 offset:34816
	ds_read_b128 v[180:183], v170 offset:35840
	ds_read_b128 v[184:187], v170 offset:36864
	ds_read_b128 v[188:191], v170 offset:37888
	ds_read_b128 v[192:195], v170 offset:38912
	ds_read_b128 v[196:199], v170 offset:39936
	global_load_lds_dwordx4 v[200:201], off
	v_lshl_add_u64 v[200:201], s[22:23], 0, v[152:153]
	s_mov_b32 m0, s42
	s_nop 0
	global_load_lds_dwordx4 v[200:201], off
	s_waitcnt lgkmcnt(8)
	s_barrier
	s_waitcnt lgkmcnt(0)
	s_waitcnt lgkmcnt(0)
	v_mfma_f32_16x16x32_bf16 v[124:127], v[128:131], v[164:167], v[124:127]
	v_mfma_f32_16x16x32_bf16 v[120:123], v[136:139], v[164:167], v[120:123]
	v_mfma_f32_16x16x32_bf16 v[116:119], v[128:131], v[176:179], v[116:119]
	v_mfma_f32_16x16x32_bf16 v[112:115], v[136:139], v[176:179], v[112:115]
	v_mfma_f32_16x16x32_bf16 v[108:111], v[128:131], v[184:187], v[108:111]
	v_mfma_f32_16x16x32_bf16 v[100:103], v[136:139], v[184:187], v[100:103]
	v_mfma_f32_16x16x32_bf16 v[92:95], v[128:131], v[192:195], v[92:95]
	v_mfma_f32_16x16x32_bf16 v[80:83], v[136:139], v[192:195], v[80:83]
	v_mfma_f32_16x16x32_bf16 v[124:127], v[132:135], v[172:175], v[124:127]
	v_mfma_f32_16x16x32_bf16 v[120:123], v[140:143], v[172:175], v[120:123]
	v_mfma_f32_16x16x32_bf16 v[116:119], v[132:135], v[180:183], v[116:119]
	v_mfma_f32_16x16x32_bf16 v[112:115], v[140:143], v[180:183], v[112:115]
	v_mfma_f32_16x16x32_bf16 v[108:111], v[132:135], v[188:191], v[108:111]
	v_mfma_f32_16x16x32_bf16 v[100:103], v[140:143], v[188:191], v[100:103]
	v_mfma_f32_16x16x32_bf16 v[92:95], v[132:135], v[196:199], v[92:95]
	v_mfma_f32_16x16x32_bf16 v[80:83], v[140:143], v[196:199], v[80:83]
	s_barrier
	s_add_i32 s22, 0, 0x1c000
	s_add_i32 s23, s30, s27
	v_add_u32_e32 v212, s22, v147
	v_lshl_add_u64 v[216:217], v[216:217], 0, s[6:7]
	s_mov_b32 m0, s23
	ds_read_b128 v[200:203], v212
	ds_read_b128 v[204:207], v212 offset:1024
	ds_read_b128 v[208:211], v212 offset:2048
	ds_read_b128 v[212:215], v212 offset:3072
	global_load_lds_dwordx4 v[216:217], off
	v_lshl_add_u64 v[216:217], v[218:219], 0, s[6:7]
	s_add_i32 m0, s23, 0x2000
	s_nop 0
	global_load_lds_dwordx4 v[216:217], off
	s_barrier
	s_waitcnt lgkmcnt(0)
	s_waitcnt lgkmcnt(0)
	v_mfma_f32_16x16x32_bf16 v[104:107], v[200:203], v[164:167], v[104:107]
	v_mfma_f32_16x16x32_bf16 v[96:99], v[208:211], v[164:167], v[96:99]
	v_mfma_f32_16x16x32_bf16 v[88:91], v[200:203], v[176:179], v[88:91]
	v_mfma_f32_16x16x32_bf16 v[84:87], v[208:211], v[176:179], v[84:87]
	v_mfma_f32_16x16x32_bf16 v[76:79], v[200:203], v[184:187], v[76:79]
	v_mfma_f32_16x16x32_bf16 v[72:75], v[208:211], v[184:187], v[72:75]
	v_mfma_f32_16x16x32_bf16 v[68:71], v[200:203], v[192:195], v[68:71]
	v_mfma_f32_16x16x32_bf16 v[64:67], v[208:211], v[192:195], v[64:67]
	v_mfma_f32_16x16x32_bf16 v[104:107], v[204:207], v[172:175], v[104:107]
	v_mfma_f32_16x16x32_bf16 v[96:99], v[212:215], v[172:175], v[96:99]
	v_mfma_f32_16x16x32_bf16 v[88:91], v[204:207], v[180:183], v[88:91]
	v_mfma_f32_16x16x32_bf16 v[84:87], v[212:215], v[180:183], v[84:87]
	v_mfma_f32_16x16x32_bf16 v[76:79], v[204:207], v[188:191], v[76:79]
	v_mfma_f32_16x16x32_bf16 v[72:75], v[212:215], v[188:191], v[72:75]
	v_mfma_f32_16x16x32_bf16 v[68:71], v[204:207], v[196:199], v[68:71]
	v_mfma_f32_16x16x32_bf16 v[64:67], v[212:215], v[196:199], v[64:67]
	s_mov_b32 m0, s44
	v_lshl_add_u64 v[216:217], v[220:221], 0, s[6:7]
	s_barrier
	ds_read_b128 v[164:167], v170 offset:49152
	ds_read_b128 v[172:175], v170 offset:50176
	ds_read_b128 v[176:179], v170 offset:51200
	ds_read_b128 v[180:183], v170 offset:52224
	ds_read_b128 v[184:187], v170 offset:53248
	ds_read_b128 v[188:191], v170 offset:54272
	ds_read_b128 v[192:195], v170 offset:55296
	ds_read_b128 v[196:199], v170 offset:56320
	global_load_lds_dwordx4 v[216:217], off
	v_lshl_add_u64 v[216:217], v[222:223], 0, s[6:7]
	s_mov_b32 m0, s45
	s_nop 0
	global_load_lds_dwordx4 v[216:217], off
	s_barrier
; #define PG8_STAGE(bufoff, gbase, voff) do { _Pragma("unroll") for (int _i = 0; _i < 2; ++_i) \
;         __builtin_amdgcn_global_load_lds((const unsigned*)((const char*)(gbase) + (voff)[_i]), (PG8_LAS unsigned*)(lds + (bufoff) + ldsw + _i * 8192), 16, 0, 0); } while (0)
; #define PG8_MMA(ai, bj, At, Bt) do { __builtin_amdgcn_s_setprio(1); _Pragma("unroll") for (int m = 0; m < 4; ++m) _Pragma("unroll") for (int n = 0; n < 2; ++n) _Pragma("unroll") for (int k = 0; k < 2; ++k) \
;         acc[ai][bj][m][n] = __builtin_amdgcn_mfma_f32_16x16x32_bf16(Bt[n][k], At[m][k], acc[ai][bj][m][n], 0, 0, 0); __builtin_amdgcn_s_setprio(0); } while (0)
; #define PG8_WAIT_V(n) asm volatile("s_waitcnt vmcnt(" #n ")" ::: "memory")
; #define PG8_WAIT_L(n) asm volatile("s_waitcnt lgkmcnt(" #n ")" ::: "memory")
; #define PG8_BAR __builtin_amdgcn_s_barrier()
; #define PG8_SCHED __builtin_amdgcn_sched_barrier(0)
; __device__ __forceinline__ uint4 pk8(f32x4 a, f32x4 b) { return make_uint4(cvt_pk_bf16(a[0], a[1]), cvt_pk_bf16(a[2], a[3]), cvt_pk_bf16(b[0], b[1]), cvt_pk_bf16(b[2], b[3])); }
; template <class Epi, class Sched>
; __device__ __forceinline__ void gemm_phase(PG8_LAS unsigned char* lds, const Gemm g, const Sched& S, const Epi& E) {
;     ...
;             PG8_BAR; PG8_WAIT_L(0); PG8_MMA(1, 0, At, B0); PG8_BAR; PG8_SCHED;
;             PG8_STAGE(PG8_SB(1, 1), b3 + hstep, voffB);
;             PG8_WAIT_V(6); PG8_BAR; PG8_MMA(1, 1, At, B1); PG8_BAR;
;     __device__ __forceinline__ void operator()(AccRef acc, const Unit& u, int wr, int wc, int fr, int fq) const {
;         const int c0 = u.pn * 256 + wc * 32 + 8 * fq;
;         f32x4 sc[2][2];
; #pragma unroll
;         for (int bj = 0; bj < 2; ++bj)
; #pragma unroll
;             for (int n = 0; n < 2; ++n) sc[bj][n] = *(const f32x4*)(rinv + c0 + bj * 128 + n * 4);
; #pragma unroll
;         for (int ai = 0; ai < 2; ++ai)
; #pragma unroll
;             for (int m = 0; m < 4; ++m) {
;                 const int r = u.pm * 256 + ai * 128 + wr * 64 + m * 16 + fr;
;                 bf16_t* rowp = O + (size_t)r * T + c0;
; #pragma unroll
;                 for (int bj = 0; bj < 2; ++bj) *(uint4*)(rowp + bj * 128) = pk8(acc[ai][bj][m][0] * sc[bj][0], acc[ai][bj][m][1] * sc[bj][1]);
;             }
;     }
	s_waitcnt lgkmcnt(0)
	s_waitcnt lgkmcnt(0)
	v_mfma_f32_16x16x32_bf16 v[60:63], v[128:131], v[164:167], v[60:63]
	v_mfma_f32_16x16x32_bf16 v[56:59], v[136:139], v[164:167], v[56:59]
	v_mfma_f32_16x16x32_bf16 v[48:51], v[128:131], v[176:179], v[48:51]
	v_mfma_f32_16x16x32_bf16 v[40:43], v[136:139], v[176:179], v[40:43]
	v_mfma_f32_16x16x32_bf16 v[32:35], v[128:131], v[184:187], v[32:35]
	v_mfma_f32_16x16x32_bf16 v[24:27], v[136:139], v[184:187], v[24:27]
	v_mfma_f32_16x16x32_bf16 v[16:19], v[128:131], v[192:195], v[16:19]
	v_mfma_f32_16x16x32_bf16 v[8:11], v[136:139], v[192:195], v[8:11]
	v_mfma_f32_16x16x32_bf16 v[60:63], v[132:135], v[172:175], v[60:63]
	v_mfma_f32_16x16x32_bf16 v[56:59], v[140:143], v[172:175], v[56:59]
	v_mfma_f32_16x16x32_bf16 v[48:51], v[132:135], v[180:183], v[48:51]
	v_mfma_f32_16x16x32_bf16 v[40:43], v[140:143], v[180:183], v[40:43]
	v_mfma_f32_16x16x32_bf16 v[32:35], v[132:135], v[188:191], v[32:35]
	v_mfma_f32_16x16x32_bf16 v[24:27], v[140:143], v[188:191], v[24:27]
	v_mfma_f32_16x16x32_bf16 v[16:19], v[132:135], v[196:199], v[16:19]
	v_mfma_f32_16x16x32_bf16 v[8:11], v[140:143], v[196:199], v[8:11]
	s_barrier
	s_add_u32 s20, s20, 0x80080
	s_addc_u32 s21, s21, 0
	s_add_i32 s22, s22, s27
	v_lshl_add_u64 v[128:129], s[20:21], 0, v[150:151]
	s_mov_b32 m0, s22
	s_nop 0
	global_load_lds_dwordx4 v[128:129], off
	v_lshl_add_u64 v[128:129], s[20:21], 0, v[154:155]
	s_add_i32 m0, s22, 0x2000
	s_nop 0
	global_load_lds_dwordx4 v[128:129], off
	s_waitcnt vmcnt(6)
	s_barrier
	v_mfma_f32_16x16x32_bf16 v[52:55], v[200:203], v[164:167], v[52:55]
	v_mfma_f32_16x16x32_bf16 v[44:47], v[208:211], v[164:167], v[44:47]
	v_mfma_f32_16x16x32_bf16 v[36:39], v[200:203], v[176:179], v[36:39]
	v_mfma_f32_16x16x32_bf16 v[28:31], v[208:211], v[176:179], v[28:31]
	v_mfma_f32_16x16x32_bf16 v[20:23], v[200:203], v[184:187], v[20:23]
	v_mfma_f32_16x16x32_bf16 v[12:15], v[208:211], v[184:187], v[12:15]
	v_mfma_f32_16x16x32_bf16 v[4:7], v[200:203], v[192:195], v[4:7]
	v_mfma_f32_16x16x32_bf16 v[0:3], v[208:211], v[192:195], v[0:3]
	v_mfma_f32_16x16x32_bf16 v[52:55], v[204:207], v[172:175], v[52:55]
	v_mfma_f32_16x16x32_bf16 v[44:47], v[212:215], v[172:175], v[44:47]
	v_mfma_f32_16x16x32_bf16 v[36:39], v[204:207], v[180:183], v[36:39]
	v_mfma_f32_16x16x32_bf16 v[28:31], v[212:215], v[180:183], v[28:31]
	v_mfma_f32_16x16x32_bf16 v[20:23], v[204:207], v[188:191], v[20:23]
	v_mfma_f32_16x16x32_bf16 v[12:15], v[212:215], v[188:191], v[12:15]
	v_mfma_f32_16x16x32_bf16 v[4:7], v[204:207], v[196:199], v[4:7]
	v_mfma_f32_16x16x32_bf16 v[0:3], v[212:215], v[196:199], v[0:3]
	s_add_i32 s59, s59, 2
	s_add_u32 s18, s18, 0x100
	s_addc_u32 s19, s19, 0
	s_add_u32 s57, s57, 0x100
	s_addc_u32 s58, s58, 0
	s_cmp_gt_u32 s59, 29
	s_barrier
	s_cbranch_scc0 .LBB0_144
	v_lshl_or_b32 v166, s50, 8, v169
	v_mov_b32_e32 v244, 0x50000
	v_mov_b32_e32 v245, 0
	v_ashrrev_i32_e32 v167, 31, v166
	v_lshl_add_u64 v[128:129], v[166:167], 2, s[28:29]
	global_load_dwordx4 v[140:143], v[128:129], off
	global_load_dwordx4 v[136:139], v[128:129], off offset:16
	global_load_dwordx4 v[132:135], v[128:129], off offset:512
	s_nop 0
	global_load_dwordx4 v[128:131], v[128:129], off offset:528
	v_lshl_add_u32 v164, s16, 8, v168
	v_ashrrev_i32_e32 v165, 31, v164
	v_or_b32_e32 v172, 16, v164
	v_lshlrev_b64 v[178:179], 4, v[164:165]
	v_mul_u32_u24_e32 v166, 0xa00, v166
	v_ashrrev_i32_e32 v173, 31, v172
	v_lshl_add_u64 v[178:179], s[0:1], 0, v[178:179]
	v_or_b32_e32 v174, 32, v164
	v_lshlrev_b64 v[172:173], 4, v[172:173]
	v_lshl_add_u64 v[178:179], v[178:179], 0, v[166:167]
	v_ashrrev_i32_e32 v175, 31, v174
	v_lshl_add_u64 v[172:173], s[0:1], 0, v[172:173]
	v_or_b32_e32 v176, 48, v164
	v_lshlrev_b64 v[174:175], 4, v[174:175]
	v_lshl_add_u64 v[172:173], v[172:173], 0, v[166:167]
	v_ashrrev_i32_e32 v177, 31, v176
	v_lshl_add_u64 v[174:175], s[0:1], 0, v[174:175]
	v_lshlrev_b64 v[176:177], 4, v[176:177]
	v_lshl_add_u64 v[174:175], v[174:175], 0, v[166:167]
	v_lshl_add_u64 v[176:177], s[0:1], 0, v[176:177]
	v_lshl_add_u64 v[176:177], v[176:177], 0, v[166:167]
	s_and_b64 vcc, exec, s[4:5]
	s_mov_b32 s50, s8
	s_mov_b32 s16, s10
	s_mov_b64 s[20:21], s[14:15]
	s_mov_b64 s[18:19], s[12:13]
	s_waitcnt vmcnt(0)
	v_pk_mul_f32 v[126:127], v[126:127], v[142:143]
	v_pk_mul_f32 v[124:125], v[124:125], v[140:141]
	v_pk_mul_f32 v[182:183], v[70:71], v[134:135]
	v_cvt_pk_bf16_f32 v70, v124, v125
	v_cvt_pk_bf16_f32 v71, v126, v127
	v_pk_mul_f32 v[122:123], v[122:123], v[138:139]
	v_pk_mul_f32 v[120:121], v[120:121], v[136:137]
	v_pk_mul_f32 v[106:107], v[106:107], v[134:135]
	v_pk_mul_f32 v[104:105], v[104:105], v[132:133]
	v_pk_mul_f32 v[180:181], v[72:73], v[128:129]
	v_cvt_pk_bf16_f32 v72, v120, v121
	v_cvt_pk_bf16_f32 v73, v122, v123
	global_store_dwordx4 v[178:179], v[70:73], off
	v_pk_mul_f32 v[98:99], v[98:99], v[130:131]
	v_pk_mul_f32 v[96:97], v[96:97], v[128:129]
	v_cvt_pk_bf16_f32 v70, v104, v105
	v_cvt_pk_bf16_f32 v71, v106, v107
	v_pk_mul_f32 v[118:119], v[118:119], v[142:143]
	v_pk_mul_f32 v[116:117], v[116:117], v[140:141]
	v_cvt_pk_bf16_f32 v72, v96, v97
	v_cvt_pk_bf16_f32 v73, v98, v99
	v_lshl_add_u64 v[246:247], v[178:179], 0, v[244:245]
	global_store_dwordx4 v[246:247], v[70:73], off
	v_pk_mul_f32 v[114:115], v[114:115], v[138:139]
	v_pk_mul_f32 v[112:113], v[112:113], v[136:137]
	v_cvt_pk_bf16_f32 v70, v116, v117
	v_cvt_pk_bf16_f32 v71, v118, v119
	v_pk_mul_f32 v[90:91], v[90:91], v[134:135]
	v_pk_mul_f32 v[88:89], v[88:89], v[132:133]
	v_cvt_pk_bf16_f32 v72, v112, v113
	v_cvt_pk_bf16_f32 v73, v114, v115
	global_store_dwordx4 v[172:173], v[70:73], off
	v_pk_mul_f32 v[86:87], v[86:87], v[130:131]
; #define PG8_WAIT_V(n) asm volatile("s_waitcnt vmcnt(" #n ")" ::: "memory")
; #define PG8_BAR __builtin_amdgcn_s_barrier()
; __device__ __forceinline__ uint4 pk8(f32x4 a, f32x4 b) { return make_uint4(cvt_pk_bf16(a[0], a[1]), cvt_pk_bf16(a[2], a[3]), cvt_pk_bf16(b[0], b[1]), cvt_pk_bf16(b[2], b[3])); }
; template <class Epi, class Sched>
; __device__ __forceinline__ void gemm_phase(PG8_LAS unsigned char* lds, const Gemm g, const Sched& S, const Epi& E) {
;     ...
;     PG8_WAIT_V(0);
;     if (wr == 0) PG8_BAR;
;     PG8_BAR;
;     __device__ __forceinline__ void operator()(AccRef acc, const Unit& u, int wr, int wc, int fr, int fq) const {
;         const int c0 = u.pn * 256 + wc * 32 + 8 * fq;
;         f32x4 sc[2][2];
; #pragma unroll
;         for (int bj = 0; bj < 2; ++bj)
; #pragma unroll
;             for (int n = 0; n < 2; ++n) sc[bj][n] = *(const f32x4*)(rinv + c0 + bj * 128 + n * 4);
; #pragma unroll
;         for (int ai = 0; ai < 2; ++ai)
; #pragma unroll
;             for (int m = 0; m < 4; ++m) {
;                 const int r = u.pm * 256 + ai * 128 + wr * 64 + m * 16 + fr;
;                 bf16_t* rowp = O + (size_t)r * T + c0;
; #pragma unroll
;                 for (int bj = 0; bj < 2; ++bj) *(uint4*)(rowp + bj * 128) = pk8(acc[ai][bj][m][0] * sc[bj][0], acc[ai][bj][m][1] * sc[bj][1]);
;             }
;     }
	v_pk_mul_f32 v[84:85], v[84:85], v[128:129]
	v_cvt_pk_bf16_f32 v70, v88, v89
	v_cvt_pk_bf16_f32 v71, v90, v91
	v_pk_mul_f32 v[110:111], v[110:111], v[142:143]
	v_pk_mul_f32 v[108:109], v[108:109], v[140:141]
	v_cvt_pk_bf16_f32 v72, v84, v85
	v_cvt_pk_bf16_f32 v73, v86, v87
	v_lshl_add_u64 v[246:247], v[172:173], 0, v[244:245]
	global_store_dwordx4 v[246:247], v[70:73], off
	v_pk_mul_f32 v[102:103], v[102:103], v[138:139]
	v_pk_mul_f32 v[100:101], v[100:101], v[136:137]
	v_cvt_pk_bf16_f32 v70, v108, v109
	v_cvt_pk_bf16_f32 v71, v110, v111
	v_pk_mul_f32 v[78:79], v[78:79], v[134:135]
	v_pk_mul_f32 v[76:77], v[76:77], v[132:133]
	v_cvt_pk_bf16_f32 v72, v100, v101
	v_cvt_pk_bf16_f32 v73, v102, v103
	global_store_dwordx4 v[174:175], v[70:73], off
	v_pk_mul_f32 v[74:75], v[74:75], v[130:131]
	v_pk_mul_f32 v[94:95], v[94:95], v[142:143]
	v_cvt_pk_bf16_f32 v70, v76, v77
	v_cvt_pk_bf16_f32 v71, v78, v79
	v_pk_mul_f32 v[92:93], v[92:93], v[140:141]
	v_cvt_pk_bf16_f32 v72, v180, v181
	v_cvt_pk_bf16_f32 v73, v74, v75
	v_lshl_add_u64 v[246:247], v[174:175], 0, v[244:245]
	global_store_dwordx4 v[246:247], v[70:73], off
	v_pk_mul_f32 v[82:83], v[82:83], v[138:139]
	v_pk_mul_f32 v[80:81], v[80:81], v[136:137]
	v_cvt_pk_bf16_f32 v70, v92, v93
	v_cvt_pk_bf16_f32 v71, v94, v95
	v_pk_mul_f32 v[68:69], v[68:69], v[132:133]
	v_cvt_pk_bf16_f32 v72, v80, v81
	v_cvt_pk_bf16_f32 v73, v82, v83
	global_store_dwordx4 v[176:177], v[70:73], off
	v_pk_mul_f32 v[62:63], v[62:63], v[142:143]
	v_pk_mul_f32 v[60:61], v[60:61], v[140:141]
	v_pk_mul_f32 v[70:71], v[66:67], v[130:131]
	v_pk_mul_f32 v[66:67], v[64:65], v[128:129]
	v_cvt_pk_bf16_f32 v64, v68, v69
	v_cvt_pk_bf16_f32 v65, v182, v183
	v_pk_mul_f32 v[52:53], v[52:53], v[132:133]
	v_cvt_pk_bf16_f32 v66, v66, v67
	v_cvt_pk_bf16_f32 v67, v70, v71
	v_lshl_add_u64 v[246:247], v[176:177], 0, v[244:245]
	global_store_dwordx4 v[246:247], v[64:67], off
	v_pk_mul_f32 v[54:55], v[54:55], v[134:135]
	v_pk_mul_f32 v[48:49], v[48:49], v[140:141]
	v_add_u32_e32 v64, 0x80, v164
	v_ashrrev_i32_e32 v65, 31, v64
	v_lshlrev_b64 v[64:65], 4, v[64:65]
	v_lshl_add_u64 v[64:65], s[0:1], 0, v[64:65]
	v_lshl_add_u64 v[64:65], v[64:65], 0, v[166:167]
	v_pk_mul_f32 v[66:67], v[58:59], v[138:139]
	v_pk_mul_f32 v[58:59], v[56:57], v[136:137]
	v_cvt_pk_bf16_f32 v56, v60, v61
	v_cvt_pk_bf16_f32 v57, v62, v63
	v_pk_mul_f32 v[36:37], v[36:37], v[132:133]
	v_cvt_pk_bf16_f32 v58, v58, v59
	v_cvt_pk_bf16_f32 v59, v66, v67
	global_store_dwordx4 v[64:65], v[56:59], off
	v_pk_mul_f32 v[38:39], v[38:39], v[134:135]
	v_pk_mul_f32 v[32:33], v[32:33], v[140:141]
	v_pk_mul_f32 v[56:57], v[46:47], v[130:131]
	v_pk_mul_f32 v[46:47], v[44:45], v[128:129]
	v_cvt_pk_bf16_f32 v44, v52, v53
	v_cvt_pk_bf16_f32 v45, v54, v55
	v_pk_mul_f32 v[20:21], v[20:21], v[132:133]
	v_cvt_pk_bf16_f32 v46, v46, v47
	v_cvt_pk_bf16_f32 v47, v56, v57
	v_lshl_add_u64 v[246:247], v[64:65], 0, v[244:245]
	global_store_dwordx4 v[246:247], v[44:47], off
	v_pk_mul_f32 v[22:23], v[22:23], v[134:135]
	v_pk_mul_f32 v[16:17], v[16:17], v[140:141]
	v_add_u32_e32 v44, 0x90, v164
	v_ashrrev_i32_e32 v45, 31, v44
	v_lshlrev_b64 v[44:45], 4, v[44:45]
	v_lshl_add_u64 v[44:45], s[0:1], 0, v[44:45]
	v_lshl_add_u64 v[44:45], v[44:45], 0, v[166:167]
	v_pk_mul_f32 v[46:47], v[50:51], v[142:143]
	v_pk_mul_f32 v[50:51], v[42:43], v[138:139]
	v_pk_mul_f32 v[42:43], v[40:41], v[136:137]
	v_cvt_pk_bf16_f32 v40, v48, v49
	v_cvt_pk_bf16_f32 v41, v46, v47
	v_pk_mul_f32 v[6:7], v[6:7], v[134:135]
	v_cvt_pk_bf16_f32 v42, v42, v43
	v_cvt_pk_bf16_f32 v43, v50, v51
	global_store_dwordx4 v[44:45], v[40:43], off
	v_pk_mul_f32 v[4:5], v[4:5], v[132:133]
	s_nop 0
	v_pk_mul_f32 v[40:41], v[30:31], v[130:131]
	v_pk_mul_f32 v[30:31], v[28:29], v[128:129]
	v_cvt_pk_bf16_f32 v28, v36, v37
	v_cvt_pk_bf16_f32 v29, v38, v39
	s_nop 0
	v_cvt_pk_bf16_f32 v30, v30, v31
	v_cvt_pk_bf16_f32 v31, v40, v41
	v_lshl_add_u64 v[246:247], v[44:45], 0, v[244:245]
	global_store_dwordx4 v[246:247], v[28:31], off
	s_nop 1
	v_add_u32_e32 v28, 0xa0, v164
	v_ashrrev_i32_e32 v29, 31, v28
	v_lshlrev_b64 v[28:29], 4, v[28:29]
	v_lshl_add_u64 v[28:29], s[0:1], 0, v[28:29]
	v_lshl_add_u64 v[28:29], v[28:29], 0, v[166:167]
	v_pk_mul_f32 v[30:31], v[34:35], v[142:143]
	v_pk_mul_f32 v[34:35], v[26:27], v[138:139]
	v_pk_mul_f32 v[26:27], v[24:25], v[136:137]
	v_cvt_pk_bf16_f32 v24, v32, v33
	v_cvt_pk_bf16_f32 v25, v30, v31
	s_nop 0
	v_cvt_pk_bf16_f32 v26, v26, v27
	v_cvt_pk_bf16_f32 v27, v34, v35
	global_store_dwordx4 v[28:29], v[24:27], off
	s_nop 1
	v_pk_mul_f32 v[24:25], v[14:15], v[130:131]
	v_pk_mul_f32 v[14:15], v[12:13], v[128:129]
	v_cvt_pk_bf16_f32 v12, v20, v21
	v_cvt_pk_bf16_f32 v13, v22, v23
	s_nop 0
	v_cvt_pk_bf16_f32 v14, v14, v15
	v_cvt_pk_bf16_f32 v15, v24, v25
	v_lshl_add_u64 v[246:247], v[28:29], 0, v[244:245]
	global_store_dwordx4 v[246:247], v[12:15], off
	s_nop 1
	v_add_u32_e32 v12, 0xb0, v164
	v_ashrrev_i32_e32 v13, 31, v12
	v_lshlrev_b64 v[12:13], 4, v[12:13]
	v_lshl_add_u64 v[12:13], s[0:1], 0, v[12:13]
	v_lshl_add_u64 v[12:13], v[12:13], 0, v[166:167]
	v_pk_mul_f32 v[14:15], v[18:19], v[142:143]
	v_pk_mul_f32 v[18:19], v[10:11], v[138:139]
	v_pk_mul_f32 v[10:11], v[8:9], v[136:137]
	v_cvt_pk_bf16_f32 v8, v16, v17
	v_cvt_pk_bf16_f32 v9, v14, v15
	s_nop 0
	v_cvt_pk_bf16_f32 v10, v10, v11
	v_cvt_pk_bf16_f32 v11, v18, v19
	global_store_dwordx4 v[12:13], v[8:11], off
	s_nop 1
	v_pk_mul_f32 v[8:9], v[2:3], v[130:131]
	v_pk_mul_f32 v[2:3], v[0:1], v[128:129]
	v_cvt_pk_bf16_f32 v0, v4, v5
	v_cvt_pk_bf16_f32 v1, v6, v7
	s_nop 0
	v_cvt_pk_bf16_f32 v2, v2, v3
	v_cvt_pk_bf16_f32 v3, v8, v9
	v_lshl_add_u64 v[246:247], v[12:13], 0, v[244:245]
	global_store_dwordx4 v[246:247], v[0:3], off
	s_cbranch_vccz .LBB0_137
	s_waitcnt vmcnt(0)
	s_cmpk_gt_u32 s3, 0xff
	s_cbranch_scc1 .LBB0_148
	s_barrier

; __device__ void phase_na(const Params& P, unsigned char* smem) {
;     const int tid = threadIdx.x, lane = tid & 63, wid = tid >> 6, l15 = lane & 15, l4 = lane >> 4;
;     float* rpb_s = (float*)smem;
;     for (int i = tid; i < 8 * 15 * 31; i += 512) rpb_s[i] = P.in[I_RPB][i];
;     __syncthreads();
.LBB0_203:
	s_setprio 0
	s_add_u32 s40, s90, 0x16000000
	s_addc_u32 s41, s91, 0
	s_cmp_lt_i32 s92, 3
	s_cselect_b64 s[0:1], -1, 0
	s_cmp_gt_i32 s93, 2
	s_cselect_b64 s[4:5], -1, 0
	s_and_b64 s[0:1], s[0:1], s[4:5]
	s_andn2_b64 vcc, exec, s[0:1]
	s_cbranch_vccnz .LBB0_434
	v_lshlrev_b32_e32 v2, 2, v144
	v_mov_b32_e32 v3, 0
	v_lshl_add_u64 v[0:1], s[64:65], 0, v[2:3]
	v_add_co_u32_e32 v4, vcc, 0x1000, v0
	v_or_b32_e32 v3, 0x1000, v2
	s_nop 0
	v_addc_co_u32_e32 v5, vcc, 0, v1, vcc
	v_add_co_u32_e32 v6, vcc, 0x2000, v0
	v_or_b32_e32 v8, 0x2000, v2
	s_nop 0
	v_addc_co_u32_e32 v7, vcc, 0, v1, vcc
	global_load_dword v9, v2, s[64:65]
	global_load_dword v10, v2, s[64:65] offset:2048
	global_load_dword v11, v3, s[64:65]
	global_load_dword v12, v[4:5], off offset:2048
	global_load_dword v13, v8, s[64:65]
	s_waitcnt lgkmcnt(0)
	global_load_dword v14, v[6:7], off offset:2048
	s_movk_i32 s0, 0x288
	v_add_u32_e32 v2, 0, v2
	v_cmp_gt_u32_e32 vcc, s0, v144
	s_waitcnt vmcnt(4)
	ds_write2st64_b32 v2, v9, v10 offset1:8
	s_waitcnt vmcnt(2)
	ds_write2st64_b32 v2, v11, v12 offset0:16 offset1:24
	s_waitcnt vmcnt(0)
	ds_write2st64_b32 v2, v13, v14 offset0:32 offset1:40
	s_and_saveexec_b64 s[0:1], vcc
	s_cbranch_execz .LBB0_207
	v_or_b32_e32 v3, 0xc00, v144
	v_lshlrev_b32_e32 v4, 2, v3
	global_load_dword v4, v4, s[64:65]
	s_movk_i32 s3, 0xc88
	v_cmp_gt_u32_e32 vcc, s3, v3
	s_waitcnt vmcnt(0)
	ds_write_b32 v2, v4 offset:12288
	s_and_saveexec_b64 s[4:5], vcc
	s_xor_b64 s[4:5], exec, s[4:5]
	s_cbranch_execz .LBB0_207
	v_add_co_u32_e32 v0, vcc, 0x3000, v0
	s_nop 1
	v_addc_co_u32_e32 v1, vcc, 0, v1, vcc
	global_load_dword v0, v[0:1], off offset:2048
	s_waitcnt vmcnt(0)
	ds_write_b32 v2, v0 offset:14336

; #define PG8_STAGE(bufoff, gbase, voff) do { _Pragma("unroll") for (int _i = 0; _i < 2; ++_i) \
;         __builtin_amdgcn_global_load_lds((const unsigned*)((const char*)(gbase) + (voff)[_i]), (PG8_LAS unsigned*)(lds + (bufoff) + ldsw + _i * 8192), 16, 0, 0); } while (0)
; #define PG8_LDA(dst, b, h) do { _Pragma("unroll") for (int m = 0; m < 4; ++m) _Pragma("unroll") for (int k = 0; k < 2; ++k) dst[m][k] = *(const PG8_LAS bf16x8*)(lds + PG8_SA(b, h) + aoff + m * 2048 + k * 1024); } while (0)
; #define PG8_LDB(dst, b, h) do { _Pragma("unroll") for (int n = 0; n < 2; ++n) _Pragma("unroll") for (int k = 0; k < 2; ++k) dst[n][k] = *(const PG8_LAS bf16x8*)(lds + PG8_SB(b, h) + boff + n * 2048 + k * 1024); } while (0)
; #define PG8_MMA(ai, bj, At, Bt) do { __builtin_amdgcn_s_setprio(1); _Pragma("unroll") for (int m = 0; m < 4; ++m) _Pragma("unroll") for (int n = 0; n < 2; ++n) _Pragma("unroll") for (int k = 0; k < 2; ++k) \
;         acc[ai][bj][m][n] = __builtin_amdgcn_mfma_f32_16x16x32_bf16(Bt[n][k], At[m][k], acc[ai][bj][m][n], 0, 0, 0); __builtin_amdgcn_s_setprio(0); } while (0)
; #define PG8_WAIT_L(n) asm volatile("s_waitcnt lgkmcnt(" #n ")" ::: "memory")
; #define PG8_BAR __builtin_amdgcn_s_barrier()
; #define PG8_SCHED __builtin_amdgcn_sched_barrier(0)
; template <class Epi, class Sched>
; __device__ __forceinline__ void gemm_phase(PG8_LAS unsigned char* lds, const Gemm g, const Sched& S, const Epi& E) {
;     ...
;             const bool last = (t == nt - 2);
;             const char* a1 = cA + (size_t)(t + 1) * kstep;
;             const char* a2 = last ? nA : cA + (size_t)(t + 2) * kstep; const char* b2 = last ? nB : cB + (size_t)(t + 2) * kstep;
;             const char* a3 = a2 + kstep; const char* b3 = b2 + kstep;
;             if (last && has_next) S.a_ready(nxt);
;             PG8_LDB(B0, 0, 0); PG8_SCHED; PG8_LDA(At, 0, 0); PG8_STAGE(PG8_SA(1, 1), a1 + hstep, voffA);
;             PG8_WAIT_L(8); PG8_BAR; PG8_WAIT_L(0); PG8_MMA(0, 0, At, B0); PG8_BAR; PG8_SCHED;
;             PG8_LDB(B1, 0, 1); PG8_STAGE(PG8_SB(0, 0), b2, voffB);
;             PG8_BAR; PG8_WAIT_L(0); PG8_MMA(0, 1, At, B1); PG8_BAR;
;             PG8_LDA(At, 0, 1); PG8_STAGE(PG8_SA(0, 0), a2, voffA);
;             PG8_BAR; PG8_WAIT_L(0); PG8_MMA(1, 0, At, B0); PG8_BAR; PG8_SCHED;
.LBB0_593:
	ds_read_b128 v[148:151], v161
	ds_read_b128 v[164:167], v161 offset:1024
	ds_read_b128 v[168:171], v161 offset:2048
	ds_read_b128 v[172:175], v161 offset:3072
	s_add_u32 s20, s18, 0xfffc0080
	s_addc_u32 s21, s19, -1
	s_cmp_eq_u32 s61, 12
	s_cselect_b32 s23, s11, s21
	s_cselect_b32 s22, s57, s20
	s_cselect_b32 s21, s9, s60
	s_cselect_b32 s20, s58, s59
	v_lshl_add_u64 v[208:209], s[18:19], 0, v[136:137]
	s_add_i32 m0, s17, 0xc000
	ds_read_b128 v[176:179], v162
	ds_read_b128 v[180:183], v162 offset:1024
	ds_read_b128 v[184:187], v162 offset:2048
	ds_read_b128 v[188:191], v162 offset:3072
	ds_read_b128 v[192:195], v162 offset:4096
	ds_read_b128 v[196:199], v162 offset:5120
	ds_read_b128 v[200:203], v162 offset:6144
	ds_read_b128 v[204:207], v162 offset:7168
	global_load_lds_dwordx4 v[208:209], off
	v_lshl_add_u64 v[208:209], s[18:19], 0, v[138:139]
	s_add_i32 m0, s17, 0xe000
	s_nop 0
	global_load_lds_dwordx4 v[208:209], off
	s_waitcnt lgkmcnt(8)
	s_barrier
	s_waitcnt lgkmcnt(0)
	s_waitcnt lgkmcnt(0)
	v_mfma_f32_16x16x32_bf16 v[124:127], v[148:151], v[176:179], v[124:127]
	v_mfma_f32_16x16x32_bf16 v[120:123], v[168:171], v[176:179], v[120:123]
	v_mfma_f32_16x16x32_bf16 v[112:115], v[148:151], v[184:187], v[112:115]
	v_mfma_f32_16x16x32_bf16 v[104:107], v[168:171], v[184:187], v[104:107]
	v_mfma_f32_16x16x32_bf16 v[96:99], v[148:151], v[192:195], v[96:99]
	v_mfma_f32_16x16x32_bf16 v[88:91], v[168:171], v[192:195], v[88:91]
	v_mfma_f32_16x16x32_bf16 v[80:83], v[148:151], v[200:203], v[80:83]
	v_mfma_f32_16x16x32_bf16 v[72:75], v[168:171], v[200:203], v[72:75]
	v_mfma_f32_16x16x32_bf16 v[124:127], v[164:167], v[180:183], v[124:127]
	v_mfma_f32_16x16x32_bf16 v[120:123], v[172:175], v[180:183], v[120:123]
	v_mfma_f32_16x16x32_bf16 v[112:115], v[164:167], v[188:191], v[112:115]
	v_mfma_f32_16x16x32_bf16 v[104:107], v[172:175], v[188:191], v[104:107]
	v_mfma_f32_16x16x32_bf16 v[96:99], v[164:167], v[196:199], v[96:99]
	v_mfma_f32_16x16x32_bf16 v[88:91], v[172:175], v[196:199], v[88:91]
	v_mfma_f32_16x16x32_bf16 v[80:83], v[164:167], v[204:207], v[80:83]
	v_mfma_f32_16x16x32_bf16 v[72:75], v[172:175], v[204:207], v[72:75]
	s_barrier
	s_add_i32 s30, s50, s27
	v_lshl_add_u64 v[224:225], s[20:21], 0, v[130:131]
	s_mov_b32 m0, s30
	ds_read_b128 v[208:211], v163
	ds_read_b128 v[212:215], v163 offset:1024
	ds_read_b128 v[216:219], v163 offset:2048
	ds_read_b128 v[220:223], v163 offset:3072
	global_load_lds_dwordx4 v[224:225], off
	v_lshl_add_u64 v[226:227], s[20:21], 0, v[134:135]
	s_add_i32 m0, s30, 0x2000
	s_nop 0
	global_load_lds_dwordx4 v[226:227], off
	s_barrier
	s_waitcnt lgkmcnt(0)
	s_waitcnt lgkmcnt(0)
	v_mfma_f32_16x16x32_bf16 v[116:119], v[208:211], v[176:179], v[116:119]
	v_mfma_f32_16x16x32_bf16 v[108:111], v[216:219], v[176:179], v[108:111]
	v_mfma_f32_16x16x32_bf16 v[100:103], v[208:211], v[184:187], v[100:103]
	v_mfma_f32_16x16x32_bf16 v[92:95], v[216:219], v[184:187], v[92:95]
	v_mfma_f32_16x16x32_bf16 v[84:87], v[208:211], v[192:195], v[84:87]
	v_mfma_f32_16x16x32_bf16 v[76:79], v[216:219], v[192:195], v[76:79]
	v_mfma_f32_16x16x32_bf16 v[68:71], v[208:211], v[200:203], v[68:71]
	v_mfma_f32_16x16x32_bf16 v[64:67], v[216:219], v[200:203], v[64:67]
	v_mfma_f32_16x16x32_bf16 v[116:119], v[212:215], v[180:183], v[116:119]
	v_mfma_f32_16x16x32_bf16 v[108:111], v[220:223], v[180:183], v[108:111]
	v_mfma_f32_16x16x32_bf16 v[100:103], v[212:215], v[188:191], v[100:103]
	v_mfma_f32_16x16x32_bf16 v[92:95], v[220:223], v[188:191], v[92:95]
	v_mfma_f32_16x16x32_bf16 v[84:87], v[212:215], v[196:199], v[84:87]
	v_mfma_f32_16x16x32_bf16 v[76:79], v[220:223], v[196:199], v[76:79]
	v_mfma_f32_16x16x32_bf16 v[68:71], v[212:215], v[204:207], v[68:71]
	v_mfma_f32_16x16x32_bf16 v[64:67], v[220:223], v[204:207], v[64:67]
	s_mov_b32 m0, s17
	v_lshl_add_u64 v[228:229], s[22:23], 0, v[128:129]
	s_barrier
	ds_read_b128 v[176:179], v162 offset:16384
	ds_read_b128 v[180:183], v162 offset:17408
	ds_read_b128 v[184:187], v162 offset:18432
	ds_read_b128 v[188:191], v162 offset:19456
	ds_read_b128 v[192:195], v162 offset:20480
	ds_read_b128 v[196:199], v162 offset:21504
	ds_read_b128 v[200:203], v162 offset:22528
	ds_read_b128 v[204:207], v162 offset:23552
	global_load_lds_dwordx4 v[228:229], off
	v_lshl_add_u64 v[230:231], s[22:23], 0, v[132:133]
	s_mov_b32 m0, s42
	s_nop 0
	global_load_lds_dwordx4 v[230:231], off
	s_barrier
	s_waitcnt lgkmcnt(0)
	s_waitcnt lgkmcnt(0)
	v_mfma_f32_16x16x32_bf16 v[60:63], v[148:151], v[176:179], v[60:63]
	v_mfma_f32_16x16x32_bf16 v[56:59], v[168:171], v[176:179], v[56:59]
	v_mfma_f32_16x16x32_bf16 v[52:55], v[148:151], v[184:187], v[52:55]
	v_mfma_f32_16x16x32_bf16 v[44:47], v[168:171], v[184:187], v[44:47]
	v_mfma_f32_16x16x32_bf16 v[36:39], v[148:151], v[192:195], v[36:39]
	v_mfma_f32_16x16x32_bf16 v[28:31], v[168:171], v[192:195], v[28:31]
	v_mfma_f32_16x16x32_bf16 v[20:23], v[148:151], v[200:203], v[20:23]
	v_mfma_f32_16x16x32_bf16 v[12:15], v[168:171], v[200:203], v[12:15]
	v_mfma_f32_16x16x32_bf16 v[60:63], v[164:167], v[180:183], v[60:63]
	v_mfma_f32_16x16x32_bf16 v[56:59], v[172:175], v[180:183], v[56:59]
	v_mfma_f32_16x16x32_bf16 v[52:55], v[164:167], v[188:191], v[52:55]
	v_mfma_f32_16x16x32_bf16 v[44:47], v[172:175], v[188:191], v[44:47]
	v_mfma_f32_16x16x32_bf16 v[36:39], v[164:167], v[196:199], v[36:39]
	v_mfma_f32_16x16x32_bf16 v[28:31], v[172:175], v[196:199], v[28:31]
	v_mfma_f32_16x16x32_bf16 v[20:23], v[164:167], v[204:207], v[20:23]
	v_mfma_f32_16x16x32_bf16 v[12:15], v[172:175], v[204:207], v[12:15]
	s_barrier
; #define PG8_STAGE(bufoff, gbase, voff) do { _Pragma("unroll") for (int _i = 0; _i < 2; ++_i) \
;         __builtin_amdgcn_global_load_lds((const unsigned*)((const char*)(gbase) + (voff)[_i]), (PG8_LAS unsigned*)(lds + (bufoff) + ldsw + _i * 8192), 16, 0, 0); } while (0)
; #define PG8_LDA(dst, b, h) do { _Pragma("unroll") for (int m = 0; m < 4; ++m) _Pragma("unroll") for (int k = 0; k < 2; ++k) dst[m][k] = *(const PG8_LAS bf16x8*)(lds + PG8_SA(b, h) + aoff + m * 2048 + k * 1024); } while (0)
; #define PG8_LDB(dst, b, h) do { _Pragma("unroll") for (int n = 0; n < 2; ++n) _Pragma("unroll") for (int k = 0; k < 2; ++k) dst[n][k] = *(const PG8_LAS bf16x8*)(lds + PG8_SB(b, h) + boff + n * 2048 + k * 1024); } while (0)
; #define PG8_MMA(ai, bj, At, Bt) do { __builtin_amdgcn_s_setprio(1); _Pragma("unroll") for (int m = 0; m < 4; ++m) _Pragma("unroll") for (int n = 0; n < 2; ++n) _Pragma("unroll") for (int k = 0; k < 2; ++k) \
;         acc[ai][bj][m][n] = __builtin_amdgcn_mfma_f32_16x16x32_bf16(Bt[n][k], At[m][k], acc[ai][bj][m][n], 0, 0, 0); __builtin_amdgcn_s_setprio(0); } while (0)
; #define PG8_WAIT_V(n) asm volatile("s_waitcnt vmcnt(" #n ")" ::: "memory")
; #define PG8_WAIT_L(n) asm volatile("s_waitcnt lgkmcnt(" #n ")" ::: "memory")
; #define PG8_BAR __builtin_amdgcn_s_barrier()
; #define PG8_SCHED __builtin_amdgcn_sched_barrier(0)
; template <class Epi, class Sched>
; __device__ __forceinline__ void gemm_phase(PG8_LAS unsigned char* lds, const Gemm g, const Sched& S, const Epi& E) {
;     ...
;             PG8_STAGE(PG8_SB(0, 1), b2 + hstep, voffB);
;             PG8_WAIT_V(6); PG8_BAR; PG8_MMA(1, 1, At, B1); PG8_BAR;
;             PG8_LDB(B0, 1, 0); PG8_SCHED; PG8_LDA(At, 1, 0); PG8_STAGE(PG8_SA(0, 1), a2 + hstep, voffA);
;             PG8_WAIT_L(8); PG8_BAR; PG8_WAIT_L(0); PG8_MMA(0, 0, At, B0); PG8_BAR; PG8_SCHED;
;             PG8_LDB(B1, 1, 1); PG8_STAGE(PG8_SB(1, 0), b3, voffB);
;             PG8_BAR; PG8_WAIT_L(0); PG8_MMA(0, 1, At, B1); PG8_BAR;
;             PG8_LDA(At, 1, 1); PG8_STAGE(PG8_SA(1, 0), a3, voffA);
	s_add_u32 s30, s20, 0x40000
	s_addc_u32 s31, s21, 0
	s_add_i32 s38, s51, s27
	v_lshl_add_u64 v[148:149], s[30:31], 0, v[130:131]
	s_mov_b32 m0, s38
	s_nop 0
	global_load_lds_dwordx4 v[148:149], off
	v_lshl_add_u64 v[148:149], s[30:31], 0, v[134:135]
	s_add_i32 m0, s38, 0x2000
	s_nop 0
	global_load_lds_dwordx4 v[148:149], off
	s_waitcnt vmcnt(6)
	s_barrier
	v_mfma_f32_16x16x32_bf16 v[48:51], v[208:211], v[176:179], v[48:51]
	v_mfma_f32_16x16x32_bf16 v[40:43], v[216:219], v[176:179], v[40:43]
	v_mfma_f32_16x16x32_bf16 v[32:35], v[208:211], v[184:187], v[32:35]
	v_mfma_f32_16x16x32_bf16 v[24:27], v[216:219], v[184:187], v[24:27]
	v_mfma_f32_16x16x32_bf16 v[16:19], v[208:211], v[192:195], v[16:19]
	v_mfma_f32_16x16x32_bf16 v[8:11], v[216:219], v[192:195], v[8:11]
	v_mfma_f32_16x16x32_bf16 v[4:7], v[208:211], v[200:203], v[4:7]
	v_mfma_f32_16x16x32_bf16 v[0:3], v[216:219], v[200:203], v[0:3]
	v_mfma_f32_16x16x32_bf16 v[48:51], v[212:215], v[180:183], v[48:51]
	v_mfma_f32_16x16x32_bf16 v[40:43], v[220:223], v[180:183], v[40:43]
	v_mfma_f32_16x16x32_bf16 v[32:35], v[212:215], v[188:191], v[32:35]
	v_mfma_f32_16x16x32_bf16 v[24:27], v[220:223], v[188:191], v[24:27]
	v_mfma_f32_16x16x32_bf16 v[16:19], v[212:215], v[196:199], v[16:19]
	v_mfma_f32_16x16x32_bf16 v[8:11], v[220:223], v[196:199], v[8:11]
	v_mfma_f32_16x16x32_bf16 v[4:7], v[212:215], v[204:207], v[4:7]
	v_mfma_f32_16x16x32_bf16 v[0:3], v[220:223], v[204:207], v[0:3]
	s_add_i32 s30, 0, 0x18000
	v_add_u32_e32 v172, s30, v159
	s_barrier
	ds_read_b128 v[148:151], v172
	ds_read_b128 v[164:167], v172 offset:1024
	ds_read_b128 v[168:171], v172 offset:2048
	ds_read_b128 v[172:175], v172 offset:3072
	s_add_u32 s22, s22, 0x40000
	s_addc_u32 s23, s23, 0
	s_mov_b32 m0, s43
	v_lshl_add_u64 v[208:209], s[22:23], 0, v[128:129]
	ds_read_b128 v[176:179], v162 offset:32768
	ds_read_b128 v[180:183], v162 offset:33792
	ds_read_b128 v[184:187], v162 offset:34816
	ds_read_b128 v[188:191], v162 offset:35840
	ds_read_b128 v[192:195], v162 offset:36864
	ds_read_b128 v[196:199], v162 offset:37888
	ds_read_b128 v[200:203], v162 offset:38912
	ds_read_b128 v[204:207], v162 offset:39936
	global_load_lds_dwordx4 v[208:209], off
	v_lshl_add_u64 v[208:209], s[22:23], 0, v[132:133]
	s_mov_b32 m0, s44
	s_nop 0
	global_load_lds_dwordx4 v[208:209], off
	s_waitcnt lgkmcnt(8)
	s_barrier
	s_waitcnt lgkmcnt(0)
	s_waitcnt lgkmcnt(0)
	v_mfma_f32_16x16x32_bf16 v[124:127], v[148:151], v[176:179], v[124:127]
	v_mfma_f32_16x16x32_bf16 v[120:123], v[168:171], v[176:179], v[120:123]
	v_mfma_f32_16x16x32_bf16 v[112:115], v[148:151], v[184:187], v[112:115]
	v_mfma_f32_16x16x32_bf16 v[104:107], v[168:171], v[184:187], v[104:107]
	v_mfma_f32_16x16x32_bf16 v[96:99], v[148:151], v[192:195], v[96:99]
	v_mfma_f32_16x16x32_bf16 v[88:91], v[168:171], v[192:195], v[88:91]
	v_mfma_f32_16x16x32_bf16 v[80:83], v[148:151], v[200:203], v[80:83]
	v_mfma_f32_16x16x32_bf16 v[72:75], v[168:171], v[200:203], v[72:75]
	v_mfma_f32_16x16x32_bf16 v[124:127], v[164:167], v[180:183], v[124:127]
	v_mfma_f32_16x16x32_bf16 v[120:123], v[172:175], v[180:183], v[120:123]
	v_mfma_f32_16x16x32_bf16 v[112:115], v[164:167], v[188:191], v[112:115]
	v_mfma_f32_16x16x32_bf16 v[104:107], v[172:175], v[188:191], v[104:107]
	v_mfma_f32_16x16x32_bf16 v[96:99], v[164:167], v[196:199], v[96:99]
	v_mfma_f32_16x16x32_bf16 v[88:91], v[172:175], v[196:199], v[88:91]
	v_mfma_f32_16x16x32_bf16 v[80:83], v[164:167], v[204:207], v[80:83]
	v_mfma_f32_16x16x32_bf16 v[72:75], v[172:175], v[204:207], v[72:75]
	s_barrier
	s_add_i32 s22, 0, 0x1c000
	s_add_i32 s23, s30, s27
	v_add_u32_e32 v220, s22, v159
	v_lshl_add_u64 v[224:225], v[224:225], 0, s[6:7]
	s_mov_b32 m0, s23
	ds_read_b128 v[208:211], v220
	ds_read_b128 v[212:215], v220 offset:1024
	ds_read_b128 v[216:219], v220 offset:2048
	ds_read_b128 v[220:223], v220 offset:3072
	global_load_lds_dwordx4 v[224:225], off
	v_lshl_add_u64 v[224:225], v[226:227], 0, s[6:7]
	s_add_i32 m0, s23, 0x2000
	s_nop 0
	global_load_lds_dwordx4 v[224:225], off
	s_barrier
	s_waitcnt lgkmcnt(0)
	s_waitcnt lgkmcnt(0)
	v_mfma_f32_16x16x32_bf16 v[116:119], v[208:211], v[176:179], v[116:119]
	v_mfma_f32_16x16x32_bf16 v[108:111], v[216:219], v[176:179], v[108:111]
	v_mfma_f32_16x16x32_bf16 v[100:103], v[208:211], v[184:187], v[100:103]
	v_mfma_f32_16x16x32_bf16 v[92:95], v[216:219], v[184:187], v[92:95]
	v_mfma_f32_16x16x32_bf16 v[84:87], v[208:211], v[192:195], v[84:87]
	v_mfma_f32_16x16x32_bf16 v[76:79], v[216:219], v[192:195], v[76:79]
	v_mfma_f32_16x16x32_bf16 v[68:71], v[208:211], v[200:203], v[68:71]
	v_mfma_f32_16x16x32_bf16 v[64:67], v[216:219], v[200:203], v[64:67]
	v_mfma_f32_16x16x32_bf16 v[116:119], v[212:215], v[180:183], v[116:119]
	v_mfma_f32_16x16x32_bf16 v[108:111], v[220:223], v[180:183], v[108:111]
	v_mfma_f32_16x16x32_bf16 v[100:103], v[212:215], v[188:191], v[100:103]
	v_mfma_f32_16x16x32_bf16 v[92:95], v[220:223], v[188:191], v[92:95]
	v_mfma_f32_16x16x32_bf16 v[84:87], v[212:215], v[196:199], v[84:87]
	v_mfma_f32_16x16x32_bf16 v[76:79], v[220:223], v[196:199], v[76:79]
	v_mfma_f32_16x16x32_bf16 v[68:71], v[212:215], v[204:207], v[68:71]
	v_mfma_f32_16x16x32_bf16 v[64:67], v[220:223], v[204:207], v[64:67]
	s_mov_b32 m0, s46
	v_lshl_add_u64 v[224:225], v[228:229], 0, s[6:7]
	s_barrier
	ds_read_b128 v[176:179], v162 offset:49152
	ds_read_b128 v[180:183], v162 offset:50176
	ds_read_b128 v[184:187], v162 offset:51200
	ds_read_b128 v[188:191], v162 offset:52224
	ds_read_b128 v[192:195], v162 offset:53248
	ds_read_b128 v[196:199], v162 offset:54272
	ds_read_b128 v[200:203], v162 offset:55296
	ds_read_b128 v[204:207], v162 offset:56320
	global_load_lds_dwordx4 v[224:225], off
	v_lshl_add_u64 v[224:225], v[230:231], 0, s[6:7]
	s_mov_b32 m0, s47
	s_nop 0
	global_load_lds_dwordx4 v[224:225], off
	s_barrier
; #define PG8_STAGE(bufoff, gbase, voff) do { _Pragma("unroll") for (int _i = 0; _i < 2; ++_i) \
;         __builtin_amdgcn_global_load_lds((const unsigned*)((const char*)(gbase) + (voff)[_i]), (PG8_LAS unsigned*)(lds + (bufoff) + ldsw + _i * 8192), 16, 0, 0); } while (0)
; #define PG8_MMA(ai, bj, At, Bt) do { __builtin_amdgcn_s_setprio(1); _Pragma("unroll") for (int m = 0; m < 4; ++m) _Pragma("unroll") for (int n = 0; n < 2; ++n) _Pragma("unroll") for (int k = 0; k < 2; ++k) \
;         acc[ai][bj][m][n] = __builtin_amdgcn_mfma_f32_16x16x32_bf16(Bt[n][k], At[m][k], acc[ai][bj][m][n], 0, 0, 0); __builtin_amdgcn_s_setprio(0); } while (0)
; #define PG8_WAIT_V(n) asm volatile("s_waitcnt vmcnt(" #n ")" ::: "memory")
; #define PG8_WAIT_L(n) asm volatile("s_waitcnt lgkmcnt(" #n ")" ::: "memory")
; #define PG8_BAR __builtin_amdgcn_s_barrier()
; #define PG8_SCHED __builtin_amdgcn_sched_barrier(0)
; template <class Epi, class Sched>
; __device__ __forceinline__ void gemm_phase(PG8_LAS unsigned char* lds, const Gemm g, const Sched& S, const Epi& E) {
;     ...
;             PG8_BAR; PG8_WAIT_L(0); PG8_MMA(1, 0, At, B0); PG8_BAR; PG8_SCHED;
;             PG8_STAGE(PG8_SB(1, 1), b3 + hstep, voffB);
;             PG8_WAIT_V(6); PG8_BAR; PG8_MMA(1, 1, At, B1); PG8_BAR;
	s_waitcnt lgkmcnt(0)
	s_waitcnt lgkmcnt(0)
	v_mfma_f32_16x16x32_bf16 v[60:63], v[148:151], v[176:179], v[60:63]
	v_mfma_f32_16x16x32_bf16 v[56:59], v[168:171], v[176:179], v[56:59]
	v_mfma_f32_16x16x32_bf16 v[52:55], v[148:151], v[184:187], v[52:55]
	v_mfma_f32_16x16x32_bf16 v[44:47], v[168:171], v[184:187], v[44:47]
	v_mfma_f32_16x16x32_bf16 v[36:39], v[148:151], v[192:195], v[36:39]
	v_mfma_f32_16x16x32_bf16 v[28:31], v[168:171], v[192:195], v[28:31]
	v_mfma_f32_16x16x32_bf16 v[20:23], v[148:151], v[200:203], v[20:23]
	v_mfma_f32_16x16x32_bf16 v[12:15], v[168:171], v[200:203], v[12:15]
	v_mfma_f32_16x16x32_bf16 v[60:63], v[164:167], v[180:183], v[60:63]
	v_mfma_f32_16x16x32_bf16 v[56:59], v[172:175], v[180:183], v[56:59]
	v_mfma_f32_16x16x32_bf16 v[52:55], v[164:167], v[188:191], v[52:55]
	v_mfma_f32_16x16x32_bf16 v[44:47], v[172:175], v[188:191], v[44:47]
	v_mfma_f32_16x16x32_bf16 v[36:39], v[164:167], v[196:199], v[36:39]
	v_mfma_f32_16x16x32_bf16 v[28:31], v[172:175], v[196:199], v[28:31]
	v_mfma_f32_16x16x32_bf16 v[20:23], v[164:167], v[204:207], v[20:23]
	v_mfma_f32_16x16x32_bf16 v[12:15], v[172:175], v[204:207], v[12:15]
	s_barrier
	s_add_u32 s20, s20, 0x40080
	s_addc_u32 s21, s21, 0
	s_add_i32 s22, s22, s27
	v_lshl_add_u64 v[148:149], s[20:21], 0, v[130:131]
	s_mov_b32 m0, s22
	s_nop 0
	global_load_lds_dwordx4 v[148:149], off
	v_lshl_add_u64 v[148:149], s[20:21], 0, v[134:135]
	s_add_i32 m0, s22, 0x2000
	s_nop 0
	global_load_lds_dwordx4 v[148:149], off
	s_waitcnt vmcnt(6)
	s_barrier
	v_mfma_f32_16x16x32_bf16 v[48:51], v[208:211], v[176:179], v[48:51]
	v_mfma_f32_16x16x32_bf16 v[40:43], v[216:219], v[176:179], v[40:43]
	v_mfma_f32_16x16x32_bf16 v[32:35], v[208:211], v[184:187], v[32:35]
	v_mfma_f32_16x16x32_bf16 v[24:27], v[216:219], v[184:187], v[24:27]
	v_mfma_f32_16x16x32_bf16 v[16:19], v[208:211], v[192:195], v[16:19]
	v_mfma_f32_16x16x32_bf16 v[8:11], v[216:219], v[192:195], v[8:11]
	v_mfma_f32_16x16x32_bf16 v[4:7], v[208:211], v[200:203], v[4:7]
	v_mfma_f32_16x16x32_bf16 v[0:3], v[216:219], v[200:203], v[0:3]
	v_mfma_f32_16x16x32_bf16 v[48:51], v[212:215], v[180:183], v[48:51]
	v_mfma_f32_16x16x32_bf16 v[40:43], v[220:223], v[180:183], v[40:43]
	v_mfma_f32_16x16x32_bf16 v[32:35], v[212:215], v[188:191], v[32:35]
	v_mfma_f32_16x16x32_bf16 v[24:27], v[220:223], v[188:191], v[24:27]
	v_mfma_f32_16x16x32_bf16 v[16:19], v[212:215], v[196:199], v[16:19]
	v_mfma_f32_16x16x32_bf16 v[8:11], v[220:223], v[196:199], v[8:11]
	v_mfma_f32_16x16x32_bf16 v[4:7], v[212:215], v[204:207], v[4:7]
	v_mfma_f32_16x16x32_bf16 v[0:3], v[220:223], v[204:207], v[0:3]
	s_add_i32 s61, s61, 2
	s_add_u32 s18, s18, 0x100
	s_addc_u32 s19, s19, 0
	s_add_u32 s59, s59, 0x100
	s_addc_u32 s60, s60, 0
	s_cmp_gt_u32 s61, 13
	s_barrier
	s_cbranch_scc0 .LBB0_593
; __device__ __forceinline__ uint4 pk8(f32x4 a, f32x4 b) { return make_uint4(cvt_pk_bf16(a[0], a[1]), cvt_pk_bf16(a[2], a[3]), cvt_pk_bf16(b[0], b[1]), cvt_pk_bf16(b[2], b[3])); }
;     __device__ __forceinline__ void operator()(AccRef acc, const Unit& u, int wr, int wc, int fr, int fq) const {
;         const int pi = u.pn / tpp; bf16_t* base = pi == 0 ? pl[0] : (pi == 1 ? pl[1] : (pi == 2 ? pl[2] : pl[3]));
;         const int cbase = (u.pn - pi * tpp) * 256 + wc * 32 + 8 * fq;
; #pragma unroll
;         for (int ai = 0; ai < 2; ++ai)
; #pragma unroll
;             for (int m = 0; m < 4; ++m) {
;                 const int r = u.pm * 256 + ai * 128 + wr * 64 + m * 16 + fr;
;                 float s = 1.f;
;                 if (SCALE == 1) s = rs[r];
;                 if (SCALE == 2) s = rsqrtf(rs[r] * (1.f / D) + EPS);
;                 bf16_t* rowp = base + (size_t)r * ldc + cbase;
; #pragma unroll
;                 for (int bj = 0; bj < 2; ++bj) *(uint4*)(rowp + bj * 128) = pk8(acc[ai][bj][m][0] * s, acc[ai][bj][m][1] * s);
;             }
;     }
	s_mul_hi_i32 s9, s56, 0x10624dd3
	s_lshr_b32 s11, s9, 31
	s_lshr_b32 s9, s9, 6
	s_add_i32 s9, s9, s11
	s_mulk_i32 s9, 0x3e8
	s_sub_i32 s9, s56, s9
	v_lshl_or_b32 v148, s9, 8, v160
	v_lshl_add_u32 v150, s16, 8, v158
	v_ashrrev_i32_e32 v149, 31, v148
	v_ashrrev_i32_e32 v151, 31, v150
	v_lshl_add_u64 v[148:149], v[148:149], 1, s[88:89]
	v_lshlrev_b64 v[164:165], 12, v[150:151]
	v_lshl_add_u64 v[164:165], v[148:149], 0, v[164:165]
	v_cvt_pk_bf16_f32 v124, v124, v125
	v_cvt_pk_bf16_f32 v125, v126, v127
	v_cvt_pk_bf16_f32 v126, v120, v121
	v_cvt_pk_bf16_f32 v127, v122, v123
	global_store_dwordx4 v[164:165], v[124:127], off
	v_cvt_pk_bf16_f32 v116, v116, v117
	v_cvt_pk_bf16_f32 v117, v118, v119
	v_cvt_pk_bf16_f32 v118, v108, v109
	v_or_b32_e32 v108, 16, v150
	v_ashrrev_i32_e32 v109, 31, v108
	v_lshlrev_b64 v[108:109], 12, v[108:109]
	v_cvt_pk_bf16_f32 v119, v110, v111
	global_store_dwordx4 v[164:165], v[116:119], off offset:256
	s_and_b64 vcc, exec, s[4:5]
	s_mov_b32 s56, s8
	v_lshl_add_u64 v[116:117], v[148:149], 0, v[108:109]
	v_cvt_pk_bf16_f32 v108, v112, v113
	v_cvt_pk_bf16_f32 v109, v114, v115
	v_cvt_pk_bf16_f32 v110, v104, v105
	v_cvt_pk_bf16_f32 v111, v106, v107
	global_store_dwordx4 v[116:117], v[108:111], off
	v_cvt_pk_bf16_f32 v100, v100, v101
	v_cvt_pk_bf16_f32 v101, v102, v103
	v_cvt_pk_bf16_f32 v102, v92, v93
	v_or_b32_e32 v92, 32, v150
	v_ashrrev_i32_e32 v93, 31, v92
	v_lshlrev_b64 v[92:93], 12, v[92:93]
	v_cvt_pk_bf16_f32 v103, v94, v95
	global_store_dwordx4 v[116:117], v[100:103], off offset:256
	s_mov_b32 s16, s10
	s_mov_b64 s[20:21], s[14:15]
	v_lshl_add_u64 v[100:101], v[148:149], 0, v[92:93]
	v_cvt_pk_bf16_f32 v92, v96, v97
	v_cvt_pk_bf16_f32 v93, v98, v99
	v_cvt_pk_bf16_f32 v94, v88, v89
	v_cvt_pk_bf16_f32 v95, v90, v91
	global_store_dwordx4 v[100:101], v[92:95], off
	v_cvt_pk_bf16_f32 v84, v84, v85
	v_cvt_pk_bf16_f32 v85, v86, v87
	v_cvt_pk_bf16_f32 v86, v76, v77
	v_or_b32_e32 v76, 48, v150
	v_ashrrev_i32_e32 v77, 31, v76
	v_lshlrev_b64 v[76:77], 12, v[76:77]
	v_cvt_pk_bf16_f32 v87, v78, v79
	global_store_dwordx4 v[100:101], v[84:87], off offset:256
	s_mov_b64 s[18:19], s[12:13]
	s_nop 0
	v_lshl_add_u64 v[84:85], v[148:149], 0, v[76:77]
	v_cvt_pk_bf16_f32 v76, v80, v81
	v_cvt_pk_bf16_f32 v77, v82, v83
	v_cvt_pk_bf16_f32 v78, v72, v73
	v_cvt_pk_bf16_f32 v79, v74, v75
	global_store_dwordx4 v[84:85], v[76:79], off
	v_cvt_pk_bf16_f32 v68, v68, v69
	v_cvt_pk_bf16_f32 v69, v70, v71
	v_cvt_pk_bf16_f32 v70, v64, v65
	v_add_u32_e32 v64, 0x80, v150
	v_ashrrev_i32_e32 v65, 31, v64
	v_lshlrev_b64 v[64:65], 12, v[64:65]
	v_lshl_add_u64 v[64:65], v[148:149], 0, v[64:65]
	v_cvt_pk_bf16_f32 v71, v66, v67
	global_store_dwordx4 v[84:85], v[68:71], off offset:256
	v_cvt_pk_bf16_f32 v60, v60, v61
	v_cvt_pk_bf16_f32 v61, v62, v63
	v_cvt_pk_bf16_f32 v62, v56, v57
	v_cvt_pk_bf16_f32 v63, v58, v59
	global_store_dwordx4 v[64:65], v[60:63], off
	v_cvt_pk_bf16_f32 v48, v48, v49
	v_cvt_pk_bf16_f32 v49, v50, v51
	v_cvt_pk_bf16_f32 v50, v40, v41
	v_add_u32_e32 v40, 0x90, v150
	v_ashrrev_i32_e32 v41, 31, v40
	v_lshlrev_b64 v[40:41], 12, v[40:41]
	v_cvt_pk_bf16_f32 v51, v42, v43
	global_store_dwordx4 v[64:65], v[48:51], off offset:256
	s_nop 1
	v_lshl_add_u64 v[48:49], v[148:149], 0, v[40:41]
	v_cvt_pk_bf16_f32 v40, v52, v53
	v_cvt_pk_bf16_f32 v41, v54, v55
	v_cvt_pk_bf16_f32 v42, v44, v45
	v_cvt_pk_bf16_f32 v43, v46, v47
	global_store_dwordx4 v[48:49], v[40:43], off
	v_cvt_pk_bf16_f32 v32, v32, v33
	v_cvt_pk_bf16_f32 v33, v34, v35
	v_cvt_pk_bf16_f32 v34, v24, v25
	v_add_u32_e32 v24, 0xa0, v150
	v_ashrrev_i32_e32 v25, 31, v24
	v_lshlrev_b64 v[24:25], 12, v[24:25]
	v_cvt_pk_bf16_f32 v35, v26, v27
	global_store_dwordx4 v[48:49], v[32:35], off offset:256
	s_nop 1
	v_lshl_add_u64 v[32:33], v[148:149], 0, v[24:25]
	v_cvt_pk_bf16_f32 v24, v36, v37
	v_cvt_pk_bf16_f32 v25, v38, v39
	v_cvt_pk_bf16_f32 v26, v28, v29
	v_cvt_pk_bf16_f32 v27, v30, v31
	global_store_dwordx4 v[32:33], v[24:27], off
	v_cvt_pk_bf16_f32 v16, v16, v17
	v_cvt_pk_bf16_f32 v17, v18, v19
	v_cvt_pk_bf16_f32 v18, v8, v9
	v_add_u32_e32 v8, 0xb0, v150
	v_ashrrev_i32_e32 v9, 31, v8
	v_lshlrev_b64 v[8:9], 12, v[8:9]
	v_cvt_pk_bf16_f32 v19, v10, v11
	global_store_dwordx4 v[32:33], v[16:19], off offset:256
	s_nop 1
	v_lshl_add_u64 v[16:17], v[148:149], 0, v[8:9]
	v_cvt_pk_bf16_f32 v8, v20, v21
	v_cvt_pk_bf16_f32 v9, v22, v23
	v_cvt_pk_bf16_f32 v10, v12, v13
	v_cvt_pk_bf16_f32 v11, v14, v15
	global_store_dwordx4 v[16:17], v[8:11], off
	v_cvt_pk_bf16_f32 v4, v4, v5
	v_cvt_pk_bf16_f32 v5, v6, v7
	v_cvt_pk_bf16_f32 v6, v0, v1
	v_cvt_pk_bf16_f32 v7, v2, v3
	global_store_dwordx4 v[16:17], v[4:7], off offset:256
	s_cbranch_vccz .LBB0_586
	s_waitcnt vmcnt(0)
	s_cmpk_gt_u32 s3, 0xff
	s_cbranch_scc1 .LBB0_597
	s_barrier

; #define PG8_STAGE(bufoff, gbase, voff) do { _Pragma("unroll") for (int _i = 0; _i < 2; ++_i) \
;         __builtin_amdgcn_global_load_lds((const unsigned*)((const char*)(gbase) + (voff)[_i]), (PG8_LAS unsigned*)(lds + (bufoff) + ldsw + _i * 8192), 16, 0, 0); } while (0)
; #define PG8_LDA(dst, b, h) do { _Pragma("unroll") for (int m = 0; m < 4; ++m) _Pragma("unroll") for (int k = 0; k < 2; ++k) dst[m][k] = *(const PG8_LAS bf16x8*)(lds + PG8_SA(b, h) + aoff + m * 2048 + k * 1024); } while (0)
; #define PG8_LDB(dst, b, h) do { _Pragma("unroll") for (int n = 0; n < 2; ++n) _Pragma("unroll") for (int k = 0; k < 2; ++k) dst[n][k] = *(const PG8_LAS bf16x8*)(lds + PG8_SB(b, h) + boff + n * 2048 + k * 1024); } while (0)
; #define PG8_MMA(ai, bj, At, Bt) do { __builtin_amdgcn_s_setprio(1); _Pragma("unroll") for (int m = 0; m < 4; ++m) _Pragma("unroll") for (int n = 0; n < 2; ++n) _Pragma("unroll") for (int k = 0; k < 2; ++k) \
;         acc[ai][bj][m][n] = __builtin_amdgcn_mfma_f32_16x16x32_bf16(Bt[n][k], At[m][k], acc[ai][bj][m][n], 0, 0, 0); __builtin_amdgcn_s_setprio(0); } while (0)
; #define PG8_WAIT_L(n) asm volatile("s_waitcnt lgkmcnt(" #n ")" ::: "memory")
; #define PG8_BAR __builtin_amdgcn_s_barrier()
; #define PG8_SCHED __builtin_amdgcn_sched_barrier(0)
; template <class Epi, class Sched>
; __device__ __forceinline__ void gemm_phase(PG8_LAS unsigned char* lds, const Gemm g, const Sched& S, const Epi& E) {
;     ...
;             const bool last = (t == nt - 2);
;             const char* a1 = cA + (size_t)(t + 1) * kstep;
;             const char* a2 = last ? nA : cA + (size_t)(t + 2) * kstep; const char* b2 = last ? nB : cB + (size_t)(t + 2) * kstep;
;             const char* a3 = a2 + kstep; const char* b3 = b2 + kstep;
;             if (last && has_next) S.a_ready(nxt);
;             PG8_LDB(B0, 0, 0); PG8_SCHED; PG8_LDA(At, 0, 0); PG8_STAGE(PG8_SA(1, 1), a1 + hstep, voffA);
;             PG8_WAIT_L(8); PG8_BAR; PG8_WAIT_L(0); PG8_MMA(0, 0, At, B0); PG8_BAR; PG8_SCHED;
;             PG8_LDB(B1, 0, 1); PG8_STAGE(PG8_SB(0, 0), b2, voffB);
;             PG8_BAR; PG8_WAIT_L(0); PG8_MMA(0, 1, At, B1); PG8_BAR;
;             PG8_LDA(At, 0, 1); PG8_STAGE(PG8_SA(0, 0), a2, voffA);
;             PG8_BAR; PG8_WAIT_L(0); PG8_MMA(1, 0, At, B0); PG8_BAR; PG8_SCHED;
.LBB0_613:
	ds_read_b128 v[148:151], v145
	ds_read_b128 v[160:163], v145 offset:1024
	ds_read_b128 v[164:167], v145 offset:2048
	ds_read_b128 v[168:171], v145 offset:3072
	s_add_u32 s18, s16, 0xfffc0080
	s_addc_u32 s19, s17, -1
	s_cmp_eq_u32 s61, 12
	s_cselect_b32 s21, s9, s19
	s_cselect_b32 s20, s57, s18
	s_cselect_b32 s19, s7, s60
	s_cselect_b32 s18, s58, s59
	v_lshl_add_u64 v[156:157], s[16:17], 0, v[136:137]
	s_add_i32 m0, s15, 0xc000
	ds_read_b128 v[172:175], v147
	ds_read_b128 v[176:179], v147 offset:1024
	ds_read_b128 v[180:183], v147 offset:2048
	ds_read_b128 v[184:187], v147 offset:3072
	ds_read_b128 v[188:191], v147 offset:4096
	ds_read_b128 v[192:195], v147 offset:5120
	ds_read_b128 v[196:199], v147 offset:6144
	ds_read_b128 v[200:203], v147 offset:7168
	global_load_lds_dwordx4 v[156:157], off
	v_lshl_add_u64 v[156:157], s[16:17], 0, v[138:139]
	s_add_i32 m0, s15, 0xe000
	s_nop 0
	global_load_lds_dwordx4 v[156:157], off
	s_waitcnt lgkmcnt(8)
	s_barrier
	s_waitcnt lgkmcnt(0)
	s_waitcnt lgkmcnt(0)
	v_mfma_f32_16x16x32_bf16 v[124:127], v[148:151], v[172:175], v[124:127]
	v_mfma_f32_16x16x32_bf16 v[120:123], v[164:167], v[172:175], v[120:123]
	v_mfma_f32_16x16x32_bf16 v[112:115], v[148:151], v[180:183], v[112:115]
	v_mfma_f32_16x16x32_bf16 v[104:107], v[164:167], v[180:183], v[104:107]
	v_mfma_f32_16x16x32_bf16 v[96:99], v[148:151], v[188:191], v[96:99]
	v_mfma_f32_16x16x32_bf16 v[88:91], v[164:167], v[188:191], v[88:91]
	v_mfma_f32_16x16x32_bf16 v[80:83], v[148:151], v[196:199], v[80:83]
	v_mfma_f32_16x16x32_bf16 v[72:75], v[164:167], v[196:199], v[72:75]
	v_mfma_f32_16x16x32_bf16 v[124:127], v[160:163], v[176:179], v[124:127]
	v_mfma_f32_16x16x32_bf16 v[120:123], v[168:171], v[176:179], v[120:123]
	v_mfma_f32_16x16x32_bf16 v[112:115], v[160:163], v[184:187], v[112:115]
	v_mfma_f32_16x16x32_bf16 v[104:107], v[168:171], v[184:187], v[104:107]
	v_mfma_f32_16x16x32_bf16 v[96:99], v[160:163], v[192:195], v[96:99]
	v_mfma_f32_16x16x32_bf16 v[88:91], v[168:171], v[192:195], v[88:91]
	v_mfma_f32_16x16x32_bf16 v[80:83], v[160:163], v[200:203], v[80:83]
	v_mfma_f32_16x16x32_bf16 v[72:75], v[168:171], v[200:203], v[72:75]
	s_barrier
	s_add_i32 s30, s50, s27
	v_lshl_add_u64 v[156:157], s[18:19], 0, v[130:131]
	s_mov_b32 m0, s30
	ds_read_b128 v[204:207], v152
	ds_read_b128 v[208:211], v152 offset:1024
	ds_read_b128 v[212:215], v152 offset:2048
	ds_read_b128 v[216:219], v152 offset:3072
	global_load_lds_dwordx4 v[156:157], off
	v_lshl_add_u64 v[220:221], s[18:19], 0, v[134:135]
	s_add_i32 m0, s30, 0x2000
	s_nop 0
	global_load_lds_dwordx4 v[220:221], off
	s_barrier
	s_waitcnt lgkmcnt(0)
	s_waitcnt lgkmcnt(0)
	v_mfma_f32_16x16x32_bf16 v[116:119], v[204:207], v[172:175], v[116:119]
	v_mfma_f32_16x16x32_bf16 v[108:111], v[212:215], v[172:175], v[108:111]
	v_mfma_f32_16x16x32_bf16 v[100:103], v[204:207], v[180:183], v[100:103]
	v_mfma_f32_16x16x32_bf16 v[92:95], v[212:215], v[180:183], v[92:95]
	v_mfma_f32_16x16x32_bf16 v[84:87], v[204:207], v[188:191], v[84:87]
	v_mfma_f32_16x16x32_bf16 v[76:79], v[212:215], v[188:191], v[76:79]
	v_mfma_f32_16x16x32_bf16 v[68:71], v[204:207], v[196:199], v[68:71]
	v_mfma_f32_16x16x32_bf16 v[64:67], v[212:215], v[196:199], v[64:67]
	v_mfma_f32_16x16x32_bf16 v[116:119], v[208:211], v[176:179], v[116:119]
	v_mfma_f32_16x16x32_bf16 v[108:111], v[216:219], v[176:179], v[108:111]
	v_mfma_f32_16x16x32_bf16 v[100:103], v[208:211], v[184:187], v[100:103]
	v_mfma_f32_16x16x32_bf16 v[92:95], v[216:219], v[184:187], v[92:95]
	v_mfma_f32_16x16x32_bf16 v[84:87], v[208:211], v[192:195], v[84:87]
	v_mfma_f32_16x16x32_bf16 v[76:79], v[216:219], v[192:195], v[76:79]
	v_mfma_f32_16x16x32_bf16 v[68:71], v[208:211], v[200:203], v[68:71]
	v_mfma_f32_16x16x32_bf16 v[64:67], v[216:219], v[200:203], v[64:67]
	s_mov_b32 m0, s15
	v_lshl_add_u64 v[222:223], s[20:21], 0, v[128:129]
	s_barrier
	ds_read_b128 v[172:175], v147 offset:16384
	ds_read_b128 v[176:179], v147 offset:17408
	ds_read_b128 v[180:183], v147 offset:18432
	ds_read_b128 v[184:187], v147 offset:19456
	ds_read_b128 v[188:191], v147 offset:20480
	ds_read_b128 v[192:195], v147 offset:21504
	ds_read_b128 v[196:199], v147 offset:22528
	ds_read_b128 v[200:203], v147 offset:23552
	global_load_lds_dwordx4 v[222:223], off
	v_lshl_add_u64 v[224:225], s[20:21], 0, v[132:133]
	s_mov_b32 m0, s42
	s_nop 0
	global_load_lds_dwordx4 v[224:225], off
	s_barrier
	s_waitcnt lgkmcnt(0)
	s_waitcnt lgkmcnt(0)
	v_mfma_f32_16x16x32_bf16 v[60:63], v[148:151], v[172:175], v[60:63]
	v_mfma_f32_16x16x32_bf16 v[56:59], v[164:167], v[172:175], v[56:59]
	v_mfma_f32_16x16x32_bf16 v[52:55], v[148:151], v[180:183], v[52:55]
	v_mfma_f32_16x16x32_bf16 v[44:47], v[164:167], v[180:183], v[44:47]
	v_mfma_f32_16x16x32_bf16 v[36:39], v[148:151], v[188:191], v[36:39]
	v_mfma_f32_16x16x32_bf16 v[28:31], v[164:167], v[188:191], v[28:31]
	v_mfma_f32_16x16x32_bf16 v[20:23], v[148:151], v[196:199], v[20:23]
	v_mfma_f32_16x16x32_bf16 v[12:15], v[164:167], v[196:199], v[12:15]
	v_mfma_f32_16x16x32_bf16 v[60:63], v[160:163], v[176:179], v[60:63]
	v_mfma_f32_16x16x32_bf16 v[56:59], v[168:171], v[176:179], v[56:59]
	v_mfma_f32_16x16x32_bf16 v[52:55], v[160:163], v[184:187], v[52:55]
	v_mfma_f32_16x16x32_bf16 v[44:47], v[168:171], v[184:187], v[44:47]
	v_mfma_f32_16x16x32_bf16 v[36:39], v[160:163], v[192:195], v[36:39]
	v_mfma_f32_16x16x32_bf16 v[28:31], v[168:171], v[192:195], v[28:31]
	v_mfma_f32_16x16x32_bf16 v[20:23], v[160:163], v[200:203], v[20:23]
	v_mfma_f32_16x16x32_bf16 v[12:15], v[168:171], v[200:203], v[12:15]
	s_barrier
; #define PG8_STAGE(bufoff, gbase, voff) do { _Pragma("unroll") for (int _i = 0; _i < 2; ++_i) \
;         __builtin_amdgcn_global_load_lds((const unsigned*)((const char*)(gbase) + (voff)[_i]), (PG8_LAS unsigned*)(lds + (bufoff) + ldsw + _i * 8192), 16, 0, 0); } while (0)
; #define PG8_LDA(dst, b, h) do { _Pragma("unroll") for (int m = 0; m < 4; ++m) _Pragma("unroll") for (int k = 0; k < 2; ++k) dst[m][k] = *(const PG8_LAS bf16x8*)(lds + PG8_SA(b, h) + aoff + m * 2048 + k * 1024); } while (0)
; #define PG8_LDB(dst, b, h) do { _Pragma("unroll") for (int n = 0; n < 2; ++n) _Pragma("unroll") for (int k = 0; k < 2; ++k) dst[n][k] = *(const PG8_LAS bf16x8*)(lds + PG8_SB(b, h) + boff + n * 2048 + k * 1024); } while (0)
; #define PG8_MMA(ai, bj, At, Bt) do { __builtin_amdgcn_s_setprio(1); _Pragma("unroll") for (int m = 0; m < 4; ++m) _Pragma("unroll") for (int n = 0; n < 2; ++n) _Pragma("unroll") for (int k = 0; k < 2; ++k) \
;         acc[ai][bj][m][n] = __builtin_amdgcn_mfma_f32_16x16x32_bf16(Bt[n][k], At[m][k], acc[ai][bj][m][n], 0, 0, 0); __builtin_amdgcn_s_setprio(0); } while (0)
; #define PG8_WAIT_V(n) asm volatile("s_waitcnt vmcnt(" #n ")" ::: "memory")
; #define PG8_WAIT_L(n) asm volatile("s_waitcnt lgkmcnt(" #n ")" ::: "memory")
; #define PG8_BAR __builtin_amdgcn_s_barrier()
; #define PG8_SCHED __builtin_amdgcn_sched_barrier(0)
; template <class Epi, class Sched>
; __device__ __forceinline__ void gemm_phase(PG8_LAS unsigned char* lds, const Gemm g, const Sched& S, const Epi& E) {
;     ...
;             PG8_STAGE(PG8_SB(0, 1), b2 + hstep, voffB);
;             PG8_WAIT_V(6); PG8_BAR; PG8_MMA(1, 1, At, B1); PG8_BAR;
;             PG8_LDB(B0, 1, 0); PG8_SCHED; PG8_LDA(At, 1, 0); PG8_STAGE(PG8_SA(0, 1), a2 + hstep, voffA);
;             PG8_WAIT_L(8); PG8_BAR; PG8_WAIT_L(0); PG8_MMA(0, 0, At, B0); PG8_BAR; PG8_SCHED;
;             PG8_LDB(B1, 1, 1); PG8_STAGE(PG8_SB(1, 0), b3, voffB);
;             PG8_BAR; PG8_WAIT_L(0); PG8_MMA(0, 1, At, B1); PG8_BAR;
;             PG8_LDA(At, 1, 1); PG8_STAGE(PG8_SA(1, 0), a3, voffA);
	s_add_u32 s30, s18, 0x40000
	s_addc_u32 s31, s19, 0
	s_add_i32 s38, s51, s27
	v_lshl_add_u64 v[148:149], s[30:31], 0, v[130:131]
	s_mov_b32 m0, s38
	s_nop 0
	global_load_lds_dwordx4 v[148:149], off
	v_lshl_add_u64 v[148:149], s[30:31], 0, v[134:135]
	s_add_i32 m0, s38, 0x2000
	s_nop 0
	global_load_lds_dwordx4 v[148:149], off
	s_waitcnt vmcnt(6)
	s_barrier
	v_mfma_f32_16x16x32_bf16 v[48:51], v[204:207], v[172:175], v[48:51]
	v_mfma_f32_16x16x32_bf16 v[40:43], v[212:215], v[172:175], v[40:43]
	v_mfma_f32_16x16x32_bf16 v[32:35], v[204:207], v[180:183], v[32:35]
	v_mfma_f32_16x16x32_bf16 v[24:27], v[212:215], v[180:183], v[24:27]
	v_mfma_f32_16x16x32_bf16 v[16:19], v[204:207], v[188:191], v[16:19]
	v_mfma_f32_16x16x32_bf16 v[8:11], v[212:215], v[188:191], v[8:11]
	v_mfma_f32_16x16x32_bf16 v[4:7], v[204:207], v[196:199], v[4:7]
	v_mfma_f32_16x16x32_bf16 v[0:3], v[212:215], v[196:199], v[0:3]
	v_mfma_f32_16x16x32_bf16 v[48:51], v[208:211], v[176:179], v[48:51]
	v_mfma_f32_16x16x32_bf16 v[40:43], v[216:219], v[176:179], v[40:43]
	v_mfma_f32_16x16x32_bf16 v[32:35], v[208:211], v[184:187], v[32:35]
	v_mfma_f32_16x16x32_bf16 v[24:27], v[216:219], v[184:187], v[24:27]
	v_mfma_f32_16x16x32_bf16 v[16:19], v[208:211], v[192:195], v[16:19]
	v_mfma_f32_16x16x32_bf16 v[8:11], v[216:219], v[192:195], v[8:11]
	v_mfma_f32_16x16x32_bf16 v[4:7], v[208:211], v[200:203], v[4:7]
	v_mfma_f32_16x16x32_bf16 v[0:3], v[216:219], v[200:203], v[0:3]
	s_add_i32 s30, 0, 0x18000
	v_add_u32_e32 v155, s30, v153
	s_barrier
	ds_read_b128 v[148:151], v155
	ds_read_b128 v[160:163], v155 offset:1024
	ds_read_b128 v[164:167], v155 offset:2048
	ds_read_b128 v[168:171], v155 offset:3072
	s_add_u32 s20, s20, 0x40000
	s_addc_u32 s21, s21, 0
	s_mov_b32 m0, s43
	v_lshl_add_u64 v[204:205], s[20:21], 0, v[128:129]
	ds_read_b128 v[172:175], v147 offset:32768
	ds_read_b128 v[176:179], v147 offset:33792
	ds_read_b128 v[180:183], v147 offset:34816
	ds_read_b128 v[184:187], v147 offset:35840
	ds_read_b128 v[188:191], v147 offset:36864
	ds_read_b128 v[192:195], v147 offset:37888
	ds_read_b128 v[196:199], v147 offset:38912
	ds_read_b128 v[200:203], v147 offset:39936
	global_load_lds_dwordx4 v[204:205], off
	v_lshl_add_u64 v[204:205], s[20:21], 0, v[132:133]
	s_mov_b32 m0, s44
	s_nop 0
	global_load_lds_dwordx4 v[204:205], off
	s_waitcnt lgkmcnt(8)
	s_barrier
	s_waitcnt lgkmcnt(0)
	s_waitcnt lgkmcnt(0)
	v_mfma_f32_16x16x32_bf16 v[124:127], v[148:151], v[172:175], v[124:127]
	v_mfma_f32_16x16x32_bf16 v[120:123], v[164:167], v[172:175], v[120:123]
	v_mfma_f32_16x16x32_bf16 v[112:115], v[148:151], v[180:183], v[112:115]
	v_mfma_f32_16x16x32_bf16 v[104:107], v[164:167], v[180:183], v[104:107]
	v_mfma_f32_16x16x32_bf16 v[96:99], v[148:151], v[188:191], v[96:99]
	v_mfma_f32_16x16x32_bf16 v[88:91], v[164:167], v[188:191], v[88:91]
	v_mfma_f32_16x16x32_bf16 v[80:83], v[148:151], v[196:199], v[80:83]
	v_mfma_f32_16x16x32_bf16 v[72:75], v[164:167], v[196:199], v[72:75]
	v_mfma_f32_16x16x32_bf16 v[124:127], v[160:163], v[176:179], v[124:127]
	v_mfma_f32_16x16x32_bf16 v[120:123], v[168:171], v[176:179], v[120:123]
	v_mfma_f32_16x16x32_bf16 v[112:115], v[160:163], v[184:187], v[112:115]
	v_mfma_f32_16x16x32_bf16 v[104:107], v[168:171], v[184:187], v[104:107]
	v_mfma_f32_16x16x32_bf16 v[96:99], v[160:163], v[192:195], v[96:99]
	v_mfma_f32_16x16x32_bf16 v[88:91], v[168:171], v[192:195], v[88:91]
	v_mfma_f32_16x16x32_bf16 v[80:83], v[160:163], v[200:203], v[80:83]
	v_mfma_f32_16x16x32_bf16 v[72:75], v[168:171], v[200:203], v[72:75]
	s_barrier
	s_add_i32 s20, 0, 0x1c000
	s_add_i32 s21, s30, s27
	v_add_u32_e32 v155, s20, v153
	v_lshl_add_u64 v[156:157], v[156:157], 0, s[0:1]
	s_mov_b32 m0, s21
	ds_read_b128 v[204:207], v155
	ds_read_b128 v[208:211], v155 offset:1024
	ds_read_b128 v[212:215], v155 offset:2048
	ds_read_b128 v[216:219], v155 offset:3072
	global_load_lds_dwordx4 v[156:157], off
	v_lshl_add_u64 v[156:157], v[220:221], 0, s[0:1]
	s_add_i32 m0, s21, 0x2000
	s_nop 0
	global_load_lds_dwordx4 v[156:157], off
	s_barrier
	s_waitcnt lgkmcnt(0)
	s_waitcnt lgkmcnt(0)
	v_mfma_f32_16x16x32_bf16 v[116:119], v[204:207], v[172:175], v[116:119]
	v_mfma_f32_16x16x32_bf16 v[108:111], v[212:215], v[172:175], v[108:111]
	v_mfma_f32_16x16x32_bf16 v[100:103], v[204:207], v[180:183], v[100:103]
	v_mfma_f32_16x16x32_bf16 v[92:95], v[212:215], v[180:183], v[92:95]
	v_mfma_f32_16x16x32_bf16 v[84:87], v[204:207], v[188:191], v[84:87]
	v_mfma_f32_16x16x32_bf16 v[76:79], v[212:215], v[188:191], v[76:79]
	v_mfma_f32_16x16x32_bf16 v[68:71], v[204:207], v[196:199], v[68:71]
	v_mfma_f32_16x16x32_bf16 v[64:67], v[212:215], v[196:199], v[64:67]
	v_mfma_f32_16x16x32_bf16 v[116:119], v[208:211], v[176:179], v[116:119]
	v_mfma_f32_16x16x32_bf16 v[108:111], v[216:219], v[176:179], v[108:111]
	v_mfma_f32_16x16x32_bf16 v[100:103], v[208:211], v[184:187], v[100:103]
	v_mfma_f32_16x16x32_bf16 v[92:95], v[216:219], v[184:187], v[92:95]
	v_mfma_f32_16x16x32_bf16 v[84:87], v[208:211], v[192:195], v[84:87]
	v_mfma_f32_16x16x32_bf16 v[76:79], v[216:219], v[192:195], v[76:79]
	v_mfma_f32_16x16x32_bf16 v[68:71], v[208:211], v[200:203], v[68:71]
	v_mfma_f32_16x16x32_bf16 v[64:67], v[216:219], v[200:203], v[64:67]
	s_mov_b32 m0, s46
	v_lshl_add_u64 v[156:157], v[222:223], 0, s[0:1]
	s_barrier
	ds_read_b128 v[172:175], v147 offset:49152
	ds_read_b128 v[176:179], v147 offset:50176
	ds_read_b128 v[180:183], v147 offset:51200
	ds_read_b128 v[184:187], v147 offset:52224
	ds_read_b128 v[188:191], v147 offset:53248
	ds_read_b128 v[192:195], v147 offset:54272
	ds_read_b128 v[196:199], v147 offset:55296
	ds_read_b128 v[200:203], v147 offset:56320
	global_load_lds_dwordx4 v[156:157], off
	v_lshl_add_u64 v[156:157], v[224:225], 0, s[0:1]
	s_mov_b32 m0, s47
	s_nop 0
	global_load_lds_dwordx4 v[156:157], off
	s_barrier
; #define PG8_STAGE(bufoff, gbase, voff) do { _Pragma("unroll") for (int _i = 0; _i < 2; ++_i) \
;         __builtin_amdgcn_global_load_lds((const unsigned*)((const char*)(gbase) + (voff)[_i]), (PG8_LAS unsigned*)(lds + (bufoff) + ldsw + _i * 8192), 16, 0, 0); } while (0)
; #define PG8_MMA(ai, bj, At, Bt) do { __builtin_amdgcn_s_setprio(1); _Pragma("unroll") for (int m = 0; m < 4; ++m) _Pragma("unroll") for (int n = 0; n < 2; ++n) _Pragma("unroll") for (int k = 0; k < 2; ++k) \
;         acc[ai][bj][m][n] = __builtin_amdgcn_mfma_f32_16x16x32_bf16(Bt[n][k], At[m][k], acc[ai][bj][m][n], 0, 0, 0); __builtin_amdgcn_s_setprio(0); } while (0)
; #define PG8_WAIT_V(n) asm volatile("s_waitcnt vmcnt(" #n ")" ::: "memory")
; #define PG8_WAIT_L(n) asm volatile("s_waitcnt lgkmcnt(" #n ")" ::: "memory")
; #define PG8_BAR __builtin_amdgcn_s_barrier()
; #define PG8_SCHED __builtin_amdgcn_sched_barrier(0)
; template <class Epi, class Sched>
; __device__ __forceinline__ void gemm_phase(PG8_LAS unsigned char* lds, const Gemm g, const Sched& S, const Epi& E) {
;     ...
;             PG8_BAR; PG8_WAIT_L(0); PG8_MMA(1, 0, At, B0); PG8_BAR; PG8_SCHED;
;             PG8_STAGE(PG8_SB(1, 1), b3 + hstep, voffB);
;             PG8_WAIT_V(6); PG8_BAR; PG8_MMA(1, 1, At, B1); PG8_BAR;
	s_waitcnt lgkmcnt(0)
	s_waitcnt lgkmcnt(0)
	v_mfma_f32_16x16x32_bf16 v[60:63], v[148:151], v[172:175], v[60:63]
	v_mfma_f32_16x16x32_bf16 v[56:59], v[164:167], v[172:175], v[56:59]
	v_mfma_f32_16x16x32_bf16 v[52:55], v[148:151], v[180:183], v[52:55]
	v_mfma_f32_16x16x32_bf16 v[44:47], v[164:167], v[180:183], v[44:47]
	v_mfma_f32_16x16x32_bf16 v[36:39], v[148:151], v[188:191], v[36:39]
	v_mfma_f32_16x16x32_bf16 v[28:31], v[164:167], v[188:191], v[28:31]
	v_mfma_f32_16x16x32_bf16 v[20:23], v[148:151], v[196:199], v[20:23]
	v_mfma_f32_16x16x32_bf16 v[12:15], v[164:167], v[196:199], v[12:15]
	v_mfma_f32_16x16x32_bf16 v[60:63], v[160:163], v[176:179], v[60:63]
	v_mfma_f32_16x16x32_bf16 v[56:59], v[168:171], v[176:179], v[56:59]
	v_mfma_f32_16x16x32_bf16 v[52:55], v[160:163], v[184:187], v[52:55]
	v_mfma_f32_16x16x32_bf16 v[44:47], v[168:171], v[184:187], v[44:47]
	v_mfma_f32_16x16x32_bf16 v[36:39], v[160:163], v[192:195], v[36:39]
	v_mfma_f32_16x16x32_bf16 v[28:31], v[168:171], v[192:195], v[28:31]
	v_mfma_f32_16x16x32_bf16 v[20:23], v[160:163], v[200:203], v[20:23]
	v_mfma_f32_16x16x32_bf16 v[12:15], v[168:171], v[200:203], v[12:15]
	s_barrier
	s_add_u32 s18, s18, 0x40080
	s_addc_u32 s19, s19, 0
	s_add_i32 s20, s20, s27
	v_lshl_add_u64 v[148:149], s[18:19], 0, v[130:131]
	s_mov_b32 m0, s20
	s_nop 0
	global_load_lds_dwordx4 v[148:149], off
	v_lshl_add_u64 v[148:149], s[18:19], 0, v[134:135]
	s_add_i32 m0, s20, 0x2000
	s_nop 0
	global_load_lds_dwordx4 v[148:149], off
	s_waitcnt vmcnt(6)
	s_barrier
	v_mfma_f32_16x16x32_bf16 v[48:51], v[204:207], v[172:175], v[48:51]
	v_mfma_f32_16x16x32_bf16 v[40:43], v[212:215], v[172:175], v[40:43]
	v_mfma_f32_16x16x32_bf16 v[32:35], v[204:207], v[180:183], v[32:35]
	v_mfma_f32_16x16x32_bf16 v[24:27], v[212:215], v[180:183], v[24:27]
	v_mfma_f32_16x16x32_bf16 v[16:19], v[204:207], v[188:191], v[16:19]
	v_mfma_f32_16x16x32_bf16 v[8:11], v[212:215], v[188:191], v[8:11]
	v_mfma_f32_16x16x32_bf16 v[4:7], v[204:207], v[196:199], v[4:7]
	v_mfma_f32_16x16x32_bf16 v[0:3], v[212:215], v[196:199], v[0:3]
	v_mfma_f32_16x16x32_bf16 v[48:51], v[208:211], v[176:179], v[48:51]
	v_mfma_f32_16x16x32_bf16 v[40:43], v[216:219], v[176:179], v[40:43]
	v_mfma_f32_16x16x32_bf16 v[32:35], v[208:211], v[184:187], v[32:35]
	v_mfma_f32_16x16x32_bf16 v[24:27], v[216:219], v[184:187], v[24:27]
	v_mfma_f32_16x16x32_bf16 v[16:19], v[208:211], v[192:195], v[16:19]
	v_mfma_f32_16x16x32_bf16 v[8:11], v[216:219], v[192:195], v[8:11]
	v_mfma_f32_16x16x32_bf16 v[4:7], v[208:211], v[200:203], v[4:7]
	v_mfma_f32_16x16x32_bf16 v[0:3], v[216:219], v[200:203], v[0:3]
	s_add_i32 s61, s61, 2
	s_add_u32 s16, s16, 0x100
	s_addc_u32 s17, s17, 0
	s_add_u32 s59, s59, 0x100
	s_addc_u32 s60, s60, 0
	s_cmp_gt_u32 s61, 13
	s_barrier
	s_cbranch_scc0 .LBB0_613
; __device__ __forceinline__ uint4 pk8(f32x4 a, f32x4 b) { return make_uint4(cvt_pk_bf16(a[0], a[1]), cvt_pk_bf16(a[2], a[3]), cvt_pk_bf16(b[0], b[1]), cvt_pk_bf16(b[2], b[3])); }
;     __device__ __forceinline__ void operator()(AccRef acc, const Unit& u, int wr, int wc, int fr, int fq) const {
;         const int pi = u.pn / tpp; bf16_t* base = pi == 0 ? pl[0] : (pi == 1 ? pl[1] : (pi == 2 ? pl[2] : pl[3]));
;         const int cbase = (u.pn - pi * tpp) * 256 + wc * 32 + 8 * fq;
; #pragma unroll
;         for (int ai = 0; ai < 2; ++ai)
; #pragma unroll
;             for (int m = 0; m < 4; ++m) {
;                 const int r = u.pm * 256 + ai * 128 + wr * 64 + m * 16 + fr;
;                 float s = 1.f;
;                 if (SCALE == 1) s = rs[r];
;                 if (SCALE == 2) s = rsqrtf(rs[r] * (1.f / D) + EPS);
;                 bf16_t* rowp = base + (size_t)r * ldc + cbase;
; #pragma unroll
;                 for (int bj = 0; bj < 2; ++bj) *(uint4*)(rowp + bj * 128) = pk8(acc[ai][bj][m][0] * s, acc[ai][bj][m][1] * s);
;             }
;     }
	s_add_i32 s7, s56, 0x3e7
	s_cmpk_lt_u32 s7, 0x7cf
	s_cselect_b32 s7, 0x8000000, 0
	s_add_u32 s16, s88, s7
	s_mul_hi_i32 s7, s56, 0x10624dd3
	s_addc_u32 s17, s89, 0
	s_lshr_b32 s9, s7, 31
	s_lshr_b32 s7, s7, 6
	s_add_i32 s7, s7, s9
	s_mulk_i32 s7, 0x3e8
	s_sub_i32 s7, s56, s7
	v_lshl_or_b32 v148, s7, 8, v154
	v_lshl_add_u32 v150, s14, 8, v158
	v_ashrrev_i32_e32 v149, 31, v148
	v_ashrrev_i32_e32 v151, 31, v150
	v_lshl_add_u64 v[148:149], v[148:149], 1, s[16:17]
	v_lshlrev_b64 v[156:157], 12, v[150:151]
	v_lshl_add_u64 v[156:157], v[148:149], 0, v[156:157]
	v_cvt_pk_bf16_f32 v124, v124, v125
	v_cvt_pk_bf16_f32 v125, v126, v127
	v_cvt_pk_bf16_f32 v126, v120, v121
	v_cvt_pk_bf16_f32 v127, v122, v123
	global_store_dwordx4 v[156:157], v[124:127], off
	v_cvt_pk_bf16_f32 v116, v116, v117
	v_cvt_pk_bf16_f32 v117, v118, v119
	v_cvt_pk_bf16_f32 v118, v108, v109
	v_or_b32_e32 v108, 16, v150
	v_ashrrev_i32_e32 v109, 31, v108
	v_lshlrev_b64 v[108:109], 12, v[108:109]
	v_cvt_pk_bf16_f32 v119, v110, v111
	global_store_dwordx4 v[156:157], v[116:119], off offset:256
	s_and_b64 vcc, exec, s[4:5]
	s_mov_b32 s56, s6
	v_lshl_add_u64 v[116:117], v[148:149], 0, v[108:109]
	v_cvt_pk_bf16_f32 v108, v112, v113
	v_cvt_pk_bf16_f32 v109, v114, v115
	v_cvt_pk_bf16_f32 v110, v104, v105
	v_cvt_pk_bf16_f32 v111, v106, v107
	global_store_dwordx4 v[116:117], v[108:111], off
	v_cvt_pk_bf16_f32 v100, v100, v101
	v_cvt_pk_bf16_f32 v101, v102, v103
	v_cvt_pk_bf16_f32 v102, v92, v93
	v_or_b32_e32 v92, 32, v150
	v_ashrrev_i32_e32 v93, 31, v92
	v_lshlrev_b64 v[92:93], 12, v[92:93]
	v_cvt_pk_bf16_f32 v103, v94, v95
	global_store_dwordx4 v[116:117], v[100:103], off offset:256
	s_mov_b32 s14, s8
	s_mov_b64 s[18:19], s[12:13]
	v_lshl_add_u64 v[100:101], v[148:149], 0, v[92:93]
	v_cvt_pk_bf16_f32 v92, v96, v97
	v_cvt_pk_bf16_f32 v93, v98, v99
	v_cvt_pk_bf16_f32 v94, v88, v89
	v_cvt_pk_bf16_f32 v95, v90, v91
	global_store_dwordx4 v[100:101], v[92:95], off
	v_cvt_pk_bf16_f32 v84, v84, v85
	v_cvt_pk_bf16_f32 v85, v86, v87
	v_cvt_pk_bf16_f32 v86, v76, v77
	v_or_b32_e32 v76, 48, v150
	v_ashrrev_i32_e32 v77, 31, v76
	v_lshlrev_b64 v[76:77], 12, v[76:77]
	v_cvt_pk_bf16_f32 v87, v78, v79
	global_store_dwordx4 v[100:101], v[84:87], off offset:256
	s_mov_b64 s[16:17], s[10:11]
	s_nop 0
	v_lshl_add_u64 v[84:85], v[148:149], 0, v[76:77]
	v_cvt_pk_bf16_f32 v76, v80, v81
	v_cvt_pk_bf16_f32 v77, v82, v83
	v_cvt_pk_bf16_f32 v78, v72, v73
	v_cvt_pk_bf16_f32 v79, v74, v75
	global_store_dwordx4 v[84:85], v[76:79], off
	v_cvt_pk_bf16_f32 v68, v68, v69
	v_cvt_pk_bf16_f32 v69, v70, v71
	v_cvt_pk_bf16_f32 v70, v64, v65
	v_add_u32_e32 v64, 0x80, v150
	v_ashrrev_i32_e32 v65, 31, v64
	v_lshlrev_b64 v[64:65], 12, v[64:65]
	v_lshl_add_u64 v[64:65], v[148:149], 0, v[64:65]
	v_cvt_pk_bf16_f32 v71, v66, v67
	global_store_dwordx4 v[84:85], v[68:71], off offset:256
	v_cvt_pk_bf16_f32 v60, v60, v61
	v_cvt_pk_bf16_f32 v61, v62, v63
	v_cvt_pk_bf16_f32 v62, v56, v57
	v_cvt_pk_bf16_f32 v63, v58, v59
	global_store_dwordx4 v[64:65], v[60:63], off
	v_cvt_pk_bf16_f32 v48, v48, v49
	v_cvt_pk_bf16_f32 v49, v50, v51
	v_cvt_pk_bf16_f32 v50, v40, v41
	v_add_u32_e32 v40, 0x90, v150
	v_ashrrev_i32_e32 v41, 31, v40
	v_lshlrev_b64 v[40:41], 12, v[40:41]
	v_cvt_pk_bf16_f32 v51, v42, v43
	global_store_dwordx4 v[64:65], v[48:51], off offset:256
	s_nop 1
	v_lshl_add_u64 v[48:49], v[148:149], 0, v[40:41]
	v_cvt_pk_bf16_f32 v40, v52, v53
	v_cvt_pk_bf16_f32 v41, v54, v55
	v_cvt_pk_bf16_f32 v42, v44, v45
	v_cvt_pk_bf16_f32 v43, v46, v47
	global_store_dwordx4 v[48:49], v[40:43], off
	v_cvt_pk_bf16_f32 v32, v32, v33
	v_cvt_pk_bf16_f32 v33, v34, v35
	v_cvt_pk_bf16_f32 v34, v24, v25
	v_add_u32_e32 v24, 0xa0, v150
	v_ashrrev_i32_e32 v25, 31, v24
	v_lshlrev_b64 v[24:25], 12, v[24:25]
	v_cvt_pk_bf16_f32 v35, v26, v27
	global_store_dwordx4 v[48:49], v[32:35], off offset:256
	s_nop 1
	v_lshl_add_u64 v[32:33], v[148:149], 0, v[24:25]
	v_cvt_pk_bf16_f32 v24, v36, v37
	v_cvt_pk_bf16_f32 v25, v38, v39
	v_cvt_pk_bf16_f32 v26, v28, v29
	v_cvt_pk_bf16_f32 v27, v30, v31
	global_store_dwordx4 v[32:33], v[24:27], off
	v_cvt_pk_bf16_f32 v16, v16, v17
	v_cvt_pk_bf16_f32 v17, v18, v19
	v_cvt_pk_bf16_f32 v18, v8, v9
	v_add_u32_e32 v8, 0xb0, v150
	v_ashrrev_i32_e32 v9, 31, v8
	v_lshlrev_b64 v[8:9], 12, v[8:9]
	v_cvt_pk_bf16_f32 v19, v10, v11
	global_store_dwordx4 v[32:33], v[16:19], off offset:256
	s_nop 1
	v_lshl_add_u64 v[16:17], v[148:149], 0, v[8:9]
	v_cvt_pk_bf16_f32 v8, v20, v21
	v_cvt_pk_bf16_f32 v9, v22, v23
	v_cvt_pk_bf16_f32 v10, v12, v13
	v_cvt_pk_bf16_f32 v11, v14, v15
	global_store_dwordx4 v[16:17], v[8:11], off
	v_cvt_pk_bf16_f32 v4, v4, v5
	v_cvt_pk_bf16_f32 v5, v6, v7
	v_cvt_pk_bf16_f32 v6, v0, v1
	v_cvt_pk_bf16_f32 v7, v2, v3
	global_store_dwordx4 v[16:17], v[4:7], off offset:256
	s_cbranch_vccz .LBB0_606
	s_waitcnt vmcnt(0)
	s_cmpk_gt_u32 s3, 0xff
	s_cbranch_scc1 .LBB0_617
	s_barrier

; #define PG8_STAGE(bufoff, gbase, voff) do { _Pragma("unroll") for (int _i = 0; _i < 2; ++_i) \
;         __builtin_amdgcn_global_load_lds((const unsigned*)((const char*)(gbase) + (voff)[_i]), (PG8_LAS unsigned*)(lds + (bufoff) + ldsw + _i * 8192), 16, 0, 0); } while (0)
; #define PG8_LDA(dst, b, h) do { _Pragma("unroll") for (int m = 0; m < 4; ++m) _Pragma("unroll") for (int k = 0; k < 2; ++k) dst[m][k] = *(const PG8_LAS bf16x8*)(lds + PG8_SA(b, h) + aoff + m * 2048 + k * 1024); } while (0)
; #define PG8_LDB(dst, b, h) do { _Pragma("unroll") for (int n = 0; n < 2; ++n) _Pragma("unroll") for (int k = 0; k < 2; ++k) dst[n][k] = *(const PG8_LAS bf16x8*)(lds + PG8_SB(b, h) + boff + n * 2048 + k * 1024); } while (0)
; #define PG8_MMA(ai, bj, At, Bt) do { __builtin_amdgcn_s_setprio(1); _Pragma("unroll") for (int m = 0; m < 4; ++m) _Pragma("unroll") for (int n = 0; n < 2; ++n) _Pragma("unroll") for (int k = 0; k < 2; ++k) \
;         acc[ai][bj][m][n] = __builtin_amdgcn_mfma_f32_16x16x32_bf16(Bt[n][k], At[m][k], acc[ai][bj][m][n], 0, 0, 0); __builtin_amdgcn_s_setprio(0); } while (0)
; #define PG8_WAIT_L(n) asm volatile("s_waitcnt lgkmcnt(" #n ")" ::: "memory")
; #define PG8_BAR __builtin_amdgcn_s_barrier()
; #define PG8_SCHED __builtin_amdgcn_sched_barrier(0)
; template <class Epi, class Sched>
; __device__ __forceinline__ void gemm_phase(PG8_LAS unsigned char* lds, const Gemm g, const Sched& S, const Epi& E) {
;     ...
;             const bool last = (t == nt - 2);
;             const char* a1 = cA + (size_t)(t + 1) * kstep;
;             const char* a2 = last ? nA : cA + (size_t)(t + 2) * kstep; const char* b2 = last ? nB : cB + (size_t)(t + 2) * kstep;
;             const char* a3 = a2 + kstep; const char* b3 = b2 + kstep;
;             if (last && has_next) S.a_ready(nxt);
;             PG8_LDB(B0, 0, 0); PG8_SCHED; PG8_LDA(At, 0, 0); PG8_STAGE(PG8_SA(1, 1), a1 + hstep, voffA);
;             PG8_WAIT_L(8); PG8_BAR; PG8_WAIT_L(0); PG8_MMA(0, 0, At, B0); PG8_BAR; PG8_SCHED;
;             PG8_LDB(B1, 0, 1); PG8_STAGE(PG8_SB(0, 0), b2, voffB);
;             PG8_BAR; PG8_WAIT_L(0); PG8_MMA(0, 1, At, B1); PG8_BAR;
;             PG8_LDA(At, 0, 1); PG8_STAGE(PG8_SA(0, 0), a2, voffA);
;             PG8_BAR; PG8_WAIT_L(0); PG8_MMA(1, 0, At, B0); PG8_BAR; PG8_SCHED;
.LBB0_688:
	ds_read_b128 v[148:151], v153
	ds_read_b128 v[156:159], v153 offset:1024
	ds_read_b128 v[160:163], v153 offset:2048
	ds_read_b128 v[164:167], v153 offset:3072
	s_add_u32 s20, s18, 0xfff80080
	s_addc_u32 s21, s19, -1
	s_cmp_eq_u32 s61, 28
	s_cselect_b32 s23, s11, s21
	s_cselect_b32 s22, s57, s20
	s_cselect_b32 s21, s9, s60
	s_cselect_b32 s20, s58, s59
	v_lshl_add_u64 v[200:201], s[18:19], 0, v[136:137]
	s_add_i32 m0, s17, 0xc000
	ds_read_b128 v[168:171], v154
	ds_read_b128 v[172:175], v154 offset:1024
	ds_read_b128 v[176:179], v154 offset:2048
	ds_read_b128 v[180:183], v154 offset:3072
	ds_read_b128 v[184:187], v154 offset:4096
	ds_read_b128 v[188:191], v154 offset:5120
	ds_read_b128 v[192:195], v154 offset:6144
	ds_read_b128 v[196:199], v154 offset:7168
	global_load_lds_dwordx4 v[200:201], off
	v_lshl_add_u64 v[200:201], s[18:19], 0, v[138:139]
	s_add_i32 m0, s17, 0xe000
	s_nop 0
	global_load_lds_dwordx4 v[200:201], off
	s_waitcnt lgkmcnt(8)
	s_barrier
	s_waitcnt lgkmcnt(0)
	s_waitcnt lgkmcnt(0)
	v_mfma_f32_16x16x32_bf16 v[124:127], v[148:151], v[168:171], v[124:127]
	v_mfma_f32_16x16x32_bf16 v[116:119], v[160:163], v[168:171], v[116:119]
	v_mfma_f32_16x16x32_bf16 v[108:111], v[148:151], v[176:179], v[108:111]
	v_mfma_f32_16x16x32_bf16 v[100:103], v[160:163], v[176:179], v[100:103]
	v_mfma_f32_16x16x32_bf16 v[92:95], v[148:151], v[184:187], v[92:95]
	v_mfma_f32_16x16x32_bf16 v[84:87], v[160:163], v[184:187], v[84:87]
	v_mfma_f32_16x16x32_bf16 v[76:79], v[148:151], v[192:195], v[76:79]
	v_mfma_f32_16x16x32_bf16 v[68:71], v[160:163], v[192:195], v[68:71]
	v_mfma_f32_16x16x32_bf16 v[124:127], v[156:159], v[172:175], v[124:127]
	v_mfma_f32_16x16x32_bf16 v[116:119], v[164:167], v[172:175], v[116:119]
	v_mfma_f32_16x16x32_bf16 v[108:111], v[156:159], v[180:183], v[108:111]
	v_mfma_f32_16x16x32_bf16 v[100:103], v[164:167], v[180:183], v[100:103]
	v_mfma_f32_16x16x32_bf16 v[92:95], v[156:159], v[188:191], v[92:95]
	v_mfma_f32_16x16x32_bf16 v[84:87], v[164:167], v[188:191], v[84:87]
	v_mfma_f32_16x16x32_bf16 v[76:79], v[156:159], v[196:199], v[76:79]
	v_mfma_f32_16x16x32_bf16 v[68:71], v[164:167], v[196:199], v[68:71]
	s_barrier
	s_add_i32 s30, s50, s27
	v_lshl_add_u64 v[216:217], s[20:21], 0, v[130:131]
	s_mov_b32 m0, s30
	ds_read_b128 v[200:203], v155
	ds_read_b128 v[204:207], v155 offset:1024
	ds_read_b128 v[208:211], v155 offset:2048
	ds_read_b128 v[212:215], v155 offset:3072
	global_load_lds_dwordx4 v[216:217], off
	v_lshl_add_u64 v[218:219], s[20:21], 0, v[134:135]
	s_add_i32 m0, s30, 0x2000
	s_nop 0
	global_load_lds_dwordx4 v[218:219], off
	s_barrier
	s_waitcnt lgkmcnt(0)
	s_waitcnt lgkmcnt(0)
	v_mfma_f32_16x16x32_bf16 v[120:123], v[200:203], v[168:171], v[120:123]
	v_mfma_f32_16x16x32_bf16 v[112:115], v[208:211], v[168:171], v[112:115]
	v_mfma_f32_16x16x32_bf16 v[104:107], v[200:203], v[176:179], v[104:107]
	v_mfma_f32_16x16x32_bf16 v[96:99], v[208:211], v[176:179], v[96:99]
	v_mfma_f32_16x16x32_bf16 v[88:91], v[200:203], v[184:187], v[88:91]
	v_mfma_f32_16x16x32_bf16 v[80:83], v[208:211], v[184:187], v[80:83]
	v_mfma_f32_16x16x32_bf16 v[72:75], v[200:203], v[192:195], v[72:75]
	v_mfma_f32_16x16x32_bf16 v[64:67], v[208:211], v[192:195], v[64:67]
	v_mfma_f32_16x16x32_bf16 v[120:123], v[204:207], v[172:175], v[120:123]
	v_mfma_f32_16x16x32_bf16 v[112:115], v[212:215], v[172:175], v[112:115]
	v_mfma_f32_16x16x32_bf16 v[104:107], v[204:207], v[180:183], v[104:107]
	v_mfma_f32_16x16x32_bf16 v[96:99], v[212:215], v[180:183], v[96:99]
	v_mfma_f32_16x16x32_bf16 v[88:91], v[204:207], v[188:191], v[88:91]
	v_mfma_f32_16x16x32_bf16 v[80:83], v[212:215], v[188:191], v[80:83]
	v_mfma_f32_16x16x32_bf16 v[72:75], v[204:207], v[196:199], v[72:75]
	v_mfma_f32_16x16x32_bf16 v[64:67], v[212:215], v[196:199], v[64:67]
	s_mov_b32 m0, s17
	v_lshl_add_u64 v[220:221], s[22:23], 0, v[128:129]
	s_barrier
	ds_read_b128 v[168:171], v154 offset:16384
	ds_read_b128 v[172:175], v154 offset:17408
	ds_read_b128 v[176:179], v154 offset:18432
	ds_read_b128 v[180:183], v154 offset:19456
	ds_read_b128 v[184:187], v154 offset:20480
	ds_read_b128 v[188:191], v154 offset:21504
	ds_read_b128 v[192:195], v154 offset:22528
	ds_read_b128 v[196:199], v154 offset:23552
	global_load_lds_dwordx4 v[220:221], off
	v_lshl_add_u64 v[222:223], s[22:23], 0, v[132:133]
	s_mov_b32 m0, s42
	s_nop 0
	global_load_lds_dwordx4 v[222:223], off
	s_barrier
	s_waitcnt lgkmcnt(0)
	s_waitcnt lgkmcnt(0)
	v_mfma_f32_16x16x32_bf16 v[60:63], v[148:151], v[168:171], v[60:63]
	v_mfma_f32_16x16x32_bf16 v[52:55], v[160:163], v[168:171], v[52:55]
	v_mfma_f32_16x16x32_bf16 v[44:47], v[148:151], v[176:179], v[44:47]
	v_mfma_f32_16x16x32_bf16 v[36:39], v[160:163], v[176:179], v[36:39]
	v_mfma_f32_16x16x32_bf16 v[28:31], v[148:151], v[184:187], v[28:31]
	v_mfma_f32_16x16x32_bf16 v[20:23], v[160:163], v[184:187], v[20:23]
	v_mfma_f32_16x16x32_bf16 v[12:15], v[148:151], v[192:195], v[12:15]
	v_mfma_f32_16x16x32_bf16 v[4:7], v[160:163], v[192:195], v[4:7]
	v_mfma_f32_16x16x32_bf16 v[60:63], v[156:159], v[172:175], v[60:63]
	v_mfma_f32_16x16x32_bf16 v[52:55], v[164:167], v[172:175], v[52:55]
	v_mfma_f32_16x16x32_bf16 v[44:47], v[156:159], v[180:183], v[44:47]
	v_mfma_f32_16x16x32_bf16 v[36:39], v[164:167], v[180:183], v[36:39]
	v_mfma_f32_16x16x32_bf16 v[28:31], v[156:159], v[188:191], v[28:31]
	v_mfma_f32_16x16x32_bf16 v[20:23], v[164:167], v[188:191], v[20:23]
	v_mfma_f32_16x16x32_bf16 v[12:15], v[156:159], v[196:199], v[12:15]
	v_mfma_f32_16x16x32_bf16 v[4:7], v[164:167], v[196:199], v[4:7]
	s_barrier
; #define PG8_STAGE(bufoff, gbase, voff) do { _Pragma("unroll") for (int _i = 0; _i < 2; ++_i) \
;         __builtin_amdgcn_global_load_lds((const unsigned*)((const char*)(gbase) + (voff)[_i]), (PG8_LAS unsigned*)(lds + (bufoff) + ldsw + _i * 8192), 16, 0, 0); } while (0)
; #define PG8_LDA(dst, b, h) do { _Pragma("unroll") for (int m = 0; m < 4; ++m) _Pragma("unroll") for (int k = 0; k < 2; ++k) dst[m][k] = *(const PG8_LAS bf16x8*)(lds + PG8_SA(b, h) + aoff + m * 2048 + k * 1024); } while (0)
; #define PG8_LDB(dst, b, h) do { _Pragma("unroll") for (int n = 0; n < 2; ++n) _Pragma("unroll") for (int k = 0; k < 2; ++k) dst[n][k] = *(const PG8_LAS bf16x8*)(lds + PG8_SB(b, h) + boff + n * 2048 + k * 1024); } while (0)
; #define PG8_MMA(ai, bj, At, Bt) do { __builtin_amdgcn_s_setprio(1); _Pragma("unroll") for (int m = 0; m < 4; ++m) _Pragma("unroll") for (int n = 0; n < 2; ++n) _Pragma("unroll") for (int k = 0; k < 2; ++k) \
;         acc[ai][bj][m][n] = __builtin_amdgcn_mfma_f32_16x16x32_bf16(Bt[n][k], At[m][k], acc[ai][bj][m][n], 0, 0, 0); __builtin_amdgcn_s_setprio(0); } while (0)
; #define PG8_WAIT_V(n) asm volatile("s_waitcnt vmcnt(" #n ")" ::: "memory")
; #define PG8_WAIT_L(n) asm volatile("s_waitcnt lgkmcnt(" #n ")" ::: "memory")
; #define PG8_BAR __builtin_amdgcn_s_barrier()
; #define PG8_SCHED __builtin_amdgcn_sched_barrier(0)
; template <class Epi, class Sched>
; __device__ __forceinline__ void gemm_phase(PG8_LAS unsigned char* lds, const Gemm g, const Sched& S, const Epi& E) {
;     ...
;             PG8_STAGE(PG8_SB(0, 1), b2 + hstep, voffB);
;             PG8_WAIT_V(6); PG8_BAR; PG8_MMA(1, 1, At, B1); PG8_BAR;
;             PG8_LDB(B0, 1, 0); PG8_SCHED; PG8_LDA(At, 1, 0); PG8_STAGE(PG8_SA(0, 1), a2 + hstep, voffA);
;             PG8_WAIT_L(8); PG8_BAR; PG8_WAIT_L(0); PG8_MMA(0, 0, At, B0); PG8_BAR; PG8_SCHED;
;             PG8_LDB(B1, 1, 1); PG8_STAGE(PG8_SB(1, 0), b3, voffB);
;             PG8_BAR; PG8_WAIT_L(0); PG8_MMA(0, 1, At, B1); PG8_BAR;
;             PG8_LDA(At, 1, 1); PG8_STAGE(PG8_SA(1, 0), a3, voffA);
	s_add_u32 s30, s20, 0x80000
	s_addc_u32 s31, s21, 0
	s_add_i32 s38, s51, s27
	v_lshl_add_u64 v[148:149], s[30:31], 0, v[130:131]
	s_mov_b32 m0, s38
	s_nop 0
	global_load_lds_dwordx4 v[148:149], off
	v_lshl_add_u64 v[148:149], s[30:31], 0, v[134:135]
	s_add_i32 m0, s38, 0x2000
	s_nop 0
	global_load_lds_dwordx4 v[148:149], off
	s_waitcnt vmcnt(6)
	s_barrier
	v_mfma_f32_16x16x32_bf16 v[56:59], v[200:203], v[168:171], v[56:59]
	v_mfma_f32_16x16x32_bf16 v[48:51], v[208:211], v[168:171], v[48:51]
	v_mfma_f32_16x16x32_bf16 v[40:43], v[200:203], v[176:179], v[40:43]
	v_mfma_f32_16x16x32_bf16 v[32:35], v[208:211], v[176:179], v[32:35]
	v_mfma_f32_16x16x32_bf16 v[24:27], v[200:203], v[184:187], v[24:27]
	v_mfma_f32_16x16x32_bf16 v[16:19], v[208:211], v[184:187], v[16:19]
	v_mfma_f32_16x16x32_bf16 v[8:11], v[200:203], v[192:195], v[8:11]
	v_mfma_f32_16x16x32_bf16 v[0:3], v[208:211], v[192:195], v[0:3]
	v_mfma_f32_16x16x32_bf16 v[56:59], v[204:207], v[172:175], v[56:59]
	v_mfma_f32_16x16x32_bf16 v[48:51], v[212:215], v[172:175], v[48:51]
	v_mfma_f32_16x16x32_bf16 v[40:43], v[204:207], v[180:183], v[40:43]
	v_mfma_f32_16x16x32_bf16 v[32:35], v[212:215], v[180:183], v[32:35]
	v_mfma_f32_16x16x32_bf16 v[24:27], v[204:207], v[188:191], v[24:27]
	v_mfma_f32_16x16x32_bf16 v[16:19], v[212:215], v[188:191], v[16:19]
	v_mfma_f32_16x16x32_bf16 v[8:11], v[204:207], v[196:199], v[8:11]
	v_mfma_f32_16x16x32_bf16 v[0:3], v[212:215], v[196:199], v[0:3]
	s_add_i32 s30, 0, 0x18000
	v_add_u32_e32 v164, s30, v147
	s_barrier
	ds_read_b128 v[148:151], v164
	ds_read_b128 v[156:159], v164 offset:1024
	ds_read_b128 v[160:163], v164 offset:2048
	ds_read_b128 v[164:167], v164 offset:3072
	s_add_u32 s22, s22, 0x80000
	s_addc_u32 s23, s23, 0
	s_mov_b32 m0, s43
	v_lshl_add_u64 v[200:201], s[22:23], 0, v[128:129]
	ds_read_b128 v[168:171], v154 offset:32768
	ds_read_b128 v[172:175], v154 offset:33792
	ds_read_b128 v[176:179], v154 offset:34816
	ds_read_b128 v[180:183], v154 offset:35840
	ds_read_b128 v[184:187], v154 offset:36864
	ds_read_b128 v[188:191], v154 offset:37888
	ds_read_b128 v[192:195], v154 offset:38912
	ds_read_b128 v[196:199], v154 offset:39936
	global_load_lds_dwordx4 v[200:201], off
	v_lshl_add_u64 v[200:201], s[22:23], 0, v[132:133]
	s_mov_b32 m0, s44
	s_nop 0
	global_load_lds_dwordx4 v[200:201], off
	s_waitcnt lgkmcnt(8)
	s_barrier
	s_waitcnt lgkmcnt(0)
	s_waitcnt lgkmcnt(0)
	v_mfma_f32_16x16x32_bf16 v[124:127], v[148:151], v[168:171], v[124:127]
	v_mfma_f32_16x16x32_bf16 v[116:119], v[160:163], v[168:171], v[116:119]
	v_mfma_f32_16x16x32_bf16 v[108:111], v[148:151], v[176:179], v[108:111]
	v_mfma_f32_16x16x32_bf16 v[100:103], v[160:163], v[176:179], v[100:103]
	v_mfma_f32_16x16x32_bf16 v[92:95], v[148:151], v[184:187], v[92:95]
	v_mfma_f32_16x16x32_bf16 v[84:87], v[160:163], v[184:187], v[84:87]
	v_mfma_f32_16x16x32_bf16 v[76:79], v[148:151], v[192:195], v[76:79]
	v_mfma_f32_16x16x32_bf16 v[68:71], v[160:163], v[192:195], v[68:71]
	v_mfma_f32_16x16x32_bf16 v[124:127], v[156:159], v[172:175], v[124:127]
	v_mfma_f32_16x16x32_bf16 v[116:119], v[164:167], v[172:175], v[116:119]
	v_mfma_f32_16x16x32_bf16 v[108:111], v[156:159], v[180:183], v[108:111]
	v_mfma_f32_16x16x32_bf16 v[100:103], v[164:167], v[180:183], v[100:103]
	v_mfma_f32_16x16x32_bf16 v[92:95], v[156:159], v[188:191], v[92:95]
	v_mfma_f32_16x16x32_bf16 v[84:87], v[164:167], v[188:191], v[84:87]
	v_mfma_f32_16x16x32_bf16 v[76:79], v[156:159], v[196:199], v[76:79]
	v_mfma_f32_16x16x32_bf16 v[68:71], v[164:167], v[196:199], v[68:71]
	s_barrier
	s_add_i32 s22, 0, 0x1c000
	s_add_i32 s23, s30, s27
	v_add_u32_e32 v212, s22, v147
	v_lshl_add_u64 v[216:217], v[216:217], 0, s[6:7]
	s_mov_b32 m0, s23
	ds_read_b128 v[200:203], v212
	ds_read_b128 v[204:207], v212 offset:1024
	ds_read_b128 v[208:211], v212 offset:2048
	ds_read_b128 v[212:215], v212 offset:3072
	global_load_lds_dwordx4 v[216:217], off
	v_lshl_add_u64 v[216:217], v[218:219], 0, s[6:7]
	s_add_i32 m0, s23, 0x2000
	s_nop 0
	global_load_lds_dwordx4 v[216:217], off
	s_barrier
	s_waitcnt lgkmcnt(0)
	s_waitcnt lgkmcnt(0)
	v_mfma_f32_16x16x32_bf16 v[120:123], v[200:203], v[168:171], v[120:123]
	v_mfma_f32_16x16x32_bf16 v[112:115], v[208:211], v[168:171], v[112:115]
	v_mfma_f32_16x16x32_bf16 v[104:107], v[200:203], v[176:179], v[104:107]
	v_mfma_f32_16x16x32_bf16 v[96:99], v[208:211], v[176:179], v[96:99]
	v_mfma_f32_16x16x32_bf16 v[88:91], v[200:203], v[184:187], v[88:91]
	v_mfma_f32_16x16x32_bf16 v[80:83], v[208:211], v[184:187], v[80:83]
	v_mfma_f32_16x16x32_bf16 v[72:75], v[200:203], v[192:195], v[72:75]
	v_mfma_f32_16x16x32_bf16 v[64:67], v[208:211], v[192:195], v[64:67]
	v_mfma_f32_16x16x32_bf16 v[120:123], v[204:207], v[172:175], v[120:123]
	v_mfma_f32_16x16x32_bf16 v[112:115], v[212:215], v[172:175], v[112:115]
	v_mfma_f32_16x16x32_bf16 v[104:107], v[204:207], v[180:183], v[104:107]
	v_mfma_f32_16x16x32_bf16 v[96:99], v[212:215], v[180:183], v[96:99]
	v_mfma_f32_16x16x32_bf16 v[88:91], v[204:207], v[188:191], v[88:91]
	v_mfma_f32_16x16x32_bf16 v[80:83], v[212:215], v[188:191], v[80:83]
	v_mfma_f32_16x16x32_bf16 v[72:75], v[204:207], v[196:199], v[72:75]
	v_mfma_f32_16x16x32_bf16 v[64:67], v[212:215], v[196:199], v[64:67]
	s_mov_b32 m0, s46
	v_lshl_add_u64 v[216:217], v[220:221], 0, s[6:7]
	s_barrier
	ds_read_b128 v[168:171], v154 offset:49152
	ds_read_b128 v[172:175], v154 offset:50176
	ds_read_b128 v[176:179], v154 offset:51200
	ds_read_b128 v[180:183], v154 offset:52224
	ds_read_b128 v[184:187], v154 offset:53248
	ds_read_b128 v[188:191], v154 offset:54272
	ds_read_b128 v[192:195], v154 offset:55296
	ds_read_b128 v[196:199], v154 offset:56320
	global_load_lds_dwordx4 v[216:217], off
	v_lshl_add_u64 v[216:217], v[222:223], 0, s[6:7]
	s_mov_b32 m0, s47
	s_nop 0
	global_load_lds_dwordx4 v[216:217], off
	s_barrier
; #define PG8_STAGE(bufoff, gbase, voff) do { _Pragma("unroll") for (int _i = 0; _i < 2; ++_i) \
;         __builtin_amdgcn_global_load_lds((const unsigned*)((const char*)(gbase) + (voff)[_i]), (PG8_LAS unsigned*)(lds + (bufoff) + ldsw + _i * 8192), 16, 0, 0); } while (0)
; #define PG8_MMA(ai, bj, At, Bt) do { __builtin_amdgcn_s_setprio(1); _Pragma("unroll") for (int m = 0; m < 4; ++m) _Pragma("unroll") for (int n = 0; n < 2; ++n) _Pragma("unroll") for (int k = 0; k < 2; ++k) \
;         acc[ai][bj][m][n] = __builtin_amdgcn_mfma_f32_16x16x32_bf16(Bt[n][k], At[m][k], acc[ai][bj][m][n], 0, 0, 0); __builtin_amdgcn_s_setprio(0); } while (0)
; #define PG8_WAIT_V(n) asm volatile("s_waitcnt vmcnt(" #n ")" ::: "memory")
; #define PG8_WAIT_L(n) asm volatile("s_waitcnt lgkmcnt(" #n ")" ::: "memory")
; #define PG8_BAR __builtin_amdgcn_s_barrier()
; #define PG8_SCHED __builtin_amdgcn_sched_barrier(0)
; template <class Epi, class Sched>
; __device__ __forceinline__ void gemm_phase(PG8_LAS unsigned char* lds, const Gemm g, const Sched& S, const Epi& E) {
;     ...
;             PG8_BAR; PG8_WAIT_L(0); PG8_MMA(1, 0, At, B0); PG8_BAR; PG8_SCHED;
;             PG8_STAGE(PG8_SB(1, 1), b3 + hstep, voffB);
;             PG8_WAIT_V(6); PG8_BAR; PG8_MMA(1, 1, At, B1); PG8_BAR;
;     __device__ __forceinline__ void operator()(AccRef acc, const Unit& u, int wr, int wc, int fr, int fq) const {
;         const int c0 = u.pn * 128 + wc * 32 + 8 * fq;
; #pragma unroll
;         for (int ai = 0; ai < 2; ++ai)
; #pragma unroll
;             for (int m = 0; m < 4; ++m) {
;                 const int r = u.pm * 256 + ai * 128 + wr * 64 + m * 16 + fr;
;                 const float s = rinv[r];
;                 const size_t o = (size_t)r * D + c0;
;                 const uint4 pa8 = *(const uint4*)(Pa + o), pb8 = *(const uint4*)(Pb + o);
	s_waitcnt lgkmcnt(0)
	s_waitcnt lgkmcnt(0)
	v_mfma_f32_16x16x32_bf16 v[60:63], v[148:151], v[168:171], v[60:63]
	v_mfma_f32_16x16x32_bf16 v[52:55], v[160:163], v[168:171], v[52:55]
	v_mfma_f32_16x16x32_bf16 v[44:47], v[148:151], v[176:179], v[44:47]
	v_mfma_f32_16x16x32_bf16 v[36:39], v[160:163], v[176:179], v[36:39]
	v_mfma_f32_16x16x32_bf16 v[28:31], v[148:151], v[184:187], v[28:31]
	v_mfma_f32_16x16x32_bf16 v[20:23], v[160:163], v[184:187], v[20:23]
	v_mfma_f32_16x16x32_bf16 v[12:15], v[148:151], v[192:195], v[12:15]
	v_mfma_f32_16x16x32_bf16 v[4:7], v[160:163], v[192:195], v[4:7]
	v_mfma_f32_16x16x32_bf16 v[60:63], v[156:159], v[172:175], v[60:63]
	v_mfma_f32_16x16x32_bf16 v[52:55], v[164:167], v[172:175], v[52:55]
	v_mfma_f32_16x16x32_bf16 v[44:47], v[156:159], v[180:183], v[44:47]
	v_mfma_f32_16x16x32_bf16 v[36:39], v[164:167], v[180:183], v[36:39]
	v_mfma_f32_16x16x32_bf16 v[28:31], v[156:159], v[188:191], v[28:31]
	v_mfma_f32_16x16x32_bf16 v[20:23], v[164:167], v[188:191], v[20:23]
	v_mfma_f32_16x16x32_bf16 v[12:15], v[156:159], v[196:199], v[12:15]
	v_mfma_f32_16x16x32_bf16 v[4:7], v[164:167], v[196:199], v[4:7]
	s_barrier
	s_add_u32 s20, s20, 0x80080
	s_addc_u32 s21, s21, 0
	s_add_i32 s22, s22, s27
	v_lshl_add_u64 v[148:149], s[20:21], 0, v[130:131]
	s_mov_b32 m0, s22
	s_nop 0
	global_load_lds_dwordx4 v[148:149], off
	v_lshl_add_u64 v[148:149], s[20:21], 0, v[134:135]
	s_add_i32 m0, s22, 0x2000
	s_nop 0
	global_load_lds_dwordx4 v[148:149], off
	s_waitcnt vmcnt(6)
	s_barrier
	v_mfma_f32_16x16x32_bf16 v[56:59], v[200:203], v[168:171], v[56:59]
	v_mfma_f32_16x16x32_bf16 v[48:51], v[208:211], v[168:171], v[48:51]
	v_mfma_f32_16x16x32_bf16 v[40:43], v[200:203], v[176:179], v[40:43]
	v_mfma_f32_16x16x32_bf16 v[32:35], v[208:211], v[176:179], v[32:35]
	v_mfma_f32_16x16x32_bf16 v[24:27], v[200:203], v[184:187], v[24:27]
	v_mfma_f32_16x16x32_bf16 v[16:19], v[208:211], v[184:187], v[16:19]
	v_mfma_f32_16x16x32_bf16 v[8:11], v[200:203], v[192:195], v[8:11]
	v_mfma_f32_16x16x32_bf16 v[0:3], v[208:211], v[192:195], v[0:3]
	v_mfma_f32_16x16x32_bf16 v[56:59], v[204:207], v[172:175], v[56:59]
	v_mfma_f32_16x16x32_bf16 v[48:51], v[212:215], v[172:175], v[48:51]
	v_mfma_f32_16x16x32_bf16 v[40:43], v[204:207], v[180:183], v[40:43]
	v_mfma_f32_16x16x32_bf16 v[32:35], v[212:215], v[180:183], v[32:35]
	v_mfma_f32_16x16x32_bf16 v[24:27], v[204:207], v[188:191], v[24:27]
	v_mfma_f32_16x16x32_bf16 v[16:19], v[212:215], v[188:191], v[16:19]
	v_mfma_f32_16x16x32_bf16 v[8:11], v[204:207], v[196:199], v[8:11]
	v_mfma_f32_16x16x32_bf16 v[0:3], v[212:215], v[196:199], v[0:3]
	s_add_i32 s61, s61, 2
	s_add_u32 s18, s18, 0x100
	s_addc_u32 s19, s19, 0
	s_add_u32 s59, s59, 0x100
	s_addc_u32 s60, s60, 0
	s_cmp_gt_u32 s61, 29
	s_barrier
	s_cbranch_scc0 .LBB0_688
	v_lshl_add_u32 v148, s16, 8, v145
	v_ashrrev_i32_e32 v149, 31, v148
	v_lshl_add_u64 v[150:151], v[148:149], 2, s[28:29]
	global_load_dword v166, v[150:151], off
	v_lshl_or_b32 v150, s56, 7, v152
	v_ashrrev_i32_e32 v151, 31, v150
	v_lshlrev_b64 v[156:157], 11, v[148:149]
	v_lshl_add_u64 v[156:157], v[156:157], 0, v[150:151]
	v_lshlrev_b64 v[164:165], 1, v[156:157]
	v_lshl_add_u64 v[156:157], s[88:89], 0, v[164:165]
	v_lshl_add_u64 v[160:161], s[0:1], 0, v[164:165]
	global_load_dwordx4 v[156:159], v[156:157], off
	s_and_b64 vcc, exec, s[4:5]
	global_load_dwordx4 v[160:163], v[160:161], off
	s_mov_b32 s56, s8
	s_mov_b32 s16, s10
	s_mov_b64 s[20:21], s[14:15]
	s_mov_b64 s[18:19], s[12:13]
	v_add_u32_e32 v244, 0x10, v148
	v_ashrrev_i32_e32 v245, 31, v244
	v_lshl_add_u64 v[246:247], v[244:245], 2, s[28:29]
	global_load_dword v182, v[246:247], off
	v_lshlrev_b64 v[244:245], 11, v[244:245]
	v_lshl_add_u64 v[244:245], v[244:245], 0, v[150:151]
	v_lshlrev_b64 v[244:245], 1, v[244:245]
	v_lshl_add_u64 v[246:247], s[88:89], 0, v[244:245]
	global_load_dwordx4 v[174:177], v[246:247], off
	v_lshl_add_u64 v[246:247], s[0:1], 0, v[244:245]
	global_load_dwordx4 v[178:181], v[246:247], off
	v_add_u32_e32 v244, 0x20, v148
	v_ashrrev_i32_e32 v245, 31, v244
	v_lshl_add_u64 v[246:247], v[244:245], 2, s[28:29]
	global_load_dword v192, v[246:247], off
	v_lshlrev_b64 v[244:245], 11, v[244:245]
	v_lshl_add_u64 v[244:245], v[244:245], 0, v[150:151]
	v_lshlrev_b64 v[244:245], 1, v[244:245]
	v_lshl_add_u64 v[246:247], s[88:89], 0, v[244:245]
	global_load_dwordx4 v[184:187], v[246:247], off
	v_lshl_add_u64 v[246:247], s[0:1], 0, v[244:245]
	global_load_dwordx4 v[188:191], v[246:247], off
	v_add_u32_e32 v244, 0x30, v148
	v_ashrrev_i32_e32 v245, 31, v244
	v_lshl_add_u64 v[246:247], v[244:245], 2, s[28:29]
	global_load_dword v202, v[246:247], off
	v_lshlrev_b64 v[244:245], 11, v[244:245]
	v_lshl_add_u64 v[244:245], v[244:245], 0, v[150:151]
	v_lshlrev_b64 v[244:245], 1, v[244:245]
	v_lshl_add_u64 v[246:247], s[88:89], 0, v[244:245]
	global_load_dwordx4 v[194:197], v[246:247], off
	v_lshl_add_u64 v[246:247], s[0:1], 0, v[244:245]
	global_load_dwordx4 v[198:201], v[246:247], off
	v_add_u32_e32 v244, 0x80, v148
	v_ashrrev_i32_e32 v245, 31, v244
	v_lshl_add_u64 v[246:247], v[244:245], 2, s[28:29]
	global_load_dword v212, v[246:247], off
	v_lshlrev_b64 v[244:245], 11, v[244:245]
	v_lshl_add_u64 v[244:245], v[244:245], 0, v[150:151]
	v_lshlrev_b64 v[244:245], 1, v[244:245]
	v_lshl_add_u64 v[246:247], s[88:89], 0, v[244:245]
	global_load_dwordx4 v[204:207], v[246:247], off
	v_lshl_add_u64 v[246:247], s[0:1], 0, v[244:245]
	global_load_dwordx4 v[208:211], v[246:247], off
	v_add_u32_e32 v244, 0x90, v148
	v_ashrrev_i32_e32 v245, 31, v244
	v_lshl_add_u64 v[246:247], v[244:245], 2, s[28:29]
	global_load_dword v222, v[246:247], off
	v_lshlrev_b64 v[244:245], 11, v[244:245]
	v_lshl_add_u64 v[244:245], v[244:245], 0, v[150:151]
	v_lshlrev_b64 v[244:245], 1, v[244:245]
	v_lshl_add_u64 v[246:247], s[88:89], 0, v[244:245]
	global_load_dwordx4 v[214:217], v[246:247], off
	v_lshl_add_u64 v[246:247], s[0:1], 0, v[244:245]
	global_load_dwordx4 v[218:221], v[246:247], off
	v_add_u32_e32 v244, 0xa0, v148
	v_ashrrev_i32_e32 v245, 31, v244
	v_lshl_add_u64 v[246:247], v[244:245], 2, s[28:29]
	global_load_dword v232, v[246:247], off
	v_lshlrev_b64 v[244:245], 11, v[244:245]
	v_lshl_add_u64 v[244:245], v[244:245], 0, v[150:151]
	v_lshlrev_b64 v[244:245], 1, v[244:245]
	v_lshl_add_u64 v[246:247], s[88:89], 0, v[244:245]
	global_load_dwordx4 v[224:227], v[246:247], off
	v_lshl_add_u64 v[246:247], s[0:1], 0, v[244:245]
	global_load_dwordx4 v[228:231], v[246:247], off
	v_add_u32_e32 v244, 0xb0, v148
	v_ashrrev_i32_e32 v245, 31, v244
	v_lshl_add_u64 v[246:247], v[244:245], 2, s[28:29]
	global_load_dword v242, v[246:247], off
	v_lshlrev_b64 v[244:245], 11, v[244:245]
	v_lshl_add_u64 v[244:245], v[244:245], 0, v[150:151]
	v_lshlrev_b64 v[244:245], 1, v[244:245]
	v_lshl_add_u64 v[246:247], s[88:89], 0, v[244:245]
	global_load_dwordx4 v[234:237], v[246:247], off
	v_lshl_add_u64 v[246:247], s[0:1], 0, v[244:245]
	global_load_dwordx4 v[238:241], v[246:247], off
	s_waitcnt vmcnt(21)
; __device__ __forceinline__ f32x4 unpk4(uint2 u) { f32x4 r; r[0] = __uint_as_float(u.x << 16); r[1] = __uint_as_float(u.x & 0xffff0000u); r[2] = __uint_as_float(u.y << 16); r[3] = __uint_as_float(u.y & 0xffff0000u); return r; }
; __device__ __forceinline__ float sigm(float x) { return __builtin_amdgcn_rcpf(1.f + __expf(-x)); }
; __device__ __forceinline__ uint4 pk8(f32x4 a, f32x4 b) { return make_uint4(cvt_pk_bf16(a[0], a[1]), cvt_pk_bf16(a[2], a[3]), cvt_pk_bf16(b[0], b[1]), cvt_pk_bf16(b[2], b[3])); }
;     __device__ __forceinline__ void operator()(AccRef acc, const Unit& u, int wr, int wc, int fr, int fq) const {
;     ...
;                 const int r = u.pm * 256 + ai * 128 + wr * 64 + m * 16 + fr;
;                 const float s = rinv[r];
;                 const size_t o = (size_t)r * D + c0;
;                 const uint4 pa8 = *(const uint4*)(Pa + o), pb8 = *(const uint4*)(Pb + o);
;                 f32x4 v[2];
; #pragma unroll
;                 for (int n = 0; n < 2; ++n) {
;                     const f32x4 pa = unpk4(n == 0 ? make_uint2(pa8.x, pa8.y) : make_uint2(pa8.z, pa8.w)), pb = unpk4(n == 0 ? make_uint2(pb8.x, pb8.y) : make_uint2(pb8.z, pb8.w));
; #pragma unroll
;                     for (int e = 0; e < 4; ++e) v[n][e] = sigm(acc[ai][0][m][n][e] * s) * pa[e] + sigm(acc[ai][1][m][n][e] * s) * pb[e];
;                 }
;                 *(uint4*)(O + o) = pk8(v[0], v[1]);
	v_mul_f32_e32 v121, v121, v166
	v_mul_f32_e32 v112, v112, v166
	v_mul_f32_e32 v121, 0xbfb8aa3b, v121
	v_mul_f32_e32 v112, 0xbfb8aa3b, v112
	v_exp_f32_e32 v121, v121
	v_exp_f32_e32 v112, v112
	v_mul_f32_e32 v113, v113, v166
	v_mul_f32_e32 v116, v116, v166
	v_mul_f32_e32 v113, 0xbfb8aa3b, v113
	v_add_f32_e32 v121, 1.0, v121
	v_add_f32_e32 v112, 1.0, v112
	v_mul_f32_e32 v116, 0xbfb8aa3b, v116
	v_exp_f32_e32 v113, v113
	v_rcp_f32_e32 v121, v121
	v_rcp_f32_e32 v112, v112
	v_exp_f32_e32 v116, v116
	v_lshlrev_b32_e32 v168, 16, v160
	v_and_b32_e32 v160, 0xffff0000, v160
	v_lshlrev_b32_e32 v172, 16, v162
	v_mul_f32_e32 v121, v121, v160
	v_mul_f32_e32 v160, v112, v172
	v_add_f32_e32 v112, 1.0, v113
	v_mul_f32_e32 v113, v118, v166
	v_add_f32_e32 v116, 1.0, v116
	v_mul_f32_e32 v113, 0xbfb8aa3b, v113
	v_rcp_f32_e32 v116, v116
	v_rcp_f32_e32 v112, v112
	v_exp_f32_e32 v113, v113
	v_mul_f32_e32 v120, v120, v166
	v_lshlrev_b32_e32 v170, 16, v158
	v_and_b32_e32 v162, 0xffff0000, v162
	v_mul_f32_e32 v124, v124, v166
	v_mul_f32_e32 v117, v117, v166
	v_mul_f32_e32 v120, 0xbfb8aa3b, v120
	v_fmac_f32_e32 v160, v116, v170
	v_mul_f32_e32 v116, v112, v162
	v_add_f32_e32 v112, 1.0, v113
	v_mul_f32_e32 v113, v114, v166
	v_mul_f32_e32 v115, v115, v166
	v_mul_f32_e32 v125, v125, v166
	v_mul_f32_e32 v122, v122, v166
	v_mul_f32_e32 v123, v123, v166
	v_mul_f32_e32 v124, 0xbfb8aa3b, v124
	v_mul_f32_e32 v117, 0xbfb8aa3b, v117
	v_exp_f32_e32 v120, v120
	v_mul_f32_e32 v113, 0xbfb8aa3b, v113
	v_mul_f32_e32 v114, v119, v166
	v_mul_f32_e32 v115, 0xbfb8aa3b, v115
	v_mul_f32_e32 v126, v126, v166
	v_mul_f32_e32 v127, v127, v166
	v_mul_f32_e32 v125, 0xbfb8aa3b, v125
	v_mul_f32_e32 v122, 0xbfb8aa3b, v122
	v_mul_f32_e32 v123, 0xbfb8aa3b, v123
	v_exp_f32_e32 v124, v124
	v_exp_f32_e32 v117, v117
	v_exp_f32_e32 v113, v113
	v_mul_f32_e32 v114, 0xbfb8aa3b, v114
	v_exp_f32_e32 v115, v115
	v_mul_f32_e32 v126, 0xbfb8aa3b, v126
	v_mul_f32_e32 v127, 0xbfb8aa3b, v127
	v_exp_f32_e32 v125, v125
	v_exp_f32_e32 v122, v122
	v_exp_f32_e32 v123, v123
	v_exp_f32_e32 v114, v114
	v_exp_f32_e32 v126, v126
	v_exp_f32_e32 v127, v127
	v_add_f32_e32 v120, 1.0, v120
	v_add_f32_e32 v124, 1.0, v124
	v_add_f32_e32 v117, 1.0, v117
	v_rcp_f32_e32 v120, v120
	v_add_f32_e32 v113, 1.0, v113
	v_add_f32_e32 v115, 1.0, v115
	v_add_f32_e32 v125, 1.0, v125
	v_add_f32_e32 v122, 1.0, v122
	v_add_f32_e32 v123, 1.0, v123
	v_rcp_f32_e32 v124, v124
	v_rcp_f32_e32 v117, v117
	v_rcp_f32_e32 v113, v113
	v_add_f32_e32 v114, 1.0, v114
	v_rcp_f32_e32 v115, v115
	v_add_f32_e32 v126, 1.0, v126
	v_add_f32_e32 v127, 1.0, v127
	v_rcp_f32_e32 v125, v125
	v_rcp_f32_e32 v122, v122
	v_rcp_f32_e32 v123, v123
	v_rcp_f32_e32 v112, v112
	v_rcp_f32_e32 v114, v114
	v_rcp_f32_e32 v126, v126
	v_rcp_f32_e32 v127, v127
	v_lshlrev_b32_e32 v149, 16, v156
	v_and_b32_e32 v158, 0xffff0000, v158
	v_lshlrev_b32_e32 v173, 16, v163
	v_and_b32_e32 v163, 0xffff0000, v163
	v_mul_f32_e32 v120, v120, v168
	v_and_b32_e32 v156, 0xffff0000, v156
	v_lshlrev_b32_e32 v169, 16, v161
	v_and_b32_e32 v161, 0xffff0000, v161
	v_lshlrev_b32_e32 v171, 16, v159
	v_and_b32_e32 v159, 0xffff0000, v159
	v_fmac_f32_e32 v120, v124, v149
	v_fmac_f32_e32 v116, v117, v158
	v_mul_f32_e32 v117, v113, v173
	v_mul_f32_e32 v115, v115, v163
	v_lshlrev_b32_e32 v167, 16, v157
	v_and_b32_e32 v157, 0xffff0000, v157
	v_mul_f32_e32 v122, v122, v169
	v_mul_f32_e32 v123, v123, v161
	v_fmac_f32_e32 v121, v125, v156
	v_fmac_f32_e32 v117, v112, v171
	v_fmac_f32_e32 v115, v114, v159
	v_cvt_pk_bf16_f32 v112, v120, v121
	v_or_b32_e32 v120, 16, v148
	v_fmac_f32_e32 v122, v126, v167
	v_fmac_f32_e32 v123, v127, v157
	v_cvt_pk_bf16_f32 v113, v122, v123
	v_cvt_pk_bf16_f32 v114, v160, v116
	v_cvt_pk_bf16_f32 v115, v117, v115
	v_lshl_add_u64 v[116:117], s[36:37], 0, v[164:165]
	v_ashrrev_i32_e32 v121, 31, v120
	global_store_dwordx4 v[116:117], v[112:115], off
	s_nop 1
	v_lshlrev_b64 v[112:113], 11, v[120:121]
	v_lshl_add_u64 v[120:121], v[120:121], 2, s[28:29]
	v_lshl_add_u64 v[112:113], v[112:113], 0, v[150:151]
	v_lshlrev_b64 v[122:123], 1, v[112:113]
	v_lshl_add_u64 v[112:113], s[88:89], 0, v[122:123]
	v_lshl_add_u64 v[116:117], s[0:1], 0, v[122:123]
	s_waitcnt vmcnt(19)
; __device__ __forceinline__ f32x4 unpk4(uint2 u) { f32x4 r; r[0] = __uint_as_float(u.x << 16); r[1] = __uint_as_float(u.x & 0xffff0000u); r[2] = __uint_as_float(u.y << 16); r[3] = __uint_as_float(u.y & 0xffff0000u); return r; }
; __device__ __forceinline__ float sigm(float x) { return __builtin_amdgcn_rcpf(1.f + __expf(-x)); }
;     __device__ __forceinline__ void operator()(AccRef acc, const Unit& u, int wr, int wc, int fr, int fq) const {
;     ...
;                     const f32x4 pa = unpk4(n == 0 ? make_uint2(pa8.x, pa8.y) : make_uint2(pa8.z, pa8.w)), pb = unpk4(n == 0 ? make_uint2(pb8.x, pb8.y) : make_uint2(pb8.z, pb8.w));
; #pragma unroll
;                     for (int e = 0; e < 4; ++e) v[n][e] = sigm(acc[ai][0][m][n][e] * s) * pa[e] + sigm(acc[ai][1][m][n][e] * s) * pb[e];
;                 }
	v_mul_f32_e32 v104, v104, v182
	v_mul_f32_e32 v108, v108, v182
	v_mul_f32_e32 v104, 0xbfb8aa3b, v104
	v_mul_f32_e32 v108, 0xbfb8aa3b, v108
	v_exp_f32_e32 v104, v104
	v_mul_f32_e32 v105, v105, v182
	v_exp_f32_e32 v108, v108
	v_mul_f32_e32 v109, v109, v182
	v_mul_f32_e32 v107, v107, v182
	v_mul_f32_e32 v105, 0xbfb8aa3b, v105
	v_mul_f32_e32 v111, v111, v182
	v_mul_f32_e32 v109, 0xbfb8aa3b, v109
	v_mul_f32_e32 v107, 0xbfb8aa3b, v107
	v_exp_f32_e32 v105, v105
	v_mul_f32_e32 v96, v96, v182
	v_mul_f32_e32 v111, 0xbfb8aa3b, v111
	v_exp_f32_e32 v109, v109
	v_exp_f32_e32 v107, v107
	v_add_f32_e32 v104, 1.0, v104
	v_mul_f32_e32 v100, v100, v182
	v_mul_f32_e32 v96, 0xbfb8aa3b, v96
	v_mul_f32_e32 v97, v97, v182
	v_exp_f32_e32 v111, v111
	v_add_f32_e32 v108, 1.0, v108
	v_rcp_f32_e32 v104, v104
	v_mul_f32_e32 v100, 0xbfb8aa3b, v100
	v_exp_f32_e32 v96, v96
	v_mul_f32_e32 v97, 0xbfb8aa3b, v97
	v_rcp_f32_e32 v108, v108
	v_exp_f32_e32 v100, v100
	v_exp_f32_e32 v97, v97
	v_add_f32_e32 v105, 1.0, v105
	v_add_f32_e32 v109, 1.0, v109
	v_rcp_f32_e32 v105, v105
	v_add_f32_e32 v107, 1.0, v107
	v_lshlrev_b32_e32 v121, 16, v174
	v_add_f32_e32 v111, 1.0, v111
	v_rcp_f32_e32 v109, v109
	v_rcp_f32_e32 v107, v107
	v_add_f32_e32 v96, 1.0, v96
	v_add_f32_e32 v100, 1.0, v100
	v_rcp_f32_e32 v96, v96
	v_mul_f32_e32 v101, v101, v182
	v_add_f32_e32 v97, 1.0, v97
	v_rcp_f32_e32 v100, v100
	v_mul_f32_e32 v101, 0xbfb8aa3b, v101
	v_rcp_f32_e32 v97, v97
	v_and_b32_e32 v174, 0xffff0000, v174
	v_exp_f32_e32 v101, v101
	v_lshlrev_b32_e32 v124, 16, v175
	v_and_b32_e32 v175, 0xffff0000, v175
	v_mul_f32_e32 v106, v106, v182
	v_mul_f32_e32 v110, v110, v182
	v_mul_f32_e32 v106, 0xbfb8aa3b, v106
	v_mul_f32_e32 v110, 0xbfb8aa3b, v110
	v_exp_f32_e32 v106, v106
	v_mul_f32_e32 v99, v99, v182
	v_exp_f32_e32 v110, v110
	v_mul_f32_e32 v99, 0xbfb8aa3b, v99
	v_exp_f32_e32 v99, v99
	v_add_f32_e32 v106, 1.0, v106
	v_add_f32_e32 v110, 1.0, v110
	v_rcp_f32_e32 v106, v106
	v_rcp_f32_e32 v110, v110
	v_add_f32_e32 v99, 1.0, v99
	v_rcp_f32_e32 v99, v99
	s_waitcnt vmcnt(19)
	v_lshlrev_b32_e32 v125, 16, v178
	v_mul_f32_e32 v104, v104, v125
	v_fmac_f32_e32 v104, v108, v121
	v_rcp_f32_e32 v108, v111
	v_and_b32_e32 v178, 0xffff0000, v178
	v_lshlrev_b32_e32 v126, 16, v179
	v_and_b32_e32 v179, 0xffff0000, v179
	v_mul_f32_e32 v105, v105, v178
	v_fmac_f32_e32 v105, v109, v174
	v_mul_f32_e32 v107, v107, v179
	v_lshlrev_b32_e32 v174, 16, v180
	v_fmac_f32_e32 v107, v108, v175
	v_lshlrev_b32_e32 v108, 16, v176
	v_and_b32_e32 v175, 0xffff0000, v180
	v_mul_f32_e32 v174, v96, v174
	v_fmac_f32_e32 v174, v100, v108
	v_mul_f32_e32 v100, v97, v175
	v_mul_f32_e32 v97, v98, v182
	v_add_f32_e32 v96, 1.0, v101
	v_mul_f32_e32 v101, v102, v182
	v_mul_f32_e32 v97, 0xbfb8aa3b, v97
	v_mul_f32_e32 v98, v103, v182
	v_mul_f32_e32 v101, 0xbfb8aa3b, v101
	v_exp_f32_e32 v97, v97
	v_mul_f32_e32 v98, 0xbfb8aa3b, v98
	v_rcp_f32_e32 v96, v96
	v_exp_f32_e32 v101, v101
	v_exp_f32_e32 v98, v98
	v_and_b32_e32 v109, 0xffff0000, v176
	v_add_f32_e32 v97, 1.0, v97
	v_fmac_f32_e32 v100, v96, v109
	v_add_f32_e32 v96, 1.0, v101
	v_rcp_f32_e32 v97, v97
	v_add_f32_e32 v98, 1.0, v98
	v_rcp_f32_e32 v96, v96
	v_rcp_f32_e32 v98, v98
	v_mul_f32_e32 v106, v106, v126
	v_fmac_f32_e32 v106, v110, v124
	v_lshlrev_b32_e32 v110, 16, v177
	v_and_b32_e32 v111, 0xffff0000, v177
	v_lshlrev_b32_e32 v176, 16, v181
	v_and_b32_e32 v177, 0xffff0000, v181
	v_mul_f32_e32 v101, v97, v176
	v_mul_f32_e32 v99, v99, v177
	v_fmac_f32_e32 v101, v96, v110
	v_fmac_f32_e32 v99, v98, v111

; __device__ __forceinline__ uint4 pk8(f32x4 a, f32x4 b) { return make_uint4(cvt_pk_bf16(a[0], a[1]), cvt_pk_bf16(a[2], a[3]), cvt_pk_bf16(b[0], b[1]), cvt_pk_bf16(b[2], b[3])); }
;     __device__ __forceinline__ void operator()(AccRef acc, const Unit& u, int wr, int wc, int fr, int fq) const {
;     ...
;                 *(uint4*)(O + o) = pk8(v[0], v[1]);
	v_cvt_pk_bf16_f32 v96, v104, v105

;     __device__ __forceinline__ void operator()(AccRef acc, const Unit& u, int wr, int wc, int fr, int fq) const {
;     ...
;                 const int r = u.pm * 256 + ai * 128 + wr * 64 + m * 16 + fr;
	v_or_b32_e32 v104, 32, v148

; __device__ __forceinline__ uint4 pk8(f32x4 a, f32x4 b) { return make_uint4(cvt_pk_bf16(a[0], a[1]), cvt_pk_bf16(a[2], a[3]), cvt_pk_bf16(b[0], b[1]), cvt_pk_bf16(b[2], b[3])); }
;     __device__ __forceinline__ void operator()(AccRef acc, const Unit& u, int wr, int wc, int fr, int fq) const {
;     ...
;                 *(uint4*)(O + o) = pk8(v[0], v[1]);
	v_cvt_pk_bf16_f32 v97, v106, v107


; __device__ __forceinline__ uint4 pk8(f32x4 a, f32x4 b) { return make_uint4(cvt_pk_bf16(a[0], a[1]), cvt_pk_bf16(a[2], a[3]), cvt_pk_bf16(b[0], b[1]), cvt_pk_bf16(b[2], b[3])); }
;     __device__ __forceinline__ void operator()(AccRef acc, const Unit& u, int wr, int wc, int fr, int fq) const {
;     ...
;                 *(uint4*)(O + o) = pk8(v[0], v[1]);
	v_cvt_pk_bf16_f32 v98, v174, v100


; __device__ __forceinline__ uint4 pk8(f32x4 a, f32x4 b) { return make_uint4(cvt_pk_bf16(a[0], a[1]), cvt_pk_bf16(a[2], a[3]), cvt_pk_bf16(b[0], b[1]), cvt_pk_bf16(b[2], b[3])); }
;     __device__ __forceinline__ void operator()(AccRef acc, const Unit& u, int wr, int wc, int fr, int fq) const {
;     ...
;                 *(uint4*)(O + o) = pk8(v[0], v[1]);
	v_cvt_pk_bf16_f32 v99, v101, v99

; __device__ __forceinline__ f32x4 unpk4(uint2 u) { f32x4 r; r[0] = __uint_as_float(u.x << 16); r[1] = __uint_as_float(u.x & 0xffff0000u); r[2] = __uint_as_float(u.y << 16); r[3] = __uint_as_float(u.y & 0xffff0000u); return r; }
; __device__ __forceinline__ float sigm(float x) { return __builtin_amdgcn_rcpf(1.f + __expf(-x)); }
; __device__ __forceinline__ uint4 pk8(f32x4 a, f32x4 b) { return make_uint4(cvt_pk_bf16(a[0], a[1]), cvt_pk_bf16(a[2], a[3]), cvt_pk_bf16(b[0], b[1]), cvt_pk_bf16(b[2], b[3])); }
;     __device__ __forceinline__ void operator()(AccRef acc, const Unit& u, int wr, int wc, int fr, int fq) const {
;     ...
;                 const int r = u.pm * 256 + ai * 128 + wr * 64 + m * 16 + fr;
;                 const float s = rinv[r];
;                 const size_t o = (size_t)r * D + c0;
;                 const uint4 pa8 = *(const uint4*)(Pa + o), pb8 = *(const uint4*)(Pb + o);
;                 f32x4 v[2];
; #pragma unroll
;                 for (int n = 0; n < 2; ++n) {
;                     const f32x4 pa = unpk4(n == 0 ? make_uint2(pa8.x, pa8.y) : make_uint2(pa8.z, pa8.w)), pb = unpk4(n == 0 ? make_uint2(pb8.x, pb8.y) : make_uint2(pb8.z, pb8.w));
; #pragma unroll
;                     for (int e = 0; e < 4; ++e) v[n][e] = sigm(acc[ai][0][m][n][e] * s) * pa[e] + sigm(acc[ai][1][m][n][e] * s) * pb[e];
;                 }
;                 *(uint4*)(O + o) = pk8(v[0], v[1]);
	v_lshl_add_u64 v[100:101], s[36:37], 0, v[122:123]
	v_ashrrev_i32_e32 v105, 31, v104
	global_store_dwordx4 v[100:101], v[96:99], off
	s_nop 1
	v_lshlrev_b64 v[96:97], 11, v[104:105]
	v_lshl_add_u64 v[104:105], v[104:105], 2, s[28:29]
	v_lshl_add_u64 v[96:97], v[96:97], 0, v[150:151]
	v_lshlrev_b64 v[106:107], 1, v[96:97]
	v_lshl_add_u64 v[96:97], s[88:89], 0, v[106:107]
	v_lshl_add_u64 v[100:101], s[0:1], 0, v[106:107]
	s_waitcnt vmcnt(17)
	v_mul_f32_e32 v89, v89, v192
	v_mul_f32_e32 v93, v93, v192
	v_mul_f32_e32 v89, 0xbfb8aa3b, v89
	v_mul_f32_e32 v93, 0xbfb8aa3b, v93
	v_exp_f32_e32 v89, v89
	v_exp_f32_e32 v93, v93
	v_mul_f32_e32 v88, v88, v192
	v_mul_f32_e32 v92, v92, v192
	v_add_f32_e32 v89, 1.0, v89
	v_mul_f32_e32 v88, 0xbfb8aa3b, v88
	v_add_f32_e32 v93, 1.0, v93
	v_rcp_f32_e32 v89, v89
	v_mul_f32_e32 v92, 0xbfb8aa3b, v92
	v_exp_f32_e32 v88, v88
	v_rcp_f32_e32 v93, v93
	v_exp_f32_e32 v92, v92
	v_lshlrev_b32_e32 v105, 16, v184
	v_and_b32_e32 v184, 0xffff0000, v184
	v_mul_f32_e32 v90, v90, v192
	v_mul_f32_e32 v91, v91, v192
	v_add_f32_e32 v88, 1.0, v88
	v_mul_f32_e32 v94, v94, v192
	v_mul_f32_e32 v90, 0xbfb8aa3b, v90
	v_mul_f32_e32 v91, 0xbfb8aa3b, v91
	v_mul_f32_e32 v80, v80, v192
	v_add_f32_e32 v92, 1.0, v92
	v_rcp_f32_e32 v88, v88
	v_mul_f32_e32 v94, 0xbfb8aa3b, v94
	v_exp_f32_e32 v90, v90
	v_exp_f32_e32 v91, v91
	v_mul_f32_e32 v84, v84, v192
	v_mul_f32_e32 v80, 0xbfb8aa3b, v80
	v_mul_f32_e32 v81, v81, v192
	v_rcp_f32_e32 v92, v92
	v_exp_f32_e32 v94, v94
	v_mul_f32_e32 v84, 0xbfb8aa3b, v84
	v_exp_f32_e32 v80, v80
	v_mul_f32_e32 v81, 0xbfb8aa3b, v81
	v_exp_f32_e32 v84, v84
	v_exp_f32_e32 v81, v81
	v_add_f32_e32 v90, 1.0, v90
	v_add_f32_e32 v91, 1.0, v91
	v_rcp_f32_e32 v90, v90
	v_rcp_f32_e32 v91, v91
	v_add_f32_e32 v80, 1.0, v80
	v_add_f32_e32 v84, 1.0, v84
	v_rcp_f32_e32 v80, v80
	v_mul_f32_e32 v85, v85, v192
	v_add_f32_e32 v81, 1.0, v81
	v_rcp_f32_e32 v84, v84
	v_mul_f32_e32 v85, 0xbfb8aa3b, v85
	v_rcp_f32_e32 v81, v81
	v_exp_f32_e32 v85, v85
	v_lshlrev_b32_e32 v108, 16, v185
	v_and_b32_e32 v185, 0xffff0000, v185
	v_mul_f32_e32 v83, v83, v192
	v_mul_f32_e32 v83, 0xbfb8aa3b, v83
	v_exp_f32_e32 v83, v83
	s_waitcnt vmcnt(17)
	v_lshlrev_b32_e32 v109, 16, v188
	v_and_b32_e32 v188, 0xffff0000, v188
	v_mul_f32_e32 v89, v89, v188
	v_fmac_f32_e32 v89, v93, v184
	v_mul_f32_e32 v93, v95, v192
	v_mul_f32_e32 v93, 0xbfb8aa3b, v93
	v_exp_f32_e32 v93, v93
	v_mul_f32_e32 v88, v88, v109
	v_fmac_f32_e32 v88, v92, v105
	v_add_f32_e32 v92, 1.0, v94
	v_add_f32_e32 v93, 1.0, v93
	v_rcp_f32_e32 v92, v92
	v_rcp_f32_e32 v93, v93
	v_lshlrev_b32_e32 v110, 16, v189
	v_and_b32_e32 v189, 0xffff0000, v189
	v_mul_f32_e32 v90, v90, v110
	v_mul_f32_e32 v91, v91, v189
	v_lshlrev_b32_e32 v184, 16, v190
	v_fmac_f32_e32 v90, v92, v108
	v_fmac_f32_e32 v91, v93, v185
	v_lshlrev_b32_e32 v92, 16, v186
	v_and_b32_e32 v185, 0xffff0000, v190
	v_mul_f32_e32 v184, v80, v184
	v_fmac_f32_e32 v184, v84, v92
	v_mul_f32_e32 v84, v81, v185
	v_mul_f32_e32 v81, v82, v192
	v_add_f32_e32 v80, 1.0, v85
	v_mul_f32_e32 v85, v86, v192
	v_mul_f32_e32 v81, 0xbfb8aa3b, v81
	v_mul_f32_e32 v82, v87, v192
	v_mul_f32_e32 v85, 0xbfb8aa3b, v85
	v_exp_f32_e32 v81, v81
	v_mul_f32_e32 v82, 0xbfb8aa3b, v82
	v_rcp_f32_e32 v80, v80
	v_exp_f32_e32 v85, v85
	v_exp_f32_e32 v82, v82
	v_and_b32_e32 v93, 0xffff0000, v186
	v_add_f32_e32 v81, 1.0, v81
	v_add_f32_e32 v83, 1.0, v83
	v_fmac_f32_e32 v84, v80, v93
	v_add_f32_e32 v80, 1.0, v85
	v_rcp_f32_e32 v81, v81
	v_add_f32_e32 v82, 1.0, v82
	v_rcp_f32_e32 v83, v83
	v_rcp_f32_e32 v80, v80
	v_rcp_f32_e32 v82, v82
	v_lshlrev_b32_e32 v94, 16, v187
	v_and_b32_e32 v95, 0xffff0000, v187
	v_lshlrev_b32_e32 v186, 16, v191
	v_and_b32_e32 v187, 0xffff0000, v191
	v_mul_f32_e32 v85, v81, v186
	v_mul_f32_e32 v83, v83, v187
	v_fmac_f32_e32 v85, v80, v94
	v_fmac_f32_e32 v83, v82, v95

; __device__ __forceinline__ uint4 pk8(f32x4 a, f32x4 b) { return make_uint4(cvt_pk_bf16(a[0], a[1]), cvt_pk_bf16(a[2], a[3]), cvt_pk_bf16(b[0], b[1]), cvt_pk_bf16(b[2], b[3])); }
;     __device__ __forceinline__ void operator()(AccRef acc, const Unit& u, int wr, int wc, int fr, int fq) const {
;     ...
;                 *(uint4*)(O + o) = pk8(v[0], v[1]);
	v_cvt_pk_bf16_f32 v80, v88, v89

;     __device__ __forceinline__ void operator()(AccRef acc, const Unit& u, int wr, int wc, int fr, int fq) const {
;     ...
;                 const int r = u.pm * 256 + ai * 128 + wr * 64 + m * 16 + fr;
	v_or_b32_e32 v88, 48, v148

; __device__ __forceinline__ uint4 pk8(f32x4 a, f32x4 b) { return make_uint4(cvt_pk_bf16(a[0], a[1]), cvt_pk_bf16(a[2], a[3]), cvt_pk_bf16(b[0], b[1]), cvt_pk_bf16(b[2], b[3])); }
;     __device__ __forceinline__ void operator()(AccRef acc, const Unit& u, int wr, int wc, int fr, int fq) const {
;     ...
;                 *(uint4*)(O + o) = pk8(v[0], v[1]);
	v_cvt_pk_bf16_f32 v81, v90, v91


; __device__ __forceinline__ uint4 pk8(f32x4 a, f32x4 b) { return make_uint4(cvt_pk_bf16(a[0], a[1]), cvt_pk_bf16(a[2], a[3]), cvt_pk_bf16(b[0], b[1]), cvt_pk_bf16(b[2], b[3])); }
;     __device__ __forceinline__ void operator()(AccRef acc, const Unit& u, int wr, int wc, int fr, int fq) const {
;     ...
;                 *(uint4*)(O + o) = pk8(v[0], v[1]);
	v_cvt_pk_bf16_f32 v82, v184, v84


; __device__ __forceinline__ uint4 pk8(f32x4 a, f32x4 b) { return make_uint4(cvt_pk_bf16(a[0], a[1]), cvt_pk_bf16(a[2], a[3]), cvt_pk_bf16(b[0], b[1]), cvt_pk_bf16(b[2], b[3])); }
;     __device__ __forceinline__ void operator()(AccRef acc, const Unit& u, int wr, int wc, int fr, int fq) const {
;     ...
;                 *(uint4*)(O + o) = pk8(v[0], v[1]);
	v_cvt_pk_bf16_f32 v83, v85, v83

; __device__ __forceinline__ f32x4 unpk4(uint2 u) { f32x4 r; r[0] = __uint_as_float(u.x << 16); r[1] = __uint_as_float(u.x & 0xffff0000u); r[2] = __uint_as_float(u.y << 16); r[3] = __uint_as_float(u.y & 0xffff0000u); return r; }
; __device__ __forceinline__ float sigm(float x) { return __builtin_amdgcn_rcpf(1.f + __expf(-x)); }
; __device__ __forceinline__ uint4 pk8(f32x4 a, f32x4 b) { return make_uint4(cvt_pk_bf16(a[0], a[1]), cvt_pk_bf16(a[2], a[3]), cvt_pk_bf16(b[0], b[1]), cvt_pk_bf16(b[2], b[3])); }
;     __device__ __forceinline__ void operator()(AccRef acc, const Unit& u, int wr, int wc, int fr, int fq) const {
;     ...
;                 const int r = u.pm * 256 + ai * 128 + wr * 64 + m * 16 + fr;
;                 const float s = rinv[r];
;                 const size_t o = (size_t)r * D + c0;
;                 const uint4 pa8 = *(const uint4*)(Pa + o), pb8 = *(const uint4*)(Pb + o);
;                 f32x4 v[2];
; #pragma unroll
;                 for (int n = 0; n < 2; ++n) {
;                     const f32x4 pa = unpk4(n == 0 ? make_uint2(pa8.x, pa8.y) : make_uint2(pa8.z, pa8.w)), pb = unpk4(n == 0 ? make_uint2(pb8.x, pb8.y) : make_uint2(pb8.z, pb8.w));
; #pragma unroll
;                     for (int e = 0; e < 4; ++e) v[n][e] = sigm(acc[ai][0][m][n][e] * s) * pa[e] + sigm(acc[ai][1][m][n][e] * s) * pb[e];
;                 }
;                 *(uint4*)(O + o) = pk8(v[0], v[1]);
	v_lshl_add_u64 v[84:85], s[36:37], 0, v[106:107]
	v_ashrrev_i32_e32 v89, 31, v88
	global_store_dwordx4 v[84:85], v[80:83], off
	s_nop 1
	v_lshlrev_b64 v[80:81], 11, v[88:89]
	v_lshl_add_u64 v[88:89], v[88:89], 2, s[28:29]
	v_lshl_add_u64 v[80:81], v[80:81], 0, v[150:151]
	v_lshlrev_b64 v[90:91], 1, v[80:81]
	v_lshl_add_u64 v[80:81], s[88:89], 0, v[90:91]
	v_lshl_add_u64 v[84:85], s[0:1], 0, v[90:91]
	s_waitcnt vmcnt(15)
	v_mul_f32_e32 v73, v73, v202
	v_mul_f32_e32 v77, v77, v202
	v_mul_f32_e32 v73, 0xbfb8aa3b, v73
	v_mul_f32_e32 v77, 0xbfb8aa3b, v77
	v_exp_f32_e32 v73, v73
	v_exp_f32_e32 v77, v77
	v_mul_f32_e32 v72, v72, v202
	v_mul_f32_e32 v76, v76, v202
	v_add_f32_e32 v73, 1.0, v73
	v_mul_f32_e32 v72, 0xbfb8aa3b, v72
	v_add_f32_e32 v77, 1.0, v77
	v_rcp_f32_e32 v73, v73
	v_mul_f32_e32 v76, 0xbfb8aa3b, v76
	v_exp_f32_e32 v72, v72
	v_rcp_f32_e32 v77, v77
	v_exp_f32_e32 v76, v76
	v_lshlrev_b32_e32 v89, 16, v194
	v_and_b32_e32 v194, 0xffff0000, v194
	v_mul_f32_e32 v74, v74, v202
	v_mul_f32_e32 v75, v75, v202
	v_add_f32_e32 v72, 1.0, v72
	v_mul_f32_e32 v78, v78, v202
	v_mul_f32_e32 v74, 0xbfb8aa3b, v74
	v_mul_f32_e32 v75, 0xbfb8aa3b, v75
	v_mul_f32_e32 v64, v64, v202
	v_add_f32_e32 v76, 1.0, v76
	v_rcp_f32_e32 v72, v72
	v_mul_f32_e32 v78, 0xbfb8aa3b, v78
	v_exp_f32_e32 v74, v74
	v_exp_f32_e32 v75, v75
	v_mul_f32_e32 v68, v68, v202
	v_mul_f32_e32 v64, 0xbfb8aa3b, v64
	v_mul_f32_e32 v65, v65, v202
	v_rcp_f32_e32 v76, v76
	v_exp_f32_e32 v78, v78
	v_mul_f32_e32 v68, 0xbfb8aa3b, v68
	v_exp_f32_e32 v64, v64
	v_mul_f32_e32 v65, 0xbfb8aa3b, v65
	v_exp_f32_e32 v68, v68
	v_exp_f32_e32 v65, v65
	v_add_f32_e32 v74, 1.0, v74
	v_add_f32_e32 v75, 1.0, v75
	v_rcp_f32_e32 v74, v74
	v_rcp_f32_e32 v75, v75
	v_add_f32_e32 v64, 1.0, v64
	v_add_f32_e32 v68, 1.0, v68
	v_rcp_f32_e32 v64, v64
	v_mul_f32_e32 v69, v69, v202
	v_add_f32_e32 v65, 1.0, v65
	v_rcp_f32_e32 v68, v68
	v_mul_f32_e32 v69, 0xbfb8aa3b, v69
	v_rcp_f32_e32 v65, v65
	v_exp_f32_e32 v69, v69
	v_lshlrev_b32_e32 v92, 16, v195
	v_and_b32_e32 v195, 0xffff0000, v195
	v_mul_f32_e32 v67, v67, v202
	v_mul_f32_e32 v67, 0xbfb8aa3b, v67
	v_exp_f32_e32 v67, v67
	s_waitcnt vmcnt(15)
	v_lshlrev_b32_e32 v93, 16, v198
	v_and_b32_e32 v198, 0xffff0000, v198
	v_mul_f32_e32 v73, v73, v198
	v_fmac_f32_e32 v73, v77, v194
	v_mul_f32_e32 v77, v79, v202
	v_mul_f32_e32 v77, 0xbfb8aa3b, v77
	v_exp_f32_e32 v77, v77
	v_mul_f32_e32 v72, v72, v93
	v_fmac_f32_e32 v72, v76, v89
	v_add_f32_e32 v76, 1.0, v78
	v_add_f32_e32 v77, 1.0, v77
	v_rcp_f32_e32 v76, v76
	v_rcp_f32_e32 v77, v77
	v_lshlrev_b32_e32 v94, 16, v199
	v_and_b32_e32 v199, 0xffff0000, v199
	v_mul_f32_e32 v74, v74, v94
	v_mul_f32_e32 v75, v75, v199
	v_lshlrev_b32_e32 v194, 16, v200
	v_fmac_f32_e32 v74, v76, v92
	v_fmac_f32_e32 v75, v77, v195
	v_lshlrev_b32_e32 v76, 16, v196
	v_and_b32_e32 v195, 0xffff0000, v200
	v_mul_f32_e32 v194, v64, v194
	v_fmac_f32_e32 v194, v68, v76
	v_mul_f32_e32 v68, v65, v195
	v_mul_f32_e32 v65, v66, v202
	v_add_f32_e32 v64, 1.0, v69
	v_mul_f32_e32 v69, v70, v202
	v_mul_f32_e32 v65, 0xbfb8aa3b, v65
	v_mul_f32_e32 v66, v71, v202
	v_mul_f32_e32 v69, 0xbfb8aa3b, v69
	v_exp_f32_e32 v65, v65
	v_mul_f32_e32 v66, 0xbfb8aa3b, v66
	v_rcp_f32_e32 v64, v64
	v_exp_f32_e32 v69, v69
	v_exp_f32_e32 v66, v66
	v_and_b32_e32 v77, 0xffff0000, v196
	v_add_f32_e32 v65, 1.0, v65
	v_add_f32_e32 v67, 1.0, v67
	v_fmac_f32_e32 v68, v64, v77
	v_add_f32_e32 v64, 1.0, v69
	v_rcp_f32_e32 v65, v65
	v_add_f32_e32 v66, 1.0, v66
	v_rcp_f32_e32 v67, v67
	v_rcp_f32_e32 v64, v64
	v_rcp_f32_e32 v66, v66
	v_lshlrev_b32_e32 v78, 16, v197
	v_and_b32_e32 v79, 0xffff0000, v197
	v_lshlrev_b32_e32 v196, 16, v201
	v_and_b32_e32 v197, 0xffff0000, v201
	v_mul_f32_e32 v69, v65, v196
	v_mul_f32_e32 v67, v67, v197
	v_fmac_f32_e32 v69, v64, v78
	v_fmac_f32_e32 v67, v66, v79

; __device__ __forceinline__ uint4 pk8(f32x4 a, f32x4 b) { return make_uint4(cvt_pk_bf16(a[0], a[1]), cvt_pk_bf16(a[2], a[3]), cvt_pk_bf16(b[0], b[1]), cvt_pk_bf16(b[2], b[3])); }
;     __device__ __forceinline__ void operator()(AccRef acc, const Unit& u, int wr, int wc, int fr, int fq) const {
;     ...
;                 *(uint4*)(O + o) = pk8(v[0], v[1]);
	v_cvt_pk_bf16_f32 v64, v72, v73

;     __device__ __forceinline__ void operator()(AccRef acc, const Unit& u, int wr, int wc, int fr, int fq) const {
;     ...
;                 const int r = u.pm * 256 + ai * 128 + wr * 64 + m * 16 + fr;
	v_add_u32_e32 v72, 0x80, v148

; __device__ __forceinline__ uint4 pk8(f32x4 a, f32x4 b) { return make_uint4(cvt_pk_bf16(a[0], a[1]), cvt_pk_bf16(a[2], a[3]), cvt_pk_bf16(b[0], b[1]), cvt_pk_bf16(b[2], b[3])); }
;     __device__ __forceinline__ void operator()(AccRef acc, const Unit& u, int wr, int wc, int fr, int fq) const {
;     ...
;                 *(uint4*)(O + o) = pk8(v[0], v[1]);
	v_cvt_pk_bf16_f32 v65, v74, v75


; __device__ __forceinline__ uint4 pk8(f32x4 a, f32x4 b) { return make_uint4(cvt_pk_bf16(a[0], a[1]), cvt_pk_bf16(a[2], a[3]), cvt_pk_bf16(b[0], b[1]), cvt_pk_bf16(b[2], b[3])); }
;     __device__ __forceinline__ void operator()(AccRef acc, const Unit& u, int wr, int wc, int fr, int fq) const {
;     ...
;                 *(uint4*)(O + o) = pk8(v[0], v[1]);
	v_cvt_pk_bf16_f32 v66, v194, v68


; __device__ __forceinline__ uint4 pk8(f32x4 a, f32x4 b) { return make_uint4(cvt_pk_bf16(a[0], a[1]), cvt_pk_bf16(a[2], a[3]), cvt_pk_bf16(b[0], b[1]), cvt_pk_bf16(b[2], b[3])); }
;     __device__ __forceinline__ void operator()(AccRef acc, const Unit& u, int wr, int wc, int fr, int fq) const {
;     ...
;                 *(uint4*)(O + o) = pk8(v[0], v[1]);
	v_cvt_pk_bf16_f32 v67, v69, v67

; __device__ __forceinline__ f32x4 unpk4(uint2 u) { f32x4 r; r[0] = __uint_as_float(u.x << 16); r[1] = __uint_as_float(u.x & 0xffff0000u); r[2] = __uint_as_float(u.y << 16); r[3] = __uint_as_float(u.y & 0xffff0000u); return r; }
; __device__ __forceinline__ float sigm(float x) { return __builtin_amdgcn_rcpf(1.f + __expf(-x)); }
; __device__ __forceinline__ uint4 pk8(f32x4 a, f32x4 b) { return make_uint4(cvt_pk_bf16(a[0], a[1]), cvt_pk_bf16(a[2], a[3]), cvt_pk_bf16(b[0], b[1]), cvt_pk_bf16(b[2], b[3])); }
;     __device__ __forceinline__ void operator()(AccRef acc, const Unit& u, int wr, int wc, int fr, int fq) const {
;     ...
;                 const int r = u.pm * 256 + ai * 128 + wr * 64 + m * 16 + fr;
;                 const float s = rinv[r];
;                 const size_t o = (size_t)r * D + c0;
;                 const uint4 pa8 = *(const uint4*)(Pa + o), pb8 = *(const uint4*)(Pb + o);
;                 f32x4 v[2];
; #pragma unroll
;                 for (int n = 0; n < 2; ++n) {
;                     const f32x4 pa = unpk4(n == 0 ? make_uint2(pa8.x, pa8.y) : make_uint2(pa8.z, pa8.w)), pb = unpk4(n == 0 ? make_uint2(pb8.x, pb8.y) : make_uint2(pb8.z, pb8.w));
; #pragma unroll
;                     for (int e = 0; e < 4; ++e) v[n][e] = sigm(acc[ai][0][m][n][e] * s) * pa[e] + sigm(acc[ai][1][m][n][e] * s) * pb[e];
;                 }
;                 *(uint4*)(O + o) = pk8(v[0], v[1]);
	v_lshl_add_u64 v[68:69], s[36:37], 0, v[90:91]
	v_ashrrev_i32_e32 v73, 31, v72
	global_store_dwordx4 v[68:69], v[64:67], off
	s_nop 1
	v_lshlrev_b64 v[64:65], 11, v[72:73]
	v_lshl_add_u64 v[72:73], v[72:73], 2, s[28:29]
	v_lshl_add_u64 v[64:65], v[64:65], 0, v[150:151]
	v_lshlrev_b64 v[74:75], 1, v[64:65]
	v_lshl_add_u64 v[64:65], s[88:89], 0, v[74:75]
	v_lshl_add_u64 v[68:69], s[0:1], 0, v[74:75]
	s_waitcnt vmcnt(13)
	v_mul_f32_e32 v57, v57, v212
	v_mul_f32_e32 v61, v61, v212
	v_mul_f32_e32 v57, 0xbfb8aa3b, v57
	v_mul_f32_e32 v61, 0xbfb8aa3b, v61
	v_exp_f32_e32 v57, v57
	v_exp_f32_e32 v61, v61
	v_mul_f32_e32 v56, v56, v212
	v_mul_f32_e32 v60, v60, v212
	v_add_f32_e32 v57, 1.0, v57
	v_mul_f32_e32 v56, 0xbfb8aa3b, v56
	v_add_f32_e32 v61, 1.0, v61
	v_rcp_f32_e32 v57, v57
	v_mul_f32_e32 v60, 0xbfb8aa3b, v60
	v_exp_f32_e32 v56, v56
	v_rcp_f32_e32 v61, v61
	v_exp_f32_e32 v60, v60
	v_lshlrev_b32_e32 v73, 16, v204
	v_and_b32_e32 v204, 0xffff0000, v204
	v_mul_f32_e32 v58, v58, v212
	v_mul_f32_e32 v59, v59, v212
	v_add_f32_e32 v56, 1.0, v56
	v_mul_f32_e32 v62, v62, v212
	v_mul_f32_e32 v58, 0xbfb8aa3b, v58
	v_mul_f32_e32 v59, 0xbfb8aa3b, v59
	v_mul_f32_e32 v48, v48, v212
	v_add_f32_e32 v60, 1.0, v60
	v_rcp_f32_e32 v56, v56
	v_mul_f32_e32 v62, 0xbfb8aa3b, v62
	v_exp_f32_e32 v58, v58
	v_exp_f32_e32 v59, v59
	v_mul_f32_e32 v52, v52, v212
	v_mul_f32_e32 v48, 0xbfb8aa3b, v48
	v_mul_f32_e32 v49, v49, v212
	v_rcp_f32_e32 v60, v60
	v_exp_f32_e32 v62, v62
	v_mul_f32_e32 v52, 0xbfb8aa3b, v52
	v_exp_f32_e32 v48, v48
	v_mul_f32_e32 v49, 0xbfb8aa3b, v49
	v_exp_f32_e32 v52, v52
	v_exp_f32_e32 v49, v49
	v_add_f32_e32 v58, 1.0, v58
	v_add_f32_e32 v59, 1.0, v59
	v_rcp_f32_e32 v58, v58
	v_rcp_f32_e32 v59, v59
	v_add_f32_e32 v48, 1.0, v48
	v_add_f32_e32 v52, 1.0, v52
	v_rcp_f32_e32 v48, v48
	v_mul_f32_e32 v53, v53, v212
	v_add_f32_e32 v49, 1.0, v49
	v_rcp_f32_e32 v52, v52
	v_mul_f32_e32 v53, 0xbfb8aa3b, v53
	v_rcp_f32_e32 v49, v49
	v_exp_f32_e32 v53, v53
	v_lshlrev_b32_e32 v76, 16, v205
	v_and_b32_e32 v205, 0xffff0000, v205
	v_mul_f32_e32 v51, v51, v212
	v_mul_f32_e32 v51, 0xbfb8aa3b, v51
	v_exp_f32_e32 v51, v51
	s_waitcnt vmcnt(13)
	v_lshlrev_b32_e32 v77, 16, v208
	v_and_b32_e32 v208, 0xffff0000, v208
	v_mul_f32_e32 v57, v57, v208
	v_fmac_f32_e32 v57, v61, v204
	v_mul_f32_e32 v61, v63, v212
	v_mul_f32_e32 v61, 0xbfb8aa3b, v61
	v_exp_f32_e32 v61, v61
	v_mul_f32_e32 v56, v56, v77
	v_fmac_f32_e32 v56, v60, v73
	v_add_f32_e32 v60, 1.0, v62
	v_add_f32_e32 v61, 1.0, v61
	v_rcp_f32_e32 v60, v60
	v_rcp_f32_e32 v61, v61
	v_lshlrev_b32_e32 v78, 16, v209
	v_and_b32_e32 v209, 0xffff0000, v209
	v_mul_f32_e32 v58, v58, v78
	v_mul_f32_e32 v59, v59, v209
	v_lshlrev_b32_e32 v204, 16, v210
	v_fmac_f32_e32 v58, v60, v76
	v_fmac_f32_e32 v59, v61, v205
	v_lshlrev_b32_e32 v60, 16, v206
	v_and_b32_e32 v205, 0xffff0000, v210
	v_mul_f32_e32 v204, v48, v204
	v_fmac_f32_e32 v204, v52, v60
	v_mul_f32_e32 v52, v49, v205
	v_mul_f32_e32 v49, v50, v212
	v_add_f32_e32 v48, 1.0, v53
	v_mul_f32_e32 v53, v54, v212
	v_mul_f32_e32 v49, 0xbfb8aa3b, v49
	v_mul_f32_e32 v50, v55, v212
	v_mul_f32_e32 v53, 0xbfb8aa3b, v53
	v_exp_f32_e32 v49, v49
	v_mul_f32_e32 v50, 0xbfb8aa3b, v50
	v_rcp_f32_e32 v48, v48
	v_exp_f32_e32 v53, v53
	v_exp_f32_e32 v50, v50
	v_and_b32_e32 v61, 0xffff0000, v206
	v_add_f32_e32 v49, 1.0, v49
	v_add_f32_e32 v51, 1.0, v51
	v_fmac_f32_e32 v52, v48, v61
	v_add_f32_e32 v48, 1.0, v53
	v_rcp_f32_e32 v49, v49
	v_add_f32_e32 v50, 1.0, v50
	v_rcp_f32_e32 v51, v51
	v_rcp_f32_e32 v48, v48
	v_rcp_f32_e32 v50, v50
	v_lshlrev_b32_e32 v62, 16, v207
	v_and_b32_e32 v63, 0xffff0000, v207
	v_lshlrev_b32_e32 v206, 16, v211
	v_and_b32_e32 v207, 0xffff0000, v211
	v_mul_f32_e32 v53, v49, v206
	v_mul_f32_e32 v51, v51, v207
	v_fmac_f32_e32 v53, v48, v62
	v_fmac_f32_e32 v51, v50, v63

; __device__ __forceinline__ uint4 pk8(f32x4 a, f32x4 b) { return make_uint4(cvt_pk_bf16(a[0], a[1]), cvt_pk_bf16(a[2], a[3]), cvt_pk_bf16(b[0], b[1]), cvt_pk_bf16(b[2], b[3])); }
;     __device__ __forceinline__ void operator()(AccRef acc, const Unit& u, int wr, int wc, int fr, int fq) const {
;     ...
;                 *(uint4*)(O + o) = pk8(v[0], v[1]);
	v_cvt_pk_bf16_f32 v48, v56, v57

;     __device__ __forceinline__ void operator()(AccRef acc, const Unit& u, int wr, int wc, int fr, int fq) const {
;     ...
;                 const int r = u.pm * 256 + ai * 128 + wr * 64 + m * 16 + fr;
	v_add_u32_e32 v56, 0x90, v148

; __device__ __forceinline__ uint4 pk8(f32x4 a, f32x4 b) { return make_uint4(cvt_pk_bf16(a[0], a[1]), cvt_pk_bf16(a[2], a[3]), cvt_pk_bf16(b[0], b[1]), cvt_pk_bf16(b[2], b[3])); }
;     __device__ __forceinline__ void operator()(AccRef acc, const Unit& u, int wr, int wc, int fr, int fq) const {
;     ...
;                 *(uint4*)(O + o) = pk8(v[0], v[1]);
	v_cvt_pk_bf16_f32 v49, v58, v59


; __device__ __forceinline__ uint4 pk8(f32x4 a, f32x4 b) { return make_uint4(cvt_pk_bf16(a[0], a[1]), cvt_pk_bf16(a[2], a[3]), cvt_pk_bf16(b[0], b[1]), cvt_pk_bf16(b[2], b[3])); }
;     __device__ __forceinline__ void operator()(AccRef acc, const Unit& u, int wr, int wc, int fr, int fq) const {
;     ...
;                 *(uint4*)(O + o) = pk8(v[0], v[1]);
	v_cvt_pk_bf16_f32 v50, v204, v52


; __device__ __forceinline__ uint4 pk8(f32x4 a, f32x4 b) { return make_uint4(cvt_pk_bf16(a[0], a[1]), cvt_pk_bf16(a[2], a[3]), cvt_pk_bf16(b[0], b[1]), cvt_pk_bf16(b[2], b[3])); }
;     __device__ __forceinline__ void operator()(AccRef acc, const Unit& u, int wr, int wc, int fr, int fq) const {
;     ...
;                 *(uint4*)(O + o) = pk8(v[0], v[1]);
	v_cvt_pk_bf16_f32 v51, v53, v51

; __device__ __forceinline__ f32x4 unpk4(uint2 u) { f32x4 r; r[0] = __uint_as_float(u.x << 16); r[1] = __uint_as_float(u.x & 0xffff0000u); r[2] = __uint_as_float(u.y << 16); r[3] = __uint_as_float(u.y & 0xffff0000u); return r; }
; __device__ __forceinline__ float sigm(float x) { return __builtin_amdgcn_rcpf(1.f + __expf(-x)); }
; __device__ __forceinline__ uint4 pk8(f32x4 a, f32x4 b) { return make_uint4(cvt_pk_bf16(a[0], a[1]), cvt_pk_bf16(a[2], a[3]), cvt_pk_bf16(b[0], b[1]), cvt_pk_bf16(b[2], b[3])); }
;     __device__ __forceinline__ void operator()(AccRef acc, const Unit& u, int wr, int wc, int fr, int fq) const {
;     ...
;                 const int r = u.pm * 256 + ai * 128 + wr * 64 + m * 16 + fr;
;                 const float s = rinv[r];
;                 const size_t o = (size_t)r * D + c0;
;                 const uint4 pa8 = *(const uint4*)(Pa + o), pb8 = *(const uint4*)(Pb + o);
;                 f32x4 v[2];
; #pragma unroll
;                 for (int n = 0; n < 2; ++n) {
;                     const f32x4 pa = unpk4(n == 0 ? make_uint2(pa8.x, pa8.y) : make_uint2(pa8.z, pa8.w)), pb = unpk4(n == 0 ? make_uint2(pb8.x, pb8.y) : make_uint2(pb8.z, pb8.w));
; #pragma unroll
;                     for (int e = 0; e < 4; ++e) v[n][e] = sigm(acc[ai][0][m][n][e] * s) * pa[e] + sigm(acc[ai][1][m][n][e] * s) * pb[e];
;                 }
;                 *(uint4*)(O + o) = pk8(v[0], v[1]);
	v_lshl_add_u64 v[52:53], s[36:37], 0, v[74:75]
	v_ashrrev_i32_e32 v57, 31, v56
	global_store_dwordx4 v[52:53], v[48:51], off
	s_nop 1
	v_lshlrev_b64 v[48:49], 11, v[56:57]
	v_lshl_add_u64 v[56:57], v[56:57], 2, s[28:29]
	v_lshl_add_u64 v[48:49], v[48:49], 0, v[150:151]
	v_lshlrev_b64 v[58:59], 1, v[48:49]
	v_lshl_add_u64 v[48:49], s[88:89], 0, v[58:59]
	v_lshl_add_u64 v[52:53], s[0:1], 0, v[58:59]
	s_waitcnt vmcnt(11)
	v_mul_f32_e32 v41, v41, v222
	v_mul_f32_e32 v45, v45, v222
	v_mul_f32_e32 v41, 0xbfb8aa3b, v41
	v_mul_f32_e32 v45, 0xbfb8aa3b, v45
	v_exp_f32_e32 v41, v41
	v_exp_f32_e32 v45, v45
	v_mul_f32_e32 v40, v40, v222
	v_mul_f32_e32 v44, v44, v222
	v_add_f32_e32 v41, 1.0, v41
	v_mul_f32_e32 v40, 0xbfb8aa3b, v40
	v_add_f32_e32 v45, 1.0, v45
	v_rcp_f32_e32 v41, v41
	v_mul_f32_e32 v44, 0xbfb8aa3b, v44
	v_exp_f32_e32 v40, v40
	v_rcp_f32_e32 v45, v45
	v_exp_f32_e32 v44, v44
	v_lshlrev_b32_e32 v57, 16, v214
	v_and_b32_e32 v214, 0xffff0000, v214
	v_mul_f32_e32 v42, v42, v222
	v_mul_f32_e32 v43, v43, v222
	v_add_f32_e32 v40, 1.0, v40
	v_mul_f32_e32 v46, v46, v222
	v_mul_f32_e32 v42, 0xbfb8aa3b, v42
	v_mul_f32_e32 v43, 0xbfb8aa3b, v43
	v_mul_f32_e32 v32, v32, v222
	v_add_f32_e32 v44, 1.0, v44
	v_rcp_f32_e32 v40, v40
	v_mul_f32_e32 v46, 0xbfb8aa3b, v46
	v_exp_f32_e32 v42, v42
	v_exp_f32_e32 v43, v43
	v_mul_f32_e32 v36, v36, v222
	v_mul_f32_e32 v32, 0xbfb8aa3b, v32
	v_mul_f32_e32 v33, v33, v222
	v_rcp_f32_e32 v44, v44
	v_exp_f32_e32 v46, v46
	v_mul_f32_e32 v36, 0xbfb8aa3b, v36
	v_exp_f32_e32 v32, v32
	v_mul_f32_e32 v33, 0xbfb8aa3b, v33
	v_exp_f32_e32 v36, v36
	v_exp_f32_e32 v33, v33
	v_add_f32_e32 v42, 1.0, v42
	v_add_f32_e32 v43, 1.0, v43
	v_rcp_f32_e32 v42, v42
	v_rcp_f32_e32 v43, v43
	v_add_f32_e32 v32, 1.0, v32
	v_add_f32_e32 v36, 1.0, v36
	v_rcp_f32_e32 v32, v32
	v_mul_f32_e32 v37, v37, v222
	v_add_f32_e32 v33, 1.0, v33
	v_rcp_f32_e32 v36, v36
	v_mul_f32_e32 v37, 0xbfb8aa3b, v37
	v_rcp_f32_e32 v33, v33
	v_exp_f32_e32 v37, v37
	v_lshlrev_b32_e32 v60, 16, v215
	v_and_b32_e32 v215, 0xffff0000, v215
	v_mul_f32_e32 v35, v35, v222
	v_mul_f32_e32 v35, 0xbfb8aa3b, v35
	v_exp_f32_e32 v35, v35
	s_waitcnt vmcnt(11)
	v_lshlrev_b32_e32 v61, 16, v218
	v_and_b32_e32 v218, 0xffff0000, v218
	v_mul_f32_e32 v41, v41, v218
	v_fmac_f32_e32 v41, v45, v214
	v_mul_f32_e32 v45, v47, v222
	v_mul_f32_e32 v45, 0xbfb8aa3b, v45
	v_exp_f32_e32 v45, v45
	v_mul_f32_e32 v40, v40, v61
	v_fmac_f32_e32 v40, v44, v57
	v_add_f32_e32 v44, 1.0, v46
	v_add_f32_e32 v45, 1.0, v45
	v_rcp_f32_e32 v44, v44
	v_rcp_f32_e32 v45, v45
	v_lshlrev_b32_e32 v62, 16, v219
	v_and_b32_e32 v219, 0xffff0000, v219
	v_mul_f32_e32 v42, v42, v62
	v_mul_f32_e32 v43, v43, v219
	v_lshlrev_b32_e32 v214, 16, v220
	v_fmac_f32_e32 v42, v44, v60
	v_fmac_f32_e32 v43, v45, v215
	v_lshlrev_b32_e32 v44, 16, v216
	v_and_b32_e32 v215, 0xffff0000, v220
	v_mul_f32_e32 v214, v32, v214
	v_fmac_f32_e32 v214, v36, v44
	v_mul_f32_e32 v36, v33, v215
	v_mul_f32_e32 v33, v34, v222
	v_add_f32_e32 v32, 1.0, v37
	v_mul_f32_e32 v37, v38, v222
	v_mul_f32_e32 v33, 0xbfb8aa3b, v33
	v_mul_f32_e32 v34, v39, v222
	v_mul_f32_e32 v37, 0xbfb8aa3b, v37
	v_exp_f32_e32 v33, v33
	v_mul_f32_e32 v34, 0xbfb8aa3b, v34
	v_rcp_f32_e32 v32, v32
	v_exp_f32_e32 v37, v37
	v_exp_f32_e32 v34, v34
	v_and_b32_e32 v45, 0xffff0000, v216
	v_add_f32_e32 v33, 1.0, v33
	v_add_f32_e32 v35, 1.0, v35
	v_fmac_f32_e32 v36, v32, v45
	v_add_f32_e32 v32, 1.0, v37
	v_rcp_f32_e32 v33, v33
	v_add_f32_e32 v34, 1.0, v34
	v_rcp_f32_e32 v35, v35
	v_rcp_f32_e32 v32, v32
	v_rcp_f32_e32 v34, v34
	v_lshlrev_b32_e32 v46, 16, v217
	v_and_b32_e32 v47, 0xffff0000, v217
	v_lshlrev_b32_e32 v216, 16, v221
	v_and_b32_e32 v217, 0xffff0000, v221
	v_mul_f32_e32 v37, v33, v216
	v_mul_f32_e32 v35, v35, v217
	v_fmac_f32_e32 v37, v32, v46
	v_fmac_f32_e32 v35, v34, v47

; __device__ __forceinline__ uint4 pk8(f32x4 a, f32x4 b) { return make_uint4(cvt_pk_bf16(a[0], a[1]), cvt_pk_bf16(a[2], a[3]), cvt_pk_bf16(b[0], b[1]), cvt_pk_bf16(b[2], b[3])); }
;     __device__ __forceinline__ void operator()(AccRef acc, const Unit& u, int wr, int wc, int fr, int fq) const {
;     ...
;                 *(uint4*)(O + o) = pk8(v[0], v[1]);
	v_cvt_pk_bf16_f32 v32, v40, v41

;     __device__ __forceinline__ void operator()(AccRef acc, const Unit& u, int wr, int wc, int fr, int fq) const {
;     ...
;                 const int r = u.pm * 256 + ai * 128 + wr * 64 + m * 16 + fr;
	v_add_u32_e32 v40, 0xa0, v148

; __device__ __forceinline__ uint4 pk8(f32x4 a, f32x4 b) { return make_uint4(cvt_pk_bf16(a[0], a[1]), cvt_pk_bf16(a[2], a[3]), cvt_pk_bf16(b[0], b[1]), cvt_pk_bf16(b[2], b[3])); }
;     __device__ __forceinline__ void operator()(AccRef acc, const Unit& u, int wr, int wc, int fr, int fq) const {
;     ...
;                 *(uint4*)(O + o) = pk8(v[0], v[1]);
	v_cvt_pk_bf16_f32 v33, v42, v43


; __device__ __forceinline__ uint4 pk8(f32x4 a, f32x4 b) { return make_uint4(cvt_pk_bf16(a[0], a[1]), cvt_pk_bf16(a[2], a[3]), cvt_pk_bf16(b[0], b[1]), cvt_pk_bf16(b[2], b[3])); }
;     __device__ __forceinline__ void operator()(AccRef acc, const Unit& u, int wr, int wc, int fr, int fq) const {
;     ...
;                 *(uint4*)(O + o) = pk8(v[0], v[1]);
	v_cvt_pk_bf16_f32 v34, v214, v36


; __device__ __forceinline__ uint4 pk8(f32x4 a, f32x4 b) { return make_uint4(cvt_pk_bf16(a[0], a[1]), cvt_pk_bf16(a[2], a[3]), cvt_pk_bf16(b[0], b[1]), cvt_pk_bf16(b[2], b[3])); }
;     __device__ __forceinline__ void operator()(AccRef acc, const Unit& u, int wr, int wc, int fr, int fq) const {
;     ...
;                 *(uint4*)(O + o) = pk8(v[0], v[1]);
	v_cvt_pk_bf16_f32 v35, v37, v35

; __device__ __forceinline__ f32x4 unpk4(uint2 u) { f32x4 r; r[0] = __uint_as_float(u.x << 16); r[1] = __uint_as_float(u.x & 0xffff0000u); r[2] = __uint_as_float(u.y << 16); r[3] = __uint_as_float(u.y & 0xffff0000u); return r; }
; __device__ __forceinline__ float sigm(float x) { return __builtin_amdgcn_rcpf(1.f + __expf(-x)); }
; __device__ __forceinline__ uint4 pk8(f32x4 a, f32x4 b) { return make_uint4(cvt_pk_bf16(a[0], a[1]), cvt_pk_bf16(a[2], a[3]), cvt_pk_bf16(b[0], b[1]), cvt_pk_bf16(b[2], b[3])); }
;     __device__ __forceinline__ void operator()(AccRef acc, const Unit& u, int wr, int wc, int fr, int fq) const {
;     ...
;                 const int r = u.pm * 256 + ai * 128 + wr * 64 + m * 16 + fr;
;                 const float s = rinv[r];
;                 const size_t o = (size_t)r * D + c0;
;                 const uint4 pa8 = *(const uint4*)(Pa + o), pb8 = *(const uint4*)(Pb + o);
;                 f32x4 v[2];
; #pragma unroll
;                 for (int n = 0; n < 2; ++n) {
;                     const f32x4 pa = unpk4(n == 0 ? make_uint2(pa8.x, pa8.y) : make_uint2(pa8.z, pa8.w)), pb = unpk4(n == 0 ? make_uint2(pb8.x, pb8.y) : make_uint2(pb8.z, pb8.w));
; #pragma unroll
;                     for (int e = 0; e < 4; ++e) v[n][e] = sigm(acc[ai][0][m][n][e] * s) * pa[e] + sigm(acc[ai][1][m][n][e] * s) * pb[e];
;                 }
;                 *(uint4*)(O + o) = pk8(v[0], v[1]);
	v_lshl_add_u64 v[36:37], s[36:37], 0, v[58:59]
	v_ashrrev_i32_e32 v41, 31, v40
	global_store_dwordx4 v[36:37], v[32:35], off
	s_nop 1
	v_lshlrev_b64 v[32:33], 11, v[40:41]
	v_lshl_add_u64 v[40:41], v[40:41], 2, s[28:29]
	v_lshl_add_u64 v[32:33], v[32:33], 0, v[150:151]
	v_lshlrev_b64 v[42:43], 1, v[32:33]
	v_lshl_add_u64 v[32:33], s[88:89], 0, v[42:43]
	v_lshl_add_u64 v[36:37], s[0:1], 0, v[42:43]
	s_waitcnt vmcnt(9)
	v_mul_f32_e32 v25, v25, v232
	v_mul_f32_e32 v29, v29, v232
	v_mul_f32_e32 v25, 0xbfb8aa3b, v25
	v_mul_f32_e32 v29, 0xbfb8aa3b, v29
	v_exp_f32_e32 v25, v25
	v_exp_f32_e32 v29, v29
	v_mul_f32_e32 v24, v24, v232
	v_mul_f32_e32 v28, v28, v232
	v_add_f32_e32 v25, 1.0, v25
	v_mul_f32_e32 v24, 0xbfb8aa3b, v24
	v_add_f32_e32 v29, 1.0, v29
	v_rcp_f32_e32 v25, v25
	v_mul_f32_e32 v28, 0xbfb8aa3b, v28
	v_exp_f32_e32 v24, v24
	v_rcp_f32_e32 v29, v29
	v_exp_f32_e32 v28, v28
	v_lshlrev_b32_e32 v41, 16, v224
	v_and_b32_e32 v224, 0xffff0000, v224
	v_mul_f32_e32 v26, v26, v232
	v_mul_f32_e32 v27, v27, v232
	v_add_f32_e32 v24, 1.0, v24
	v_mul_f32_e32 v30, v30, v232
	v_mul_f32_e32 v26, 0xbfb8aa3b, v26
	v_mul_f32_e32 v27, 0xbfb8aa3b, v27
	v_mul_f32_e32 v16, v16, v232
	v_add_f32_e32 v28, 1.0, v28
	v_rcp_f32_e32 v24, v24
	v_mul_f32_e32 v30, 0xbfb8aa3b, v30
	v_exp_f32_e32 v26, v26
	v_exp_f32_e32 v27, v27
	v_mul_f32_e32 v20, v20, v232
	v_mul_f32_e32 v16, 0xbfb8aa3b, v16
	v_mul_f32_e32 v17, v17, v232
	v_rcp_f32_e32 v28, v28
	v_exp_f32_e32 v30, v30
	v_mul_f32_e32 v20, 0xbfb8aa3b, v20
	v_exp_f32_e32 v16, v16
	v_mul_f32_e32 v17, 0xbfb8aa3b, v17
	v_exp_f32_e32 v20, v20
	v_exp_f32_e32 v17, v17
	v_add_f32_e32 v26, 1.0, v26
	v_add_f32_e32 v27, 1.0, v27
	v_rcp_f32_e32 v26, v26
	v_rcp_f32_e32 v27, v27
	v_add_f32_e32 v16, 1.0, v16
	v_add_f32_e32 v20, 1.0, v20
	v_rcp_f32_e32 v16, v16
	v_mul_f32_e32 v21, v21, v232
	v_add_f32_e32 v17, 1.0, v17
	v_rcp_f32_e32 v20, v20
	v_mul_f32_e32 v21, 0xbfb8aa3b, v21
	v_rcp_f32_e32 v17, v17
	v_exp_f32_e32 v21, v21
	v_lshlrev_b32_e32 v44, 16, v225
	v_and_b32_e32 v225, 0xffff0000, v225
	v_mul_f32_e32 v19, v19, v232
	v_mul_f32_e32 v19, 0xbfb8aa3b, v19
	v_exp_f32_e32 v19, v19
	s_waitcnt vmcnt(9)
	v_lshlrev_b32_e32 v45, 16, v228
	v_and_b32_e32 v228, 0xffff0000, v228
	v_mul_f32_e32 v25, v25, v228
	v_fmac_f32_e32 v25, v29, v224
	v_mul_f32_e32 v29, v31, v232
	v_mul_f32_e32 v29, 0xbfb8aa3b, v29
	v_exp_f32_e32 v29, v29
	v_mul_f32_e32 v24, v24, v45
	v_fmac_f32_e32 v24, v28, v41
	v_add_f32_e32 v28, 1.0, v30
	v_add_f32_e32 v29, 1.0, v29
	v_rcp_f32_e32 v28, v28
	v_rcp_f32_e32 v29, v29
	v_lshlrev_b32_e32 v46, 16, v229
	v_and_b32_e32 v229, 0xffff0000, v229
	v_mul_f32_e32 v26, v26, v46
	v_mul_f32_e32 v27, v27, v229
	v_lshlrev_b32_e32 v224, 16, v230
	v_fmac_f32_e32 v26, v28, v44
	v_fmac_f32_e32 v27, v29, v225
	v_lshlrev_b32_e32 v28, 16, v226
	v_and_b32_e32 v225, 0xffff0000, v230
	v_mul_f32_e32 v224, v16, v224
	v_fmac_f32_e32 v224, v20, v28
	v_mul_f32_e32 v20, v17, v225
	v_mul_f32_e32 v17, v18, v232
	v_add_f32_e32 v16, 1.0, v21
	v_mul_f32_e32 v21, v22, v232
	v_mul_f32_e32 v17, 0xbfb8aa3b, v17
	v_mul_f32_e32 v18, v23, v232
	v_mul_f32_e32 v21, 0xbfb8aa3b, v21
	v_exp_f32_e32 v17, v17
	v_mul_f32_e32 v18, 0xbfb8aa3b, v18
	v_rcp_f32_e32 v16, v16
	v_exp_f32_e32 v21, v21
	v_exp_f32_e32 v18, v18
	v_and_b32_e32 v29, 0xffff0000, v226
	v_add_f32_e32 v17, 1.0, v17
	v_add_f32_e32 v19, 1.0, v19
	v_fmac_f32_e32 v20, v16, v29
	v_add_f32_e32 v16, 1.0, v21
	v_rcp_f32_e32 v17, v17
	v_add_f32_e32 v18, 1.0, v18
	v_rcp_f32_e32 v19, v19
	v_rcp_f32_e32 v16, v16
	v_rcp_f32_e32 v18, v18
	v_lshlrev_b32_e32 v30, 16, v227
	v_and_b32_e32 v31, 0xffff0000, v227
	v_lshlrev_b32_e32 v226, 16, v231
	v_and_b32_e32 v227, 0xffff0000, v231
	v_mul_f32_e32 v21, v17, v226
	v_mul_f32_e32 v19, v19, v227
	v_fmac_f32_e32 v21, v16, v30
	v_fmac_f32_e32 v19, v18, v31

; __device__ __forceinline__ uint4 pk8(f32x4 a, f32x4 b) { return make_uint4(cvt_pk_bf16(a[0], a[1]), cvt_pk_bf16(a[2], a[3]), cvt_pk_bf16(b[0], b[1]), cvt_pk_bf16(b[2], b[3])); }
;     __device__ __forceinline__ void operator()(AccRef acc, const Unit& u, int wr, int wc, int fr, int fq) const {
;     ...
;                 *(uint4*)(O + o) = pk8(v[0], v[1]);
	v_cvt_pk_bf16_f32 v16, v24, v25

;     __device__ __forceinline__ void operator()(AccRef acc, const Unit& u, int wr, int wc, int fr, int fq) const {
;     ...
;                 const int r = u.pm * 256 + ai * 128 + wr * 64 + m * 16 + fr;
	v_add_u32_e32 v24, 0xb0, v148

; __device__ __forceinline__ uint4 pk8(f32x4 a, f32x4 b) { return make_uint4(cvt_pk_bf16(a[0], a[1]), cvt_pk_bf16(a[2], a[3]), cvt_pk_bf16(b[0], b[1]), cvt_pk_bf16(b[2], b[3])); }
;     __device__ __forceinline__ void operator()(AccRef acc, const Unit& u, int wr, int wc, int fr, int fq) const {
;     ...
;                 *(uint4*)(O + o) = pk8(v[0], v[1]);
	v_cvt_pk_bf16_f32 v17, v26, v27


; __device__ __forceinline__ uint4 pk8(f32x4 a, f32x4 b) { return make_uint4(cvt_pk_bf16(a[0], a[1]), cvt_pk_bf16(a[2], a[3]), cvt_pk_bf16(b[0], b[1]), cvt_pk_bf16(b[2], b[3])); }
;     __device__ __forceinline__ void operator()(AccRef acc, const Unit& u, int wr, int wc, int fr, int fq) const {
;     ...
;                 *(uint4*)(O + o) = pk8(v[0], v[1]);
	v_cvt_pk_bf16_f32 v18, v224, v20


; __device__ __forceinline__ uint4 pk8(f32x4 a, f32x4 b) { return make_uint4(cvt_pk_bf16(a[0], a[1]), cvt_pk_bf16(a[2], a[3]), cvt_pk_bf16(b[0], b[1]), cvt_pk_bf16(b[2], b[3])); }
;     __device__ __forceinline__ void operator()(AccRef acc, const Unit& u, int wr, int wc, int fr, int fq) const {
;     ...
;                 *(uint4*)(O + o) = pk8(v[0], v[1]);
	v_cvt_pk_bf16_f32 v19, v21, v19

; __device__ __forceinline__ f32x4 unpk4(uint2 u) { f32x4 r; r[0] = __uint_as_float(u.x << 16); r[1] = __uint_as_float(u.x & 0xffff0000u); r[2] = __uint_as_float(u.y << 16); r[3] = __uint_as_float(u.y & 0xffff0000u); return r; }
; __device__ __forceinline__ float sigm(float x) { return __builtin_amdgcn_rcpf(1.f + __expf(-x)); }
; __device__ __forceinline__ uint4 pk8(f32x4 a, f32x4 b) { return make_uint4(cvt_pk_bf16(a[0], a[1]), cvt_pk_bf16(a[2], a[3]), cvt_pk_bf16(b[0], b[1]), cvt_pk_bf16(b[2], b[3])); }
;     __device__ __forceinline__ void operator()(AccRef acc, const Unit& u, int wr, int wc, int fr, int fq) const {
;     ...
;                 const int r = u.pm * 256 + ai * 128 + wr * 64 + m * 16 + fr;
;                 const float s = rinv[r];
;                 const size_t o = (size_t)r * D + c0;
;                 const uint4 pa8 = *(const uint4*)(Pa + o), pb8 = *(const uint4*)(Pb + o);
;                 f32x4 v[2];
; #pragma unroll
;                 for (int n = 0; n < 2; ++n) {
;                     const f32x4 pa = unpk4(n == 0 ? make_uint2(pa8.x, pa8.y) : make_uint2(pa8.z, pa8.w)), pb = unpk4(n == 0 ? make_uint2(pb8.x, pb8.y) : make_uint2(pb8.z, pb8.w));
; #pragma unroll
;                     for (int e = 0; e < 4; ++e) v[n][e] = sigm(acc[ai][0][m][n][e] * s) * pa[e] + sigm(acc[ai][1][m][n][e] * s) * pb[e];
;                 }
;                 *(uint4*)(O + o) = pk8(v[0], v[1]);
	v_lshl_add_u64 v[20:21], s[36:37], 0, v[42:43]
	v_ashrrev_i32_e32 v25, 31, v24
	global_store_dwordx4 v[20:21], v[16:19], off
	s_nop 1
	v_lshlrev_b64 v[16:17], 11, v[24:25]
	v_lshl_add_u64 v[24:25], v[24:25], 2, s[28:29]
	v_lshl_add_u64 v[16:17], v[16:17], 0, v[150:151]
	v_lshlrev_b64 v[26:27], 1, v[16:17]
	v_lshl_add_u64 v[16:17], s[88:89], 0, v[26:27]
	v_lshl_add_u64 v[20:21], s[0:1], 0, v[26:27]
	s_waitcnt vmcnt(7)
	v_mul_f32_e32 v9, v9, v242
	v_mul_f32_e32 v13, v13, v242
	v_mul_f32_e32 v9, 0xbfb8aa3b, v9
	v_mul_f32_e32 v13, 0xbfb8aa3b, v13
	v_exp_f32_e32 v9, v9
	v_exp_f32_e32 v13, v13
	v_mul_f32_e32 v8, v8, v242
	v_mul_f32_e32 v12, v12, v242
	v_add_f32_e32 v9, 1.0, v9
	v_mul_f32_e32 v8, 0xbfb8aa3b, v8
	v_add_f32_e32 v13, 1.0, v13
	v_rcp_f32_e32 v9, v9
	v_mul_f32_e32 v12, 0xbfb8aa3b, v12
	v_exp_f32_e32 v8, v8
	v_rcp_f32_e32 v13, v13
	v_exp_f32_e32 v12, v12
	v_lshlrev_b32_e32 v25, 16, v234
	v_and_b32_e32 v234, 0xffff0000, v234
	v_mul_f32_e32 v10, v10, v242
	v_mul_f32_e32 v11, v11, v242
	v_add_f32_e32 v8, 1.0, v8
	v_mul_f32_e32 v14, v14, v242
	v_mul_f32_e32 v10, 0xbfb8aa3b, v10
	v_mul_f32_e32 v11, 0xbfb8aa3b, v11
	v_mul_f32_e32 v0, v0, v242
	v_add_f32_e32 v12, 1.0, v12
	v_rcp_f32_e32 v8, v8
	v_mul_f32_e32 v14, 0xbfb8aa3b, v14
	v_exp_f32_e32 v10, v10
	v_exp_f32_e32 v11, v11
	v_mul_f32_e32 v4, v4, v242
	v_mul_f32_e32 v0, 0xbfb8aa3b, v0
	v_mul_f32_e32 v1, v1, v242
	v_rcp_f32_e32 v12, v12
	v_exp_f32_e32 v14, v14
	v_mul_f32_e32 v4, 0xbfb8aa3b, v4
	v_exp_f32_e32 v0, v0
	v_mul_f32_e32 v1, 0xbfb8aa3b, v1
	v_exp_f32_e32 v4, v4
	v_exp_f32_e32 v1, v1
	v_add_f32_e32 v10, 1.0, v10
	v_add_f32_e32 v11, 1.0, v11
	v_rcp_f32_e32 v10, v10
	v_rcp_f32_e32 v11, v11
	v_add_f32_e32 v0, 1.0, v0
	v_add_f32_e32 v4, 1.0, v4
	v_rcp_f32_e32 v0, v0
	v_mul_f32_e32 v5, v5, v242
	v_add_f32_e32 v1, 1.0, v1
	v_rcp_f32_e32 v4, v4
	v_mul_f32_e32 v5, 0xbfb8aa3b, v5
	v_rcp_f32_e32 v1, v1
	v_exp_f32_e32 v5, v5
	v_lshlrev_b32_e32 v28, 16, v235
	v_and_b32_e32 v235, 0xffff0000, v235
	v_mul_f32_e32 v3, v3, v242
	v_mul_f32_e32 v3, 0xbfb8aa3b, v3
	v_exp_f32_e32 v3, v3
	s_waitcnt vmcnt(7)
	v_lshlrev_b32_e32 v29, 16, v238
	v_and_b32_e32 v238, 0xffff0000, v238
	v_mul_f32_e32 v9, v9, v238
	v_fmac_f32_e32 v9, v13, v234
	v_mul_f32_e32 v13, v15, v242
	v_mul_f32_e32 v13, 0xbfb8aa3b, v13
	v_exp_f32_e32 v13, v13
	v_mul_f32_e32 v8, v8, v29
	v_fmac_f32_e32 v8, v12, v25
	v_add_f32_e32 v12, 1.0, v14
	v_add_f32_e32 v13, 1.0, v13
	v_rcp_f32_e32 v12, v12
	v_rcp_f32_e32 v13, v13
	v_lshlrev_b32_e32 v30, 16, v239
	v_and_b32_e32 v239, 0xffff0000, v239
	v_mul_f32_e32 v10, v10, v30
	v_mul_f32_e32 v11, v11, v239
	v_lshlrev_b32_e32 v234, 16, v240
	v_fmac_f32_e32 v10, v12, v28
	v_fmac_f32_e32 v11, v13, v235
	v_lshlrev_b32_e32 v12, 16, v236
	v_and_b32_e32 v235, 0xffff0000, v240
	v_mul_f32_e32 v234, v0, v234
	v_fmac_f32_e32 v234, v4, v12
	v_mul_f32_e32 v4, v1, v235
	v_mul_f32_e32 v1, v2, v242
	v_add_f32_e32 v0, 1.0, v5
	v_mul_f32_e32 v5, v6, v242
	v_mul_f32_e32 v1, 0xbfb8aa3b, v1
	v_mul_f32_e32 v2, v7, v242
	v_mul_f32_e32 v5, 0xbfb8aa3b, v5
	v_exp_f32_e32 v1, v1
	v_mul_f32_e32 v2, 0xbfb8aa3b, v2
	v_rcp_f32_e32 v0, v0
	v_exp_f32_e32 v5, v5
	v_exp_f32_e32 v2, v2
	v_and_b32_e32 v13, 0xffff0000, v236
	v_add_f32_e32 v1, 1.0, v1
	v_add_f32_e32 v3, 1.0, v3
	v_fmac_f32_e32 v4, v0, v13
	v_add_f32_e32 v0, 1.0, v5
	v_rcp_f32_e32 v1, v1
	v_add_f32_e32 v2, 1.0, v2
	v_rcp_f32_e32 v3, v3
	v_rcp_f32_e32 v0, v0
	v_rcp_f32_e32 v2, v2
	v_lshlrev_b32_e32 v14, 16, v237
	v_and_b32_e32 v15, 0xffff0000, v237
	v_lshlrev_b32_e32 v236, 16, v241
	v_and_b32_e32 v237, 0xffff0000, v241
	v_mul_f32_e32 v5, v1, v236
	v_mul_f32_e32 v3, v3, v237
	v_fmac_f32_e32 v5, v0, v14
	v_fmac_f32_e32 v3, v2, v15

; __device__ __forceinline__ uint4 pk8(f32x4 a, f32x4 b) { return make_uint4(cvt_pk_bf16(a[0], a[1]), cvt_pk_bf16(a[2], a[3]), cvt_pk_bf16(b[0], b[1]), cvt_pk_bf16(b[2], b[3])); }
;     __device__ __forceinline__ void operator()(AccRef acc, const Unit& u, int wr, int wc, int fr, int fq) const {
;     ...
;                 *(uint4*)(O + o) = pk8(v[0], v[1]);
	v_cvt_pk_bf16_f32 v0, v8, v9


; __device__ __forceinline__ uint4 pk8(f32x4 a, f32x4 b) { return make_uint4(cvt_pk_bf16(a[0], a[1]), cvt_pk_bf16(a[2], a[3]), cvt_pk_bf16(b[0], b[1]), cvt_pk_bf16(b[2], b[3])); }
;     __device__ __forceinline__ void operator()(AccRef acc, const Unit& u, int wr, int wc, int fr, int fq) const {
;     ...
;                 *(uint4*)(O + o) = pk8(v[0], v[1]);
	v_cvt_pk_bf16_f32 v1, v10, v11


; __device__ __forceinline__ uint4 pk8(f32x4 a, f32x4 b) { return make_uint4(cvt_pk_bf16(a[0], a[1]), cvt_pk_bf16(a[2], a[3]), cvt_pk_bf16(b[0], b[1]), cvt_pk_bf16(b[2], b[3])); }
;     __device__ __forceinline__ void operator()(AccRef acc, const Unit& u, int wr, int wc, int fr, int fq) const {
;     ...
;                 *(uint4*)(O + o) = pk8(v[0], v[1]);
	v_cvt_pk_bf16_f32 v2, v234, v4


; __device__ __forceinline__ uint4 pk8(f32x4 a, f32x4 b) { return make_uint4(cvt_pk_bf16(a[0], a[1]), cvt_pk_bf16(a[2], a[3]), cvt_pk_bf16(b[0], b[1]), cvt_pk_bf16(b[2], b[3])); }
;     __device__ __forceinline__ void operator()(AccRef acc, const Unit& u, int wr, int wc, int fr, int fq) const {
;     ...
;                 *(uint4*)(O + o) = pk8(v[0], v[1]);
	v_cvt_pk_bf16_f32 v3, v5, v3

; #define PG8_WAIT_V(n) asm volatile("s_waitcnt vmcnt(" #n ")" ::: "memory")
; #define PG8_BAR __builtin_amdgcn_s_barrier()
; __device__ __forceinline__ uint4 pk8(f32x4 a, f32x4 b) { return make_uint4(cvt_pk_bf16(a[0], a[1]), cvt_pk_bf16(a[2], a[3]), cvt_pk_bf16(b[0], b[1]), cvt_pk_bf16(b[2], b[3])); }
; template <class Epi, class Sched>
; __device__ __forceinline__ void gemm_phase(PG8_LAS unsigned char* lds, const Gemm g, const Sched& S, const Epi& E) {
;     ...
;     PG8_WAIT_V(0);
;     if (wr == 0) PG8_BAR;
;     PG8_BAR;
;     __device__ __forceinline__ void operator()(AccRef acc, const Unit& u, int wr, int wc, int fr, int fq) const {
;     ...
;                 *(uint4*)(O + o) = pk8(v[0], v[1]);
	v_lshl_add_u64 v[4:5], s[36:37], 0, v[26:27]
	global_store_dwordx4 v[4:5], v[0:3], off
	s_cbranch_vccz .LBB0_681
	s_waitcnt vmcnt(0)
	s_cmpk_gt_u32 s3, 0xff
	s_cbranch_scc1 .LBB0_692
	s_barrier

; #define PG8_STAGE(bufoff, gbase, voff) do { _Pragma("unroll") for (int _i = 0; _i < 2; ++_i) \
;         __builtin_amdgcn_global_load_lds((const unsigned*)((const char*)(gbase) + (voff)[_i]), (PG8_LAS unsigned*)(lds + (bufoff) + ldsw + _i * 8192), 16, 0, 0); } while (0)
; #define PG8_LDA(dst, b, h) do { _Pragma("unroll") for (int m = 0; m < 4; ++m) _Pragma("unroll") for (int k = 0; k < 2; ++k) dst[m][k] = *(const PG8_LAS bf16x8*)(lds + PG8_SA(b, h) + aoff + m * 2048 + k * 1024); } while (0)
; #define PG8_LDB(dst, b, h) do { _Pragma("unroll") for (int n = 0; n < 2; ++n) _Pragma("unroll") for (int k = 0; k < 2; ++k) dst[n][k] = *(const PG8_LAS bf16x8*)(lds + PG8_SB(b, h) + boff + n * 2048 + k * 1024); } while (0)
; #define PG8_MMA(ai, bj, At, Bt) do { __builtin_amdgcn_s_setprio(1); _Pragma("unroll") for (int m = 0; m < 4; ++m) _Pragma("unroll") for (int n = 0; n < 2; ++n) _Pragma("unroll") for (int k = 0; k < 2; ++k) \
;         acc[ai][bj][m][n] = __builtin_amdgcn_mfma_f32_16x16x32_bf16(Bt[n][k], At[m][k], acc[ai][bj][m][n], 0, 0, 0); __builtin_amdgcn_s_setprio(0); } while (0)
; #define PG8_WAIT_L(n) asm volatile("s_waitcnt lgkmcnt(" #n ")" ::: "memory")
; #define PG8_BAR __builtin_amdgcn_s_barrier()
; #define PG8_SCHED __builtin_amdgcn_sched_barrier(0)
; template <class Epi, class Sched>
; __device__ __forceinline__ void gemm_phase(PG8_LAS unsigned char* lds, const Gemm g, const Sched& S, const Epi& E) {
;     ...
;             const bool last = (t == nt - 2);
;             const char* a1 = cA + (size_t)(t + 1) * kstep;
;             const char* a2 = last ? nA : cA + (size_t)(t + 2) * kstep; const char* b2 = last ? nB : cB + (size_t)(t + 2) * kstep;
;             const char* a3 = a2 + kstep; const char* b3 = b2 + kstep;
;             if (last && has_next) S.a_ready(nxt);
;             PG8_LDB(B0, 0, 0); PG8_SCHED; PG8_LDA(At, 0, 0); PG8_STAGE(PG8_SA(1, 1), a1 + hstep, voffA);
;             PG8_WAIT_L(8); PG8_BAR; PG8_WAIT_L(0); PG8_MMA(0, 0, At, B0); PG8_BAR; PG8_SCHED;
;             PG8_LDB(B1, 0, 1); PG8_STAGE(PG8_SB(0, 0), b2, voffB);
;             PG8_BAR; PG8_WAIT_L(0); PG8_MMA(0, 1, At, B1); PG8_BAR;
;             PG8_LDA(At, 0, 1); PG8_STAGE(PG8_SA(0, 0), a2, voffA);
;             PG8_BAR; PG8_WAIT_L(0); PG8_MMA(1, 0, At, B0); PG8_BAR; PG8_SCHED;
.LBB0_766:
	ds_read_b128 v[150:153], v157
	ds_read_b128 v[160:163], v157 offset:1024
	ds_read_b128 v[164:167], v157 offset:2048
	ds_read_b128 v[168:171], v157 offset:3072
	s_add_u32 s20, s18, 0xfff80080
	s_addc_u32 s21, s19, -1
	s_cmp_eq_u32 s58, 28
	s_cselect_b32 s23, s9, s21
	s_cselect_b32 s22, s15, s20
	s_cselect_b32 s21, s7, s57
	s_cselect_b32 s20, s17, s56
	v_lshl_add_u64 v[154:155], s[18:19], 0, v[138:139]
	s_add_i32 m0, s27, 0xc000
	ds_read_b128 v[172:175], v158
	ds_read_b128 v[176:179], v158 offset:1024
	ds_read_b128 v[180:183], v158 offset:2048
	ds_read_b128 v[184:187], v158 offset:3072
	ds_read_b128 v[188:191], v158 offset:4096
	ds_read_b128 v[192:195], v158 offset:5120
	ds_read_b128 v[196:199], v158 offset:6144
	ds_read_b128 v[200:203], v158 offset:7168
	global_load_lds_dwordx4 v[154:155], off
	v_lshl_add_u64 v[154:155], s[18:19], 0, v[140:141]
	s_add_i32 m0, s27, 0xe000
	s_nop 0
	global_load_lds_dwordx4 v[154:155], off
	s_waitcnt lgkmcnt(8)
	s_barrier
	s_waitcnt lgkmcnt(0)
	s_waitcnt lgkmcnt(0)
	v_mfma_f32_16x16x32_bf16 v[124:127], v[150:153], v[172:175], v[124:127]
	v_mfma_f32_16x16x32_bf16 v[120:123], v[164:167], v[172:175], v[120:123]
	v_mfma_f32_16x16x32_bf16 v[108:111], v[150:153], v[180:183], v[108:111]
	v_mfma_f32_16x16x32_bf16 v[104:107], v[164:167], v[180:183], v[104:107]
	v_mfma_f32_16x16x32_bf16 v[92:95], v[150:153], v[188:191], v[92:95]
	v_mfma_f32_16x16x32_bf16 v[88:91], v[164:167], v[188:191], v[88:91]
	v_mfma_f32_16x16x32_bf16 v[76:79], v[150:153], v[196:199], v[76:79]
	v_mfma_f32_16x16x32_bf16 v[72:75], v[164:167], v[196:199], v[72:75]
	v_mfma_f32_16x16x32_bf16 v[124:127], v[160:163], v[176:179], v[124:127]
	v_mfma_f32_16x16x32_bf16 v[120:123], v[168:171], v[176:179], v[120:123]
	v_mfma_f32_16x16x32_bf16 v[108:111], v[160:163], v[184:187], v[108:111]
	v_mfma_f32_16x16x32_bf16 v[104:107], v[168:171], v[184:187], v[104:107]
	v_mfma_f32_16x16x32_bf16 v[92:95], v[160:163], v[192:195], v[92:95]
	v_mfma_f32_16x16x32_bf16 v[88:91], v[168:171], v[192:195], v[88:91]
	v_mfma_f32_16x16x32_bf16 v[76:79], v[160:163], v[200:203], v[76:79]
	v_mfma_f32_16x16x32_bf16 v[72:75], v[168:171], v[200:203], v[72:75]
	s_barrier
	s_add_i32 s30, s49, s26
	v_lshl_add_u64 v[154:155], s[20:21], 0, v[130:131]
	s_mov_b32 m0, s30
	ds_read_b128 v[204:207], v159
	ds_read_b128 v[208:211], v159 offset:1024
	ds_read_b128 v[212:215], v159 offset:2048
	ds_read_b128 v[216:219], v159 offset:3072
	global_load_lds_dwordx4 v[154:155], off
	v_lshl_add_u64 v[220:221], s[20:21], 0, v[134:135]
	s_add_i32 m0, s30, 0x2000
	s_nop 0
	global_load_lds_dwordx4 v[220:221], off
	s_barrier
	s_waitcnt lgkmcnt(0)
	s_waitcnt lgkmcnt(0)
	v_mfma_f32_16x16x32_bf16 v[116:119], v[204:207], v[172:175], v[116:119]
	v_mfma_f32_16x16x32_bf16 v[112:115], v[212:215], v[172:175], v[112:115]
	v_mfma_f32_16x16x32_bf16 v[100:103], v[204:207], v[180:183], v[100:103]
	v_mfma_f32_16x16x32_bf16 v[96:99], v[212:215], v[180:183], v[96:99]
	v_mfma_f32_16x16x32_bf16 v[84:87], v[204:207], v[188:191], v[84:87]
	v_mfma_f32_16x16x32_bf16 v[80:83], v[212:215], v[188:191], v[80:83]
	v_mfma_f32_16x16x32_bf16 v[68:71], v[204:207], v[196:199], v[68:71]
	v_mfma_f32_16x16x32_bf16 v[64:67], v[212:215], v[196:199], v[64:67]
	v_mfma_f32_16x16x32_bf16 v[116:119], v[208:211], v[176:179], v[116:119]
	v_mfma_f32_16x16x32_bf16 v[112:115], v[216:219], v[176:179], v[112:115]
	v_mfma_f32_16x16x32_bf16 v[100:103], v[208:211], v[184:187], v[100:103]
	v_mfma_f32_16x16x32_bf16 v[96:99], v[216:219], v[184:187], v[96:99]
	v_mfma_f32_16x16x32_bf16 v[84:87], v[208:211], v[192:195], v[84:87]
	v_mfma_f32_16x16x32_bf16 v[80:83], v[216:219], v[192:195], v[80:83]
	v_mfma_f32_16x16x32_bf16 v[68:71], v[208:211], v[200:203], v[68:71]
	v_mfma_f32_16x16x32_bf16 v[64:67], v[216:219], v[200:203], v[64:67]
	s_mov_b32 m0, s27
	v_lshl_add_u64 v[222:223], s[22:23], 0, v[128:129]
	s_barrier
	ds_read_b128 v[172:175], v158 offset:16384
	ds_read_b128 v[176:179], v158 offset:17408
	ds_read_b128 v[180:183], v158 offset:18432
	ds_read_b128 v[184:187], v158 offset:19456
	ds_read_b128 v[188:191], v158 offset:20480
	ds_read_b128 v[192:195], v158 offset:21504
	ds_read_b128 v[196:199], v158 offset:22528
	ds_read_b128 v[200:203], v158 offset:23552
	global_load_lds_dwordx4 v[222:223], off
	v_lshl_add_u64 v[224:225], s[22:23], 0, v[132:133]
	s_mov_b32 m0, s28
	s_nop 0
	global_load_lds_dwordx4 v[224:225], off
	s_barrier
	s_waitcnt lgkmcnt(0)
	s_waitcnt lgkmcnt(0)
	v_mfma_f32_16x16x32_bf16 v[60:63], v[150:153], v[172:175], v[60:63]
	v_mfma_f32_16x16x32_bf16 v[56:59], v[164:167], v[172:175], v[56:59]
	v_mfma_f32_16x16x32_bf16 v[44:47], v[150:153], v[180:183], v[44:47]
	v_mfma_f32_16x16x32_bf16 v[40:43], v[164:167], v[180:183], v[40:43]
	v_mfma_f32_16x16x32_bf16 v[28:31], v[150:153], v[188:191], v[28:31]
	v_mfma_f32_16x16x32_bf16 v[24:27], v[164:167], v[188:191], v[24:27]
	v_mfma_f32_16x16x32_bf16 v[12:15], v[150:153], v[196:199], v[12:15]
	v_mfma_f32_16x16x32_bf16 v[8:11], v[164:167], v[196:199], v[8:11]
	v_mfma_f32_16x16x32_bf16 v[60:63], v[160:163], v[176:179], v[60:63]
	v_mfma_f32_16x16x32_bf16 v[56:59], v[168:171], v[176:179], v[56:59]
	v_mfma_f32_16x16x32_bf16 v[44:47], v[160:163], v[184:187], v[44:47]
	v_mfma_f32_16x16x32_bf16 v[40:43], v[168:171], v[184:187], v[40:43]
	v_mfma_f32_16x16x32_bf16 v[28:31], v[160:163], v[192:195], v[28:31]
	v_mfma_f32_16x16x32_bf16 v[24:27], v[168:171], v[192:195], v[24:27]
	v_mfma_f32_16x16x32_bf16 v[12:15], v[160:163], v[200:203], v[12:15]
	v_mfma_f32_16x16x32_bf16 v[8:11], v[168:171], v[200:203], v[8:11]
	s_barrier
; #define PG8_STAGE(bufoff, gbase, voff) do { _Pragma("unroll") for (int _i = 0; _i < 2; ++_i) \
;         __builtin_amdgcn_global_load_lds((const unsigned*)((const char*)(gbase) + (voff)[_i]), (PG8_LAS unsigned*)(lds + (bufoff) + ldsw + _i * 8192), 16, 0, 0); } while (0)
; #define PG8_LDA(dst, b, h) do { _Pragma("unroll") for (int m = 0; m < 4; ++m) _Pragma("unroll") for (int k = 0; k < 2; ++k) dst[m][k] = *(const PG8_LAS bf16x8*)(lds + PG8_SA(b, h) + aoff + m * 2048 + k * 1024); } while (0)
; #define PG8_LDB(dst, b, h) do { _Pragma("unroll") for (int n = 0; n < 2; ++n) _Pragma("unroll") for (int k = 0; k < 2; ++k) dst[n][k] = *(const PG8_LAS bf16x8*)(lds + PG8_SB(b, h) + boff + n * 2048 + k * 1024); } while (0)
; #define PG8_MMA(ai, bj, At, Bt) do { __builtin_amdgcn_s_setprio(1); _Pragma("unroll") for (int m = 0; m < 4; ++m) _Pragma("unroll") for (int n = 0; n < 2; ++n) _Pragma("unroll") for (int k = 0; k < 2; ++k) \
;         acc[ai][bj][m][n] = __builtin_amdgcn_mfma_f32_16x16x32_bf16(Bt[n][k], At[m][k], acc[ai][bj][m][n], 0, 0, 0); __builtin_amdgcn_s_setprio(0); } while (0)
; #define PG8_WAIT_V(n) asm volatile("s_waitcnt vmcnt(" #n ")" ::: "memory")
; #define PG8_WAIT_L(n) asm volatile("s_waitcnt lgkmcnt(" #n ")" ::: "memory")
; #define PG8_BAR __builtin_amdgcn_s_barrier()
; #define PG8_SCHED __builtin_amdgcn_sched_barrier(0)
; template <class Epi, class Sched>
; __device__ __forceinline__ void gemm_phase(PG8_LAS unsigned char* lds, const Gemm g, const Sched& S, const Epi& E) {
;     ...
;             PG8_STAGE(PG8_SB(0, 1), b2 + hstep, voffB);
;             PG8_WAIT_V(6); PG8_BAR; PG8_MMA(1, 1, At, B1); PG8_BAR;
;             PG8_LDB(B0, 1, 0); PG8_SCHED; PG8_LDA(At, 1, 0); PG8_STAGE(PG8_SA(0, 1), a2 + hstep, voffA);
;             PG8_WAIT_L(8); PG8_BAR; PG8_WAIT_L(0); PG8_MMA(0, 0, At, B0); PG8_BAR; PG8_SCHED;
;             PG8_LDB(B1, 1, 1); PG8_STAGE(PG8_SB(1, 0), b3, voffB);
;             PG8_BAR; PG8_WAIT_L(0); PG8_MMA(0, 1, At, B1); PG8_BAR;
;             PG8_LDA(At, 1, 1); PG8_STAGE(PG8_SA(1, 0), a3, voffA);
	s_add_u32 s30, s20, 0x80000
	s_addc_u32 s31, s21, 0
	s_add_i32 s38, s50, s26
	v_lshl_add_u64 v[150:151], s[30:31], 0, v[130:131]
	s_mov_b32 m0, s38
	s_nop 0
	global_load_lds_dwordx4 v[150:151], off
	v_lshl_add_u64 v[150:151], s[30:31], 0, v[134:135]
	s_add_i32 m0, s38, 0x2000
	s_nop 0
	global_load_lds_dwordx4 v[150:151], off
	s_waitcnt vmcnt(6)
	s_barrier
	v_mfma_f32_16x16x32_bf16 v[52:55], v[204:207], v[172:175], v[52:55]
	v_mfma_f32_16x16x32_bf16 v[48:51], v[212:215], v[172:175], v[48:51]
	v_mfma_f32_16x16x32_bf16 v[36:39], v[204:207], v[180:183], v[36:39]
	v_mfma_f32_16x16x32_bf16 v[32:35], v[212:215], v[180:183], v[32:35]
	v_mfma_f32_16x16x32_bf16 v[20:23], v[204:207], v[188:191], v[20:23]
	v_mfma_f32_16x16x32_bf16 v[16:19], v[212:215], v[188:191], v[16:19]
	v_mfma_f32_16x16x32_bf16 v[4:7], v[204:207], v[196:199], v[4:7]
	v_mfma_f32_16x16x32_bf16 v[0:3], v[212:215], v[196:199], v[0:3]
	v_mfma_f32_16x16x32_bf16 v[52:55], v[208:211], v[176:179], v[52:55]
	v_mfma_f32_16x16x32_bf16 v[48:51], v[216:219], v[176:179], v[48:51]
	v_mfma_f32_16x16x32_bf16 v[36:39], v[208:211], v[184:187], v[36:39]
	v_mfma_f32_16x16x32_bf16 v[32:35], v[216:219], v[184:187], v[32:35]
	v_mfma_f32_16x16x32_bf16 v[20:23], v[208:211], v[192:195], v[20:23]
	v_mfma_f32_16x16x32_bf16 v[16:19], v[216:219], v[192:195], v[16:19]
	v_mfma_f32_16x16x32_bf16 v[4:7], v[208:211], v[200:203], v[4:7]
	v_mfma_f32_16x16x32_bf16 v[0:3], v[216:219], v[200:203], v[0:3]
	s_add_i32 s30, 0, 0x18000
	v_add_u32_e32 v136, s30, v147
	s_barrier
	ds_read_b128 v[150:153], v136
	ds_read_b128 v[160:163], v136 offset:1024
	ds_read_b128 v[164:167], v136 offset:2048
	ds_read_b128 v[168:171], v136 offset:3072
	s_add_u32 s22, s22, 0x80000
	s_addc_u32 s23, s23, 0
	s_mov_b32 m0, s29
	v_lshl_add_u64 v[204:205], s[22:23], 0, v[128:129]
	ds_read_b128 v[172:175], v158 offset:32768
	ds_read_b128 v[176:179], v158 offset:33792
	ds_read_b128 v[180:183], v158 offset:34816
	ds_read_b128 v[184:187], v158 offset:35840
	ds_read_b128 v[188:191], v158 offset:36864
	ds_read_b128 v[192:195], v158 offset:37888
	ds_read_b128 v[196:199], v158 offset:38912
	ds_read_b128 v[200:203], v158 offset:39936
	global_load_lds_dwordx4 v[204:205], off
	v_lshl_add_u64 v[204:205], s[22:23], 0, v[132:133]
	s_mov_b32 m0, s42
	s_nop 0
	global_load_lds_dwordx4 v[204:205], off
	s_waitcnt lgkmcnt(8)
	s_barrier
	s_waitcnt lgkmcnt(0)
	s_waitcnt lgkmcnt(0)
	v_mfma_f32_16x16x32_bf16 v[124:127], v[150:153], v[172:175], v[124:127]
	v_mfma_f32_16x16x32_bf16 v[120:123], v[164:167], v[172:175], v[120:123]
	v_mfma_f32_16x16x32_bf16 v[108:111], v[150:153], v[180:183], v[108:111]
	v_mfma_f32_16x16x32_bf16 v[104:107], v[164:167], v[180:183], v[104:107]
	v_mfma_f32_16x16x32_bf16 v[92:95], v[150:153], v[188:191], v[92:95]
	v_mfma_f32_16x16x32_bf16 v[88:91], v[164:167], v[188:191], v[88:91]
	v_mfma_f32_16x16x32_bf16 v[76:79], v[150:153], v[196:199], v[76:79]
	v_mfma_f32_16x16x32_bf16 v[72:75], v[164:167], v[196:199], v[72:75]
	v_mfma_f32_16x16x32_bf16 v[124:127], v[160:163], v[176:179], v[124:127]
	v_mfma_f32_16x16x32_bf16 v[120:123], v[168:171], v[176:179], v[120:123]
	v_mfma_f32_16x16x32_bf16 v[108:111], v[160:163], v[184:187], v[108:111]
	v_mfma_f32_16x16x32_bf16 v[104:107], v[168:171], v[184:187], v[104:107]
	v_mfma_f32_16x16x32_bf16 v[92:95], v[160:163], v[192:195], v[92:95]
	v_mfma_f32_16x16x32_bf16 v[88:91], v[168:171], v[192:195], v[88:91]
	v_mfma_f32_16x16x32_bf16 v[76:79], v[160:163], v[200:203], v[76:79]
	v_mfma_f32_16x16x32_bf16 v[72:75], v[168:171], v[200:203], v[72:75]
	s_barrier
	s_add_i32 s22, 0, 0x1c000
	s_add_i32 s23, s30, s26
	v_add_u32_e32 v136, s22, v147
	v_lshl_add_u64 v[154:155], v[154:155], 0, s[0:1]
	s_mov_b32 m0, s23
	ds_read_b128 v[204:207], v136
	ds_read_b128 v[208:211], v136 offset:1024
	ds_read_b128 v[212:215], v136 offset:2048
	ds_read_b128 v[216:219], v136 offset:3072
	global_load_lds_dwordx4 v[154:155], off
	v_lshl_add_u64 v[154:155], v[220:221], 0, s[0:1]
	s_add_i32 m0, s23, 0x2000
	s_nop 0
	global_load_lds_dwordx4 v[154:155], off
	s_barrier
	s_waitcnt lgkmcnt(0)
	s_waitcnt lgkmcnt(0)
	v_mfma_f32_16x16x32_bf16 v[116:119], v[204:207], v[172:175], v[116:119]
	v_mfma_f32_16x16x32_bf16 v[112:115], v[212:215], v[172:175], v[112:115]
	v_mfma_f32_16x16x32_bf16 v[100:103], v[204:207], v[180:183], v[100:103]
	v_mfma_f32_16x16x32_bf16 v[96:99], v[212:215], v[180:183], v[96:99]
	v_mfma_f32_16x16x32_bf16 v[84:87], v[204:207], v[188:191], v[84:87]
	v_mfma_f32_16x16x32_bf16 v[80:83], v[212:215], v[188:191], v[80:83]
	v_mfma_f32_16x16x32_bf16 v[68:71], v[204:207], v[196:199], v[68:71]
	v_mfma_f32_16x16x32_bf16 v[64:67], v[212:215], v[196:199], v[64:67]
	v_mfma_f32_16x16x32_bf16 v[116:119], v[208:211], v[176:179], v[116:119]
	v_mfma_f32_16x16x32_bf16 v[112:115], v[216:219], v[176:179], v[112:115]
	v_mfma_f32_16x16x32_bf16 v[100:103], v[208:211], v[184:187], v[100:103]
	v_mfma_f32_16x16x32_bf16 v[96:99], v[216:219], v[184:187], v[96:99]
	v_mfma_f32_16x16x32_bf16 v[84:87], v[208:211], v[192:195], v[84:87]
	v_mfma_f32_16x16x32_bf16 v[80:83], v[216:219], v[192:195], v[80:83]
	v_mfma_f32_16x16x32_bf16 v[68:71], v[208:211], v[200:203], v[68:71]
	v_mfma_f32_16x16x32_bf16 v[64:67], v[216:219], v[200:203], v[64:67]
	s_mov_b32 m0, s44
	v_lshl_add_u64 v[154:155], v[222:223], 0, s[0:1]
	s_barrier
	ds_read_b128 v[172:175], v158 offset:49152
	ds_read_b128 v[176:179], v158 offset:50176
	ds_read_b128 v[180:183], v158 offset:51200
	ds_read_b128 v[184:187], v158 offset:52224
	ds_read_b128 v[188:191], v158 offset:53248
	ds_read_b128 v[192:195], v158 offset:54272
	ds_read_b128 v[196:199], v158 offset:55296
	ds_read_b128 v[200:203], v158 offset:56320
	global_load_lds_dwordx4 v[154:155], off
	v_lshl_add_u64 v[154:155], v[224:225], 0, s[0:1]
	s_mov_b32 m0, s45
	s_nop 0
	global_load_lds_dwordx4 v[154:155], off
	s_barrier
; #define PG8_STAGE(bufoff, gbase, voff) do { _Pragma("unroll") for (int _i = 0; _i < 2; ++_i) \
;         __builtin_amdgcn_global_load_lds((const unsigned*)((const char*)(gbase) + (voff)[_i]), (PG8_LAS unsigned*)(lds + (bufoff) + ldsw + _i * 8192), 16, 0, 0); } while (0)
; #define PG8_MMA(ai, bj, At, Bt) do { __builtin_amdgcn_s_setprio(1); _Pragma("unroll") for (int m = 0; m < 4; ++m) _Pragma("unroll") for (int n = 0; n < 2; ++n) _Pragma("unroll") for (int k = 0; k < 2; ++k) \
;         acc[ai][bj][m][n] = __builtin_amdgcn_mfma_f32_16x16x32_bf16(Bt[n][k], At[m][k], acc[ai][bj][m][n], 0, 0, 0); __builtin_amdgcn_s_setprio(0); } while (0)
; #define PG8_WAIT_V(n) asm volatile("s_waitcnt vmcnt(" #n ")" ::: "memory")
; #define PG8_WAIT_L(n) asm volatile("s_waitcnt lgkmcnt(" #n ")" ::: "memory")
; #define PG8_BAR __builtin_amdgcn_s_barrier()
; #define PG8_SCHED __builtin_amdgcn_sched_barrier(0)
; template <class Epi, class Sched>
; __device__ __forceinline__ void gemm_phase(PG8_LAS unsigned char* lds, const Gemm g, const Sched& S, const Epi& E) {
;     ...
;             PG8_BAR; PG8_WAIT_L(0); PG8_MMA(1, 0, At, B0); PG8_BAR; PG8_SCHED;
;             PG8_STAGE(PG8_SB(1, 1), b3 + hstep, voffB);
;             PG8_WAIT_V(6); PG8_BAR; PG8_MMA(1, 1, At, B1); PG8_BAR;
;     __device__ __forceinline__ void operator()(AccRef acc, const Unit& u, int wr, int wc, int fr, int fq) const {
;         const int c0 = u.pn * 256 + wc * 32 + 8 * fq;
; #pragma unroll
;         for (int ai = 0; ai < 2; ++ai)
; #pragma unroll
;             for (int m = 0; m < 4; ++m) {
;                 const int r = u.pm * 256 + ai * 128 + wr * 64 + m * 16 + fr;
;                 const float* xrow = r < TP ? xp + (size_t)r * D : xs + (size_t)(r - TP) * D;
;                 float ss = 0.f;
; #pragma unroll
;                 for (int bj = 0; bj < 2; ++bj) {
;                     const int c = c0 + bj * 128;
;                     const f32x4 v0 = *(const f32x4*)(xrow + c) + acc[ai][bj][m][0], v1 = *(const f32x4*)(xrow + c + 4) + acc[ai][bj][m][1];
;                     ss += v0[0] * v0[0] + v0[1] * v0[1] + v0[2] * v0[2] + v0[3] * v0[3] + v1[0] * v1[0] + v1[1] * v1[1] + v1[2] * v1[2] + v1[3] * v1[3];
;                     *(uint4*)(Hb + (size_t)r * D + c) = pk8(v0, v1);
	s_waitcnt lgkmcnt(0)
	s_waitcnt lgkmcnt(0)
	v_mfma_f32_16x16x32_bf16 v[60:63], v[150:153], v[172:175], v[60:63]
	v_mfma_f32_16x16x32_bf16 v[56:59], v[164:167], v[172:175], v[56:59]
	v_mfma_f32_16x16x32_bf16 v[44:47], v[150:153], v[180:183], v[44:47]
	v_mfma_f32_16x16x32_bf16 v[40:43], v[164:167], v[180:183], v[40:43]
	v_mfma_f32_16x16x32_bf16 v[28:31], v[150:153], v[188:191], v[28:31]
	v_mfma_f32_16x16x32_bf16 v[24:27], v[164:167], v[188:191], v[24:27]
	v_mfma_f32_16x16x32_bf16 v[12:15], v[150:153], v[196:199], v[12:15]
	v_mfma_f32_16x16x32_bf16 v[8:11], v[164:167], v[196:199], v[8:11]
	v_mfma_f32_16x16x32_bf16 v[60:63], v[160:163], v[176:179], v[60:63]
	v_mfma_f32_16x16x32_bf16 v[56:59], v[168:171], v[176:179], v[56:59]
	v_mfma_f32_16x16x32_bf16 v[44:47], v[160:163], v[184:187], v[44:47]
	v_mfma_f32_16x16x32_bf16 v[40:43], v[168:171], v[184:187], v[40:43]
	v_mfma_f32_16x16x32_bf16 v[28:31], v[160:163], v[192:195], v[28:31]
	v_mfma_f32_16x16x32_bf16 v[24:27], v[168:171], v[192:195], v[24:27]
	v_mfma_f32_16x16x32_bf16 v[12:15], v[160:163], v[200:203], v[12:15]
	v_mfma_f32_16x16x32_bf16 v[8:11], v[168:171], v[200:203], v[8:11]
	s_barrier
	s_add_u32 s20, s20, 0x80080
	s_addc_u32 s21, s21, 0
	s_add_i32 s22, s22, s26
	v_lshl_add_u64 v[150:151], s[20:21], 0, v[130:131]
	s_mov_b32 m0, s22
	s_nop 0
	global_load_lds_dwordx4 v[150:151], off
	v_lshl_add_u64 v[150:151], s[20:21], 0, v[134:135]
	s_add_i32 m0, s22, 0x2000
	s_nop 0
	global_load_lds_dwordx4 v[150:151], off
	s_waitcnt vmcnt(6)
	s_barrier
	v_mfma_f32_16x16x32_bf16 v[52:55], v[204:207], v[172:175], v[52:55]
	v_mfma_f32_16x16x32_bf16 v[48:51], v[212:215], v[172:175], v[48:51]
	v_mfma_f32_16x16x32_bf16 v[36:39], v[204:207], v[180:183], v[36:39]
	v_mfma_f32_16x16x32_bf16 v[32:35], v[212:215], v[180:183], v[32:35]
	v_mfma_f32_16x16x32_bf16 v[20:23], v[204:207], v[188:191], v[20:23]
	v_mfma_f32_16x16x32_bf16 v[16:19], v[212:215], v[188:191], v[16:19]
	v_mfma_f32_16x16x32_bf16 v[4:7], v[204:207], v[196:199], v[4:7]
	v_mfma_f32_16x16x32_bf16 v[0:3], v[212:215], v[196:199], v[0:3]
	v_mfma_f32_16x16x32_bf16 v[52:55], v[208:211], v[176:179], v[52:55]
	v_mfma_f32_16x16x32_bf16 v[48:51], v[216:219], v[176:179], v[48:51]
	v_mfma_f32_16x16x32_bf16 v[36:39], v[208:211], v[184:187], v[36:39]
	v_mfma_f32_16x16x32_bf16 v[32:35], v[216:219], v[184:187], v[32:35]
	v_mfma_f32_16x16x32_bf16 v[20:23], v[208:211], v[192:195], v[20:23]
	v_mfma_f32_16x16x32_bf16 v[16:19], v[216:219], v[192:195], v[16:19]
	v_mfma_f32_16x16x32_bf16 v[4:7], v[208:211], v[200:203], v[4:7]
	v_mfma_f32_16x16x32_bf16 v[0:3], v[216:219], v[200:203], v[0:3]
	s_add_i32 s58, s58, 2
	s_add_u32 s18, s18, 0x100
	s_addc_u32 s19, s19, 0
	s_add_u32 s56, s56, 0x100
	s_addc_u32 s57, s57, 0
	s_cmp_gt_u32 s58, 29
	s_barrier
	s_cbranch_scc0 .LBB0_766
	v_lshl_add_u32 v152, s16, 8, v145
	v_cmp_lt_i32_e32 vcc, s51, v152
	s_and_saveexec_b64 s[16:17], vcc
	s_xor_b64 s[16:17], exec, s[16:17]
	v_add_u32_e32 v136, 0xffffc000, v152
	v_lshlrev_b64 v[150:151], 13, v[136:137]
	v_lshl_add_u64 v[154:155], s[54:55], 0, v[150:151]
	v_mov_b32_e32 v153, v137
	s_andn2_saveexec_b64 s[16:17], s[16:17]
	v_ashrrev_i32_e32 v153, 31, v152
	v_lshlrev_b64 v[150:151], 13, v[152:153]
	v_lshl_add_u64 v[154:155], s[52:53], 0, v[150:151]
	s_or_b64 exec, exec, s[16:17]
	v_lshl_or_b32 v150, s14, 8, v156
	v_ashrrev_i32_e32 v151, 31, v150
	v_lshl_add_u64 v[154:155], v[150:151], 2, v[154:155]
	global_load_dwordx4 v[160:163], v[154:155], off
	global_load_dwordx4 v[164:167], v[154:155], off offset:16
	v_lshlrev_b64 v[168:169], 12, v[152:153]
	v_lshl_add_u64 v[168:169], s[34:35], 0, v[168:169]
	v_lshl_add_u64 v[168:169], v[150:151], 1, v[168:169]
	v_mov_b32_e32 v238, 0x20000
	v_mov_b32_e32 v239, 0
	v_mov_b32_e32 v240, 0xa0000
	v_mov_b32_e32 v241, 0
	v_lshl_add_u64 v[236:237], v[154:155], 0, 0
	global_load_dwordx4 v[170:173], v[236:237], off offset:512
	global_load_dwordx4 v[174:177], v[236:237], off offset:528
	v_lshl_add_u64 v[236:237], v[236:237], 0, v[238:239]
	global_load_dwordx4 v[178:181], v[236:237], off
	global_load_dwordx4 v[182:185], v[236:237], off offset:16
	global_load_dwordx4 v[186:189], v[236:237], off offset:512
	global_load_dwordx4 v[190:193], v[236:237], off offset:528
	v_lshl_add_u64 v[236:237], v[236:237], 0, v[238:239]
	global_load_dwordx4 v[194:197], v[236:237], off
	global_load_dwordx4 v[198:201], v[236:237], off offset:16
	global_load_dwordx4 v[202:205], v[236:237], off offset:512
	global_load_dwordx4 v[206:209], v[236:237], off offset:528
	v_lshl_add_u64 v[236:237], v[236:237], 0, v[238:239]
	global_load_dwordx4 v[210:213], v[236:237], off
	global_load_dwordx4 v[214:217], v[236:237], off offset:16
	global_load_dwordx4 v[218:221], v[236:237], off offset:512
	global_load_dwordx4 v[222:225], v[236:237], off offset:528
	s_waitcnt vmcnt(14)
	v_pk_add_f32 v[124:125], v[124:125], v[160:161]
	v_pk_add_f32 v[160:161], v[122:123], v[166:167]
	v_pk_add_f32 v[122:123], v[120:121], v[164:165]
	v_pk_add_f32 v[126:127], v[126:127], v[162:163]
	v_cvt_pk_bf16_f32 v120, v124, v125
	s_nop 0
	v_cvt_pk_bf16_f32 v121, v126, v127
	v_cvt_pk_bf16_f32 v122, v122, v123
	v_cvt_pk_bf16_f32 v123, v160, v161
	global_store_dwordx4 v[168:169], v[120:123], off
	s_nop 0
	v_or_b32_e32 v120, 16, v152
	v_cmp_lt_i32_e32 vcc, s51, v120
	v_lshl_add_u64 v[236:237], v[236:237], 0, v[240:241]
	global_load_dwordx4 v[226:229], v[236:237], off
	global_load_dwordx4 v[230:233], v[236:237], off offset:16
	s_waitcnt vmcnt(15)
; __device__ __forceinline__ uint4 pk8(f32x4 a, f32x4 b) { return make_uint4(cvt_pk_bf16(a[0], a[1]), cvt_pk_bf16(a[2], a[3]), cvt_pk_bf16(b[0], b[1]), cvt_pk_bf16(b[2], b[3])); }
;     __device__ __forceinline__ void operator()(AccRef acc, const Unit& u, int wr, int wc, int fr, int fq) const {
;     ...
;         for (int ai = 0; ai < 2; ++ai)
; #pragma unroll
;             for (int m = 0; m < 4; ++m) {
;                 const int r = u.pm * 256 + ai * 128 + wr * 64 + m * 16 + fr;
;                 const float* xrow = r < TP ? xp + (size_t)r * D : xs + (size_t)(r - TP) * D;
;                 float ss = 0.f;
; #pragma unroll
;                 for (int bj = 0; bj < 2; ++bj) {
;                     const int c = c0 + bj * 128;
;                     const f32x4 v0 = *(const f32x4*)(xrow + c) + acc[ai][bj][m][0], v1 = *(const f32x4*)(xrow + c + 4) + acc[ai][bj][m][1];
;                     ss += v0[0] * v0[0] + v0[1] * v0[1] + v0[2] * v0[2] + v0[3] * v0[3] + v1[0] * v1[0] + v1[1] * v1[1] + v1[2] * v1[2] + v1[3] * v1[3];
;                     *(uint4*)(Hb + (size_t)r * D + c) = pk8(v0, v1);
;                 }
	v_pk_add_f32 v[118:119], v[118:119], v[172:173]
	v_pk_add_f32 v[116:117], v[116:117], v[170:171]
	v_pk_add_f32 v[122:123], v[114:115], v[176:177]
	v_pk_add_f32 v[114:115], v[112:113], v[174:175]
	v_cvt_pk_bf16_f32 v112, v116, v117
	v_cvt_pk_bf16_f32 v113, v118, v119
	s_nop 0
	v_cvt_pk_bf16_f32 v114, v114, v115
	v_cvt_pk_bf16_f32 v115, v122, v123
	global_store_dwordx4 v[168:169], v[112:115], off offset:256
	s_and_saveexec_b64 s[14:15], vcc
	s_xor_b64 s[14:15], exec, s[14:15]
	v_add_u32_e32 v136, 0xffffc010, v152
	v_lshlrev_b64 v[112:113], 13, v[136:137]
	v_lshl_add_u64 v[112:113], s[54:55], 0, v[112:113]
	v_mov_b32_e32 v121, v137
	s_andn2_saveexec_b64 s[14:15], s[14:15]
	v_ashrrev_i32_e32 v121, 31, v120
	v_lshlrev_b64 v[112:113], 13, v[120:121]
	v_lshl_add_u64 v[112:113], s[52:53], 0, v[112:113]
	s_or_b64 exec, exec, s[14:15]
	v_lshl_add_u64 v[122:123], v[150:151], 2, v[112:113]
	v_lshlrev_b64 v[120:121], 12, v[120:121]
	v_lshl_add_u64 v[120:121], s[34:35], 0, v[120:121]
	v_lshl_add_u64 v[120:121], v[150:151], 1, v[120:121]
	global_load_dwordx4 v[170:173], v[236:237], off offset:512
	global_load_dwordx4 v[174:177], v[236:237], off offset:528
	s_waitcnt vmcnt(16)
	v_pk_add_f32 v[108:109], v[108:109], v[178:179]
	v_pk_add_f32 v[112:113], v[106:107], v[184:185]
	v_pk_add_f32 v[106:107], v[104:105], v[182:183]
	v_pk_add_f32 v[110:111], v[110:111], v[180:181]
	v_cvt_pk_bf16_f32 v104, v108, v109
	s_nop 0
	v_cvt_pk_bf16_f32 v105, v110, v111
	v_cvt_pk_bf16_f32 v106, v106, v107
	v_cvt_pk_bf16_f32 v107, v112, v113
	global_store_dwordx4 v[120:121], v[104:107], off
	s_nop 0
	v_or_b32_e32 v104, 32, v152
	v_cmp_lt_i32_e32 vcc, s51, v104
	v_lshl_add_u64 v[236:237], v[236:237], 0, v[238:239]
	global_load_dwordx4 v[178:181], v[236:237], off
	global_load_dwordx4 v[182:185], v[236:237], off offset:16
	s_waitcnt vmcnt(17)
	v_pk_add_f32 v[102:103], v[102:103], v[188:189]
	v_pk_add_f32 v[100:101], v[100:101], v[186:187]
	v_pk_add_f32 v[106:107], v[98:99], v[192:193]
	v_pk_add_f32 v[98:99], v[96:97], v[190:191]
	v_cvt_pk_bf16_f32 v96, v100, v101
	v_cvt_pk_bf16_f32 v97, v102, v103
	s_nop 0
	v_cvt_pk_bf16_f32 v98, v98, v99
	v_cvt_pk_bf16_f32 v99, v106, v107
	global_store_dwordx4 v[120:121], v[96:99], off offset:256
	s_and_saveexec_b64 s[14:15], vcc
	s_xor_b64 s[14:15], exec, s[14:15]
	v_add_u32_e32 v136, 0xffffc020, v152
	v_lshlrev_b64 v[96:97], 13, v[136:137]
	v_lshl_add_u64 v[96:97], s[54:55], 0, v[96:97]
	v_mov_b32_e32 v105, v137
	s_andn2_saveexec_b64 s[14:15], s[14:15]
	v_ashrrev_i32_e32 v105, 31, v104
	v_lshlrev_b64 v[96:97], 13, v[104:105]
	v_lshl_add_u64 v[96:97], s[52:53], 0, v[96:97]
	s_or_b64 exec, exec, s[14:15]
	v_lshl_add_u64 v[106:107], v[150:151], 2, v[96:97]
	v_lshlrev_b64 v[104:105], 12, v[104:105]
	v_lshl_add_u64 v[104:105], s[34:35], 0, v[104:105]
	v_lshl_add_u64 v[104:105], v[150:151], 1, v[104:105]
	global_load_dwordx4 v[186:189], v[236:237], off offset:512
	global_load_dwordx4 v[190:193], v[236:237], off offset:528
	s_waitcnt vmcnt(18)
	v_pk_add_f32 v[92:93], v[92:93], v[194:195]
	v_pk_add_f32 v[96:97], v[90:91], v[200:201]
	v_pk_add_f32 v[90:91], v[88:89], v[198:199]
	v_pk_add_f32 v[94:95], v[94:95], v[196:197]
	v_cvt_pk_bf16_f32 v88, v92, v93
	s_nop 0
	v_cvt_pk_bf16_f32 v89, v94, v95
	v_cvt_pk_bf16_f32 v90, v90, v91
	v_cvt_pk_bf16_f32 v91, v96, v97
	global_store_dwordx4 v[104:105], v[88:91], off
	s_nop 0
	v_or_b32_e32 v88, 48, v152
	v_cmp_lt_i32_e32 vcc, s51, v88
	v_lshl_add_u64 v[236:237], v[236:237], 0, v[238:239]
	global_load_dwordx4 v[194:197], v[236:237], off
	global_load_dwordx4 v[198:201], v[236:237], off offset:16
	s_waitcnt vmcnt(19)
	v_pk_add_f32 v[86:87], v[86:87], v[204:205]
	v_pk_add_f32 v[84:85], v[84:85], v[202:203]
	v_pk_add_f32 v[90:91], v[82:83], v[208:209]
	v_pk_add_f32 v[82:83], v[80:81], v[206:207]
	v_cvt_pk_bf16_f32 v80, v84, v85
	v_cvt_pk_bf16_f32 v81, v86, v87
	s_nop 0
	v_cvt_pk_bf16_f32 v82, v82, v83
	v_cvt_pk_bf16_f32 v83, v90, v91
	global_store_dwordx4 v[104:105], v[80:83], off offset:256
	s_and_saveexec_b64 s[14:15], vcc
	s_xor_b64 s[14:15], exec, s[14:15]
	v_add_u32_e32 v136, 0xffffc030, v152
	v_lshlrev_b64 v[80:81], 13, v[136:137]
	v_lshl_add_u64 v[80:81], s[54:55], 0, v[80:81]
	v_mov_b32_e32 v89, v137
	s_andn2_saveexec_b64 s[14:15], s[14:15]
	v_ashrrev_i32_e32 v89, 31, v88
	v_lshlrev_b64 v[80:81], 13, v[88:89]
	v_lshl_add_u64 v[80:81], s[52:53], 0, v[80:81]
	s_or_b64 exec, exec, s[14:15]
	v_lshl_add_u64 v[90:91], v[150:151], 2, v[80:81]
	v_lshlrev_b64 v[88:89], 12, v[88:89]
	v_lshl_add_u64 v[88:89], s[34:35], 0, v[88:89]
	v_lshl_add_u64 v[88:89], v[150:151], 1, v[88:89]
	global_load_dwordx4 v[202:205], v[236:237], off offset:512
	global_load_dwordx4 v[206:209], v[236:237], off offset:528
	s_waitcnt vmcnt(20)
	v_pk_add_f32 v[76:77], v[76:77], v[210:211]
	v_pk_add_f32 v[80:81], v[74:75], v[216:217]
	v_pk_add_f32 v[74:75], v[72:73], v[214:215]
	v_pk_add_f32 v[78:79], v[78:79], v[212:213]
	v_cvt_pk_bf16_f32 v72, v76, v77
	s_nop 0
	v_cvt_pk_bf16_f32 v73, v78, v79
	v_cvt_pk_bf16_f32 v74, v74, v75
	v_cvt_pk_bf16_f32 v75, v80, v81
	global_store_dwordx4 v[88:89], v[72:75], off
	s_nop 0
	v_add_u32_e32 v72, 0x80, v152
	v_cmp_lt_i32_e32 vcc, s51, v72
	s_waitcnt vmcnt(19)
; __device__ __forceinline__ uint4 pk8(f32x4 a, f32x4 b) { return make_uint4(cvt_pk_bf16(a[0], a[1]), cvt_pk_bf16(a[2], a[3]), cvt_pk_bf16(b[0], b[1]), cvt_pk_bf16(b[2], b[3])); }
;     __device__ __forceinline__ void operator()(AccRef acc, const Unit& u, int wr, int wc, int fr, int fq) const {
;     ...
;         for (int ai = 0; ai < 2; ++ai)
; #pragma unroll
;             for (int m = 0; m < 4; ++m) {
;                 const int r = u.pm * 256 + ai * 128 + wr * 64 + m * 16 + fr;
;                 const float* xrow = r < TP ? xp + (size_t)r * D : xs + (size_t)(r - TP) * D;
;                 float ss = 0.f;
; #pragma unroll
;                 for (int bj = 0; bj < 2; ++bj) {
;                     const int c = c0 + bj * 128;
;                     const f32x4 v0 = *(const f32x4*)(xrow + c) + acc[ai][bj][m][0], v1 = *(const f32x4*)(xrow + c + 4) + acc[ai][bj][m][1];
;                     ss += v0[0] * v0[0] + v0[1] * v0[1] + v0[2] * v0[2] + v0[3] * v0[3] + v1[0] * v1[0] + v1[1] * v1[1] + v1[2] * v1[2] + v1[3] * v1[3];
;                     *(uint4*)(Hb + (size_t)r * D + c) = pk8(v0, v1);
;                 }
	v_pk_add_f32 v[70:71], v[70:71], v[220:221]
	v_pk_add_f32 v[68:69], v[68:69], v[218:219]
	v_pk_add_f32 v[74:75], v[66:67], v[224:225]
	v_pk_add_f32 v[66:67], v[64:65], v[222:223]
	v_cvt_pk_bf16_f32 v64, v68, v69
	v_cvt_pk_bf16_f32 v65, v70, v71
	s_nop 0
	v_cvt_pk_bf16_f32 v66, v66, v67
	v_cvt_pk_bf16_f32 v67, v74, v75
	global_store_dwordx4 v[88:89], v[64:67], off offset:256
	s_and_saveexec_b64 s[14:15], vcc
	s_xor_b64 s[14:15], exec, s[14:15]
	v_add_u32_e32 v136, 0xffffc080, v152
	v_lshlrev_b64 v[64:65], 13, v[136:137]
	v_lshl_add_u64 v[64:65], s[54:55], 0, v[64:65]
	v_mov_b32_e32 v73, v137
	s_andn2_saveexec_b64 s[14:15], s[14:15]
	v_ashrrev_i32_e32 v73, 31, v72
	v_lshlrev_b64 v[64:65], 13, v[72:73]
	v_lshl_add_u64 v[64:65], s[52:53], 0, v[64:65]
	s_or_b64 exec, exec, s[14:15]
	v_lshl_add_u64 v[74:75], v[150:151], 2, v[64:65]
	v_lshlrev_b64 v[72:73], 12, v[72:73]
	v_lshl_add_u64 v[72:73], s[34:35], 0, v[72:73]
	v_lshl_add_u64 v[72:73], v[150:151], 1, v[72:73]
	s_waitcnt vmcnt(17)
	v_pk_add_f32 v[60:61], v[60:61], v[226:227]
	v_pk_add_f32 v[64:65], v[58:59], v[232:233]
	v_pk_add_f32 v[58:59], v[56:57], v[230:231]
	v_pk_add_f32 v[62:63], v[62:63], v[228:229]
	v_cvt_pk_bf16_f32 v56, v60, v61
	s_nop 0
	v_cvt_pk_bf16_f32 v57, v62, v63
	v_cvt_pk_bf16_f32 v58, v58, v59
	v_cvt_pk_bf16_f32 v59, v64, v65
	global_store_dwordx4 v[72:73], v[56:59], off
	s_nop 0
	v_add_u32_e32 v56, 0x90, v152
	v_cmp_lt_i32_e32 vcc, s51, v56
	s_waitcnt vmcnt(15)
	v_pk_add_f32 v[54:55], v[54:55], v[172:173]
	v_pk_add_f32 v[52:53], v[52:53], v[170:171]
	v_pk_add_f32 v[58:59], v[50:51], v[176:177]
	v_pk_add_f32 v[50:51], v[48:49], v[174:175]
	v_cvt_pk_bf16_f32 v48, v52, v53
	v_cvt_pk_bf16_f32 v49, v54, v55
	s_nop 0
	v_cvt_pk_bf16_f32 v50, v50, v51
	v_cvt_pk_bf16_f32 v51, v58, v59
	global_store_dwordx4 v[72:73], v[48:51], off offset:256
	s_and_saveexec_b64 s[14:15], vcc
	s_xor_b64 s[14:15], exec, s[14:15]
	v_add_u32_e32 v136, 0xffffc090, v152
	v_lshlrev_b64 v[48:49], 13, v[136:137]
	v_lshl_add_u64 v[48:49], s[54:55], 0, v[48:49]
	v_mov_b32_e32 v57, v137
	s_andn2_saveexec_b64 s[14:15], s[14:15]
	v_ashrrev_i32_e32 v57, 31, v56
	v_lshlrev_b64 v[48:49], 13, v[56:57]
	v_lshl_add_u64 v[48:49], s[52:53], 0, v[48:49]
	s_or_b64 exec, exec, s[14:15]
	v_lshl_add_u64 v[58:59], v[150:151], 2, v[48:49]
	v_lshlrev_b64 v[56:57], 12, v[56:57]
	v_lshl_add_u64 v[56:57], s[34:35], 0, v[56:57]
	v_lshl_add_u64 v[56:57], v[150:151], 1, v[56:57]
	s_waitcnt vmcnt(13)
	v_pk_add_f32 v[44:45], v[44:45], v[178:179]
	v_pk_add_f32 v[48:49], v[42:43], v[184:185]
	v_pk_add_f32 v[42:43], v[40:41], v[182:183]
	v_pk_add_f32 v[46:47], v[46:47], v[180:181]
	v_cvt_pk_bf16_f32 v40, v44, v45
	s_nop 0
	v_cvt_pk_bf16_f32 v41, v46, v47
	v_cvt_pk_bf16_f32 v42, v42, v43
	v_cvt_pk_bf16_f32 v43, v48, v49
	global_store_dwordx4 v[56:57], v[40:43], off
	s_nop 0
	v_add_u32_e32 v40, 0xa0, v152
	v_cmp_lt_i32_e32 vcc, s51, v40
	s_waitcnt vmcnt(11)
	v_pk_add_f32 v[38:39], v[38:39], v[188:189]
	v_pk_add_f32 v[36:37], v[36:37], v[186:187]
	v_pk_add_f32 v[42:43], v[34:35], v[192:193]
	v_pk_add_f32 v[34:35], v[32:33], v[190:191]
	v_cvt_pk_bf16_f32 v32, v36, v37
	v_cvt_pk_bf16_f32 v33, v38, v39
	s_nop 0
	v_cvt_pk_bf16_f32 v34, v34, v35
	v_cvt_pk_bf16_f32 v35, v42, v43
	global_store_dwordx4 v[56:57], v[32:35], off offset:256
	s_and_saveexec_b64 s[14:15], vcc
	s_xor_b64 s[14:15], exec, s[14:15]
	v_add_u32_e32 v136, 0xffffc0a0, v152
	v_lshlrev_b64 v[32:33], 13, v[136:137]
	v_lshl_add_u64 v[32:33], s[54:55], 0, v[32:33]
	v_mov_b32_e32 v41, v137
	s_andn2_saveexec_b64 s[14:15], s[14:15]
	v_ashrrev_i32_e32 v41, 31, v40
	v_lshlrev_b64 v[32:33], 13, v[40:41]
	v_lshl_add_u64 v[32:33], s[52:53], 0, v[32:33]
	s_or_b64 exec, exec, s[14:15]
	v_lshl_add_u64 v[42:43], v[150:151], 2, v[32:33]
	v_lshlrev_b64 v[40:41], 12, v[40:41]
	v_lshl_add_u64 v[40:41], s[34:35], 0, v[40:41]
	v_lshl_add_u64 v[40:41], v[150:151], 1, v[40:41]
	s_waitcnt vmcnt(9)
	v_pk_add_f32 v[28:29], v[28:29], v[194:195]
	v_pk_add_f32 v[32:33], v[26:27], v[200:201]
	v_pk_add_f32 v[26:27], v[24:25], v[198:199]
	v_pk_add_f32 v[30:31], v[30:31], v[196:197]
	v_cvt_pk_bf16_f32 v24, v28, v29
	s_nop 0
	v_cvt_pk_bf16_f32 v25, v30, v31
	v_cvt_pk_bf16_f32 v26, v26, v27
	v_cvt_pk_bf16_f32 v27, v32, v33
	global_store_dwordx4 v[40:41], v[24:27], off
	s_nop 0
	v_add_u32_e32 v24, 0xb0, v152
	v_cmp_lt_i32_e32 vcc, s51, v24
	s_waitcnt vmcnt(7)
	v_pk_add_f32 v[22:23], v[22:23], v[204:205]
	v_pk_add_f32 v[20:21], v[20:21], v[202:203]
	v_pk_add_f32 v[26:27], v[18:19], v[208:209]
	v_pk_add_f32 v[18:19], v[16:17], v[206:207]
	v_cvt_pk_bf16_f32 v16, v20, v21
	v_cvt_pk_bf16_f32 v17, v22, v23
	s_nop 0
	v_cvt_pk_bf16_f32 v18, v18, v19
	v_cvt_pk_bf16_f32 v19, v26, v27
	global_store_dwordx4 v[40:41], v[16:19], off offset:256
	s_and_saveexec_b64 s[14:15], vcc
	s_xor_b64 s[14:15], exec, s[14:15]
	v_add_u32_e32 v136, 0xffffc0b0, v152
	v_lshlrev_b64 v[16:17], 13, v[136:137]
	v_lshl_add_u64 v[16:17], s[54:55], 0, v[16:17]
	v_mov_b32_e32 v25, v137
	s_andn2_saveexec_b64 s[14:15], s[14:15]
	s_cbranch_execz .LBB0_758
	v_ashrrev_i32_e32 v25, 31, v24
	v_lshlrev_b64 v[16:17], 13, v[24:25]
	v_lshl_add_u64 v[16:17], s[52:53], 0, v[16:17]
	s_branch .LBB0_758

; #define PG8_STAGE(bufoff, gbase, voff) do { _Pragma("unroll") for (int _i = 0; _i < 2; ++_i) \
;         __builtin_amdgcn_global_load_lds((const unsigned*)((const char*)(gbase) + (voff)[_i]), (PG8_LAS unsigned*)(lds + (bufoff) + ldsw + _i * 8192), 16, 0, 0); } while (0)
; #define PG8_LDA(dst, b, h) do { _Pragma("unroll") for (int m = 0; m < 4; ++m) _Pragma("unroll") for (int k = 0; k < 2; ++k) dst[m][k] = *(const PG8_LAS bf16x8*)(lds + PG8_SA(b, h) + aoff + m * 2048 + k * 1024); } while (0)
; #define PG8_LDB(dst, b, h) do { _Pragma("unroll") for (int n = 0; n < 2; ++n) _Pragma("unroll") for (int k = 0; k < 2; ++k) dst[n][k] = *(const PG8_LAS bf16x8*)(lds + PG8_SB(b, h) + boff + n * 2048 + k * 1024); } while (0)
; #define PG8_MMA(ai, bj, At, Bt) do { __builtin_amdgcn_s_setprio(1); _Pragma("unroll") for (int m = 0; m < 4; ++m) _Pragma("unroll") for (int n = 0; n < 2; ++n) _Pragma("unroll") for (int k = 0; k < 2; ++k) \
;         acc[ai][bj][m][n] = __builtin_amdgcn_mfma_f32_16x16x32_bf16(Bt[n][k], At[m][k], acc[ai][bj][m][n], 0, 0, 0); __builtin_amdgcn_s_setprio(0); } while (0)
; #define PG8_WAIT_L(n) asm volatile("s_waitcnt lgkmcnt(" #n ")" ::: "memory")
; #define PG8_BAR __builtin_amdgcn_s_barrier()
; #define PG8_SCHED __builtin_amdgcn_sched_barrier(0)
; template <class Epi, class Sched>
; __device__ __forceinline__ void gemm_phase(PG8_LAS unsigned char* lds, const Gemm g, const Sched& S, const Epi& E) {
;     ...
;             const bool last = (t == nt - 2);
;             const char* a1 = cA + (size_t)(t + 1) * kstep;
;             const char* a2 = last ? nA : cA + (size_t)(t + 2) * kstep; const char* b2 = last ? nB : cB + (size_t)(t + 2) * kstep;
;             const char* a3 = a2 + kstep; const char* b3 = b2 + kstep;
;             if (last && has_next) S.a_ready(nxt);
;             PG8_LDB(B0, 0, 0); PG8_SCHED; PG8_LDA(At, 0, 0); PG8_STAGE(PG8_SA(1, 1), a1 + hstep, voffA);
;             PG8_WAIT_L(8); PG8_BAR; PG8_WAIT_L(0); PG8_MMA(0, 0, At, B0); PG8_BAR; PG8_SCHED;
;             PG8_LDB(B1, 0, 1); PG8_STAGE(PG8_SB(0, 0), b2, voffB);
;             PG8_BAR; PG8_WAIT_L(0); PG8_MMA(0, 1, At, B1); PG8_BAR;
;             PG8_LDA(At, 0, 1); PG8_STAGE(PG8_SA(0, 0), a2, voffA);
;             PG8_BAR; PG8_WAIT_L(0); PG8_MMA(1, 0, At, B0); PG8_BAR; PG8_SCHED;
.LBB0_872:
	ds_read_b128 v[148:151], v162
	ds_read_b128 v[166:169], v162 offset:1024
	ds_read_b128 v[170:173], v162 offset:2048
	ds_read_b128 v[174:177], v162 offset:3072
	s_add_u32 s20, s18, 0xfff80080
	s_addc_u32 s21, s19, -1
	s_cmp_eq_u32 s55, 28
	s_cselect_b32 s23, s11, s21
	s_cselect_b32 s22, s51, s20
	s_cselect_b32 s21, s9, s54
	s_cselect_b32 s20, s52, s53
	v_lshl_add_u64 v[210:211], s[18:19], 0, v[136:137]
	s_add_i32 m0, s17, 0xc000
	ds_read_b128 v[178:181], v163
	ds_read_b128 v[182:185], v163 offset:1024
	ds_read_b128 v[186:189], v163 offset:2048
	ds_read_b128 v[190:193], v163 offset:3072
	ds_read_b128 v[194:197], v163 offset:4096
	ds_read_b128 v[198:201], v163 offset:5120
	ds_read_b128 v[202:205], v163 offset:6144
	ds_read_b128 v[206:209], v163 offset:7168
	global_load_lds_dwordx4 v[210:211], off
	v_lshl_add_u64 v[210:211], s[18:19], 0, v[138:139]
	s_add_i32 m0, s17, 0xe000
	s_nop 0
	global_load_lds_dwordx4 v[210:211], off
	s_waitcnt lgkmcnt(8)
	s_barrier
	s_waitcnt lgkmcnt(0)
	s_waitcnt lgkmcnt(0)
	v_mfma_f32_16x16x32_bf16 v[124:127], v[148:151], v[178:181], v[124:127]
	v_mfma_f32_16x16x32_bf16 v[120:123], v[170:173], v[178:181], v[120:123]
	v_mfma_f32_16x16x32_bf16 v[112:115], v[148:151], v[186:189], v[112:115]
	v_mfma_f32_16x16x32_bf16 v[104:107], v[170:173], v[186:189], v[104:107]
	v_mfma_f32_16x16x32_bf16 v[96:99], v[148:151], v[194:197], v[96:99]
	v_mfma_f32_16x16x32_bf16 v[88:91], v[170:173], v[194:197], v[88:91]
	v_mfma_f32_16x16x32_bf16 v[80:83], v[148:151], v[202:205], v[80:83]
	v_mfma_f32_16x16x32_bf16 v[72:75], v[170:173], v[202:205], v[72:75]
	v_mfma_f32_16x16x32_bf16 v[124:127], v[166:169], v[182:185], v[124:127]
	v_mfma_f32_16x16x32_bf16 v[120:123], v[174:177], v[182:185], v[120:123]
	v_mfma_f32_16x16x32_bf16 v[112:115], v[166:169], v[190:193], v[112:115]
	v_mfma_f32_16x16x32_bf16 v[104:107], v[174:177], v[190:193], v[104:107]
	v_mfma_f32_16x16x32_bf16 v[96:99], v[166:169], v[198:201], v[96:99]
	v_mfma_f32_16x16x32_bf16 v[88:91], v[174:177], v[198:201], v[88:91]
	v_mfma_f32_16x16x32_bf16 v[80:83], v[166:169], v[206:209], v[80:83]
	v_mfma_f32_16x16x32_bf16 v[72:75], v[174:177], v[206:209], v[72:75]
	s_barrier
	s_add_i32 s30, s48, s27
	v_lshl_add_u64 v[226:227], s[20:21], 0, v[130:131]
	s_mov_b32 m0, s30
	ds_read_b128 v[210:213], v164
	ds_read_b128 v[214:217], v164 offset:1024
	ds_read_b128 v[218:221], v164 offset:2048
	ds_read_b128 v[222:225], v164 offset:3072
	global_load_lds_dwordx4 v[226:227], off
	v_lshl_add_u64 v[228:229], s[20:21], 0, v[134:135]
	s_add_i32 m0, s30, 0x2000
	s_nop 0
	global_load_lds_dwordx4 v[228:229], off
	s_barrier
	s_waitcnt lgkmcnt(0)
	s_waitcnt lgkmcnt(0)
	v_mfma_f32_16x16x32_bf16 v[116:119], v[210:213], v[178:181], v[116:119]
	v_mfma_f32_16x16x32_bf16 v[108:111], v[218:221], v[178:181], v[108:111]
	v_mfma_f32_16x16x32_bf16 v[100:103], v[210:213], v[186:189], v[100:103]
	v_mfma_f32_16x16x32_bf16 v[92:95], v[218:221], v[186:189], v[92:95]
	v_mfma_f32_16x16x32_bf16 v[84:87], v[210:213], v[194:197], v[84:87]
	v_mfma_f32_16x16x32_bf16 v[76:79], v[218:221], v[194:197], v[76:79]
	v_mfma_f32_16x16x32_bf16 v[68:71], v[210:213], v[202:205], v[68:71]
	v_mfma_f32_16x16x32_bf16 v[64:67], v[218:221], v[202:205], v[64:67]
	v_mfma_f32_16x16x32_bf16 v[116:119], v[214:217], v[182:185], v[116:119]
	v_mfma_f32_16x16x32_bf16 v[108:111], v[222:225], v[182:185], v[108:111]
	v_mfma_f32_16x16x32_bf16 v[100:103], v[214:217], v[190:193], v[100:103]
	v_mfma_f32_16x16x32_bf16 v[92:95], v[222:225], v[190:193], v[92:95]
	v_mfma_f32_16x16x32_bf16 v[84:87], v[214:217], v[198:201], v[84:87]
	v_mfma_f32_16x16x32_bf16 v[76:79], v[222:225], v[198:201], v[76:79]
	v_mfma_f32_16x16x32_bf16 v[68:71], v[214:217], v[206:209], v[68:71]
	v_mfma_f32_16x16x32_bf16 v[64:67], v[222:225], v[206:209], v[64:67]
	s_mov_b32 m0, s17
	v_lshl_add_u64 v[230:231], s[22:23], 0, v[128:129]
	s_barrier
	ds_read_b128 v[178:181], v163 offset:16384
	ds_read_b128 v[182:185], v163 offset:17408
	ds_read_b128 v[186:189], v163 offset:18432
	ds_read_b128 v[190:193], v163 offset:19456
	ds_read_b128 v[194:197], v163 offset:20480
	ds_read_b128 v[198:201], v163 offset:21504
	ds_read_b128 v[202:205], v163 offset:22528
	ds_read_b128 v[206:209], v163 offset:23552
	global_load_lds_dwordx4 v[230:231], off
	v_lshl_add_u64 v[232:233], s[22:23], 0, v[132:133]
	s_mov_b32 m0, s28
	s_nop 0
	global_load_lds_dwordx4 v[232:233], off
	s_barrier
	s_waitcnt lgkmcnt(0)
	s_waitcnt lgkmcnt(0)
	v_mfma_f32_16x16x32_bf16 v[60:63], v[148:151], v[178:181], v[60:63]
	v_mfma_f32_16x16x32_bf16 v[56:59], v[170:173], v[178:181], v[56:59]
	v_mfma_f32_16x16x32_bf16 v[52:55], v[148:151], v[186:189], v[52:55]
	v_mfma_f32_16x16x32_bf16 v[44:47], v[170:173], v[186:189], v[44:47]
	v_mfma_f32_16x16x32_bf16 v[36:39], v[148:151], v[194:197], v[36:39]
	v_mfma_f32_16x16x32_bf16 v[28:31], v[170:173], v[194:197], v[28:31]
	v_mfma_f32_16x16x32_bf16 v[20:23], v[148:151], v[202:205], v[20:23]
	v_mfma_f32_16x16x32_bf16 v[12:15], v[170:173], v[202:205], v[12:15]
	v_mfma_f32_16x16x32_bf16 v[60:63], v[166:169], v[182:185], v[60:63]
	v_mfma_f32_16x16x32_bf16 v[56:59], v[174:177], v[182:185], v[56:59]
	v_mfma_f32_16x16x32_bf16 v[52:55], v[166:169], v[190:193], v[52:55]
	v_mfma_f32_16x16x32_bf16 v[44:47], v[174:177], v[190:193], v[44:47]
	v_mfma_f32_16x16x32_bf16 v[36:39], v[166:169], v[198:201], v[36:39]
	v_mfma_f32_16x16x32_bf16 v[28:31], v[174:177], v[198:201], v[28:31]
	v_mfma_f32_16x16x32_bf16 v[20:23], v[166:169], v[206:209], v[20:23]
	v_mfma_f32_16x16x32_bf16 v[12:15], v[174:177], v[206:209], v[12:15]
	s_barrier
; #define PG8_STAGE(bufoff, gbase, voff) do { _Pragma("unroll") for (int _i = 0; _i < 2; ++_i) \
;         __builtin_amdgcn_global_load_lds((const unsigned*)((const char*)(gbase) + (voff)[_i]), (PG8_LAS unsigned*)(lds + (bufoff) + ldsw + _i * 8192), 16, 0, 0); } while (0)
; #define PG8_LDA(dst, b, h) do { _Pragma("unroll") for (int m = 0; m < 4; ++m) _Pragma("unroll") for (int k = 0; k < 2; ++k) dst[m][k] = *(const PG8_LAS bf16x8*)(lds + PG8_SA(b, h) + aoff + m * 2048 + k * 1024); } while (0)
; #define PG8_LDB(dst, b, h) do { _Pragma("unroll") for (int n = 0; n < 2; ++n) _Pragma("unroll") for (int k = 0; k < 2; ++k) dst[n][k] = *(const PG8_LAS bf16x8*)(lds + PG8_SB(b, h) + boff + n * 2048 + k * 1024); } while (0)
; #define PG8_MMA(ai, bj, At, Bt) do { __builtin_amdgcn_s_setprio(1); _Pragma("unroll") for (int m = 0; m < 4; ++m) _Pragma("unroll") for (int n = 0; n < 2; ++n) _Pragma("unroll") for (int k = 0; k < 2; ++k) \
;         acc[ai][bj][m][n] = __builtin_amdgcn_mfma_f32_16x16x32_bf16(Bt[n][k], At[m][k], acc[ai][bj][m][n], 0, 0, 0); __builtin_amdgcn_s_setprio(0); } while (0)
; #define PG8_WAIT_V(n) asm volatile("s_waitcnt vmcnt(" #n ")" ::: "memory")
; #define PG8_WAIT_L(n) asm volatile("s_waitcnt lgkmcnt(" #n ")" ::: "memory")
; #define PG8_BAR __builtin_amdgcn_s_barrier()
; #define PG8_SCHED __builtin_amdgcn_sched_barrier(0)
; template <class Epi, class Sched>
; __device__ __forceinline__ void gemm_phase(PG8_LAS unsigned char* lds, const Gemm g, const Sched& S, const Epi& E) {
;     ...
;             PG8_STAGE(PG8_SB(0, 1), b2 + hstep, voffB);
;             PG8_WAIT_V(6); PG8_BAR; PG8_MMA(1, 1, At, B1); PG8_BAR;
;             PG8_LDB(B0, 1, 0); PG8_SCHED; PG8_LDA(At, 1, 0); PG8_STAGE(PG8_SA(0, 1), a2 + hstep, voffA);
;             PG8_WAIT_L(8); PG8_BAR; PG8_WAIT_L(0); PG8_MMA(0, 0, At, B0); PG8_BAR; PG8_SCHED;
;             PG8_LDB(B1, 1, 1); PG8_STAGE(PG8_SB(1, 0), b3, voffB);
;             PG8_BAR; PG8_WAIT_L(0); PG8_MMA(0, 1, At, B1); PG8_BAR;
;             PG8_LDA(At, 1, 1); PG8_STAGE(PG8_SA(1, 0), a3, voffA);
	s_add_u32 s30, s20, 0x80000
	s_addc_u32 s31, s21, 0
	s_add_i32 s38, s49, s27
	v_lshl_add_u64 v[148:149], s[30:31], 0, v[130:131]
	s_mov_b32 m0, s38
	s_nop 0
	global_load_lds_dwordx4 v[148:149], off
	v_lshl_add_u64 v[148:149], s[30:31], 0, v[134:135]
	s_add_i32 m0, s38, 0x2000
	s_nop 0
	global_load_lds_dwordx4 v[148:149], off
	s_waitcnt vmcnt(6)
	s_barrier
	v_mfma_f32_16x16x32_bf16 v[48:51], v[210:213], v[178:181], v[48:51]
	v_mfma_f32_16x16x32_bf16 v[40:43], v[218:221], v[178:181], v[40:43]
	v_mfma_f32_16x16x32_bf16 v[32:35], v[210:213], v[186:189], v[32:35]
	v_mfma_f32_16x16x32_bf16 v[24:27], v[218:221], v[186:189], v[24:27]
	v_mfma_f32_16x16x32_bf16 v[16:19], v[210:213], v[194:197], v[16:19]
	v_mfma_f32_16x16x32_bf16 v[8:11], v[218:221], v[194:197], v[8:11]
	v_mfma_f32_16x16x32_bf16 v[4:7], v[210:213], v[202:205], v[4:7]
	v_mfma_f32_16x16x32_bf16 v[0:3], v[218:221], v[202:205], v[0:3]
	v_mfma_f32_16x16x32_bf16 v[48:51], v[214:217], v[182:185], v[48:51]
	v_mfma_f32_16x16x32_bf16 v[40:43], v[222:225], v[182:185], v[40:43]
	v_mfma_f32_16x16x32_bf16 v[32:35], v[214:217], v[190:193], v[32:35]
	v_mfma_f32_16x16x32_bf16 v[24:27], v[222:225], v[190:193], v[24:27]
	v_mfma_f32_16x16x32_bf16 v[16:19], v[214:217], v[198:201], v[16:19]
	v_mfma_f32_16x16x32_bf16 v[8:11], v[222:225], v[198:201], v[8:11]
	v_mfma_f32_16x16x32_bf16 v[4:7], v[214:217], v[206:209], v[4:7]
	v_mfma_f32_16x16x32_bf16 v[0:3], v[222:225], v[206:209], v[0:3]
	s_add_i32 s30, 0, 0x18000
	v_add_u32_e32 v165, s30, v160
	s_barrier
	ds_read_b128 v[148:151], v165
	ds_read_b128 v[166:169], v165 offset:1024
	ds_read_b128 v[170:173], v165 offset:2048
	ds_read_b128 v[174:177], v165 offset:3072
	s_add_u32 s22, s22, 0x80000
	s_addc_u32 s23, s23, 0
	s_mov_b32 m0, s29
	v_lshl_add_u64 v[210:211], s[22:23], 0, v[128:129]
	ds_read_b128 v[178:181], v163 offset:32768
	ds_read_b128 v[182:185], v163 offset:33792
	ds_read_b128 v[186:189], v163 offset:34816
	ds_read_b128 v[190:193], v163 offset:35840
	ds_read_b128 v[194:197], v163 offset:36864
	ds_read_b128 v[198:201], v163 offset:37888
	ds_read_b128 v[202:205], v163 offset:38912
	ds_read_b128 v[206:209], v163 offset:39936
	global_load_lds_dwordx4 v[210:211], off
	v_lshl_add_u64 v[210:211], s[22:23], 0, v[132:133]
	s_mov_b32 m0, s42
	s_nop 0
	global_load_lds_dwordx4 v[210:211], off
	s_waitcnt lgkmcnt(8)
	s_barrier
	s_waitcnt lgkmcnt(0)
	s_waitcnt lgkmcnt(0)
	v_mfma_f32_16x16x32_bf16 v[124:127], v[148:151], v[178:181], v[124:127]
	v_mfma_f32_16x16x32_bf16 v[120:123], v[170:173], v[178:181], v[120:123]
	v_mfma_f32_16x16x32_bf16 v[112:115], v[148:151], v[186:189], v[112:115]
	v_mfma_f32_16x16x32_bf16 v[104:107], v[170:173], v[186:189], v[104:107]
	v_mfma_f32_16x16x32_bf16 v[96:99], v[148:151], v[194:197], v[96:99]
	v_mfma_f32_16x16x32_bf16 v[88:91], v[170:173], v[194:197], v[88:91]
	v_mfma_f32_16x16x32_bf16 v[80:83], v[148:151], v[202:205], v[80:83]
	v_mfma_f32_16x16x32_bf16 v[72:75], v[170:173], v[202:205], v[72:75]
	v_mfma_f32_16x16x32_bf16 v[124:127], v[166:169], v[182:185], v[124:127]
	v_mfma_f32_16x16x32_bf16 v[120:123], v[174:177], v[182:185], v[120:123]
	v_mfma_f32_16x16x32_bf16 v[112:115], v[166:169], v[190:193], v[112:115]
	v_mfma_f32_16x16x32_bf16 v[104:107], v[174:177], v[190:193], v[104:107]
	v_mfma_f32_16x16x32_bf16 v[96:99], v[166:169], v[198:201], v[96:99]
	v_mfma_f32_16x16x32_bf16 v[88:91], v[174:177], v[198:201], v[88:91]
	v_mfma_f32_16x16x32_bf16 v[80:83], v[166:169], v[206:209], v[80:83]
	v_mfma_f32_16x16x32_bf16 v[72:75], v[174:177], v[206:209], v[72:75]
	s_barrier
	s_add_i32 s22, 0, 0x1c000
	s_add_i32 s23, s30, s27
	v_add_u32_e32 v165, s22, v160
	v_lshl_add_u64 v[226:227], v[226:227], 0, s[6:7]
	s_mov_b32 m0, s23
	ds_read_b128 v[210:213], v165
	ds_read_b128 v[214:217], v165 offset:1024
	ds_read_b128 v[218:221], v165 offset:2048
	ds_read_b128 v[222:225], v165 offset:3072
	global_load_lds_dwordx4 v[226:227], off
	v_lshl_add_u64 v[226:227], v[228:229], 0, s[6:7]
	s_add_i32 m0, s23, 0x2000
	s_nop 0
	global_load_lds_dwordx4 v[226:227], off
	s_barrier
	s_waitcnt lgkmcnt(0)
	s_waitcnt lgkmcnt(0)
	v_mfma_f32_16x16x32_bf16 v[116:119], v[210:213], v[178:181], v[116:119]
	v_mfma_f32_16x16x32_bf16 v[108:111], v[218:221], v[178:181], v[108:111]
	v_mfma_f32_16x16x32_bf16 v[100:103], v[210:213], v[186:189], v[100:103]
	v_mfma_f32_16x16x32_bf16 v[92:95], v[218:221], v[186:189], v[92:95]
	v_mfma_f32_16x16x32_bf16 v[84:87], v[210:213], v[194:197], v[84:87]
	v_mfma_f32_16x16x32_bf16 v[76:79], v[218:221], v[194:197], v[76:79]
	v_mfma_f32_16x16x32_bf16 v[68:71], v[210:213], v[202:205], v[68:71]
	v_mfma_f32_16x16x32_bf16 v[64:67], v[218:221], v[202:205], v[64:67]
	v_mfma_f32_16x16x32_bf16 v[116:119], v[214:217], v[182:185], v[116:119]
	v_mfma_f32_16x16x32_bf16 v[108:111], v[222:225], v[182:185], v[108:111]
	v_mfma_f32_16x16x32_bf16 v[100:103], v[214:217], v[190:193], v[100:103]
	v_mfma_f32_16x16x32_bf16 v[92:95], v[222:225], v[190:193], v[92:95]
	v_mfma_f32_16x16x32_bf16 v[84:87], v[214:217], v[198:201], v[84:87]
	v_mfma_f32_16x16x32_bf16 v[76:79], v[222:225], v[198:201], v[76:79]
	v_mfma_f32_16x16x32_bf16 v[68:71], v[214:217], v[206:209], v[68:71]
	v_mfma_f32_16x16x32_bf16 v[64:67], v[222:225], v[206:209], v[64:67]
	s_mov_b32 m0, s44
	v_lshl_add_u64 v[226:227], v[230:231], 0, s[6:7]
	s_barrier
	ds_read_b128 v[178:181], v163 offset:49152
	ds_read_b128 v[182:185], v163 offset:50176
	ds_read_b128 v[186:189], v163 offset:51200
	ds_read_b128 v[190:193], v163 offset:52224
	ds_read_b128 v[194:197], v163 offset:53248
	ds_read_b128 v[198:201], v163 offset:54272
	ds_read_b128 v[202:205], v163 offset:55296
	ds_read_b128 v[206:209], v163 offset:56320
	global_load_lds_dwordx4 v[226:227], off
	v_lshl_add_u64 v[226:227], v[232:233], 0, s[6:7]
	s_mov_b32 m0, s45
	s_nop 0
	global_load_lds_dwordx4 v[226:227], off
	s_barrier
; #define PG8_STAGE(bufoff, gbase, voff) do { _Pragma("unroll") for (int _i = 0; _i < 2; ++_i) \
;         __builtin_amdgcn_global_load_lds((const unsigned*)((const char*)(gbase) + (voff)[_i]), (PG8_LAS unsigned*)(lds + (bufoff) + ldsw + _i * 8192), 16, 0, 0); } while (0)
; #define PG8_MMA(ai, bj, At, Bt) do { __builtin_amdgcn_s_setprio(1); _Pragma("unroll") for (int m = 0; m < 4; ++m) _Pragma("unroll") for (int n = 0; n < 2; ++n) _Pragma("unroll") for (int k = 0; k < 2; ++k) \
;         acc[ai][bj][m][n] = __builtin_amdgcn_mfma_f32_16x16x32_bf16(Bt[n][k], At[m][k], acc[ai][bj][m][n], 0, 0, 0); __builtin_amdgcn_s_setprio(0); } while (0)
; #define PG8_WAIT_V(n) asm volatile("s_waitcnt vmcnt(" #n ")" ::: "memory")
; #define PG8_WAIT_L(n) asm volatile("s_waitcnt lgkmcnt(" #n ")" ::: "memory")
; #define PG8_BAR __builtin_amdgcn_s_barrier()
; #define PG8_SCHED __builtin_amdgcn_sched_barrier(0)
; template <class Epi, class Sched>
; __device__ __forceinline__ void gemm_phase(PG8_LAS unsigned char* lds, const Gemm g, const Sched& S, const Epi& E) {
;     ...
;             PG8_BAR; PG8_WAIT_L(0); PG8_MMA(1, 0, At, B0); PG8_BAR; PG8_SCHED;
;             PG8_STAGE(PG8_SB(1, 1), b3 + hstep, voffB);
;             PG8_WAIT_V(6); PG8_BAR; PG8_MMA(1, 1, At, B1); PG8_BAR;
	s_waitcnt lgkmcnt(0)
	s_waitcnt lgkmcnt(0)
	v_mfma_f32_16x16x32_bf16 v[60:63], v[148:151], v[178:181], v[60:63]
	v_mfma_f32_16x16x32_bf16 v[56:59], v[170:173], v[178:181], v[56:59]
	v_mfma_f32_16x16x32_bf16 v[52:55], v[148:151], v[186:189], v[52:55]
	v_mfma_f32_16x16x32_bf16 v[44:47], v[170:173], v[186:189], v[44:47]
	v_mfma_f32_16x16x32_bf16 v[36:39], v[148:151], v[194:197], v[36:39]
	v_mfma_f32_16x16x32_bf16 v[28:31], v[170:173], v[194:197], v[28:31]
	v_mfma_f32_16x16x32_bf16 v[20:23], v[148:151], v[202:205], v[20:23]
	v_mfma_f32_16x16x32_bf16 v[12:15], v[170:173], v[202:205], v[12:15]
	v_mfma_f32_16x16x32_bf16 v[60:63], v[166:169], v[182:185], v[60:63]
	v_mfma_f32_16x16x32_bf16 v[56:59], v[174:177], v[182:185], v[56:59]
	v_mfma_f32_16x16x32_bf16 v[52:55], v[166:169], v[190:193], v[52:55]
	v_mfma_f32_16x16x32_bf16 v[44:47], v[174:177], v[190:193], v[44:47]
	v_mfma_f32_16x16x32_bf16 v[36:39], v[166:169], v[198:201], v[36:39]
	v_mfma_f32_16x16x32_bf16 v[28:31], v[174:177], v[198:201], v[28:31]
	v_mfma_f32_16x16x32_bf16 v[20:23], v[166:169], v[206:209], v[20:23]
	v_mfma_f32_16x16x32_bf16 v[12:15], v[174:177], v[206:209], v[12:15]
	s_barrier
	s_add_u32 s20, s20, 0x80080
	s_addc_u32 s21, s21, 0
	s_add_i32 s22, s22, s27
	v_lshl_add_u64 v[148:149], s[20:21], 0, v[130:131]
	s_mov_b32 m0, s22
	s_nop 0
	global_load_lds_dwordx4 v[148:149], off
	v_lshl_add_u64 v[148:149], s[20:21], 0, v[134:135]
	s_add_i32 m0, s22, 0x2000
	s_nop 0
	global_load_lds_dwordx4 v[148:149], off
	s_waitcnt vmcnt(6)
	s_barrier
	v_mfma_f32_16x16x32_bf16 v[48:51], v[210:213], v[178:181], v[48:51]
	v_mfma_f32_16x16x32_bf16 v[40:43], v[218:221], v[178:181], v[40:43]
	v_mfma_f32_16x16x32_bf16 v[32:35], v[210:213], v[186:189], v[32:35]
	v_mfma_f32_16x16x32_bf16 v[24:27], v[218:221], v[186:189], v[24:27]
	v_mfma_f32_16x16x32_bf16 v[16:19], v[210:213], v[194:197], v[16:19]
	v_mfma_f32_16x16x32_bf16 v[8:11], v[218:221], v[194:197], v[8:11]
	v_mfma_f32_16x16x32_bf16 v[4:7], v[210:213], v[202:205], v[4:7]
	v_mfma_f32_16x16x32_bf16 v[0:3], v[218:221], v[202:205], v[0:3]
	v_mfma_f32_16x16x32_bf16 v[48:51], v[214:217], v[182:185], v[48:51]
	v_mfma_f32_16x16x32_bf16 v[40:43], v[222:225], v[182:185], v[40:43]
	v_mfma_f32_16x16x32_bf16 v[32:35], v[214:217], v[190:193], v[32:35]
	v_mfma_f32_16x16x32_bf16 v[24:27], v[222:225], v[190:193], v[24:27]
	v_mfma_f32_16x16x32_bf16 v[16:19], v[214:217], v[198:201], v[16:19]
	v_mfma_f32_16x16x32_bf16 v[8:11], v[222:225], v[198:201], v[8:11]
	v_mfma_f32_16x16x32_bf16 v[4:7], v[214:217], v[206:209], v[4:7]
	v_mfma_f32_16x16x32_bf16 v[0:3], v[222:225], v[206:209], v[0:3]
	s_add_i32 s55, s55, 2
	s_add_u32 s18, s18, 0x100
	s_addc_u32 s19, s19, 0
	s_add_u32 s53, s53, 0x100
	s_addc_u32 s54, s54, 0
	s_cmp_gt_u32 s55, 29
	s_barrier
	s_cbranch_scc0 .LBB0_872
; __device__ __forceinline__ uint4 pk8(f32x4 a, f32x4 b) { return make_uint4(cvt_pk_bf16(a[0], a[1]), cvt_pk_bf16(a[2], a[3]), cvt_pk_bf16(b[0], b[1]), cvt_pk_bf16(b[2], b[3])); }
;     __device__ __forceinline__ void operator()(AccRef acc, const Unit& u, int wr, int wc, int fr, int fq) const {
;         const int pi = u.pn / tpp; bf16_t* base = pi == 0 ? pl[0] : (pi == 1 ? pl[1] : (pi == 2 ? pl[2] : pl[3]));
;         const int cbase = (u.pn - pi * tpp) * 256 + wc * 32 + 8 * fq;
; #pragma unroll
;         for (int ai = 0; ai < 2; ++ai)
; #pragma unroll
;             for (int m = 0; m < 4; ++m) {
;                 const int r = u.pm * 256 + ai * 128 + wr * 64 + m * 16 + fr;
;                 float s = 1.f;
;                 if (SCALE == 1) s = rs[r];
;                 if (SCALE == 2) s = rsqrtf(rs[r] * (1.f / D) + EPS);
;                 bf16_t* rowp = base + (size_t)r * ldc + cbase;
; #pragma unroll
;                 for (int bj = 0; bj < 2; ++bj) *(uint4*)(rowp + bj * 128) = pk8(acc[ai][bj][m][0] * s, acc[ai][bj][m][1] * s);
	s_mul_hi_i32 s9, s50, 0x10624dd3
	s_lshr_b32 s11, s9, 31
	s_lshr_b32 s9, s9, 6
	s_add_i32 s9, s9, s11
	s_mulk_i32 s9, 0x3e8
	s_sub_i32 s9, s50, s9
	v_lshl_or_b32 v148, s9, 8, v161
	v_lshl_add_u32 v150, s16, 8, v159
	v_ashrrev_i32_e32 v149, 31, v148
	v_ashrrev_i32_e32 v151, 31, v150
	v_lshl_add_u64 v[148:149], v[148:149], 1, s[40:41]
	v_lshlrev_b64 v[166:167], 12, v[150:151]
	v_lshl_add_u64 v[166:167], v[148:149], 0, v[166:167]
	v_cvt_pk_bf16_f32 v124, v124, v125
	v_cvt_pk_bf16_f32 v125, v126, v127
	v_cvt_pk_bf16_f32 v126, v120, v121
	v_cvt_pk_bf16_f32 v127, v122, v123
	global_store_dwordx4 v[166:167], v[124:127], off
	v_cvt_pk_bf16_f32 v116, v116, v117
	v_cvt_pk_bf16_f32 v117, v118, v119
	v_cvt_pk_bf16_f32 v118, v108, v109
	v_or_b32_e32 v108, 16, v150
	v_ashrrev_i32_e32 v109, 31, v108
	v_lshlrev_b64 v[108:109], 12, v[108:109]
	v_cvt_pk_bf16_f32 v119, v110, v111
	global_store_dwordx4 v[166:167], v[116:119], off offset:256
	s_and_b64 vcc, exec, s[4:5]
	s_mov_b32 s50, s8
	v_lshl_add_u64 v[116:117], v[148:149], 0, v[108:109]
	v_cvt_pk_bf16_f32 v108, v112, v113
	v_cvt_pk_bf16_f32 v109, v114, v115
	v_cvt_pk_bf16_f32 v110, v104, v105
	v_cvt_pk_bf16_f32 v111, v106, v107
	global_store_dwordx4 v[116:117], v[108:111], off
	v_cvt_pk_bf16_f32 v100, v100, v101
	v_cvt_pk_bf16_f32 v101, v102, v103
	v_cvt_pk_bf16_f32 v102, v92, v93
	v_or_b32_e32 v92, 32, v150
	v_ashrrev_i32_e32 v93, 31, v92
	v_lshlrev_b64 v[92:93], 12, v[92:93]
	v_cvt_pk_bf16_f32 v103, v94, v95
	global_store_dwordx4 v[116:117], v[100:103], off offset:256
	s_mov_b32 s16, s10
	s_mov_b64 s[20:21], s[14:15]
	v_lshl_add_u64 v[100:101], v[148:149], 0, v[92:93]
	v_cvt_pk_bf16_f32 v92, v96, v97
	v_cvt_pk_bf16_f32 v93, v98, v99
	v_cvt_pk_bf16_f32 v94, v88, v89
	v_cvt_pk_bf16_f32 v95, v90, v91
	global_store_dwordx4 v[100:101], v[92:95], off
	v_cvt_pk_bf16_f32 v84, v84, v85
	v_cvt_pk_bf16_f32 v85, v86, v87
	v_cvt_pk_bf16_f32 v86, v76, v77
	v_or_b32_e32 v76, 48, v150
	v_ashrrev_i32_e32 v77, 31, v76
	v_lshlrev_b64 v[76:77], 12, v[76:77]
	v_cvt_pk_bf16_f32 v87, v78, v79
	global_store_dwordx4 v[100:101], v[84:87], off offset:256
	s_mov_b64 s[18:19], s[12:13]
	s_nop 0
	v_lshl_add_u64 v[84:85], v[148:149], 0, v[76:77]
	v_cvt_pk_bf16_f32 v76, v80, v81
	v_cvt_pk_bf16_f32 v77, v82, v83
	v_cvt_pk_bf16_f32 v78, v72, v73
	v_cvt_pk_bf16_f32 v79, v74, v75
	global_store_dwordx4 v[84:85], v[76:79], off
	v_cvt_pk_bf16_f32 v68, v68, v69
	v_cvt_pk_bf16_f32 v69, v70, v71
	v_cvt_pk_bf16_f32 v70, v64, v65
	v_add_u32_e32 v64, 0x80, v150
	v_ashrrev_i32_e32 v65, 31, v64
	v_lshlrev_b64 v[64:65], 12, v[64:65]
	v_lshl_add_u64 v[64:65], v[148:149], 0, v[64:65]
	v_cvt_pk_bf16_f32 v71, v66, v67
	global_store_dwordx4 v[84:85], v[68:71], off offset:256
	v_cvt_pk_bf16_f32 v60, v60, v61
	v_cvt_pk_bf16_f32 v61, v62, v63
	v_cvt_pk_bf16_f32 v62, v56, v57
	v_cvt_pk_bf16_f32 v63, v58, v59
	global_store_dwordx4 v[64:65], v[60:63], off
	v_cvt_pk_bf16_f32 v48, v48, v49
	v_cvt_pk_bf16_f32 v49, v50, v51
	v_cvt_pk_bf16_f32 v50, v40, v41
	v_add_u32_e32 v40, 0x90, v150
	v_ashrrev_i32_e32 v41, 31, v40
	v_lshlrev_b64 v[40:41], 12, v[40:41]
	v_cvt_pk_bf16_f32 v51, v42, v43
	global_store_dwordx4 v[64:65], v[48:51], off offset:256
	s_nop 1
	v_lshl_add_u64 v[48:49], v[148:149], 0, v[40:41]
	v_cvt_pk_bf16_f32 v40, v52, v53
	v_cvt_pk_bf16_f32 v41, v54, v55
	v_cvt_pk_bf16_f32 v42, v44, v45
	v_cvt_pk_bf16_f32 v43, v46, v47
	global_store_dwordx4 v[48:49], v[40:43], off
	v_cvt_pk_bf16_f32 v32, v32, v33
	v_cvt_pk_bf16_f32 v33, v34, v35
	v_cvt_pk_bf16_f32 v34, v24, v25
	v_add_u32_e32 v24, 0xa0, v150
	v_ashrrev_i32_e32 v25, 31, v24
	v_lshlrev_b64 v[24:25], 12, v[24:25]
	v_cvt_pk_bf16_f32 v35, v26, v27
	global_store_dwordx4 v[48:49], v[32:35], off offset:256
	s_nop 1
	v_lshl_add_u64 v[32:33], v[148:149], 0, v[24:25]
	v_cvt_pk_bf16_f32 v24, v36, v37
	v_cvt_pk_bf16_f32 v25, v38, v39
	v_cvt_pk_bf16_f32 v26, v28, v29
	v_cvt_pk_bf16_f32 v27, v30, v31
	global_store_dwordx4 v[32:33], v[24:27], off
	v_cvt_pk_bf16_f32 v16, v16, v17
	v_cvt_pk_bf16_f32 v17, v18, v19
	v_cvt_pk_bf16_f32 v18, v8, v9
	v_add_u32_e32 v8, 0xb0, v150
	v_ashrrev_i32_e32 v9, 31, v8
	v_lshlrev_b64 v[8:9], 12, v[8:9]
	v_cvt_pk_bf16_f32 v19, v10, v11
	global_store_dwordx4 v[32:33], v[16:19], off offset:256
	s_nop 1
	v_lshl_add_u64 v[16:17], v[148:149], 0, v[8:9]
	v_cvt_pk_bf16_f32 v8, v20, v21
	v_cvt_pk_bf16_f32 v9, v22, v23
	v_cvt_pk_bf16_f32 v10, v12, v13
	v_cvt_pk_bf16_f32 v11, v14, v15
	global_store_dwordx4 v[16:17], v[8:11], off
	v_cvt_pk_bf16_f32 v4, v4, v5
	v_cvt_pk_bf16_f32 v5, v6, v7
	v_cvt_pk_bf16_f32 v6, v0, v1
	v_cvt_pk_bf16_f32 v7, v2, v3
	global_store_dwordx4 v[16:17], v[4:7], off offset:256
	s_cbranch_vccz .LBB0_865
	s_waitcnt vmcnt(0)
	s_cmpk_gt_u32 s3, 0xff
	s_cbranch_scc1 .LBB0_876
	s_barrier

; #define PG8_STAGE(bufoff, gbase, voff) do { _Pragma("unroll") for (int _i = 0; _i < 2; ++_i) \
;         __builtin_amdgcn_global_load_lds((const unsigned*)((const char*)(gbase) + (voff)[_i]), (PG8_LAS unsigned*)(lds + (bufoff) + ldsw + _i * 8192), 16, 0, 0); } while (0)
; #define PG8_LDA(dst, b, h) do { _Pragma("unroll") for (int m = 0; m < 4; ++m) _Pragma("unroll") for (int k = 0; k < 2; ++k) dst[m][k] = *(const PG8_LAS bf16x8*)(lds + PG8_SA(b, h) + aoff + m * 2048 + k * 1024); } while (0)
; #define PG8_LDB(dst, b, h) do { _Pragma("unroll") for (int n = 0; n < 2; ++n) _Pragma("unroll") for (int k = 0; k < 2; ++k) dst[n][k] = *(const PG8_LAS bf16x8*)(lds + PG8_SB(b, h) + boff + n * 2048 + k * 1024); } while (0)
; #define PG8_MMA(ai, bj, At, Bt) do { __builtin_amdgcn_s_setprio(1); _Pragma("unroll") for (int m = 0; m < 4; ++m) _Pragma("unroll") for (int n = 0; n < 2; ++n) _Pragma("unroll") for (int k = 0; k < 2; ++k) \
;         acc[ai][bj][m][n] = __builtin_amdgcn_mfma_f32_16x16x32_bf16(Bt[n][k], At[m][k], acc[ai][bj][m][n], 0, 0, 0); __builtin_amdgcn_s_setprio(0); } while (0)
; #define PG8_WAIT_L(n) asm volatile("s_waitcnt lgkmcnt(" #n ")" ::: "memory")
; #define PG8_BAR __builtin_amdgcn_s_barrier()
; #define PG8_SCHED __builtin_amdgcn_sched_barrier(0)
; template <class Epi, class Sched>
; __device__ __forceinline__ void gemm_phase(PG8_LAS unsigned char* lds, const Gemm g, const Sched& S, const Epi& E) {
;     ...
;             const bool last = (t == nt - 2);
;             const char* a1 = cA + (size_t)(t + 1) * kstep;
;             const char* a2 = last ? nA : cA + (size_t)(t + 2) * kstep; const char* b2 = last ? nB : cB + (size_t)(t + 2) * kstep;
;             const char* a3 = a2 + kstep; const char* b3 = b2 + kstep;
;             if (last && has_next) S.a_ready(nxt);
;             PG8_LDB(B0, 0, 0); PG8_SCHED; PG8_LDA(At, 0, 0); PG8_STAGE(PG8_SA(1, 1), a1 + hstep, voffA);
;             PG8_WAIT_L(8); PG8_BAR; PG8_WAIT_L(0); PG8_MMA(0, 0, At, B0); PG8_BAR; PG8_SCHED;
;             PG8_LDB(B1, 0, 1); PG8_STAGE(PG8_SB(0, 0), b2, voffB);
;             PG8_BAR; PG8_WAIT_L(0); PG8_MMA(0, 1, At, B1); PG8_BAR;
;             PG8_LDA(At, 0, 1); PG8_STAGE(PG8_SA(0, 0), a2, voffA);
;             PG8_BAR; PG8_WAIT_L(0); PG8_MMA(1, 0, At, B0); PG8_BAR; PG8_SCHED;
.LBB0_892:
	s_add_u32 s25, s18, s24
	s_addc_u32 s30, s19, 0
	s_add_u32 s28, s25, 0x100
	s_addc_u32 s29, s30, 0
	s_and_b64 s[26:27], s[22:23], exec
	s_cselect_b32 s29, s9, s29
	s_cselect_b32 s28, s63, s28
	s_add_u32 s24, s16, s24
	s_addc_u32 s26, s17, 0
	s_add_u32 s24, s24, 0x100
	s_addc_u32 s26, s26, 0
	s_and_b64 s[22:23], s[22:23], exec
	s_cselect_b32 s43, s7, s26
	s_cselect_b32 s42, s64, s24
	s_add_u32 s44, s25, 0x10080
	s_addc_u32 s45, s30, 0
	s_add_i32 s31, s60, s51
	s_add_i32 m0, s15, 0xc000
	s_add_i32 s30, s15, 0xe000
	s_add_i32 s73, s31, 0x2000
	s_add_u32 s26, s42, 0x10000
	s_addc_u32 s27, s43, 0
	s_add_i32 s70, s61, s51
	ds_read_b128 v[140:143], v149
	ds_read_b128 v[152:155], v149 offset:1024
	ds_read_b128 v[156:159], v149 offset:2048
	ds_read_b128 v[160:163], v149 offset:3072
	s_add_i32 s69, s70, 0x2000
	s_add_i32 s68, 0, 0x18000
	s_add_u32 s24, s28, 0x10000
	s_addc_u32 s25, s29, 0
	s_add_i32 s67, s68, s51
	s_add_i32 s66, 0, 0x1c000
	s_add_i32 s65, s67, 0x2000
	s_add_u32 s22, s42, 0x10080
	s_addc_u32 s23, s43, 0
	s_add_i32 s72, s66, s51
	s_add_i32 s71, s72, 0x2000
	v_lshl_add_u64 v[196:197], s[44:45], 0, v[128:129]
	ds_read_b128 v[164:167], v150
	ds_read_b128 v[168:171], v150 offset:1024
	ds_read_b128 v[172:175], v150 offset:2048
	ds_read_b128 v[176:179], v150 offset:3072
	ds_read_b128 v[180:183], v150 offset:4096
	ds_read_b128 v[184:187], v150 offset:5120
	ds_read_b128 v[188:191], v150 offset:6144
	ds_read_b128 v[192:195], v150 offset:7168
	global_load_lds_dwordx4 v[196:197], off
	v_lshl_add_u64 v[196:197], s[44:45], 0, v[132:133]
	s_mov_b32 m0, s30
	s_nop 0
	global_load_lds_dwordx4 v[196:197], off
	s_waitcnt lgkmcnt(8)
	s_barrier
	s_waitcnt lgkmcnt(0)
	s_waitcnt lgkmcnt(0)
	v_mfma_f32_16x16x32_bf16 v[124:127], v[140:143], v[164:167], v[124:127]
	v_mfma_f32_16x16x32_bf16 v[120:123], v[156:159], v[164:167], v[120:123]
	v_mfma_f32_16x16x32_bf16 v[116:119], v[140:143], v[172:175], v[116:119]
	v_mfma_f32_16x16x32_bf16 v[108:111], v[156:159], v[172:175], v[108:111]
	v_mfma_f32_16x16x32_bf16 v[100:103], v[140:143], v[180:183], v[100:103]
	v_mfma_f32_16x16x32_bf16 v[92:95], v[156:159], v[180:183], v[92:95]
	v_mfma_f32_16x16x32_bf16 v[84:87], v[140:143], v[188:191], v[84:87]
	v_mfma_f32_16x16x32_bf16 v[76:79], v[156:159], v[188:191], v[76:79]
	v_mfma_f32_16x16x32_bf16 v[124:127], v[152:155], v[168:171], v[124:127]
	v_mfma_f32_16x16x32_bf16 v[120:123], v[160:163], v[168:171], v[120:123]
	v_mfma_f32_16x16x32_bf16 v[116:119], v[152:155], v[176:179], v[116:119]
	v_mfma_f32_16x16x32_bf16 v[108:111], v[160:163], v[176:179], v[108:111]
	v_mfma_f32_16x16x32_bf16 v[100:103], v[152:155], v[184:187], v[100:103]
	v_mfma_f32_16x16x32_bf16 v[92:95], v[160:163], v[184:187], v[92:95]
	v_mfma_f32_16x16x32_bf16 v[84:87], v[152:155], v[192:195], v[84:87]
	v_mfma_f32_16x16x32_bf16 v[76:79], v[160:163], v[192:195], v[76:79]
	s_barrier
	s_mov_b32 m0, s31
	v_lshl_add_u64 v[212:213], s[42:43], 0, v[130:131]
	ds_read_b128 v[196:199], v151
	ds_read_b128 v[200:203], v151 offset:1024
	ds_read_b128 v[204:207], v151 offset:2048
	ds_read_b128 v[208:211], v151 offset:3072
	global_load_lds_dwordx4 v[212:213], off
	v_lshl_add_u64 v[214:215], s[42:43], 0, v[134:135]
	s_mov_b32 m0, s73
	s_nop 0
	global_load_lds_dwordx4 v[214:215], off
	s_barrier
	s_waitcnt lgkmcnt(0)
	s_waitcnt lgkmcnt(0)
	v_mfma_f32_16x16x32_bf16 v[112:115], v[196:199], v[164:167], v[112:115]
	v_mfma_f32_16x16x32_bf16 v[104:107], v[204:207], v[164:167], v[104:107]
	v_mfma_f32_16x16x32_bf16 v[96:99], v[196:199], v[172:175], v[96:99]
	v_mfma_f32_16x16x32_bf16 v[88:91], v[204:207], v[172:175], v[88:91]
	v_mfma_f32_16x16x32_bf16 v[80:83], v[196:199], v[180:183], v[80:83]
	v_mfma_f32_16x16x32_bf16 v[72:75], v[204:207], v[180:183], v[72:75]
	v_mfma_f32_16x16x32_bf16 v[68:71], v[196:199], v[188:191], v[68:71]
	v_mfma_f32_16x16x32_bf16 v[64:67], v[204:207], v[188:191], v[64:67]
	v_mfma_f32_16x16x32_bf16 v[112:115], v[200:203], v[168:171], v[112:115]
	v_mfma_f32_16x16x32_bf16 v[104:107], v[208:211], v[168:171], v[104:107]
	v_mfma_f32_16x16x32_bf16 v[96:99], v[200:203], v[176:179], v[96:99]
	v_mfma_f32_16x16x32_bf16 v[88:91], v[208:211], v[176:179], v[88:91]
	v_mfma_f32_16x16x32_bf16 v[80:83], v[200:203], v[184:187], v[80:83]
	v_mfma_f32_16x16x32_bf16 v[72:75], v[208:211], v[184:187], v[72:75]
	v_mfma_f32_16x16x32_bf16 v[68:71], v[200:203], v[192:195], v[68:71]
	v_mfma_f32_16x16x32_bf16 v[64:67], v[208:211], v[192:195], v[64:67]
	s_mov_b32 m0, s15
	v_lshl_add_u64 v[216:217], s[28:29], 0, v[128:129]
	s_barrier
	ds_read_b128 v[164:167], v150 offset:16384
	ds_read_b128 v[168:171], v150 offset:17408
	ds_read_b128 v[172:175], v150 offset:18432
	ds_read_b128 v[176:179], v150 offset:19456
	ds_read_b128 v[180:183], v150 offset:20480
	ds_read_b128 v[184:187], v150 offset:21504
	ds_read_b128 v[188:191], v150 offset:22528
	ds_read_b128 v[192:195], v150 offset:23552
	global_load_lds_dwordx4 v[216:217], off
	v_lshl_add_u64 v[218:219], s[28:29], 0, v[132:133]
	s_mov_b32 m0, s52
	s_nop 0
	global_load_lds_dwordx4 v[218:219], off
	s_barrier
	s_waitcnt lgkmcnt(0)
	s_waitcnt lgkmcnt(0)
	v_mfma_f32_16x16x32_bf16 v[60:63], v[140:143], v[164:167], v[60:63]
	v_mfma_f32_16x16x32_bf16 v[56:59], v[156:159], v[164:167], v[56:59]
	v_mfma_f32_16x16x32_bf16 v[52:55], v[140:143], v[172:175], v[52:55]
	v_mfma_f32_16x16x32_bf16 v[44:47], v[156:159], v[172:175], v[44:47]
	v_mfma_f32_16x16x32_bf16 v[36:39], v[140:143], v[180:183], v[36:39]
	v_mfma_f32_16x16x32_bf16 v[28:31], v[156:159], v[180:183], v[28:31]
	v_mfma_f32_16x16x32_bf16 v[20:23], v[140:143], v[188:191], v[20:23]
	v_mfma_f32_16x16x32_bf16 v[12:15], v[156:159], v[188:191], v[12:15]
	v_mfma_f32_16x16x32_bf16 v[60:63], v[152:155], v[168:171], v[60:63]
	v_mfma_f32_16x16x32_bf16 v[56:59], v[160:163], v[168:171], v[56:59]
	v_mfma_f32_16x16x32_bf16 v[52:55], v[152:155], v[176:179], v[52:55]
	v_mfma_f32_16x16x32_bf16 v[44:47], v[160:163], v[176:179], v[44:47]
	v_mfma_f32_16x16x32_bf16 v[36:39], v[152:155], v[184:187], v[36:39]
	v_mfma_f32_16x16x32_bf16 v[28:31], v[160:163], v[184:187], v[28:31]
	v_mfma_f32_16x16x32_bf16 v[20:23], v[152:155], v[192:195], v[20:23]
	v_mfma_f32_16x16x32_bf16 v[12:15], v[160:163], v[192:195], v[12:15]
	s_barrier
; #define PG8_STAGE(bufoff, gbase, voff) do { _Pragma("unroll") for (int _i = 0; _i < 2; ++_i) \
;         __builtin_amdgcn_global_load_lds((const unsigned*)((const char*)(gbase) + (voff)[_i]), (PG8_LAS unsigned*)(lds + (bufoff) + ldsw + _i * 8192), 16, 0, 0); } while (0)
; #define PG8_LDA(dst, b, h) do { _Pragma("unroll") for (int m = 0; m < 4; ++m) _Pragma("unroll") for (int k = 0; k < 2; ++k) dst[m][k] = *(const PG8_LAS bf16x8*)(lds + PG8_SA(b, h) + aoff + m * 2048 + k * 1024); } while (0)
; #define PG8_LDB(dst, b, h) do { _Pragma("unroll") for (int n = 0; n < 2; ++n) _Pragma("unroll") for (int k = 0; k < 2; ++k) dst[n][k] = *(const PG8_LAS bf16x8*)(lds + PG8_SB(b, h) + boff + n * 2048 + k * 1024); } while (0)
; #define PG8_MMA(ai, bj, At, Bt) do { __builtin_amdgcn_s_setprio(1); _Pragma("unroll") for (int m = 0; m < 4; ++m) _Pragma("unroll") for (int n = 0; n < 2; ++n) _Pragma("unroll") for (int k = 0; k < 2; ++k) \
;         acc[ai][bj][m][n] = __builtin_amdgcn_mfma_f32_16x16x32_bf16(Bt[n][k], At[m][k], acc[ai][bj][m][n], 0, 0, 0); __builtin_amdgcn_s_setprio(0); } while (0)
; #define PG8_WAIT_V(n) asm volatile("s_waitcnt vmcnt(" #n ")" ::: "memory")
; #define PG8_WAIT_L(n) asm volatile("s_waitcnt lgkmcnt(" #n ")" ::: "memory")
; #define PG8_BAR __builtin_amdgcn_s_barrier()
; #define PG8_SCHED __builtin_amdgcn_sched_barrier(0)
; template <class Epi, class Sched>
; __device__ __forceinline__ void gemm_phase(PG8_LAS unsigned char* lds, const Gemm g, const Sched& S, const Epi& E) {
;     ...
;             PG8_STAGE(PG8_SB(0, 1), b2 + hstep, voffB);
;             PG8_WAIT_V(6); PG8_BAR; PG8_MMA(1, 1, At, B1); PG8_BAR;
;             PG8_LDB(B0, 1, 0); PG8_SCHED; PG8_LDA(At, 1, 0); PG8_STAGE(PG8_SA(0, 1), a2 + hstep, voffA);
;             PG8_WAIT_L(8); PG8_BAR; PG8_WAIT_L(0); PG8_MMA(0, 0, At, B0); PG8_BAR; PG8_SCHED;
;             PG8_LDB(B1, 1, 1); PG8_STAGE(PG8_SB(1, 0), b3, voffB);
;             PG8_BAR; PG8_WAIT_L(0); PG8_MMA(0, 1, At, B1); PG8_BAR;
;             PG8_LDA(At, 1, 1); PG8_STAGE(PG8_SA(1, 0), a3, voffA);
	s_mov_b32 m0, s70
	v_lshl_add_u64 v[140:141], s[26:27], 0, v[130:131]
	global_load_lds_dwordx4 v[140:141], off
	v_lshl_add_u64 v[140:141], s[26:27], 0, v[134:135]
	s_mov_b32 m0, s69
	s_nop 0
	global_load_lds_dwordx4 v[140:141], off
	s_waitcnt vmcnt(6)
	s_barrier
	v_mfma_f32_16x16x32_bf16 v[48:51], v[196:199], v[164:167], v[48:51]
	v_mfma_f32_16x16x32_bf16 v[40:43], v[204:207], v[164:167], v[40:43]
	v_mfma_f32_16x16x32_bf16 v[32:35], v[196:199], v[172:175], v[32:35]
	v_mfma_f32_16x16x32_bf16 v[24:27], v[204:207], v[172:175], v[24:27]
	v_mfma_f32_16x16x32_bf16 v[16:19], v[196:199], v[180:183], v[16:19]
	v_mfma_f32_16x16x32_bf16 v[8:11], v[204:207], v[180:183], v[8:11]
	v_mfma_f32_16x16x32_bf16 v[4:7], v[196:199], v[188:191], v[4:7]
	v_mfma_f32_16x16x32_bf16 v[0:3], v[204:207], v[188:191], v[0:3]
	v_mfma_f32_16x16x32_bf16 v[48:51], v[200:203], v[168:171], v[48:51]
	v_mfma_f32_16x16x32_bf16 v[40:43], v[208:211], v[168:171], v[40:43]
	v_mfma_f32_16x16x32_bf16 v[32:35], v[200:203], v[176:179], v[32:35]
	v_mfma_f32_16x16x32_bf16 v[24:27], v[208:211], v[176:179], v[24:27]
	v_mfma_f32_16x16x32_bf16 v[16:19], v[200:203], v[184:187], v[16:19]
	v_mfma_f32_16x16x32_bf16 v[8:11], v[208:211], v[184:187], v[8:11]
	v_mfma_f32_16x16x32_bf16 v[4:7], v[200:203], v[192:195], v[4:7]
	v_mfma_f32_16x16x32_bf16 v[0:3], v[208:211], v[192:195], v[0:3]
	v_add_u32_e32 v160, s68, v145
	s_barrier
	ds_read_b128 v[140:143], v160
	ds_read_b128 v[152:155], v160 offset:1024
	ds_read_b128 v[156:159], v160 offset:2048
	ds_read_b128 v[160:163], v160 offset:3072
	s_mov_b32 m0, s53
	v_lshl_add_u64 v[196:197], s[24:25], 0, v[128:129]
	ds_read_b128 v[164:167], v150 offset:32768
	ds_read_b128 v[168:171], v150 offset:33792
	ds_read_b128 v[172:175], v150 offset:34816
	ds_read_b128 v[176:179], v150 offset:35840
	ds_read_b128 v[180:183], v150 offset:36864
	ds_read_b128 v[184:187], v150 offset:37888
	ds_read_b128 v[188:191], v150 offset:38912
	ds_read_b128 v[192:195], v150 offset:39936
	global_load_lds_dwordx4 v[196:197], off
	v_lshl_add_u64 v[196:197], s[24:25], 0, v[132:133]
	s_mov_b32 m0, s54
	s_nop 0
	global_load_lds_dwordx4 v[196:197], off
	s_waitcnt lgkmcnt(8)
	s_barrier
	s_waitcnt lgkmcnt(0)
	s_waitcnt lgkmcnt(0)
	v_mfma_f32_16x16x32_bf16 v[124:127], v[140:143], v[164:167], v[124:127]
	v_mfma_f32_16x16x32_bf16 v[120:123], v[156:159], v[164:167], v[120:123]
	v_mfma_f32_16x16x32_bf16 v[116:119], v[140:143], v[172:175], v[116:119]
	v_mfma_f32_16x16x32_bf16 v[108:111], v[156:159], v[172:175], v[108:111]
	v_mfma_f32_16x16x32_bf16 v[100:103], v[140:143], v[180:183], v[100:103]
	v_mfma_f32_16x16x32_bf16 v[92:95], v[156:159], v[180:183], v[92:95]
	v_mfma_f32_16x16x32_bf16 v[84:87], v[140:143], v[188:191], v[84:87]
	v_mfma_f32_16x16x32_bf16 v[76:79], v[156:159], v[188:191], v[76:79]
	v_mfma_f32_16x16x32_bf16 v[124:127], v[152:155], v[168:171], v[124:127]
	v_mfma_f32_16x16x32_bf16 v[120:123], v[160:163], v[168:171], v[120:123]
	v_mfma_f32_16x16x32_bf16 v[116:119], v[152:155], v[176:179], v[116:119]
	v_mfma_f32_16x16x32_bf16 v[108:111], v[160:163], v[176:179], v[108:111]
	v_mfma_f32_16x16x32_bf16 v[100:103], v[152:155], v[184:187], v[100:103]
	v_mfma_f32_16x16x32_bf16 v[92:95], v[160:163], v[184:187], v[92:95]
	v_mfma_f32_16x16x32_bf16 v[84:87], v[152:155], v[192:195], v[84:87]
	v_mfma_f32_16x16x32_bf16 v[76:79], v[160:163], v[192:195], v[76:79]
	s_barrier
	s_mov_b32 m0, s67
	v_add_u32_e32 v208, s66, v145
	v_lshl_add_u64 v[212:213], v[212:213], 0, s[0:1]
	ds_read_b128 v[196:199], v208
	ds_read_b128 v[200:203], v208 offset:1024
	ds_read_b128 v[204:207], v208 offset:2048
	ds_read_b128 v[208:211], v208 offset:3072
	global_load_lds_dwordx4 v[212:213], off
	v_lshl_add_u64 v[212:213], v[214:215], 0, s[0:1]
	s_mov_b32 m0, s65
	s_nop 0
	global_load_lds_dwordx4 v[212:213], off
	s_barrier
	s_waitcnt lgkmcnt(0)
	s_waitcnt lgkmcnt(0)
	v_mfma_f32_16x16x32_bf16 v[112:115], v[196:199], v[164:167], v[112:115]
	v_mfma_f32_16x16x32_bf16 v[104:107], v[204:207], v[164:167], v[104:107]
	v_mfma_f32_16x16x32_bf16 v[96:99], v[196:199], v[172:175], v[96:99]
	v_mfma_f32_16x16x32_bf16 v[88:91], v[204:207], v[172:175], v[88:91]
	v_mfma_f32_16x16x32_bf16 v[80:83], v[196:199], v[180:183], v[80:83]
	v_mfma_f32_16x16x32_bf16 v[72:75], v[204:207], v[180:183], v[72:75]
	v_mfma_f32_16x16x32_bf16 v[68:71], v[196:199], v[188:191], v[68:71]
	v_mfma_f32_16x16x32_bf16 v[64:67], v[204:207], v[188:191], v[64:67]
	v_mfma_f32_16x16x32_bf16 v[112:115], v[200:203], v[168:171], v[112:115]
	v_mfma_f32_16x16x32_bf16 v[104:107], v[208:211], v[168:171], v[104:107]
	v_mfma_f32_16x16x32_bf16 v[96:99], v[200:203], v[176:179], v[96:99]
	v_mfma_f32_16x16x32_bf16 v[88:91], v[208:211], v[176:179], v[88:91]
	v_mfma_f32_16x16x32_bf16 v[80:83], v[200:203], v[184:187], v[80:83]
	v_mfma_f32_16x16x32_bf16 v[72:75], v[208:211], v[184:187], v[72:75]
	v_mfma_f32_16x16x32_bf16 v[68:71], v[200:203], v[192:195], v[68:71]
	v_mfma_f32_16x16x32_bf16 v[64:67], v[208:211], v[192:195], v[64:67]
	s_mov_b32 m0, s56
	v_lshl_add_u64 v[212:213], v[216:217], 0, s[0:1]
	s_barrier
	ds_read_b128 v[164:167], v150 offset:49152
	ds_read_b128 v[168:171], v150 offset:50176
	ds_read_b128 v[172:175], v150 offset:51200
	ds_read_b128 v[176:179], v150 offset:52224
	ds_read_b128 v[180:183], v150 offset:53248
	ds_read_b128 v[184:187], v150 offset:54272
	ds_read_b128 v[188:191], v150 offset:55296
	ds_read_b128 v[192:195], v150 offset:56320
	global_load_lds_dwordx4 v[212:213], off
	v_lshl_add_u64 v[212:213], v[218:219], 0, s[0:1]
	s_mov_b32 m0, s57
	s_nop 0
	global_load_lds_dwordx4 v[212:213], off
	s_barrier
; #define PG8_STAGE(bufoff, gbase, voff) do { _Pragma("unroll") for (int _i = 0; _i < 2; ++_i) \
;         __builtin_amdgcn_global_load_lds((const unsigned*)((const char*)(gbase) + (voff)[_i]), (PG8_LAS unsigned*)(lds + (bufoff) + ldsw + _i * 8192), 16, 0, 0); } while (0)
; #define PG8_MMA(ai, bj, At, Bt) do { __builtin_amdgcn_s_setprio(1); _Pragma("unroll") for (int m = 0; m < 4; ++m) _Pragma("unroll") for (int n = 0; n < 2; ++n) _Pragma("unroll") for (int k = 0; k < 2; ++k) \
;         acc[ai][bj][m][n] = __builtin_amdgcn_mfma_f32_16x16x32_bf16(Bt[n][k], At[m][k], acc[ai][bj][m][n], 0, 0, 0); __builtin_amdgcn_s_setprio(0); } while (0)
; #define PG8_WAIT_V(n) asm volatile("s_waitcnt vmcnt(" #n ")" ::: "memory")
; #define PG8_WAIT_L(n) asm volatile("s_waitcnt lgkmcnt(" #n ")" ::: "memory")
; #define PG8_BAR __builtin_amdgcn_s_barrier()
; #define PG8_SCHED __builtin_amdgcn_sched_barrier(0)
; template <class Epi, class Sched>
; __device__ __forceinline__ void gemm_phase(PG8_LAS unsigned char* lds, const Gemm g, const Sched& S, const Epi& E) {
;     ...
;             PG8_BAR; PG8_WAIT_L(0); PG8_MMA(1, 0, At, B0); PG8_BAR; PG8_SCHED;
;             PG8_STAGE(PG8_SB(1, 1), b3 + hstep, voffB);
;             PG8_WAIT_V(6); PG8_BAR; PG8_MMA(1, 1, At, B1); PG8_BAR;
	s_waitcnt lgkmcnt(0)
	s_waitcnt lgkmcnt(0)
	v_mfma_f32_16x16x32_bf16 v[60:63], v[140:143], v[164:167], v[60:63]
	v_mfma_f32_16x16x32_bf16 v[56:59], v[156:159], v[164:167], v[56:59]
	v_mfma_f32_16x16x32_bf16 v[52:55], v[140:143], v[172:175], v[52:55]
	v_mfma_f32_16x16x32_bf16 v[44:47], v[156:159], v[172:175], v[44:47]
	v_mfma_f32_16x16x32_bf16 v[36:39], v[140:143], v[180:183], v[36:39]
	v_mfma_f32_16x16x32_bf16 v[28:31], v[156:159], v[180:183], v[28:31]
	v_mfma_f32_16x16x32_bf16 v[20:23], v[140:143], v[188:191], v[20:23]
	v_mfma_f32_16x16x32_bf16 v[12:15], v[156:159], v[188:191], v[12:15]
	v_mfma_f32_16x16x32_bf16 v[60:63], v[152:155], v[168:171], v[60:63]
	v_mfma_f32_16x16x32_bf16 v[56:59], v[160:163], v[168:171], v[56:59]
	v_mfma_f32_16x16x32_bf16 v[52:55], v[152:155], v[176:179], v[52:55]
	v_mfma_f32_16x16x32_bf16 v[44:47], v[160:163], v[176:179], v[44:47]
	v_mfma_f32_16x16x32_bf16 v[36:39], v[152:155], v[184:187], v[36:39]
	v_mfma_f32_16x16x32_bf16 v[28:31], v[160:163], v[184:187], v[28:31]
	v_mfma_f32_16x16x32_bf16 v[20:23], v[152:155], v[192:195], v[20:23]
	v_mfma_f32_16x16x32_bf16 v[12:15], v[160:163], v[192:195], v[12:15]
	s_barrier
	s_mov_b32 m0, s72
	v_lshl_add_u64 v[140:141], s[22:23], 0, v[130:131]
	global_load_lds_dwordx4 v[140:141], off
	v_lshl_add_u64 v[140:141], s[22:23], 0, v[134:135]
	s_mov_b32 m0, s71
	s_nop 0
	global_load_lds_dwordx4 v[140:141], off
	s_waitcnt vmcnt(6)
	s_barrier
	v_mfma_f32_16x16x32_bf16 v[48:51], v[196:199], v[164:167], v[48:51]
	v_mfma_f32_16x16x32_bf16 v[40:43], v[204:207], v[164:167], v[40:43]
	v_mfma_f32_16x16x32_bf16 v[32:35], v[196:199], v[172:175], v[32:35]
	v_mfma_f32_16x16x32_bf16 v[24:27], v[204:207], v[172:175], v[24:27]
	v_mfma_f32_16x16x32_bf16 v[16:19], v[196:199], v[180:183], v[16:19]
	v_mfma_f32_16x16x32_bf16 v[8:11], v[204:207], v[180:183], v[8:11]
	v_mfma_f32_16x16x32_bf16 v[4:7], v[196:199], v[188:191], v[4:7]
	v_mfma_f32_16x16x32_bf16 v[0:3], v[204:207], v[188:191], v[0:3]
	v_mfma_f32_16x16x32_bf16 v[48:51], v[200:203], v[168:171], v[48:51]
	v_mfma_f32_16x16x32_bf16 v[40:43], v[208:211], v[168:171], v[40:43]
	v_mfma_f32_16x16x32_bf16 v[32:35], v[200:203], v[176:179], v[32:35]
	v_mfma_f32_16x16x32_bf16 v[24:27], v[208:211], v[176:179], v[24:27]
	v_mfma_f32_16x16x32_bf16 v[16:19], v[200:203], v[184:187], v[16:19]
	v_mfma_f32_16x16x32_bf16 v[8:11], v[208:211], v[184:187], v[8:11]
	v_mfma_f32_16x16x32_bf16 v[4:7], v[200:203], v[192:195], v[4:7]
	v_mfma_f32_16x16x32_bf16 v[0:3], v[208:211], v[192:195], v[0:3]
	s_movk_i32 s24, 0x100
	s_andn2_b64 vcc, exec, s[20:21]
	s_mov_b64 s[22:23], -1
	s_mov_b64 s[20:21], 0
	s_barrier
	s_cbranch_vccz .LBB0_892
; __device__ __forceinline__ uint4 pk8(f32x4 a, f32x4 b) { return make_uint4(cvt_pk_bf16(a[0], a[1]), cvt_pk_bf16(a[2], a[3]), cvt_pk_bf16(b[0], b[1]), cvt_pk_bf16(b[2], b[3])); }
;     __device__ __forceinline__ void operator()(AccRef acc, const Unit& u, int wr, int wc, int fr, int fq) const {
;         const int pi = u.pn / tpp; bf16_t* base = pi == 0 ? pl[0] : (pi == 1 ? pl[1] : (pi == 2 ? pl[2] : pl[3]));
;         const int cbase = (u.pn - pi * tpp) * 256 + wc * 32 + 8 * fq;
; #pragma unroll
;         for (int ai = 0; ai < 2; ++ai)
; #pragma unroll
;             for (int m = 0; m < 4; ++m) {
;                 const int r = u.pm * 256 + ai * 128 + wr * 64 + m * 16 + fr;
;                 float s = 1.f;
;                 if (SCALE == 1) s = rs[r];
;                 if (SCALE == 2) s = rsqrtf(rs[r] * (1.f / D) + EPS);
;                 bf16_t* rowp = base + (size_t)r * ldc + cbase;
; #pragma unroll
;                 for (int bj = 0; bj < 2; ++bj) *(uint4*)(rowp + bj * 128) = pk8(acc[ai][bj][m][0] * s, acc[ai][bj][m][1] * s);
	s_mul_hi_i32 s7, s62, 0x10624dd3
	s_lshr_b32 s9, s7, 31
	s_lshr_b32 s7, s7, 6
	s_add_i32 s7, s7, s9
	s_mulk_i32 s7, 0x3e8
	s_sub_i32 s7, s62, s7
	v_lshl_or_b32 v140, s7, 8, v147
	v_lshl_add_u32 v142, s14, 8, v148
	v_ashrrev_i32_e32 v141, 31, v140
	v_ashrrev_i32_e32 v143, 31, v142
	v_lshl_add_u64 v[140:141], v[140:141], 1, s[36:37]
	v_lshlrev_b64 v[152:153], 12, v[142:143]
	v_lshl_add_u64 v[152:153], v[140:141], 0, v[152:153]
	v_cvt_pk_bf16_f32 v124, v124, v125
	v_cvt_pk_bf16_f32 v125, v126, v127
	v_cvt_pk_bf16_f32 v126, v120, v121
	v_cvt_pk_bf16_f32 v127, v122, v123
	global_store_dwordx4 v[152:153], v[124:127], off
	v_cvt_pk_bf16_f32 v112, v112, v113
	v_cvt_pk_bf16_f32 v113, v114, v115
	v_cvt_pk_bf16_f32 v114, v104, v105
	v_or_b32_e32 v104, 16, v142
	v_ashrrev_i32_e32 v105, 31, v104
	v_lshlrev_b64 v[104:105], 12, v[104:105]
	v_cvt_pk_bf16_f32 v115, v106, v107
	global_store_dwordx4 v[152:153], v[112:115], off offset:256
	s_and_b64 vcc, exec, s[4:5]
	s_mov_b32 s62, s6
	v_lshl_add_u64 v[112:113], v[140:141], 0, v[104:105]
	v_cvt_pk_bf16_f32 v104, v116, v117
	v_cvt_pk_bf16_f32 v105, v118, v119
	v_cvt_pk_bf16_f32 v106, v108, v109
	v_cvt_pk_bf16_f32 v107, v110, v111
	global_store_dwordx4 v[112:113], v[104:107], off
	v_cvt_pk_bf16_f32 v96, v96, v97
	v_cvt_pk_bf16_f32 v97, v98, v99
	v_cvt_pk_bf16_f32 v98, v88, v89
	v_or_b32_e32 v88, 32, v142
	v_ashrrev_i32_e32 v89, 31, v88
	v_lshlrev_b64 v[88:89], 12, v[88:89]
	v_cvt_pk_bf16_f32 v99, v90, v91
	global_store_dwordx4 v[112:113], v[96:99], off offset:256
	s_mov_b32 s14, s8
	s_mov_b64 s[16:17], s[12:13]
	v_lshl_add_u64 v[96:97], v[140:141], 0, v[88:89]
	v_cvt_pk_bf16_f32 v88, v100, v101
	v_cvt_pk_bf16_f32 v89, v102, v103
	v_cvt_pk_bf16_f32 v90, v92, v93
	v_cvt_pk_bf16_f32 v91, v94, v95
	global_store_dwordx4 v[96:97], v[88:91], off
	v_cvt_pk_bf16_f32 v80, v80, v81
	v_cvt_pk_bf16_f32 v81, v82, v83
	v_cvt_pk_bf16_f32 v82, v72, v73
	v_or_b32_e32 v72, 48, v142
	v_ashrrev_i32_e32 v73, 31, v72
	v_lshlrev_b64 v[72:73], 12, v[72:73]
	v_cvt_pk_bf16_f32 v83, v74, v75
	global_store_dwordx4 v[96:97], v[80:83], off offset:256
	s_mov_b64 s[18:19], s[10:11]
	s_nop 0
	v_lshl_add_u64 v[80:81], v[140:141], 0, v[72:73]
	v_cvt_pk_bf16_f32 v72, v84, v85
	v_cvt_pk_bf16_f32 v73, v86, v87
	v_cvt_pk_bf16_f32 v74, v76, v77
	v_cvt_pk_bf16_f32 v75, v78, v79
	global_store_dwordx4 v[80:81], v[72:75], off
	v_cvt_pk_bf16_f32 v68, v68, v69
	v_cvt_pk_bf16_f32 v69, v70, v71
	v_cvt_pk_bf16_f32 v70, v64, v65
	v_add_u32_e32 v64, 0x80, v142
	v_ashrrev_i32_e32 v65, 31, v64
	v_lshlrev_b64 v[64:65], 12, v[64:65]
	v_lshl_add_u64 v[64:65], v[140:141], 0, v[64:65]
	v_cvt_pk_bf16_f32 v71, v66, v67
	global_store_dwordx4 v[80:81], v[68:71], off offset:256
	v_cvt_pk_bf16_f32 v60, v60, v61
	v_cvt_pk_bf16_f32 v61, v62, v63
	v_cvt_pk_bf16_f32 v62, v56, v57
	v_cvt_pk_bf16_f32 v63, v58, v59
	global_store_dwordx4 v[64:65], v[60:63], off
	v_cvt_pk_bf16_f32 v48, v48, v49
	v_cvt_pk_bf16_f32 v49, v50, v51
	v_cvt_pk_bf16_f32 v50, v40, v41
	v_add_u32_e32 v40, 0x90, v142
	v_ashrrev_i32_e32 v41, 31, v40
	v_lshlrev_b64 v[40:41], 12, v[40:41]
	v_cvt_pk_bf16_f32 v51, v42, v43
	global_store_dwordx4 v[64:65], v[48:51], off offset:256
	s_nop 1
	v_lshl_add_u64 v[48:49], v[140:141], 0, v[40:41]
	v_cvt_pk_bf16_f32 v40, v52, v53
	v_cvt_pk_bf16_f32 v41, v54, v55
	v_cvt_pk_bf16_f32 v42, v44, v45
	v_cvt_pk_bf16_f32 v43, v46, v47
	global_store_dwordx4 v[48:49], v[40:43], off
	v_cvt_pk_bf16_f32 v32, v32, v33
	v_cvt_pk_bf16_f32 v33, v34, v35
	v_cvt_pk_bf16_f32 v34, v24, v25
	v_add_u32_e32 v24, 0xa0, v142
	v_ashrrev_i32_e32 v25, 31, v24
	v_lshlrev_b64 v[24:25], 12, v[24:25]
	v_cvt_pk_bf16_f32 v35, v26, v27
	global_store_dwordx4 v[48:49], v[32:35], off offset:256
	s_nop 1
	v_lshl_add_u64 v[32:33], v[140:141], 0, v[24:25]
	v_cvt_pk_bf16_f32 v24, v36, v37
	v_cvt_pk_bf16_f32 v25, v38, v39
	v_cvt_pk_bf16_f32 v26, v28, v29
	v_cvt_pk_bf16_f32 v27, v30, v31
	global_store_dwordx4 v[32:33], v[24:27], off
	v_cvt_pk_bf16_f32 v16, v16, v17
	v_cvt_pk_bf16_f32 v17, v18, v19
	v_cvt_pk_bf16_f32 v18, v8, v9
	v_add_u32_e32 v8, 0xb0, v142
	v_ashrrev_i32_e32 v9, 31, v8
	v_lshlrev_b64 v[8:9], 12, v[8:9]
	v_cvt_pk_bf16_f32 v19, v10, v11
	global_store_dwordx4 v[32:33], v[16:19], off offset:256
	s_nop 1
	v_lshl_add_u64 v[16:17], v[140:141], 0, v[8:9]
	v_cvt_pk_bf16_f32 v8, v20, v21
	v_cvt_pk_bf16_f32 v9, v22, v23
	v_cvt_pk_bf16_f32 v10, v12, v13
	v_cvt_pk_bf16_f32 v11, v14, v15
	global_store_dwordx4 v[16:17], v[8:11], off
	v_cvt_pk_bf16_f32 v4, v4, v5
	v_cvt_pk_bf16_f32 v5, v6, v7
	v_cvt_pk_bf16_f32 v6, v0, v1
	v_cvt_pk_bf16_f32 v7, v2, v3
	global_store_dwordx4 v[16:17], v[4:7], off offset:256
	s_cbranch_vccz .LBB0_885
	s_waitcnt vmcnt(0)
	s_cmpk_gt_u32 s3, 0xff
	s_cbranch_scc1 .LBB0_896
	s_barrier

; __device__ void phase_peer(const Params& P, unsigned char* smem) {
;     const int tid = threadIdx.x, lane = tid & 63, wid = tid >> 6, l15 = lane & 15, l4 = lane >> 4;
;     float* sv = (float*)(smem + 98304);
;     unsigned char* si = smem + 131072;
;     const bf16_t* QP = (const bf16_t*)(P.ws + O_R3);
;     const bf16_t* SKB = (const bf16_t*)(P.ws + O_SKB);
;     const unsigned char* UB8 = P.ws + O_UB;
;     const unsigned char* VB8 = P.ws + O_VB;
;     bf16_t* H2B = (bf16_t*)(P.ws + O_R1);
;     float* rinv3 = (float*)(P.ws + O_SMALL) + 2 * T;
;     const float* gffn = P.in[I_NFFN];
;     float* WL = (float*)(P.ws + O_UB + 16 * MiB);
;     unsigned short* IDS = (unsigned short*)(P.ws + O_UB + 32 * MiB);
; #pragma unroll 1
;     for (int item0 = blockIdx.x; item0 < T / 32; item0 += 4 * gridDim.x) {
; #pragma unroll 1
;     for (int slot = 0; slot < 4; ++slot) {
;         const int item = item0 + slot * (int)gridDim.x; if (item >= T / 32) break;
;         const int tok0 = item * 32;
;         unsigned short* ids = (unsigned short*)(smem + slot * 24576); float* gts = (float*)(smem + slot * 24576 + 8192);
;         {
;             const int h = wid;
; #pragma unroll 1
;             for (int p = 0; p < (((REPMASK >> 3) & 1) ? 4 : 2); ++p) {
;                 const int hp_ = h * 2 + (p & 1);
;                 const bf16_t* qp_ = QP + (size_t)(tok0 + l15) * D + hp_ * 128 + l4 * 8;
;     ...
;             const int tok = wid + 8 * ti; const size_t gtok = (size_t)tok0 + tok;
;             const bf16_t* hrow = H2B + gtok * D + lane * 32;
;             f32x2 xn2[16]; float ss = 0.f;
; #pragma unroll
;             for (int q = 0; q < 8; ++q) {
;                 const f32x4 v = unpk4(*(const uint2*)(hrow + q * 4)); const f32x4 gv = *(const f32x4*)(gffn + lane * 32 + q * 4);
;                 ss += v[0] * v[0] + v[1] * v[1] + v[2] * v[2] + v[3] * v[3];
;                 xn2[q * 2] = (f32x2){v[0] * gv[0], v[1] * gv[1]}; xn2[q * 2 + 1] = (f32x2){v[2] * gv[2], v[3] * gv[3]};
;             }
;             ss = wave_sum(ss);
;             const float ri = rsqrtf(ss * (1.f / D) + EPS);
;             const int e_lane = ((lane >> 2) & 1) + 2 * ((lane >> 3) & 1) + 4 * ((lane >> 4) & 1) + 8 * (lane >> 5);
.LBB0_951:
	s_setprio 0
	s_add_u32 s26, s90, 0x5840000
	s_addc_u32 s27, s91, 0
	s_cmp_lt_i32 s92, 9
	s_cselect_b64 s[0:1], -1, 0
	s_cmp_gt_i32 s93, 8
	s_cselect_b64 s[4:5], -1, 0
	s_and_b64 s[0:1], s[0:1], s[4:5]
	s_andn2_b64 vcc, exec, s[0:1]
	s_cbranch_vccnz .LBB0_1043
	s_cmpk_gt_i32 s2, 0x3ff
	s_cbranch_scc1 .LBB0_989
	v_readlane_b32 s0, v248, 1
	v_readlane_b32 s1, v248, 2
	s_load_dword s0, s[0:1], 0x10
	v_and_b32_e32 v48, 48, v144
	v_mov_b32_e32 v49, 0
	v_lshl_add_u64 v[0:1], s[90:91], 0, v[48:49]
	v_and_b32_e32 v107, 63, v144
	s_waitcnt lgkmcnt(0)
	s_lshr_b32 s0, s0, 16
	s_cmp_lg_u32 s0, 0
	s_cselect_b64 s[0:1], -1, 0
	s_cmp_lg_u64 s[0:1], 0
	s_mov_b64 s[0:1], 0x4500000
	v_bfe_u32 v2, v144, 4, 2
	v_lshl_add_u64 v[52:53], v[0:1], 0, s[0:1]
	v_readlane_b32 s8, v248, 22
	v_lshrrev_b32_e32 v0, 2, v144
	v_lshl_add_u64 v[50:51], s[40:41], 0, v[48:49]
	v_lshlrev_b32_e32 v109, 2, v2
	v_lshlrev_b32_e32 v48, 6, v107
	v_readlane_b32 s9, v248, 23
	v_and_b32_e32 v2, 11, v0
	v_and_b32_e32 v0, 32, v144
	v_lshl_add_u64 v[64:65], s[34:35], 0, v[48:49]
	v_lshlrev_b32_e32 v48, 7, v107
	v_readlane_b32 s10, v248, 24
	v_readlane_b32 s11, v248, 25
	v_cmp_eq_u32_e64 s[8:9], 0, v0
	v_and_b32_e32 v0, 16, v144
	v_readlane_b32 s12, v248, 26
	v_readlane_b32 s13, v248, 27
	v_lshl_add_u64 v[54:55], s[10:11], 0, v[48:49]
	v_cmp_eq_u32_e64 s[10:11], 0, v0
	v_and_b32_e32 v0, 8, v144
	v_readlane_b32 s14, v248, 28
	v_readlane_b32 s15, v248, 29
	v_cmp_eq_u32_e64 s[12:13], 0, v0
	v_and_b32_e32 v0, 4, v144
	v_readlane_b32 s16, v248, 30
	v_readlane_b32 s17, v248, 31
	v_cmp_eq_u32_e64 s[14:15], 0, v0
	v_and_b32_e32 v0, 3, v144
	v_and_b32_e32 v106, 15, v144
	s_movk_i32 s0, 0x100
	v_cmp_eq_u32_e64 s[16:17], 0, v0
	v_lshlrev_b32_e32 v0, 5, v146
	v_bfe_u32 v4, v107, 4, 1
	s_addc_u32 s3, s94, 0
	v_cmp_gt_u32_e64 s[6:7], s0, v144
	s_add_i32 s0, 0, 0x18000
	v_lshl_add_u32 v149, v106, 8, v0
	v_lshlrev_b32_e32 v0, 9, v146
	v_lshlrev_b32_e32 v1, 4, v4
	v_lshlrev_b32_e32 v5, 2, v2
	v_lshlrev_b32_e32 v110, 5, v144
	v_lshl_add_u32 v111, v144, 7, s0
	s_add_i32 s0, 0, 0x20000
	v_lshlrev_b32_e32 v48, 4, v107
	v_or3_b32 v0, v0, v1, v5
	v_and_or_b32 v5, v109, 4, v2
	v_add_u32_e32 v113, s0, v110
	v_lshl_add_u64 v[56:57], s[90:91], 0, v[48:49]
	s_mov_b64 s[0:1], 0x1e000000
	v_add_u32_e32 v0, 0, v0
	v_lshlrev_b32_e32 v48, 2, v5
	v_lshl_add_u64 v[58:59], v[56:57], 0, s[0:1]
	v_add_u32_e32 v151, 0x2000, v0
	v_lshl_add_u64 v[0:1], s[90:91], 0, v[48:49]
	s_mov_b64 s[0:1], 0x1f000000
	v_lshlrev_b32_e32 v48, 1, v5
	v_lshl_add_u64 v[60:61], v[0:1], 0, s[0:1]
	v_lshl_add_u64 v[0:1], s[90:91], 0, v[48:49]
	s_mov_b64 s[0:1], 0x20000000
	v_lshl_add_u64 v[62:63], v[0:1], 0, s[0:1]
	v_lshlrev_b32_e32 v0, 8, v146
	v_lshlrev_b32_e32 v1, 3, v4
	v_lshlrev_b32_e32 v2, 1, v2
	v_or3_b32 v1, v0, v1, v2
	v_add_u32_e32 v153, 0, v0
	v_lshlrev_b32_e32 v3, 7, v106
	s_lshl_b32 s28, s2, 5
	v_mbcnt_lo_u32_b32 v0, -1, 0
	s_mov_b32 s43, 0
	v_lshlrev_b32_e32 v108, 1, v146
	v_cmp_gt_u32_e64 s[4:5], 16, v107
	v_lshlrev_b32_e32 v114, 6, v144
	v_or_b32_e32 v115, 1, v109
	v_or_b32_e32 v116, 2, v109
	v_or_b32_e32 v117, 3, v109
	v_or_b32_e32 v118, 16, v109
	v_or_b32_e32 v119, 17, v109
	v_or_b32_e32 v120, 18, v109
	v_or_b32_e32 v121, 19, v109
	v_or_b32_e32 v122, 32, v109
	v_or_b32_e32 v123, 33, v109
	v_or_b32_e32 v124, 34, v109
	v_or_b32_e32 v125, 35, v109
	v_or_b32_e32 v126, 48, v109
	v_or_b32_e32 v127, 49, v109
	v_or_b32_e32 v128, 50, v109
	v_or_b32_e32 v129, 51, v109
	v_or_b32_e32 v130, 64, v109
	v_or_b32_e32 v131, 0x41, v109
	v_or_b32_e32 v132, 0x42, v109
	v_or_b32_e32 v133, 0x43, v109
	v_or_b32_e32 v134, 0x50, v109
	v_or_b32_e32 v135, 0x51, v109
	v_or_b32_e32 v136, 0x52, v109
	v_or_b32_e32 v137, 0x53, v109
	v_or_b32_e32 v138, 0x60, v109
	v_or_b32_e32 v139, 0x61, v109
	v_or_b32_e32 v140, 0x62, v109
	v_or_b32_e32 v141, 0x63, v109
	v_or_b32_e32 v142, 0x70, v109
	v_or_b32_e32 v143, 0x71, v109
	v_or_b32_e32 v145, 0x72, v109
	v_or_b32_e32 v148, 0x73, v109
	s_movk_i32 s29, 0x1000
	v_add_u32_e32 v150, 0x1000, v149
	s_lshl_b32 s48, s3, 2
	s_movk_i32 s49, 0x2000
	v_mov_b32_e32 v147, v49
	s_lshl_b32 s50, s3, 7
	s_lshl_b32 s51, s3, 5
	v_add_u32_e32 v152, 0, v1
	v_lshlrev_b32_e32 v154, 1, v3
	s_movk_i32 s52, 0x3000
	s_movk_i32 s53, 0x4000
	s_movk_i32 s54, 0x5000
	s_movk_i32 s55, 0x6000
	s_movk_i32 s56, 0x7000
	s_brev_b32 s57, 1
	s_movk_i32 s58, 0xff80
	s_movk_i32 s59, 0x7f
	s_movk_i32 s60, 0xff00
	s_mov_b32 s61, 0xf149f2ca
	v_mov_b32_e32 v155, 0x358637bd
	s_mov_b32 s62, 0x800000
	s_mov_b32 s63, 0x42c00000
	s_mov_b32 s64, 0x378e98ab
	s_mov_b32 s65, 0x3b7cd369
	s_mov_b32 s66, 0xbcc618b2
	s_mov_b32 s67, 0x3dda74e4
	s_mov_b32 s68, 0x3f228afd
	s_mov_b32 s69, 0x3e03c728
	s_mov_b32 s70, 0xbfb8aa3b
	s_mov_b32 s71, 0x42ce8ed0
	s_mov_b32 s72, 0xc2b17218
	v_mov_b32_e32 v156, 0x3ba10414
	s_brev_b32 s73, -2
	s_mov_b64 s[38:39], 0x1000
	s_mov_b64 s[44:45], 0x800
	v_mbcnt_hi_u32_b32 v112, -1, v0
	v_bfrev_b32_e32 v157, 1
	v_mov_b32_e32 v158, 0xb9c68948
	v_mov_b32_e32 v159, 0x7f800000
	s_mov_b32 s74, s28
	s_mov_b32 s75, s2
	v_readlane_b32 s18, v248, 32
	v_readlane_b32 s19, v248, 33
	v_readlane_b32 s20, v248, 34
	v_readlane_b32 s21, v248, 35
	v_readlane_b32 s22, v248, 36
	v_readlane_b32 s23, v248, 37
	s_branch .LBB0_955

; #define PG8_STAGE(bufoff, gbase, voff) do { _Pragma("unroll") for (int _i = 0; _i < 2; ++_i) \
;         __builtin_amdgcn_global_load_lds((const unsigned*)((const char*)(gbase) + (voff)[_i]), (PG8_LAS unsigned*)(lds + (bufoff) + ldsw + _i * 8192), 16, 0, 0); } while (0)
; #define PG8_LDA(dst, b, h) do { _Pragma("unroll") for (int m = 0; m < 4; ++m) _Pragma("unroll") for (int k = 0; k < 2; ++k) dst[m][k] = *(const PG8_LAS bf16x8*)(lds + PG8_SA(b, h) + aoff + m * 2048 + k * 1024); } while (0)
; #define PG8_LDB(dst, b, h) do { _Pragma("unroll") for (int n = 0; n < 2; ++n) _Pragma("unroll") for (int k = 0; k < 2; ++k) dst[n][k] = *(const PG8_LAS bf16x8*)(lds + PG8_SB(b, h) + boff + n * 2048 + k * 1024); } while (0)
; #define PG8_MMA(ai, bj, At, Bt) do { __builtin_amdgcn_s_setprio(1); _Pragma("unroll") for (int m = 0; m < 4; ++m) _Pragma("unroll") for (int n = 0; n < 2; ++n) _Pragma("unroll") for (int k = 0; k < 2; ++k) \
;         acc[ai][bj][m][n] = __builtin_amdgcn_mfma_f32_16x16x32_bf16(Bt[n][k], At[m][k], acc[ai][bj][m][n], 0, 0, 0); __builtin_amdgcn_s_setprio(0); } while (0)
; #define PG8_WAIT_L(n) asm volatile("s_waitcnt lgkmcnt(" #n ")" ::: "memory")
; #define PG8_BAR __builtin_amdgcn_s_barrier()
; #define PG8_SCHED __builtin_amdgcn_sched_barrier(0)
; template <class Epi, class Sched>
; __device__ __forceinline__ void gemm_phase(PG8_LAS unsigned char* lds, const Gemm g, const Sched& S, const Epi& E) {
;     ...
;             const bool last = (t == nt - 2);
;             const char* a1 = cA + (size_t)(t + 1) * kstep;
;             const char* a2 = last ? nA : cA + (size_t)(t + 2) * kstep; const char* b2 = last ? nB : cB + (size_t)(t + 2) * kstep;
;             const char* a3 = a2 + kstep; const char* b3 = b2 + kstep;
;             if (last && has_next) S.a_ready(nxt);
;             PG8_LDB(B0, 0, 0); PG8_SCHED; PG8_LDA(At, 0, 0); PG8_STAGE(PG8_SA(1, 1), a1 + hstep, voffA);
;             PG8_WAIT_L(8); PG8_BAR; PG8_WAIT_L(0); PG8_MMA(0, 0, At, B0); PG8_BAR; PG8_SCHED;
;             PG8_LDB(B1, 0, 1); PG8_STAGE(PG8_SB(0, 0), b2, voffB);
;             PG8_BAR; PG8_WAIT_L(0); PG8_MMA(0, 1, At, B1); PG8_BAR;
;             PG8_LDA(At, 0, 1); PG8_STAGE(PG8_SA(0, 0), a2, voffA);
;             PG8_BAR; PG8_WAIT_L(0); PG8_MMA(1, 0, At, B0); PG8_BAR; PG8_SCHED;
.LBB0_1059:
	ds_read_b128 v[148:151], v153
	ds_read_b128 v[156:159], v153 offset:1024
	ds_read_b128 v[160:163], v153 offset:2048
	ds_read_b128 v[164:167], v153 offset:3072
	s_add_u32 s18, s16, 0xfff80080
	s_addc_u32 s19, s17, -1
	s_cmp_eq_u32 s53, 28
	s_cselect_b32 s21, s9, s19
	s_cselect_b32 s20, s49, s18
	s_cselect_b32 s19, s7, s52
	s_cselect_b32 s18, s50, s51
	v_lshl_add_u64 v[200:201], s[16:17], 0, v[136:137]
	s_add_i32 m0, s15, 0xc000
	ds_read_b128 v[168:171], v154
	ds_read_b128 v[172:175], v154 offset:1024
	ds_read_b128 v[176:179], v154 offset:2048
	ds_read_b128 v[180:183], v154 offset:3072
	ds_read_b128 v[184:187], v154 offset:4096
	ds_read_b128 v[188:191], v154 offset:5120
	ds_read_b128 v[192:195], v154 offset:6144
	ds_read_b128 v[196:199], v154 offset:7168
	global_load_lds_dwordx4 v[200:201], off
	v_lshl_add_u64 v[200:201], s[16:17], 0, v[138:139]
	s_add_i32 m0, s15, 0xe000
	s_nop 0
	global_load_lds_dwordx4 v[200:201], off
	s_waitcnt lgkmcnt(8)
	s_barrier
	s_waitcnt lgkmcnt(0)
	s_waitcnt lgkmcnt(0)
	v_mfma_f32_16x16x32_bf16 v[124:127], v[148:151], v[168:171], v[124:127]
	v_mfma_f32_16x16x32_bf16 v[120:123], v[160:163], v[168:171], v[120:123]
	v_mfma_f32_16x16x32_bf16 v[108:111], v[148:151], v[176:179], v[108:111]
	v_mfma_f32_16x16x32_bf16 v[104:107], v[160:163], v[176:179], v[104:107]
	v_mfma_f32_16x16x32_bf16 v[92:95], v[148:151], v[184:187], v[92:95]
	v_mfma_f32_16x16x32_bf16 v[88:91], v[160:163], v[184:187], v[88:91]
	v_mfma_f32_16x16x32_bf16 v[76:79], v[148:151], v[192:195], v[76:79]
	v_mfma_f32_16x16x32_bf16 v[72:75], v[160:163], v[192:195], v[72:75]
	v_mfma_f32_16x16x32_bf16 v[124:127], v[156:159], v[172:175], v[124:127]
	v_mfma_f32_16x16x32_bf16 v[120:123], v[164:167], v[172:175], v[120:123]
	v_mfma_f32_16x16x32_bf16 v[108:111], v[156:159], v[180:183], v[108:111]
	v_mfma_f32_16x16x32_bf16 v[104:107], v[164:167], v[180:183], v[104:107]
	v_mfma_f32_16x16x32_bf16 v[92:95], v[156:159], v[188:191], v[92:95]
	v_mfma_f32_16x16x32_bf16 v[88:91], v[164:167], v[188:191], v[88:91]
	v_mfma_f32_16x16x32_bf16 v[76:79], v[156:159], v[196:199], v[76:79]
	v_mfma_f32_16x16x32_bf16 v[72:75], v[164:167], v[196:199], v[72:75]
	s_barrier
	s_add_i32 s30, s46, s25
	v_lshl_add_u64 v[216:217], s[18:19], 0, v[130:131]
	s_mov_b32 m0, s30
	ds_read_b128 v[200:203], v155
	ds_read_b128 v[204:207], v155 offset:1024
	ds_read_b128 v[208:211], v155 offset:2048
	ds_read_b128 v[212:215], v155 offset:3072
	global_load_lds_dwordx4 v[216:217], off
	v_lshl_add_u64 v[218:219], s[18:19], 0, v[134:135]
	s_add_i32 m0, s30, 0x2000
	s_nop 0
	global_load_lds_dwordx4 v[218:219], off
	s_barrier
	s_waitcnt lgkmcnt(0)
	s_waitcnt lgkmcnt(0)
	v_mfma_f32_16x16x32_bf16 v[116:119], v[200:203], v[168:171], v[116:119]
	v_mfma_f32_16x16x32_bf16 v[112:115], v[208:211], v[168:171], v[112:115]
	v_mfma_f32_16x16x32_bf16 v[100:103], v[200:203], v[176:179], v[100:103]
	v_mfma_f32_16x16x32_bf16 v[96:99], v[208:211], v[176:179], v[96:99]
	v_mfma_f32_16x16x32_bf16 v[84:87], v[200:203], v[184:187], v[84:87]
	v_mfma_f32_16x16x32_bf16 v[80:83], v[208:211], v[184:187], v[80:83]
	v_mfma_f32_16x16x32_bf16 v[68:71], v[200:203], v[192:195], v[68:71]
	v_mfma_f32_16x16x32_bf16 v[64:67], v[208:211], v[192:195], v[64:67]
	v_mfma_f32_16x16x32_bf16 v[116:119], v[204:207], v[172:175], v[116:119]
	v_mfma_f32_16x16x32_bf16 v[112:115], v[212:215], v[172:175], v[112:115]
	v_mfma_f32_16x16x32_bf16 v[100:103], v[204:207], v[180:183], v[100:103]
	v_mfma_f32_16x16x32_bf16 v[96:99], v[212:215], v[180:183], v[96:99]
	v_mfma_f32_16x16x32_bf16 v[84:87], v[204:207], v[188:191], v[84:87]
	v_mfma_f32_16x16x32_bf16 v[80:83], v[212:215], v[188:191], v[80:83]
	v_mfma_f32_16x16x32_bf16 v[68:71], v[204:207], v[196:199], v[68:71]
	v_mfma_f32_16x16x32_bf16 v[64:67], v[212:215], v[196:199], v[64:67]
	s_mov_b32 m0, s15
	v_lshl_add_u64 v[220:221], s[20:21], 0, v[128:129]
	s_barrier
	ds_read_b128 v[168:171], v154 offset:16384
	ds_read_b128 v[172:175], v154 offset:17408
	ds_read_b128 v[176:179], v154 offset:18432
	ds_read_b128 v[180:183], v154 offset:19456
	ds_read_b128 v[184:187], v154 offset:20480
	ds_read_b128 v[188:191], v154 offset:21504
	ds_read_b128 v[192:195], v154 offset:22528
	ds_read_b128 v[196:199], v154 offset:23552
	global_load_lds_dwordx4 v[220:221], off
	v_lshl_add_u64 v[222:223], s[20:21], 0, v[132:133]
	s_mov_b32 m0, s28
	s_nop 0
	global_load_lds_dwordx4 v[222:223], off
	s_barrier
	s_waitcnt lgkmcnt(0)
	s_waitcnt lgkmcnt(0)
	v_mfma_f32_16x16x32_bf16 v[60:63], v[148:151], v[168:171], v[60:63]
	v_mfma_f32_16x16x32_bf16 v[56:59], v[160:163], v[168:171], v[56:59]
	v_mfma_f32_16x16x32_bf16 v[44:47], v[148:151], v[176:179], v[44:47]
	v_mfma_f32_16x16x32_bf16 v[40:43], v[160:163], v[176:179], v[40:43]
	v_mfma_f32_16x16x32_bf16 v[28:31], v[148:151], v[184:187], v[28:31]
	v_mfma_f32_16x16x32_bf16 v[24:27], v[160:163], v[184:187], v[24:27]
	v_mfma_f32_16x16x32_bf16 v[12:15], v[148:151], v[192:195], v[12:15]
	v_mfma_f32_16x16x32_bf16 v[8:11], v[160:163], v[192:195], v[8:11]
	v_mfma_f32_16x16x32_bf16 v[60:63], v[156:159], v[172:175], v[60:63]
	v_mfma_f32_16x16x32_bf16 v[56:59], v[164:167], v[172:175], v[56:59]
	v_mfma_f32_16x16x32_bf16 v[44:47], v[156:159], v[180:183], v[44:47]
	v_mfma_f32_16x16x32_bf16 v[40:43], v[164:167], v[180:183], v[40:43]
	v_mfma_f32_16x16x32_bf16 v[28:31], v[156:159], v[188:191], v[28:31]
	v_mfma_f32_16x16x32_bf16 v[24:27], v[164:167], v[188:191], v[24:27]
	v_mfma_f32_16x16x32_bf16 v[12:15], v[156:159], v[196:199], v[12:15]
	v_mfma_f32_16x16x32_bf16 v[8:11], v[164:167], v[196:199], v[8:11]
	s_barrier
; #define PG8_STAGE(bufoff, gbase, voff) do { _Pragma("unroll") for (int _i = 0; _i < 2; ++_i) \
;         __builtin_amdgcn_global_load_lds((const unsigned*)((const char*)(gbase) + (voff)[_i]), (PG8_LAS unsigned*)(lds + (bufoff) + ldsw + _i * 8192), 16, 0, 0); } while (0)
; #define PG8_LDA(dst, b, h) do { _Pragma("unroll") for (int m = 0; m < 4; ++m) _Pragma("unroll") for (int k = 0; k < 2; ++k) dst[m][k] = *(const PG8_LAS bf16x8*)(lds + PG8_SA(b, h) + aoff + m * 2048 + k * 1024); } while (0)
; #define PG8_LDB(dst, b, h) do { _Pragma("unroll") for (int n = 0; n < 2; ++n) _Pragma("unroll") for (int k = 0; k < 2; ++k) dst[n][k] = *(const PG8_LAS bf16x8*)(lds + PG8_SB(b, h) + boff + n * 2048 + k * 1024); } while (0)
; #define PG8_MMA(ai, bj, At, Bt) do { __builtin_amdgcn_s_setprio(1); _Pragma("unroll") for (int m = 0; m < 4; ++m) _Pragma("unroll") for (int n = 0; n < 2; ++n) _Pragma("unroll") for (int k = 0; k < 2; ++k) \
;         acc[ai][bj][m][n] = __builtin_amdgcn_mfma_f32_16x16x32_bf16(Bt[n][k], At[m][k], acc[ai][bj][m][n], 0, 0, 0); __builtin_amdgcn_s_setprio(0); } while (0)
; #define PG8_WAIT_V(n) asm volatile("s_waitcnt vmcnt(" #n ")" ::: "memory")
; #define PG8_WAIT_L(n) asm volatile("s_waitcnt lgkmcnt(" #n ")" ::: "memory")
; #define PG8_BAR __builtin_amdgcn_s_barrier()
; #define PG8_SCHED __builtin_amdgcn_sched_barrier(0)
; template <class Epi, class Sched>
; __device__ __forceinline__ void gemm_phase(PG8_LAS unsigned char* lds, const Gemm g, const Sched& S, const Epi& E) {
;     ...
;             PG8_STAGE(PG8_SB(0, 1), b2 + hstep, voffB);
;             PG8_WAIT_V(6); PG8_BAR; PG8_MMA(1, 1, At, B1); PG8_BAR;
;             PG8_LDB(B0, 1, 0); PG8_SCHED; PG8_LDA(At, 1, 0); PG8_STAGE(PG8_SA(0, 1), a2 + hstep, voffA);
;             PG8_WAIT_L(8); PG8_BAR; PG8_WAIT_L(0); PG8_MMA(0, 0, At, B0); PG8_BAR; PG8_SCHED;
;             PG8_LDB(B1, 1, 1); PG8_STAGE(PG8_SB(1, 0), b3, voffB);
;             PG8_BAR; PG8_WAIT_L(0); PG8_MMA(0, 1, At, B1); PG8_BAR;
;             PG8_LDA(At, 1, 1); PG8_STAGE(PG8_SA(1, 0), a3, voffA);
	s_add_u32 s30, s18, 0x80000
	s_addc_u32 s31, s19, 0
	s_add_i32 s54, s47, s25
	v_lshl_add_u64 v[148:149], s[30:31], 0, v[130:131]
	s_mov_b32 m0, s54
	s_nop 0
	global_load_lds_dwordx4 v[148:149], off
	v_lshl_add_u64 v[148:149], s[30:31], 0, v[134:135]
	s_add_i32 m0, s54, 0x2000
	s_nop 0
	global_load_lds_dwordx4 v[148:149], off
	s_waitcnt vmcnt(6)
	s_barrier
	v_mfma_f32_16x16x32_bf16 v[52:55], v[200:203], v[168:171], v[52:55]
	v_mfma_f32_16x16x32_bf16 v[48:51], v[208:211], v[168:171], v[48:51]
	v_mfma_f32_16x16x32_bf16 v[36:39], v[200:203], v[176:179], v[36:39]
	v_mfma_f32_16x16x32_bf16 v[32:35], v[208:211], v[176:179], v[32:35]
	v_mfma_f32_16x16x32_bf16 v[20:23], v[200:203], v[184:187], v[20:23]
	v_mfma_f32_16x16x32_bf16 v[16:19], v[208:211], v[184:187], v[16:19]
	v_mfma_f32_16x16x32_bf16 v[4:7], v[200:203], v[192:195], v[4:7]
	v_mfma_f32_16x16x32_bf16 v[0:3], v[208:211], v[192:195], v[0:3]
	v_mfma_f32_16x16x32_bf16 v[52:55], v[204:207], v[172:175], v[52:55]
	v_mfma_f32_16x16x32_bf16 v[48:51], v[212:215], v[172:175], v[48:51]
	v_mfma_f32_16x16x32_bf16 v[36:39], v[204:207], v[180:183], v[36:39]
	v_mfma_f32_16x16x32_bf16 v[32:35], v[212:215], v[180:183], v[32:35]
	v_mfma_f32_16x16x32_bf16 v[20:23], v[204:207], v[188:191], v[20:23]
	v_mfma_f32_16x16x32_bf16 v[16:19], v[212:215], v[188:191], v[16:19]
	v_mfma_f32_16x16x32_bf16 v[4:7], v[204:207], v[196:199], v[4:7]
	v_mfma_f32_16x16x32_bf16 v[0:3], v[212:215], v[196:199], v[0:3]
	s_add_i32 s30, 0, 0x18000
	v_add_u32_e32 v164, s30, v147
	s_barrier
	ds_read_b128 v[148:151], v164
	ds_read_b128 v[156:159], v164 offset:1024
	ds_read_b128 v[160:163], v164 offset:2048
	ds_read_b128 v[164:167], v164 offset:3072
	s_add_u32 s20, s20, 0x80000
	s_addc_u32 s21, s21, 0
	s_mov_b32 m0, s29
	v_lshl_add_u64 v[200:201], s[20:21], 0, v[128:129]
	ds_read_b128 v[168:171], v154 offset:32768
	ds_read_b128 v[172:175], v154 offset:33792
	ds_read_b128 v[176:179], v154 offset:34816
	ds_read_b128 v[180:183], v154 offset:35840
	ds_read_b128 v[184:187], v154 offset:36864
	ds_read_b128 v[188:191], v154 offset:37888
	ds_read_b128 v[192:195], v154 offset:38912
	ds_read_b128 v[196:199], v154 offset:39936
	global_load_lds_dwordx4 v[200:201], off
	v_lshl_add_u64 v[200:201], s[20:21], 0, v[132:133]
	s_mov_b32 m0, s38
	s_nop 0
	global_load_lds_dwordx4 v[200:201], off
	s_waitcnt lgkmcnt(8)
	s_barrier
	s_waitcnt lgkmcnt(0)
	s_waitcnt lgkmcnt(0)
	v_mfma_f32_16x16x32_bf16 v[124:127], v[148:151], v[168:171], v[124:127]
	v_mfma_f32_16x16x32_bf16 v[120:123], v[160:163], v[168:171], v[120:123]
	v_mfma_f32_16x16x32_bf16 v[108:111], v[148:151], v[176:179], v[108:111]
	v_mfma_f32_16x16x32_bf16 v[104:107], v[160:163], v[176:179], v[104:107]
	v_mfma_f32_16x16x32_bf16 v[92:95], v[148:151], v[184:187], v[92:95]
	v_mfma_f32_16x16x32_bf16 v[88:91], v[160:163], v[184:187], v[88:91]
	v_mfma_f32_16x16x32_bf16 v[76:79], v[148:151], v[192:195], v[76:79]
	v_mfma_f32_16x16x32_bf16 v[72:75], v[160:163], v[192:195], v[72:75]
	v_mfma_f32_16x16x32_bf16 v[124:127], v[156:159], v[172:175], v[124:127]
	v_mfma_f32_16x16x32_bf16 v[120:123], v[164:167], v[172:175], v[120:123]
	v_mfma_f32_16x16x32_bf16 v[108:111], v[156:159], v[180:183], v[108:111]
	v_mfma_f32_16x16x32_bf16 v[104:107], v[164:167], v[180:183], v[104:107]
	v_mfma_f32_16x16x32_bf16 v[92:95], v[156:159], v[188:191], v[92:95]
	v_mfma_f32_16x16x32_bf16 v[88:91], v[164:167], v[188:191], v[88:91]
	v_mfma_f32_16x16x32_bf16 v[76:79], v[156:159], v[196:199], v[76:79]
	v_mfma_f32_16x16x32_bf16 v[72:75], v[164:167], v[196:199], v[72:75]
	s_barrier
	s_add_i32 s20, 0, 0x1c000
	s_add_i32 s21, s30, s25
	v_add_u32_e32 v212, s20, v147
	v_lshl_add_u64 v[216:217], v[216:217], 0, s[0:1]
	s_mov_b32 m0, s21
	ds_read_b128 v[200:203], v212
	ds_read_b128 v[204:207], v212 offset:1024
	ds_read_b128 v[208:211], v212 offset:2048
	ds_read_b128 v[212:215], v212 offset:3072
	global_load_lds_dwordx4 v[216:217], off
	v_lshl_add_u64 v[216:217], v[218:219], 0, s[0:1]
	s_add_i32 m0, s21, 0x2000
	s_nop 0
	global_load_lds_dwordx4 v[216:217], off
	s_barrier
	s_waitcnt lgkmcnt(0)
	s_waitcnt lgkmcnt(0)
	v_mfma_f32_16x16x32_bf16 v[116:119], v[200:203], v[168:171], v[116:119]
	v_mfma_f32_16x16x32_bf16 v[112:115], v[208:211], v[168:171], v[112:115]
	v_mfma_f32_16x16x32_bf16 v[100:103], v[200:203], v[176:179], v[100:103]
	v_mfma_f32_16x16x32_bf16 v[96:99], v[208:211], v[176:179], v[96:99]
	v_mfma_f32_16x16x32_bf16 v[84:87], v[200:203], v[184:187], v[84:87]
	v_mfma_f32_16x16x32_bf16 v[80:83], v[208:211], v[184:187], v[80:83]
	v_mfma_f32_16x16x32_bf16 v[68:71], v[200:203], v[192:195], v[68:71]
	v_mfma_f32_16x16x32_bf16 v[64:67], v[208:211], v[192:195], v[64:67]
	v_mfma_f32_16x16x32_bf16 v[116:119], v[204:207], v[172:175], v[116:119]
	v_mfma_f32_16x16x32_bf16 v[112:115], v[212:215], v[172:175], v[112:115]
	v_mfma_f32_16x16x32_bf16 v[100:103], v[204:207], v[180:183], v[100:103]
	v_mfma_f32_16x16x32_bf16 v[96:99], v[212:215], v[180:183], v[96:99]
	v_mfma_f32_16x16x32_bf16 v[84:87], v[204:207], v[188:191], v[84:87]
	v_mfma_f32_16x16x32_bf16 v[80:83], v[212:215], v[188:191], v[80:83]
	v_mfma_f32_16x16x32_bf16 v[68:71], v[204:207], v[196:199], v[68:71]
	v_mfma_f32_16x16x32_bf16 v[64:67], v[212:215], v[196:199], v[64:67]
	s_mov_b32 m0, s42
	v_lshl_add_u64 v[216:217], v[220:221], 0, s[0:1]
	s_barrier
	ds_read_b128 v[168:171], v154 offset:49152
	ds_read_b128 v[172:175], v154 offset:50176
	ds_read_b128 v[176:179], v154 offset:51200
	ds_read_b128 v[180:183], v154 offset:52224
	ds_read_b128 v[184:187], v154 offset:53248
	ds_read_b128 v[188:191], v154 offset:54272
	ds_read_b128 v[192:195], v154 offset:55296
	ds_read_b128 v[196:199], v154 offset:56320
	global_load_lds_dwordx4 v[216:217], off
	v_lshl_add_u64 v[216:217], v[222:223], 0, s[0:1]
	s_mov_b32 m0, s43
	s_nop 0
	global_load_lds_dwordx4 v[216:217], off
	s_barrier
; #define PG8_STAGE(bufoff, gbase, voff) do { _Pragma("unroll") for (int _i = 0; _i < 2; ++_i) \
;         __builtin_amdgcn_global_load_lds((const unsigned*)((const char*)(gbase) + (voff)[_i]), (PG8_LAS unsigned*)(lds + (bufoff) + ldsw + _i * 8192), 16, 0, 0); } while (0)
; #define PG8_MMA(ai, bj, At, Bt) do { __builtin_amdgcn_s_setprio(1); _Pragma("unroll") for (int m = 0; m < 4; ++m) _Pragma("unroll") for (int n = 0; n < 2; ++n) _Pragma("unroll") for (int k = 0; k < 2; ++k) \
;         acc[ai][bj][m][n] = __builtin_amdgcn_mfma_f32_16x16x32_bf16(Bt[n][k], At[m][k], acc[ai][bj][m][n], 0, 0, 0); __builtin_amdgcn_s_setprio(0); } while (0)
; #define PG8_WAIT_V(n) asm volatile("s_waitcnt vmcnt(" #n ")" ::: "memory")
; #define PG8_WAIT_L(n) asm volatile("s_waitcnt lgkmcnt(" #n ")" ::: "memory")
; #define PG8_BAR __builtin_amdgcn_s_barrier()
; #define PG8_SCHED __builtin_amdgcn_sched_barrier(0)
; __device__ __forceinline__ f32x4 unpk4(uint2 u) { f32x4 r; r[0] = __uint_as_float(u.x << 16); r[1] = __uint_as_float(u.x & 0xffff0000u); r[2] = __uint_as_float(u.y << 16); r[3] = __uint_as_float(u.y & 0xffff0000u); return r; }
; template <class Epi, class Sched>
; __device__ __forceinline__ void gemm_phase(PG8_LAS unsigned char* lds, const Gemm g, const Sched& S, const Epi& E) {
;     ...
;             PG8_BAR; PG8_WAIT_L(0); PG8_MMA(1, 0, At, B0); PG8_BAR; PG8_SCHED;
;             PG8_STAGE(PG8_SB(1, 1), b3 + hstep, voffB);
;             PG8_WAIT_V(6); PG8_BAR; PG8_MMA(1, 1, At, B1); PG8_BAR;
;     __device__ __forceinline__ void operator()(AccRef acc, const Unit& u, int wr, int wc, int fr, int fq) const {
;         const int c0 = u.pn * 256 + wc * 32 + 8 * fq;
; #pragma unroll
;         for (int ai = 0; ai < 2; ++ai)
; #pragma unroll
;             for (int m = 0; m < 4; ++m) {
;                 const int r = u.pm * 256 + ai * 128 + wr * 64 + m * 16 + fr;
;                 const float s = rinv[r];
;                 float ss = 0.f;
; #pragma unroll
;                 for (int bj = 0; bj < 2; ++bj) {
;                     const size_t o = (size_t)r * D + c0 + bj * 128;
;                     const uint4 h8 = *(const uint4*)(H2 + o);
;                     f32x4 v0 = unpk4(make_uint2(h8.x, h8.y)), v1 = unpk4(make_uint2(h8.z, h8.w));
;                     const uint4 pp8 = *(const uint4*)(PPb + o);
	s_waitcnt lgkmcnt(0)
	s_waitcnt lgkmcnt(0)
	v_mfma_f32_16x16x32_bf16 v[60:63], v[148:151], v[168:171], v[60:63]
	v_mfma_f32_16x16x32_bf16 v[56:59], v[160:163], v[168:171], v[56:59]
	v_mfma_f32_16x16x32_bf16 v[44:47], v[148:151], v[176:179], v[44:47]
	v_mfma_f32_16x16x32_bf16 v[40:43], v[160:163], v[176:179], v[40:43]
	v_mfma_f32_16x16x32_bf16 v[28:31], v[148:151], v[184:187], v[28:31]
	v_mfma_f32_16x16x32_bf16 v[24:27], v[160:163], v[184:187], v[24:27]
	v_mfma_f32_16x16x32_bf16 v[12:15], v[148:151], v[192:195], v[12:15]
	v_mfma_f32_16x16x32_bf16 v[8:11], v[160:163], v[192:195], v[8:11]
	v_mfma_f32_16x16x32_bf16 v[60:63], v[156:159], v[172:175], v[60:63]
	v_mfma_f32_16x16x32_bf16 v[56:59], v[164:167], v[172:175], v[56:59]
	v_mfma_f32_16x16x32_bf16 v[44:47], v[156:159], v[180:183], v[44:47]
	v_mfma_f32_16x16x32_bf16 v[40:43], v[164:167], v[180:183], v[40:43]
	v_mfma_f32_16x16x32_bf16 v[28:31], v[156:159], v[188:191], v[28:31]
	v_mfma_f32_16x16x32_bf16 v[24:27], v[164:167], v[188:191], v[24:27]
	v_mfma_f32_16x16x32_bf16 v[12:15], v[156:159], v[196:199], v[12:15]
	v_mfma_f32_16x16x32_bf16 v[8:11], v[164:167], v[196:199], v[8:11]
	s_barrier
	s_add_u32 s18, s18, 0x80080
	s_addc_u32 s19, s19, 0
	s_add_i32 s20, s20, s25
	v_lshl_add_u64 v[148:149], s[18:19], 0, v[130:131]
	s_mov_b32 m0, s20
	s_nop 0
	global_load_lds_dwordx4 v[148:149], off
	v_lshl_add_u64 v[148:149], s[18:19], 0, v[134:135]
	s_add_i32 m0, s20, 0x2000
	s_nop 0
	global_load_lds_dwordx4 v[148:149], off
	s_waitcnt vmcnt(6)
	s_barrier
	v_mfma_f32_16x16x32_bf16 v[52:55], v[200:203], v[168:171], v[52:55]
	v_mfma_f32_16x16x32_bf16 v[48:51], v[208:211], v[168:171], v[48:51]
	v_mfma_f32_16x16x32_bf16 v[36:39], v[200:203], v[176:179], v[36:39]
	v_mfma_f32_16x16x32_bf16 v[32:35], v[208:211], v[176:179], v[32:35]
	v_mfma_f32_16x16x32_bf16 v[20:23], v[200:203], v[184:187], v[20:23]
	v_mfma_f32_16x16x32_bf16 v[16:19], v[208:211], v[184:187], v[16:19]
	v_mfma_f32_16x16x32_bf16 v[4:7], v[200:203], v[192:195], v[4:7]
	v_mfma_f32_16x16x32_bf16 v[0:3], v[208:211], v[192:195], v[0:3]
	v_mfma_f32_16x16x32_bf16 v[52:55], v[204:207], v[172:175], v[52:55]
	v_mfma_f32_16x16x32_bf16 v[48:51], v[212:215], v[172:175], v[48:51]
	v_mfma_f32_16x16x32_bf16 v[36:39], v[204:207], v[180:183], v[36:39]
	v_mfma_f32_16x16x32_bf16 v[32:35], v[212:215], v[180:183], v[32:35]
	v_mfma_f32_16x16x32_bf16 v[20:23], v[204:207], v[188:191], v[20:23]
	v_mfma_f32_16x16x32_bf16 v[16:19], v[212:215], v[188:191], v[16:19]
	v_mfma_f32_16x16x32_bf16 v[4:7], v[204:207], v[196:199], v[4:7]
	v_mfma_f32_16x16x32_bf16 v[0:3], v[212:215], v[196:199], v[0:3]
	s_add_i32 s53, s53, 2
	s_add_u32 s16, s16, 0x100
	s_addc_u32 s17, s17, 0
	s_add_u32 s51, s51, 0x100
	s_addc_u32 s52, s52, 0
	s_cmp_gt_u32 s53, 29
	s_barrier
	s_cbranch_scc0 .LBB0_1059
	v_lshl_add_u32 v148, s14, 8, v145
	v_ashrrev_i32_e32 v149, 31, v148
	v_lshl_add_u64 v[150:151], v[148:149], 2, s[26:27]
	global_load_dword v170, v[150:151], off
	v_lshl_or_b32 v150, s48, 8, v152
	v_ashrrev_i32_e32 v151, 31, v150
	v_lshlrev_b64 v[156:157], 11, v[148:149]
	v_lshl_add_u64 v[156:157], v[156:157], 0, v[150:151]
	v_lshlrev_b64 v[164:165], 1, v[156:157]
	v_lshl_add_u64 v[156:157], s[34:35], 0, v[164:165]
	v_lshl_add_u64 v[160:161], s[36:37], 0, v[164:165]
	global_load_dwordx4 v[156:159], v[156:157], off
	v_lshl_add_u64 v[166:167], s[40:41], 0, v[164:165]
	global_load_dwordx4 v[160:163], v[160:161], off
	v_or_b32_e32 v164, 0x100, v164
	v_lshl_add_u64 v[168:169], s[34:35], 0, v[164:165]
	s_and_b64 vcc, exec, s[4:5]
	s_mov_b32 s48, s6
	s_mov_b32 s14, s8
	s_mov_b64 s[18:19], s[12:13]
	s_mov_b64 s[16:17], s[10:11]
	global_load_dwordx4 v[178:181], v[168:169], off
	v_lshl_add_u64 v[236:237], s[36:37], 0, v[164:165]
	global_load_dwordx4 v[182:185], v[236:237], off
	v_or_b32_e32 v240, 16, v148
	v_ashrrev_i32_e32 v241, 31, v240
	v_lshlrev_b64 v[238:239], 11, v[240:241]
	v_lshl_add_u64 v[238:239], v[238:239], 0, v[150:151]
	v_lshlrev_b64 v[238:239], 1, v[238:239]
	v_lshl_add_u64 v[236:237], s[36:37], 0, v[238:239]
	global_load_dwordx4 v[186:189], v[236:237], off
	v_or_b32_e32 v238, 16, v148
	v_ashrrev_i32_e32 v239, 31, v238
	v_lshl_add_u64 v[236:237], v[238:239], 2, s[26:27]
	global_load_dword v190, v[236:237], off
	v_or_b32_e32 v238, 16, v148
	v_ashrrev_i32_e32 v239, 31, v238
	v_lshlrev_b64 v[236:237], 11, v[238:239]
	v_lshl_add_u64 v[236:237], v[236:237], 0, v[150:151]
	v_lshlrev_b64 v[236:237], 1, v[236:237]
	v_lshl_add_u64 v[240:241], s[34:35], 0, v[236:237]
	global_load_dwordx4 v[192:195], v[240:241], off
	v_or_b32_e32 v240, 16, v148
	v_ashrrev_i32_e32 v241, 31, v240
	v_lshlrev_b64 v[236:237], 11, v[240:241]
	v_lshl_add_u64 v[236:237], v[236:237], 0, v[150:151]
	v_lshlrev_b64 v[236:237], 1, v[236:237]
	v_or_b32_e32 v236, 0x100, v236
	v_lshl_add_u64 v[238:239], s[34:35], 0, v[236:237]
	global_load_dwordx4 v[196:199], v[238:239], off
	v_or_b32_e32 v240, 16, v148
	v_ashrrev_i32_e32 v241, 31, v240
	v_lshlrev_b64 v[238:239], 11, v[240:241]
	v_lshl_add_u64 v[238:239], v[238:239], 0, v[150:151]
	v_lshlrev_b64 v[238:239], 1, v[238:239]
	v_or_b32_e32 v238, 0x100, v238
	v_lshl_add_u64 v[236:237], s[36:37], 0, v[238:239]
	global_load_dwordx4 v[200:203], v[236:237], off
	v_or_b32_e32 v240, 32, v148
	v_ashrrev_i32_e32 v241, 31, v240
	v_lshlrev_b64 v[238:239], 11, v[240:241]
	v_lshl_add_u64 v[238:239], v[238:239], 0, v[150:151]
	v_lshlrev_b64 v[238:239], 1, v[238:239]
	v_lshl_add_u64 v[236:237], s[36:37], 0, v[238:239]
	global_load_dwordx4 v[204:207], v[236:237], off
	v_or_b32_e32 v238, 32, v148
	v_ashrrev_i32_e32 v239, 31, v238
	v_lshl_add_u64 v[236:237], v[238:239], 2, s[26:27]
	global_load_dword v191, v[236:237], off
	v_or_b32_e32 v238, 32, v148
	v_ashrrev_i32_e32 v239, 31, v238
	v_lshlrev_b64 v[236:237], 11, v[238:239]
	v_lshl_add_u64 v[236:237], v[236:237], 0, v[150:151]
	v_lshlrev_b64 v[236:237], 1, v[236:237]
	v_lshl_add_u64 v[240:241], s[34:35], 0, v[236:237]
	global_load_dwordx4 v[208:211], v[240:241], off
	v_or_b32_e32 v240, 32, v148
	v_ashrrev_i32_e32 v241, 31, v240
	v_lshlrev_b64 v[236:237], 11, v[240:241]
	v_lshl_add_u64 v[236:237], v[236:237], 0, v[150:151]
	v_lshlrev_b64 v[236:237], 1, v[236:237]
	v_or_b32_e32 v236, 0x100, v236
	v_lshl_add_u64 v[238:239], s[34:35], 0, v[236:237]
	global_load_dwordx4 v[212:215], v[238:239], off
	v_or_b32_e32 v240, 32, v148
	v_ashrrev_i32_e32 v241, 31, v240
	v_lshlrev_b64 v[238:239], 11, v[240:241]
	v_lshl_add_u64 v[238:239], v[238:239], 0, v[150:151]
	v_lshlrev_b64 v[238:239], 1, v[238:239]
	v_or_b32_e32 v238, 0x100, v238
	v_lshl_add_u64 v[236:237], s[36:37], 0, v[238:239]
	global_load_dwordx4 v[216:219], v[236:237], off
	s_waitcnt vmcnt(12)
; __device__ __forceinline__ f32x4 unpk4(uint2 u) { f32x4 r; r[0] = __uint_as_float(u.x << 16); r[1] = __uint_as_float(u.x & 0xffff0000u); r[2] = __uint_as_float(u.y << 16); r[3] = __uint_as_float(u.y & 0xffff0000u); return r; }
; __device__ __forceinline__ float sigm(float x) { return __builtin_amdgcn_rcpf(1.f + __expf(-x)); }
; __device__ __forceinline__ uint4 pk8(f32x4 a, f32x4 b) { return make_uint4(cvt_pk_bf16(a[0], a[1]), cvt_pk_bf16(a[2], a[3]), cvt_pk_bf16(b[0], b[1]), cvt_pk_bf16(b[2], b[3])); }
;     __device__ __forceinline__ void operator()(AccRef acc, const Unit& u, int wr, int wc, int fr, int fq) const {
;     ...
;         for (int ai = 0; ai < 2; ++ai)
; #pragma unroll
;             for (int m = 0; m < 4; ++m) {
;                 const int r = u.pm * 256 + ai * 128 + wr * 64 + m * 16 + fr;
;                 const float s = rinv[r];
;                 float ss = 0.f;
; #pragma unroll
;                 for (int bj = 0; bj < 2; ++bj) {
;                     const size_t o = (size_t)r * D + c0 + bj * 128;
;                     const uint4 h8 = *(const uint4*)(H2 + o);
;                     f32x4 v0 = unpk4(make_uint2(h8.x, h8.y)), v1 = unpk4(make_uint2(h8.z, h8.w));
;                     const uint4 pp8 = *(const uint4*)(PPb + o);
;                     const f32x4 p0 = unpk4(make_uint2(pp8.x, pp8.y)), p1 = unpk4(make_uint2(pp8.z, pp8.w));
; #pragma unroll
;                     for (int e = 0; e < 4; ++e) { v0[e] += sigm(acc[ai][bj][m][0][e] * s) * p0[e]; v1[e] += sigm(acc[ai][bj][m][1][e] * s) * p1[e]; }
;                     ss += v0[0] * v0[0] + v0[1] * v0[1] + v0[2] * v0[2] + v0[3] * v0[3] + v1[0] * v1[0] + v1[1] * v1[1] + v1[2] * v1[2] + v1[3] * v1[3];
;                     *(uint4*)(H3 + o) = pk8(v0, v1);
;                 }
	v_mul_f32_e32 v120, v120, v170
	v_mul_f32_e32 v125, v125, v170
	v_mul_f32_e32 v121, v121, v170
	v_mul_f32_e32 v127, v127, v170
	v_mul_f32_e32 v123, v123, v170
	v_mul_f32_e32 v124, v124, v170
	v_mul_f32_e32 v126, v126, v170
	v_mul_f32_e32 v122, v122, v170
	v_mul_f32_e32 v120, 0xbfb8aa3b, v120
	v_mul_f32_e32 v125, 0xbfb8aa3b, v125
	v_mul_f32_e32 v121, 0xbfb8aa3b, v121
	v_mul_f32_e32 v127, 0xbfb8aa3b, v127
	v_mul_f32_e32 v123, 0xbfb8aa3b, v123
	v_mul_f32_e32 v124, 0xbfb8aa3b, v124
	v_mul_f32_e32 v126, 0xbfb8aa3b, v126
	v_mul_f32_e32 v122, 0xbfb8aa3b, v122
	v_exp_f32_e32 v120, v120
	v_exp_f32_e32 v125, v125
	v_exp_f32_e32 v121, v121
	v_exp_f32_e32 v127, v127
	v_exp_f32_e32 v123, v123
	v_exp_f32_e32 v124, v124
	v_exp_f32_e32 v126, v126
	v_exp_f32_e32 v122, v122
	v_add_f32_e32 v120, 1.0, v120
	v_add_f32_e32 v125, 1.0, v125
	v_add_f32_e32 v121, 1.0, v121
	v_add_f32_e32 v127, 1.0, v127
	v_add_f32_e32 v123, 1.0, v123
	v_add_f32_e32 v124, 1.0, v124
	v_add_f32_e32 v126, 1.0, v126
	v_add_f32_e32 v122, 1.0, v122
	v_rcp_f32_e32 v120, v120
	v_rcp_f32_e32 v125, v125
	v_rcp_f32_e32 v121, v121
	v_rcp_f32_e32 v127, v127
	v_rcp_f32_e32 v123, v123
	v_rcp_f32_e32 v124, v124
	v_rcp_f32_e32 v126, v126
	v_rcp_f32_e32 v122, v122
	v_lshlrev_b32_e32 v149, 16, v156
	v_and_b32_e32 v156, 0xffff0000, v156
	v_lshlrev_b32_e32 v171, 16, v157
	v_and_b32_e32 v157, 0xffff0000, v157
	v_lshlrev_b32_e32 v172, 16, v158
	v_and_b32_e32 v158, 0xffff0000, v158
	v_lshlrev_b32_e32 v173, 16, v159
	v_and_b32_e32 v159, 0xffff0000, v159
	v_lshlrev_b32_e32 v174, 16, v160
	v_and_b32_e32 v160, 0xffff0000, v160
	v_lshlrev_b32_e32 v175, 16, v161
	v_and_b32_e32 v161, 0xffff0000, v161
	v_lshlrev_b32_e32 v176, 16, v162
	v_and_b32_e32 v162, 0xffff0000, v162
	v_lshlrev_b32_e32 v177, 16, v163
	v_and_b32_e32 v163, 0xffff0000, v163
	v_fmac_f32_e32 v172, v120, v176
	v_fmac_f32_e32 v156, v125, v160
	v_fmac_f32_e32 v158, v121, v162
	v_fmac_f32_e32 v157, v127, v161
	v_fmac_f32_e32 v159, v123, v163
	v_lshl_add_u64 v[120:121], s[36:37], 0, v[164:165]
	v_fmac_f32_e32 v149, v124, v174
	v_fmac_f32_e32 v171, v126, v175
	v_fmac_f32_e32 v173, v122, v177
	v_cvt_pk_bf16_f32 v122, v149, v156
	v_cvt_pk_bf16_f32 v123, v171, v157
	v_cvt_pk_bf16_f32 v124, v172, v158
	v_cvt_pk_bf16_f32 v125, v173, v159
	v_mul_f32_e32 v116, v116, v170
	v_mul_f32_e32 v117, v117, v170
	v_mul_f32_e32 v112, v112, v170
	v_mul_f32_e32 v113, v113, v170
	v_mul_f32_e32 v118, v118, v170
	v_mul_f32_e32 v114, v114, v170
	v_mul_f32_e32 v119, v119, v170
	v_mul_f32_e32 v115, v115, v170
	v_mul_f32_e32 v116, 0xbfb8aa3b, v116
	v_mul_f32_e32 v117, 0xbfb8aa3b, v117
	v_mul_f32_e32 v112, 0xbfb8aa3b, v112
	v_mul_f32_e32 v113, 0xbfb8aa3b, v113
	v_mul_f32_e32 v118, 0xbfb8aa3b, v118
	v_mul_f32_e32 v114, 0xbfb8aa3b, v114
	v_mul_f32_e32 v119, 0xbfb8aa3b, v119
	v_mul_f32_e32 v115, 0xbfb8aa3b, v115
	v_exp_f32_e32 v116, v116
	v_exp_f32_e32 v117, v117
	v_exp_f32_e32 v112, v112
	v_exp_f32_e32 v113, v113
	v_exp_f32_e32 v118, v118
	v_exp_f32_e32 v114, v114
	v_exp_f32_e32 v119, v119
	v_exp_f32_e32 v115, v115
	v_add_f32_e32 v116, 1.0, v116
	v_add_f32_e32 v117, 1.0, v117
	v_or_b32_e32 v126, 16, v148
	v_add_f32_e32 v112, 1.0, v112
	v_add_f32_e32 v113, 1.0, v113
	v_add_f32_e32 v118, 1.0, v118
	v_add_f32_e32 v114, 1.0, v114
	v_add_f32_e32 v119, 1.0, v119
	v_add_f32_e32 v115, 1.0, v115
	v_rcp_f32_e32 v116, v116
	v_rcp_f32_e32 v117, v117
	v_ashrrev_i32_e32 v127, 31, v126
	v_rcp_f32_e32 v112, v112
	v_rcp_f32_e32 v113, v113
	v_rcp_f32_e32 v118, v118
	v_rcp_f32_e32 v114, v114
	v_rcp_f32_e32 v119, v119
	v_rcp_f32_e32 v115, v115
	v_lshlrev_b64 v[120:121], 11, v[126:127]
	v_lshl_add_u64 v[120:121], v[120:121], 0, v[150:151]
	global_store_dwordx4 v[166:167], v[122:125], off
	v_lshlrev_b64 v[120:121], 1, v[120:121]
	v_lshl_add_u64 v[164:165], s[40:41], 0, v[164:165]
	v_lshl_add_u64 v[168:169], s[34:35], 0, v[120:121]
	v_or_b32_e32 v240, 48, v148
	v_ashrrev_i32_e32 v241, 31, v240
	v_lshlrev_b64 v[238:239], 11, v[240:241]
	v_lshl_add_u64 v[238:239], v[238:239], 0, v[150:151]
	v_lshlrev_b64 v[238:239], 1, v[238:239]
	v_lshl_add_u64 v[236:237], s[36:37], 0, v[238:239]
	global_load_dwordx4 v[220:223], v[236:237], off
	v_or_b32_e32 v238, 48, v148
	v_ashrrev_i32_e32 v239, 31, v238
	v_lshl_add_u64 v[236:237], v[238:239], 2, s[26:27]
	global_load_dword v224, v[236:237], off
	v_or_b32_e32 v238, 48, v148
	v_ashrrev_i32_e32 v239, 31, v238
	v_lshlrev_b64 v[236:237], 11, v[238:239]
	v_lshl_add_u64 v[236:237], v[236:237], 0, v[150:151]
	v_lshlrev_b64 v[236:237], 1, v[236:237]
	v_lshl_add_u64 v[240:241], s[34:35], 0, v[236:237]
	global_load_dwordx4 v[226:229], v[240:241], off
	s_waitcnt vmcnt(14)
	v_lshlrev_b32_e32 v122, 16, v178
	v_and_b32_e32 v123, 0xffff0000, v178
	v_lshlrev_b32_e32 v124, 16, v179
	v_and_b32_e32 v125, 0xffff0000, v179
	v_lshlrev_b32_e32 v149, 16, v180
	v_and_b32_e32 v156, 0xffff0000, v180
	v_lshlrev_b32_e32 v157, 16, v181
	v_and_b32_e32 v158, 0xffff0000, v181
	v_lshlrev_b32_e32 v159, 16, v182
	v_and_b32_e32 v160, 0xffff0000, v182
	v_lshlrev_b32_e32 v166, 16, v183
	v_and_b32_e32 v161, 0xffff0000, v183
	v_lshlrev_b32_e32 v167, 16, v184
	v_and_b32_e32 v162, 0xffff0000, v184
	v_lshlrev_b32_e32 v170, 16, v185
	v_and_b32_e32 v163, 0xffff0000, v185
	v_fmac_f32_e32 v122, v116, v159
	v_fmac_f32_e32 v123, v117, v160
	v_fmac_f32_e32 v149, v112, v167
	v_fmac_f32_e32 v156, v113, v162
	v_fmac_f32_e32 v124, v118, v166
	v_fmac_f32_e32 v157, v114, v170
	v_fmac_f32_e32 v125, v119, v161
	v_fmac_f32_e32 v158, v115, v163
	v_cvt_pk_bf16_f32 v112, v122, v123
	v_cvt_pk_bf16_f32 v113, v124, v125
	v_cvt_pk_bf16_f32 v114, v149, v156
	v_cvt_pk_bf16_f32 v115, v157, v158
	global_store_dwordx4 v[164:165], v[112:115], off
	v_lshl_add_u64 v[116:117], s[36:37], 0, v[120:121]
	v_lshl_add_u64 v[122:123], v[126:127], 2, s[26:27]
	s_nop 0
	v_lshl_add_u64 v[122:123], s[40:41], 0, v[120:121]
	v_or_b32_e32 v120, 0x100, v120
	v_lshl_add_u64 v[124:125], s[34:35], 0, v[120:121]
	v_or_b32_e32 v240, 48, v148
	v_ashrrev_i32_e32 v241, 31, v240
	v_lshlrev_b64 v[236:237], 11, v[240:241]
	v_lshl_add_u64 v[236:237], v[236:237], 0, v[150:151]
	v_lshlrev_b64 v[236:237], 1, v[236:237]
	v_or_b32_e32 v236, 0x100, v236
	v_lshl_add_u64 v[238:239], s[34:35], 0, v[236:237]
	global_load_dwordx4 v[178:181], v[238:239], off
	v_or_b32_e32 v240, 48, v148
	v_ashrrev_i32_e32 v241, 31, v240
	v_lshlrev_b64 v[238:239], 11, v[240:241]
	v_lshl_add_u64 v[238:239], v[238:239], 0, v[150:151]
	v_lshlrev_b64 v[238:239], 1, v[238:239]
	v_or_b32_e32 v238, 0x100, v238
	v_lshl_add_u64 v[236:237], s[36:37], 0, v[238:239]
	global_load_dwordx4 v[182:185], v[236:237], off
	s_waitcnt vmcnt(14)
; __device__ __forceinline__ f32x4 unpk4(uint2 u) { f32x4 r; r[0] = __uint_as_float(u.x << 16); r[1] = __uint_as_float(u.x & 0xffff0000u); r[2] = __uint_as_float(u.y << 16); r[3] = __uint_as_float(u.y & 0xffff0000u); return r; }
; __device__ __forceinline__ float sigm(float x) { return __builtin_amdgcn_rcpf(1.f + __expf(-x)); }
; __device__ __forceinline__ uint4 pk8(f32x4 a, f32x4 b) { return make_uint4(cvt_pk_bf16(a[0], a[1]), cvt_pk_bf16(a[2], a[3]), cvt_pk_bf16(b[0], b[1]), cvt_pk_bf16(b[2], b[3])); }
;     __device__ __forceinline__ void operator()(AccRef acc, const Unit& u, int wr, int wc, int fr, int fq) const {
;     ...
;         for (int ai = 0; ai < 2; ++ai)
; #pragma unroll
;             for (int m = 0; m < 4; ++m) {
;                 const int r = u.pm * 256 + ai * 128 + wr * 64 + m * 16 + fr;
;                 const float s = rinv[r];
;                 float ss = 0.f;
; #pragma unroll
;                 for (int bj = 0; bj < 2; ++bj) {
;                     const size_t o = (size_t)r * D + c0 + bj * 128;
;                     const uint4 h8 = *(const uint4*)(H2 + o);
;                     f32x4 v0 = unpk4(make_uint2(h8.x, h8.y)), v1 = unpk4(make_uint2(h8.z, h8.w));
;                     const uint4 pp8 = *(const uint4*)(PPb + o);
;                     const f32x4 p0 = unpk4(make_uint2(pp8.x, pp8.y)), p1 = unpk4(make_uint2(pp8.z, pp8.w));
; #pragma unroll
;                     for (int e = 0; e < 4; ++e) { v0[e] += sigm(acc[ai][bj][m][0][e] * s) * p0[e]; v1[e] += sigm(acc[ai][bj][m][1][e] * s) * p1[e]; }
;                     ss += v0[0] * v0[0] + v0[1] * v0[1] + v0[2] * v0[2] + v0[3] * v0[3] + v1[0] * v1[0] + v1[1] * v1[1] + v1[2] * v1[2] + v1[3] * v1[3];
;                     *(uint4*)(H3 + o) = pk8(v0, v1);
;                 }
	v_lshlrev_b32_e32 v158, 16, v186
	v_and_b32_e32 v116, 0xffff0000, v186
	v_mul_f32_e32 v104, v104, v190
	v_mul_f32_e32 v109, v109, v190
	v_mul_f32_e32 v105, v105, v190
	v_mul_f32_e32 v111, v111, v190
	v_mul_f32_e32 v107, v107, v190
	v_mul_f32_e32 v108, v108, v190
	v_mul_f32_e32 v110, v110, v190
	v_mul_f32_e32 v106, v106, v190
	v_mul_f32_e32 v104, 0xbfb8aa3b, v104
	v_mul_f32_e32 v109, 0xbfb8aa3b, v109
	v_mul_f32_e32 v105, 0xbfb8aa3b, v105
	v_mul_f32_e32 v111, 0xbfb8aa3b, v111
	v_mul_f32_e32 v107, 0xbfb8aa3b, v107
	v_mul_f32_e32 v108, 0xbfb8aa3b, v108
	v_mul_f32_e32 v110, 0xbfb8aa3b, v110
	v_mul_f32_e32 v106, 0xbfb8aa3b, v106
	v_exp_f32_e32 v104, v104
	v_exp_f32_e32 v109, v109
	v_exp_f32_e32 v105, v105
	v_exp_f32_e32 v111, v111
	v_exp_f32_e32 v107, v107
	v_exp_f32_e32 v108, v108
	v_exp_f32_e32 v110, v110
	v_exp_f32_e32 v106, v106
	v_add_f32_e32 v104, 1.0, v104
	v_add_f32_e32 v109, 1.0, v109
	v_add_f32_e32 v105, 1.0, v105
	v_add_f32_e32 v111, 1.0, v111
	v_add_f32_e32 v107, 1.0, v107
	v_add_f32_e32 v108, 1.0, v108
	v_add_f32_e32 v110, 1.0, v110
	v_add_f32_e32 v106, 1.0, v106
	v_rcp_f32_e32 v104, v104
	v_rcp_f32_e32 v109, v109
	v_rcp_f32_e32 v105, v105
	v_rcp_f32_e32 v111, v111
	v_rcp_f32_e32 v107, v107
	v_rcp_f32_e32 v108, v108
	v_rcp_f32_e32 v110, v110
	v_rcp_f32_e32 v106, v106
	v_lshlrev_b32_e32 v127, 16, v192
	v_and_b32_e32 v112, 0xffff0000, v192
	v_lshlrev_b32_e32 v149, 16, v193
	v_and_b32_e32 v113, 0xffff0000, v193
	v_lshlrev_b32_e32 v156, 16, v194
	v_and_b32_e32 v114, 0xffff0000, v194
	v_lshlrev_b32_e32 v157, 16, v195
	v_and_b32_e32 v115, 0xffff0000, v195
	v_lshlrev_b32_e32 v159, 16, v187
	v_and_b32_e32 v117, 0xffff0000, v187
	v_lshlrev_b32_e32 v160, 16, v188
	v_and_b32_e32 v118, 0xffff0000, v188
	v_lshlrev_b32_e32 v161, 16, v189
	v_and_b32_e32 v119, 0xffff0000, v189
	v_fmac_f32_e32 v156, v104, v160
	v_fmac_f32_e32 v112, v109, v116
	v_fmac_f32_e32 v114, v105, v118
	v_fmac_f32_e32 v113, v111, v117
	v_fmac_f32_e32 v115, v107, v119
	v_lshl_add_u64 v[104:105], s[36:37], 0, v[120:121]
	v_fmac_f32_e32 v127, v108, v158
	v_fmac_f32_e32 v149, v110, v159
	v_fmac_f32_e32 v157, v106, v161
	v_cvt_pk_bf16_f32 v106, v127, v112
	v_cvt_pk_bf16_f32 v107, v149, v113
	v_cvt_pk_bf16_f32 v108, v156, v114
	v_cvt_pk_bf16_f32 v109, v157, v115
	v_mul_f32_e32 v100, v100, v190
	v_mul_f32_e32 v101, v101, v190
	v_mul_f32_e32 v96, v96, v190
	v_mul_f32_e32 v97, v97, v190
	v_mul_f32_e32 v102, v102, v190
	v_mul_f32_e32 v98, v98, v190
	v_mul_f32_e32 v103, v103, v190
	v_mul_f32_e32 v99, v99, v190
	v_mul_f32_e32 v100, 0xbfb8aa3b, v100
	v_mul_f32_e32 v101, 0xbfb8aa3b, v101
	v_mul_f32_e32 v96, 0xbfb8aa3b, v96
	v_mul_f32_e32 v97, 0xbfb8aa3b, v97
	v_mul_f32_e32 v102, 0xbfb8aa3b, v102
	v_mul_f32_e32 v98, 0xbfb8aa3b, v98
	v_mul_f32_e32 v103, 0xbfb8aa3b, v103
	v_mul_f32_e32 v99, 0xbfb8aa3b, v99
	v_exp_f32_e32 v100, v100
	v_exp_f32_e32 v101, v101
	v_exp_f32_e32 v96, v96
	v_exp_f32_e32 v97, v97
	v_exp_f32_e32 v102, v102
	v_exp_f32_e32 v98, v98
	v_exp_f32_e32 v103, v103
	v_exp_f32_e32 v99, v99
	v_add_f32_e32 v100, 1.0, v100
	v_add_f32_e32 v101, 1.0, v101
	v_or_b32_e32 v118, 32, v148
	v_add_f32_e32 v96, 1.0, v96
	v_add_f32_e32 v97, 1.0, v97
	v_add_f32_e32 v102, 1.0, v102
	v_add_f32_e32 v98, 1.0, v98
	v_add_f32_e32 v103, 1.0, v103
	v_add_f32_e32 v99, 1.0, v99
	v_rcp_f32_e32 v100, v100
	v_rcp_f32_e32 v101, v101
	v_ashrrev_i32_e32 v119, 31, v118
	v_rcp_f32_e32 v96, v96
	v_rcp_f32_e32 v97, v97
	v_rcp_f32_e32 v102, v102
	v_rcp_f32_e32 v98, v98
	v_rcp_f32_e32 v103, v103
	v_rcp_f32_e32 v99, v99
	v_lshlrev_b64 v[104:105], 11, v[118:119]
	v_lshl_add_u64 v[104:105], v[104:105], 0, v[150:151]
	global_store_dwordx4 v[122:123], v[106:109], off
	v_lshlrev_b64 v[104:105], 1, v[104:105]
	v_lshl_add_u64 v[120:121], s[40:41], 0, v[120:121]
	v_lshl_add_u64 v[124:125], s[34:35], 0, v[104:105]
	v_add_u32_e32 v240, 0x80, v148
	v_ashrrev_i32_e32 v241, 31, v240
	v_lshlrev_b64 v[238:239], 11, v[240:241]
	v_lshl_add_u64 v[238:239], v[238:239], 0, v[150:151]
	v_lshlrev_b64 v[238:239], 1, v[238:239]
	v_lshl_add_u64 v[236:237], s[36:37], 0, v[238:239]
	global_load_dwordx4 v[186:189], v[236:237], off
	v_add_u32_e32 v238, 0x80, v148
	v_ashrrev_i32_e32 v239, 31, v238
	v_lshl_add_u64 v[236:237], v[238:239], 2, s[26:27]
	global_load_dword v190, v[236:237], off
	v_add_u32_e32 v238, 0x80, v148
	v_ashrrev_i32_e32 v239, 31, v238
	v_lshlrev_b64 v[236:237], 11, v[238:239]
	v_lshl_add_u64 v[236:237], v[236:237], 0, v[150:151]
	v_lshlrev_b64 v[236:237], 1, v[236:237]
	v_lshl_add_u64 v[240:241], s[34:35], 0, v[236:237]
	global_load_dwordx4 v[192:195], v[240:241], off
	s_waitcnt vmcnt(16)
	v_lshlrev_b32_e32 v106, 16, v196
	v_and_b32_e32 v107, 0xffff0000, v196
	v_lshlrev_b32_e32 v122, 16, v200
	v_and_b32_e32 v114, 0xffff0000, v200
	v_lshlrev_b32_e32 v108, 16, v197
	v_and_b32_e32 v109, 0xffff0000, v197
	v_lshlrev_b32_e32 v110, 16, v198
	v_and_b32_e32 v111, 0xffff0000, v198
	v_lshlrev_b32_e32 v112, 16, v199
	v_and_b32_e32 v113, 0xffff0000, v199
	v_lshlrev_b32_e32 v123, 16, v201
	v_and_b32_e32 v115, 0xffff0000, v201
	v_lshlrev_b32_e32 v126, 16, v202
	v_and_b32_e32 v116, 0xffff0000, v202
	v_lshlrev_b32_e32 v127, 16, v203
	v_and_b32_e32 v117, 0xffff0000, v203
	v_fmac_f32_e32 v106, v100, v122
	v_fmac_f32_e32 v107, v101, v114
	v_fmac_f32_e32 v110, v96, v126
	v_fmac_f32_e32 v111, v97, v116
	v_fmac_f32_e32 v108, v102, v123
	v_fmac_f32_e32 v112, v98, v127
	v_fmac_f32_e32 v109, v103, v115
	v_fmac_f32_e32 v113, v99, v117
	v_cvt_pk_bf16_f32 v96, v106, v107
	v_cvt_pk_bf16_f32 v97, v108, v109
	v_cvt_pk_bf16_f32 v98, v110, v111
	v_cvt_pk_bf16_f32 v99, v112, v113
	global_store_dwordx4 v[120:121], v[96:99], off
	v_lshl_add_u64 v[100:101], s[36:37], 0, v[104:105]
	v_lshl_add_u64 v[106:107], v[118:119], 2, s[26:27]
	s_nop 0
	v_lshl_add_u64 v[106:107], s[40:41], 0, v[104:105]
	v_or_b32_e32 v104, 0x100, v104
	v_lshl_add_u64 v[108:109], s[34:35], 0, v[104:105]
	v_add_u32_e32 v240, 0x80, v148
	v_ashrrev_i32_e32 v241, 31, v240
	v_lshlrev_b64 v[236:237], 11, v[240:241]
	v_lshl_add_u64 v[236:237], v[236:237], 0, v[150:151]
	v_lshlrev_b64 v[236:237], 1, v[236:237]
	v_or_b32_e32 v236, 0x100, v236
	v_lshl_add_u64 v[238:239], s[34:35], 0, v[236:237]
	global_load_dwordx4 v[196:199], v[238:239], off
	v_add_u32_e32 v240, 0x80, v148
	v_ashrrev_i32_e32 v241, 31, v240
	v_lshlrev_b64 v[238:239], 11, v[240:241]
	v_lshl_add_u64 v[238:239], v[238:239], 0, v[150:151]
	v_lshlrev_b64 v[238:239], 1, v[238:239]
	v_or_b32_e32 v238, 0x100, v238
	v_lshl_add_u64 v[236:237], s[36:37], 0, v[238:239]
	global_load_dwordx4 v[200:203], v[236:237], off
	s_waitcnt vmcnt(16)
; __device__ __forceinline__ f32x4 unpk4(uint2 u) { f32x4 r; r[0] = __uint_as_float(u.x << 16); r[1] = __uint_as_float(u.x & 0xffff0000u); r[2] = __uint_as_float(u.y << 16); r[3] = __uint_as_float(u.y & 0xffff0000u); return r; }
; __device__ __forceinline__ float sigm(float x) { return __builtin_amdgcn_rcpf(1.f + __expf(-x)); }
; __device__ __forceinline__ uint4 pk8(f32x4 a, f32x4 b) { return make_uint4(cvt_pk_bf16(a[0], a[1]), cvt_pk_bf16(a[2], a[3]), cvt_pk_bf16(b[0], b[1]), cvt_pk_bf16(b[2], b[3])); }
;     __device__ __forceinline__ void operator()(AccRef acc, const Unit& u, int wr, int wc, int fr, int fq) const {
;     ...
;         for (int ai = 0; ai < 2; ++ai)
; #pragma unroll
;             for (int m = 0; m < 4; ++m) {
;                 const int r = u.pm * 256 + ai * 128 + wr * 64 + m * 16 + fr;
;                 const float s = rinv[r];
;                 float ss = 0.f;
; #pragma unroll
;                 for (int bj = 0; bj < 2; ++bj) {
;                     const size_t o = (size_t)r * D + c0 + bj * 128;
;                     const uint4 h8 = *(const uint4*)(H2 + o);
;                     f32x4 v0 = unpk4(make_uint2(h8.x, h8.y)), v1 = unpk4(make_uint2(h8.z, h8.w));
;                     const uint4 pp8 = *(const uint4*)(PPb + o);
;                     const f32x4 p0 = unpk4(make_uint2(pp8.x, pp8.y)), p1 = unpk4(make_uint2(pp8.z, pp8.w));
; #pragma unroll
;                     for (int e = 0; e < 4; ++e) { v0[e] += sigm(acc[ai][bj][m][0][e] * s) * p0[e]; v1[e] += sigm(acc[ai][bj][m][1][e] * s) * p1[e]; }
;                     ss += v0[0] * v0[0] + v0[1] * v0[1] + v0[2] * v0[2] + v0[3] * v0[3] + v1[0] * v1[0] + v1[1] * v1[1] + v1[2] * v1[2] + v1[3] * v1[3];
;                     *(uint4*)(H3 + o) = pk8(v0, v1);
;                 }
	v_lshlrev_b32_e32 v115, 16, v204
	v_and_b32_e32 v100, 0xffff0000, v204
	v_mul_f32_e32 v88, v88, v191
	v_mul_f32_e32 v93, v93, v191
	v_mul_f32_e32 v89, v89, v191
	v_mul_f32_e32 v95, v95, v191
	v_mul_f32_e32 v91, v91, v191
	v_mul_f32_e32 v92, v92, v191
	v_mul_f32_e32 v94, v94, v191
	v_mul_f32_e32 v90, v90, v191
	v_mul_f32_e32 v88, 0xbfb8aa3b, v88
	v_mul_f32_e32 v93, 0xbfb8aa3b, v93
	v_mul_f32_e32 v89, 0xbfb8aa3b, v89
	v_mul_f32_e32 v95, 0xbfb8aa3b, v95
	v_mul_f32_e32 v91, 0xbfb8aa3b, v91
	v_mul_f32_e32 v92, 0xbfb8aa3b, v92
	v_mul_f32_e32 v94, 0xbfb8aa3b, v94
	v_mul_f32_e32 v90, 0xbfb8aa3b, v90
	v_exp_f32_e32 v88, v88
	v_exp_f32_e32 v93, v93
	v_exp_f32_e32 v89, v89
	v_exp_f32_e32 v95, v95
	v_exp_f32_e32 v91, v91
	v_exp_f32_e32 v92, v92
	v_exp_f32_e32 v94, v94
	v_exp_f32_e32 v90, v90
	v_add_f32_e32 v88, 1.0, v88
	v_add_f32_e32 v93, 1.0, v93
	v_add_f32_e32 v89, 1.0, v89
	v_add_f32_e32 v95, 1.0, v95
	v_add_f32_e32 v91, 1.0, v91
	v_add_f32_e32 v92, 1.0, v92
	v_add_f32_e32 v94, 1.0, v94
	v_add_f32_e32 v90, 1.0, v90
	v_rcp_f32_e32 v88, v88
	v_rcp_f32_e32 v93, v93
	v_rcp_f32_e32 v89, v89
	v_rcp_f32_e32 v95, v95
	v_rcp_f32_e32 v91, v91
	v_rcp_f32_e32 v92, v92
	v_rcp_f32_e32 v94, v94
	v_rcp_f32_e32 v90, v90
	v_lshlrev_b32_e32 v111, 16, v208
	v_and_b32_e32 v96, 0xffff0000, v208
	v_lshlrev_b32_e32 v112, 16, v209
	v_and_b32_e32 v97, 0xffff0000, v209
	v_lshlrev_b32_e32 v113, 16, v210
	v_and_b32_e32 v98, 0xffff0000, v210
	v_lshlrev_b32_e32 v114, 16, v211
	v_and_b32_e32 v99, 0xffff0000, v211
	v_lshlrev_b32_e32 v116, 16, v205
	v_and_b32_e32 v101, 0xffff0000, v205
	v_lshlrev_b32_e32 v117, 16, v206
	v_and_b32_e32 v102, 0xffff0000, v206
	v_lshlrev_b32_e32 v118, 16, v207
	v_and_b32_e32 v103, 0xffff0000, v207
	v_fmac_f32_e32 v113, v88, v117
	v_fmac_f32_e32 v96, v93, v100
	v_fmac_f32_e32 v98, v89, v102
	v_fmac_f32_e32 v97, v95, v101
	v_fmac_f32_e32 v99, v91, v103
	v_lshl_add_u64 v[88:89], s[36:37], 0, v[104:105]
	v_fmac_f32_e32 v111, v92, v115
	v_fmac_f32_e32 v112, v94, v116
	v_fmac_f32_e32 v114, v90, v118
	v_cvt_pk_bf16_f32 v90, v111, v96
	v_cvt_pk_bf16_f32 v91, v112, v97
	v_cvt_pk_bf16_f32 v92, v113, v98
	v_cvt_pk_bf16_f32 v93, v114, v99
	v_mul_f32_e32 v84, v84, v191
	v_mul_f32_e32 v85, v85, v191
	v_mul_f32_e32 v80, v80, v191
	v_mul_f32_e32 v81, v81, v191
	v_mul_f32_e32 v86, v86, v191
	v_mul_f32_e32 v82, v82, v191
	v_mul_f32_e32 v87, v87, v191
	v_mul_f32_e32 v83, v83, v191
	v_mul_f32_e32 v84, 0xbfb8aa3b, v84
	v_mul_f32_e32 v85, 0xbfb8aa3b, v85
	v_mul_f32_e32 v80, 0xbfb8aa3b, v80
	v_mul_f32_e32 v81, 0xbfb8aa3b, v81
	v_mul_f32_e32 v86, 0xbfb8aa3b, v86
	v_mul_f32_e32 v82, 0xbfb8aa3b, v82
	v_mul_f32_e32 v87, 0xbfb8aa3b, v87
	v_mul_f32_e32 v83, 0xbfb8aa3b, v83
	v_exp_f32_e32 v84, v84
	v_exp_f32_e32 v85, v85
	v_exp_f32_e32 v80, v80
	v_exp_f32_e32 v81, v81
	v_exp_f32_e32 v86, v86
	v_exp_f32_e32 v82, v82
	v_exp_f32_e32 v87, v87
	v_exp_f32_e32 v83, v83
	v_add_f32_e32 v84, 1.0, v84
	v_add_f32_e32 v85, 1.0, v85
	v_or_b32_e32 v102, 48, v148
	v_add_f32_e32 v80, 1.0, v80
	v_add_f32_e32 v81, 1.0, v81
	v_add_f32_e32 v86, 1.0, v86
	v_add_f32_e32 v82, 1.0, v82
	v_add_f32_e32 v87, 1.0, v87
	v_add_f32_e32 v83, 1.0, v83
	v_rcp_f32_e32 v84, v84
	v_rcp_f32_e32 v85, v85
	v_ashrrev_i32_e32 v103, 31, v102
	v_rcp_f32_e32 v80, v80
	v_rcp_f32_e32 v81, v81
	v_rcp_f32_e32 v86, v86
	v_rcp_f32_e32 v82, v82
	v_rcp_f32_e32 v87, v87
	v_rcp_f32_e32 v83, v83
	v_lshlrev_b64 v[88:89], 11, v[102:103]
	v_lshl_add_u64 v[88:89], v[88:89], 0, v[150:151]
	global_store_dwordx4 v[106:107], v[90:93], off
	v_lshlrev_b64 v[88:89], 1, v[88:89]
	v_lshl_add_u64 v[104:105], s[40:41], 0, v[104:105]
	v_lshl_add_u64 v[108:109], s[34:35], 0, v[88:89]
	v_add_u32_e32 v240, 0x90, v148
	v_ashrrev_i32_e32 v241, 31, v240
	v_lshlrev_b64 v[238:239], 11, v[240:241]
	v_lshl_add_u64 v[238:239], v[238:239], 0, v[150:151]
	v_lshlrev_b64 v[238:239], 1, v[238:239]
	v_lshl_add_u64 v[236:237], s[36:37], 0, v[238:239]
	global_load_dwordx4 v[204:207], v[236:237], off
	v_add_u32_e32 v238, 0x90, v148
	v_ashrrev_i32_e32 v239, 31, v238
	v_lshl_add_u64 v[236:237], v[238:239], 2, s[26:27]
	global_load_dword v191, v[236:237], off
	v_add_u32_e32 v238, 0x90, v148
	v_ashrrev_i32_e32 v239, 31, v238
	v_lshlrev_b64 v[236:237], 11, v[238:239]
	v_lshl_add_u64 v[236:237], v[236:237], 0, v[150:151]
	v_lshlrev_b64 v[236:237], 1, v[236:237]
	v_lshl_add_u64 v[240:241], s[34:35], 0, v[236:237]
	global_load_dwordx4 v[208:211], v[240:241], off
	s_waitcnt vmcnt(18)
	v_lshlrev_b32_e32 v90, 16, v212
	v_and_b32_e32 v91, 0xffff0000, v212
	v_lshlrev_b32_e32 v106, 16, v216
	v_and_b32_e32 v98, 0xffff0000, v216
	v_lshlrev_b32_e32 v92, 16, v213
	v_and_b32_e32 v93, 0xffff0000, v213
	v_lshlrev_b32_e32 v94, 16, v214
	v_and_b32_e32 v95, 0xffff0000, v214
	v_lshlrev_b32_e32 v96, 16, v215
	v_and_b32_e32 v97, 0xffff0000, v215
	v_lshlrev_b32_e32 v107, 16, v217
	v_and_b32_e32 v99, 0xffff0000, v217
	v_lshlrev_b32_e32 v110, 16, v218
	v_and_b32_e32 v100, 0xffff0000, v218
	v_lshlrev_b32_e32 v111, 16, v219
	v_and_b32_e32 v101, 0xffff0000, v219
	v_fmac_f32_e32 v90, v84, v106
	v_fmac_f32_e32 v91, v85, v98
	v_fmac_f32_e32 v94, v80, v110
	v_fmac_f32_e32 v95, v81, v100
	v_fmac_f32_e32 v92, v86, v107
	v_fmac_f32_e32 v96, v82, v111
	v_fmac_f32_e32 v93, v87, v99
	v_fmac_f32_e32 v97, v83, v101
	v_cvt_pk_bf16_f32 v80, v90, v91
	v_cvt_pk_bf16_f32 v81, v92, v93
	v_cvt_pk_bf16_f32 v82, v94, v95
	v_cvt_pk_bf16_f32 v83, v96, v97
	global_store_dwordx4 v[104:105], v[80:83], off
	v_lshl_add_u64 v[84:85], s[36:37], 0, v[88:89]
	v_lshl_add_u64 v[90:91], v[102:103], 2, s[26:27]
	s_nop 0
	v_lshl_add_u64 v[90:91], s[40:41], 0, v[88:89]
	v_or_b32_e32 v88, 0x100, v88
	v_lshl_add_u64 v[92:93], s[34:35], 0, v[88:89]
	v_add_u32_e32 v240, 0x90, v148
	v_ashrrev_i32_e32 v241, 31, v240
	v_lshlrev_b64 v[236:237], 11, v[240:241]
	v_lshl_add_u64 v[236:237], v[236:237], 0, v[150:151]
	v_lshlrev_b64 v[236:237], 1, v[236:237]
	v_or_b32_e32 v236, 0x100, v236
	v_lshl_add_u64 v[238:239], s[34:35], 0, v[236:237]
	global_load_dwordx4 v[212:215], v[238:239], off
	v_add_u32_e32 v240, 0x90, v148
	v_ashrrev_i32_e32 v241, 31, v240
	v_lshlrev_b64 v[238:239], 11, v[240:241]
	v_lshl_add_u64 v[238:239], v[238:239], 0, v[150:151]
	v_lshlrev_b64 v[238:239], 1, v[238:239]
	v_or_b32_e32 v238, 0x100, v238
	v_lshl_add_u64 v[236:237], s[36:37], 0, v[238:239]
	global_load_dwordx4 v[216:219], v[236:237], off
	s_waitcnt vmcnt(17)
; __device__ __forceinline__ f32x4 unpk4(uint2 u) { f32x4 r; r[0] = __uint_as_float(u.x << 16); r[1] = __uint_as_float(u.x & 0xffff0000u); r[2] = __uint_as_float(u.y << 16); r[3] = __uint_as_float(u.y & 0xffff0000u); return r; }
; __device__ __forceinline__ float sigm(float x) { return __builtin_amdgcn_rcpf(1.f + __expf(-x)); }
; __device__ __forceinline__ uint4 pk8(f32x4 a, f32x4 b) { return make_uint4(cvt_pk_bf16(a[0], a[1]), cvt_pk_bf16(a[2], a[3]), cvt_pk_bf16(b[0], b[1]), cvt_pk_bf16(b[2], b[3])); }
;     __device__ __forceinline__ void operator()(AccRef acc, const Unit& u, int wr, int wc, int fr, int fq) const {
;     ...
;         for (int ai = 0; ai < 2; ++ai)
; #pragma unroll
;             for (int m = 0; m < 4; ++m) {
;                 const int r = u.pm * 256 + ai * 128 + wr * 64 + m * 16 + fr;
;                 const float s = rinv[r];
;                 float ss = 0.f;
; #pragma unroll
;                 for (int bj = 0; bj < 2; ++bj) {
;                     const size_t o = (size_t)r * D + c0 + bj * 128;
;                     const uint4 h8 = *(const uint4*)(H2 + o);
;                     f32x4 v0 = unpk4(make_uint2(h8.x, h8.y)), v1 = unpk4(make_uint2(h8.z, h8.w));
;                     const uint4 pp8 = *(const uint4*)(PPb + o);
;                     const f32x4 p0 = unpk4(make_uint2(pp8.x, pp8.y)), p1 = unpk4(make_uint2(pp8.z, pp8.w));
; #pragma unroll
;                     for (int e = 0; e < 4; ++e) { v0[e] += sigm(acc[ai][bj][m][0][e] * s) * p0[e]; v1[e] += sigm(acc[ai][bj][m][1][e] * s) * p1[e]; }
;                     ss += v0[0] * v0[0] + v0[1] * v0[1] + v0[2] * v0[2] + v0[3] * v0[3] + v1[0] * v1[0] + v1[1] * v1[1] + v1[2] * v1[2] + v1[3] * v1[3];
;                     *(uint4*)(H3 + o) = pk8(v0, v1);
;                 }
	v_lshlrev_b32_e32 v99, 16, v220
	v_and_b32_e32 v84, 0xffff0000, v220
	v_mul_f32_e32 v72, v72, v224
	v_mul_f32_e32 v77, v77, v224
	v_mul_f32_e32 v73, v73, v224
	v_mul_f32_e32 v79, v79, v224
	v_mul_f32_e32 v75, v75, v224
	v_mul_f32_e32 v76, v76, v224
	v_mul_f32_e32 v78, v78, v224
	v_mul_f32_e32 v74, v74, v224
	v_mul_f32_e32 v72, 0xbfb8aa3b, v72
	v_mul_f32_e32 v77, 0xbfb8aa3b, v77
	v_mul_f32_e32 v73, 0xbfb8aa3b, v73
	v_mul_f32_e32 v79, 0xbfb8aa3b, v79
	v_mul_f32_e32 v75, 0xbfb8aa3b, v75
	v_mul_f32_e32 v76, 0xbfb8aa3b, v76
	v_mul_f32_e32 v78, 0xbfb8aa3b, v78
	v_mul_f32_e32 v74, 0xbfb8aa3b, v74
	v_exp_f32_e32 v72, v72
	v_exp_f32_e32 v77, v77
	v_exp_f32_e32 v73, v73
	v_exp_f32_e32 v79, v79
	v_exp_f32_e32 v75, v75
	v_exp_f32_e32 v76, v76
	v_exp_f32_e32 v78, v78
	v_exp_f32_e32 v74, v74
	v_add_f32_e32 v72, 1.0, v72
	v_add_f32_e32 v77, 1.0, v77
	v_add_f32_e32 v73, 1.0, v73
	v_add_f32_e32 v79, 1.0, v79
	v_add_f32_e32 v75, 1.0, v75
	v_add_f32_e32 v76, 1.0, v76
	v_add_f32_e32 v78, 1.0, v78
	v_add_f32_e32 v74, 1.0, v74
	v_rcp_f32_e32 v72, v72
	v_rcp_f32_e32 v77, v77
	v_rcp_f32_e32 v73, v73
	v_rcp_f32_e32 v79, v79
	v_rcp_f32_e32 v75, v75
	v_rcp_f32_e32 v76, v76
	v_rcp_f32_e32 v78, v78
	v_rcp_f32_e32 v74, v74
	v_lshlrev_b32_e32 v95, 16, v226
	v_and_b32_e32 v80, 0xffff0000, v226
	v_lshlrev_b32_e32 v96, 16, v227
	v_and_b32_e32 v81, 0xffff0000, v227
	v_lshlrev_b32_e32 v97, 16, v228
	v_and_b32_e32 v82, 0xffff0000, v228
	v_lshlrev_b32_e32 v98, 16, v229
	v_and_b32_e32 v83, 0xffff0000, v229
	v_lshlrev_b32_e32 v100, 16, v221
	v_and_b32_e32 v85, 0xffff0000, v221
	v_lshlrev_b32_e32 v101, 16, v222
	v_and_b32_e32 v86, 0xffff0000, v222
	v_lshlrev_b32_e32 v102, 16, v223
	v_and_b32_e32 v87, 0xffff0000, v223
	v_fmac_f32_e32 v97, v72, v101
	v_fmac_f32_e32 v80, v77, v84
	v_fmac_f32_e32 v82, v73, v86
	v_fmac_f32_e32 v81, v79, v85
	v_fmac_f32_e32 v83, v75, v87
	v_lshl_add_u64 v[72:73], s[36:37], 0, v[88:89]
	v_fmac_f32_e32 v95, v76, v99
	v_fmac_f32_e32 v96, v78, v100
	v_fmac_f32_e32 v98, v74, v102
	v_cvt_pk_bf16_f32 v74, v95, v80
	v_cvt_pk_bf16_f32 v75, v96, v81
	v_cvt_pk_bf16_f32 v76, v97, v82
	v_cvt_pk_bf16_f32 v77, v98, v83
	v_mul_f32_e32 v68, v68, v224
	v_mul_f32_e32 v69, v69, v224
	v_mul_f32_e32 v64, v64, v224
	v_mul_f32_e32 v65, v65, v224
	v_mul_f32_e32 v70, v70, v224
	v_mul_f32_e32 v66, v66, v224
	v_mul_f32_e32 v71, v71, v224
	v_mul_f32_e32 v67, v67, v224
	v_mul_f32_e32 v68, 0xbfb8aa3b, v68
	v_mul_f32_e32 v69, 0xbfb8aa3b, v69
	v_mul_f32_e32 v64, 0xbfb8aa3b, v64
	v_mul_f32_e32 v65, 0xbfb8aa3b, v65
	v_mul_f32_e32 v70, 0xbfb8aa3b, v70
	v_mul_f32_e32 v66, 0xbfb8aa3b, v66
	v_mul_f32_e32 v71, 0xbfb8aa3b, v71
	v_mul_f32_e32 v67, 0xbfb8aa3b, v67
	v_exp_f32_e32 v68, v68
	v_exp_f32_e32 v69, v69
	v_exp_f32_e32 v64, v64
	v_exp_f32_e32 v65, v65
	v_exp_f32_e32 v70, v70
	v_exp_f32_e32 v66, v66
	v_exp_f32_e32 v71, v71
	v_exp_f32_e32 v67, v67
	v_add_f32_e32 v68, 1.0, v68
	v_add_f32_e32 v69, 1.0, v69
	v_add_u32_e32 v86, 0x80, v148
	v_add_f32_e32 v64, 1.0, v64
	v_add_f32_e32 v65, 1.0, v65
	v_add_f32_e32 v70, 1.0, v70
	v_add_f32_e32 v66, 1.0, v66
	v_add_f32_e32 v71, 1.0, v71
	v_add_f32_e32 v67, 1.0, v67
	v_rcp_f32_e32 v68, v68
	v_rcp_f32_e32 v69, v69
	v_ashrrev_i32_e32 v87, 31, v86
	v_rcp_f32_e32 v64, v64
	v_rcp_f32_e32 v65, v65
	v_rcp_f32_e32 v70, v70
	v_rcp_f32_e32 v66, v66
	v_rcp_f32_e32 v71, v71
	v_rcp_f32_e32 v67, v67
	v_lshlrev_b64 v[72:73], 11, v[86:87]
	v_lshl_add_u64 v[72:73], v[72:73], 0, v[150:151]
	global_store_dwordx4 v[90:91], v[74:77], off
	v_lshlrev_b64 v[72:73], 1, v[72:73]
	v_lshl_add_u64 v[88:89], s[40:41], 0, v[88:89]
	v_lshl_add_u64 v[92:93], s[34:35], 0, v[72:73]
	v_add_u32_e32 v240, 0xa0, v148
	v_ashrrev_i32_e32 v241, 31, v240
	v_lshlrev_b64 v[238:239], 11, v[240:241]
	v_lshl_add_u64 v[238:239], v[238:239], 0, v[150:151]
	v_lshlrev_b64 v[238:239], 1, v[238:239]
	v_lshl_add_u64 v[236:237], s[36:37], 0, v[238:239]
	global_load_dwordx4 v[220:223], v[236:237], off
	v_add_u32_e32 v238, 0xa0, v148
	v_ashrrev_i32_e32 v239, 31, v238
	v_lshl_add_u64 v[236:237], v[238:239], 2, s[26:27]
	global_load_dword v224, v[236:237], off
	v_add_u32_e32 v238, 0xa0, v148
	v_ashrrev_i32_e32 v239, 31, v238
	v_lshlrev_b64 v[236:237], 11, v[238:239]
	v_lshl_add_u64 v[236:237], v[236:237], 0, v[150:151]
	v_lshlrev_b64 v[236:237], 1, v[236:237]
	v_lshl_add_u64 v[240:241], s[34:35], 0, v[236:237]
	global_load_dwordx4 v[226:229], v[240:241], off
	s_waitcnt vmcnt(18)
	v_lshlrev_b32_e32 v74, 16, v178
	v_and_b32_e32 v75, 0xffff0000, v178
	v_lshlrev_b32_e32 v90, 16, v182
	v_and_b32_e32 v82, 0xffff0000, v182
	v_lshlrev_b32_e32 v76, 16, v179
	v_and_b32_e32 v77, 0xffff0000, v179
	v_lshlrev_b32_e32 v78, 16, v180
	v_and_b32_e32 v79, 0xffff0000, v180
	v_lshlrev_b32_e32 v80, 16, v181
	v_and_b32_e32 v81, 0xffff0000, v181
	v_lshlrev_b32_e32 v91, 16, v183
	v_and_b32_e32 v83, 0xffff0000, v183
	v_lshlrev_b32_e32 v94, 16, v184
	v_and_b32_e32 v84, 0xffff0000, v184
	v_lshlrev_b32_e32 v95, 16, v185
	v_and_b32_e32 v85, 0xffff0000, v185
	v_fmac_f32_e32 v74, v68, v90
	v_fmac_f32_e32 v75, v69, v82
	v_fmac_f32_e32 v78, v64, v94
	v_fmac_f32_e32 v79, v65, v84
	v_fmac_f32_e32 v76, v70, v91
	v_fmac_f32_e32 v80, v66, v95
	v_fmac_f32_e32 v77, v71, v83
	v_fmac_f32_e32 v81, v67, v85
	v_cvt_pk_bf16_f32 v64, v74, v75
	v_cvt_pk_bf16_f32 v65, v76, v77
	v_cvt_pk_bf16_f32 v66, v78, v79
	v_cvt_pk_bf16_f32 v67, v80, v81
	global_store_dwordx4 v[88:89], v[64:67], off
	v_lshl_add_u64 v[68:69], s[36:37], 0, v[72:73]
	v_lshl_add_u64 v[74:75], v[86:87], 2, s[26:27]
	s_nop 0
	v_lshl_add_u64 v[74:75], s[40:41], 0, v[72:73]
	v_or_b32_e32 v72, 0x100, v72
	v_lshl_add_u64 v[76:77], s[34:35], 0, v[72:73]
	v_add_u32_e32 v240, 0xa0, v148
	v_ashrrev_i32_e32 v241, 31, v240
	v_lshlrev_b64 v[236:237], 11, v[240:241]
	v_lshl_add_u64 v[236:237], v[236:237], 0, v[150:151]
	v_lshlrev_b64 v[236:237], 1, v[236:237]
	v_or_b32_e32 v236, 0x100, v236
	v_lshl_add_u64 v[238:239], s[34:35], 0, v[236:237]
	global_load_dwordx4 v[178:181], v[238:239], off
	v_add_u32_e32 v240, 0xa0, v148
	v_ashrrev_i32_e32 v241, 31, v240
	v_lshlrev_b64 v[238:239], 11, v[240:241]
	v_lshl_add_u64 v[238:239], v[238:239], 0, v[150:151]
	v_lshlrev_b64 v[238:239], 1, v[238:239]
	v_or_b32_e32 v238, 0x100, v238
	v_lshl_add_u64 v[236:237], s[36:37], 0, v[238:239]
	global_load_dwordx4 v[182:185], v[236:237], off
	s_waitcnt vmcnt(17)
; __device__ __forceinline__ f32x4 unpk4(uint2 u) { f32x4 r; r[0] = __uint_as_float(u.x << 16); r[1] = __uint_as_float(u.x & 0xffff0000u); r[2] = __uint_as_float(u.y << 16); r[3] = __uint_as_float(u.y & 0xffff0000u); return r; }
; __device__ __forceinline__ float sigm(float x) { return __builtin_amdgcn_rcpf(1.f + __expf(-x)); }
; __device__ __forceinline__ uint4 pk8(f32x4 a, f32x4 b) { return make_uint4(cvt_pk_bf16(a[0], a[1]), cvt_pk_bf16(a[2], a[3]), cvt_pk_bf16(b[0], b[1]), cvt_pk_bf16(b[2], b[3])); }
;     __device__ __forceinline__ void operator()(AccRef acc, const Unit& u, int wr, int wc, int fr, int fq) const {
;     ...
;         for (int ai = 0; ai < 2; ++ai)
; #pragma unroll
;             for (int m = 0; m < 4; ++m) {
;                 const int r = u.pm * 256 + ai * 128 + wr * 64 + m * 16 + fr;
;                 const float s = rinv[r];
;                 float ss = 0.f;
; #pragma unroll
;                 for (int bj = 0; bj < 2; ++bj) {
;                     const size_t o = (size_t)r * D + c0 + bj * 128;
;                     const uint4 h8 = *(const uint4*)(H2 + o);
;                     f32x4 v0 = unpk4(make_uint2(h8.x, h8.y)), v1 = unpk4(make_uint2(h8.z, h8.w));
;                     const uint4 pp8 = *(const uint4*)(PPb + o);
;                     const f32x4 p0 = unpk4(make_uint2(pp8.x, pp8.y)), p1 = unpk4(make_uint2(pp8.z, pp8.w));
; #pragma unroll
;                     for (int e = 0; e < 4; ++e) { v0[e] += sigm(acc[ai][bj][m][0][e] * s) * p0[e]; v1[e] += sigm(acc[ai][bj][m][1][e] * s) * p1[e]; }
;                     ss += v0[0] * v0[0] + v0[1] * v0[1] + v0[2] * v0[2] + v0[3] * v0[3] + v1[0] * v1[0] + v1[1] * v1[1] + v1[2] * v1[2] + v1[3] * v1[3];
;                     *(uint4*)(H3 + o) = pk8(v0, v1);
;                 }
	v_lshlrev_b32_e32 v83, 16, v186
	v_and_b32_e32 v68, 0xffff0000, v186
	v_mul_f32_e32 v56, v56, v190
	v_mul_f32_e32 v61, v61, v190
	v_mul_f32_e32 v57, v57, v190
	v_mul_f32_e32 v63, v63, v190
	v_mul_f32_e32 v59, v59, v190
	v_mul_f32_e32 v60, v60, v190
	v_mul_f32_e32 v62, v62, v190
	v_mul_f32_e32 v58, v58, v190
	v_mul_f32_e32 v56, 0xbfb8aa3b, v56
	v_mul_f32_e32 v61, 0xbfb8aa3b, v61
	v_mul_f32_e32 v57, 0xbfb8aa3b, v57
	v_mul_f32_e32 v63, 0xbfb8aa3b, v63
	v_mul_f32_e32 v59, 0xbfb8aa3b, v59
	v_mul_f32_e32 v60, 0xbfb8aa3b, v60
	v_mul_f32_e32 v62, 0xbfb8aa3b, v62
	v_mul_f32_e32 v58, 0xbfb8aa3b, v58
	v_exp_f32_e32 v56, v56
	v_exp_f32_e32 v61, v61
	v_exp_f32_e32 v57, v57
	v_exp_f32_e32 v63, v63
	v_exp_f32_e32 v59, v59
	v_exp_f32_e32 v60, v60
	v_exp_f32_e32 v62, v62
	v_exp_f32_e32 v58, v58
	v_add_f32_e32 v56, 1.0, v56
	v_add_f32_e32 v61, 1.0, v61
	v_add_f32_e32 v57, 1.0, v57
	v_add_f32_e32 v63, 1.0, v63
	v_add_f32_e32 v59, 1.0, v59
	v_add_f32_e32 v60, 1.0, v60
	v_add_f32_e32 v62, 1.0, v62
	v_add_f32_e32 v58, 1.0, v58
	v_rcp_f32_e32 v56, v56
	v_rcp_f32_e32 v61, v61
	v_rcp_f32_e32 v57, v57
	v_rcp_f32_e32 v63, v63
	v_rcp_f32_e32 v59, v59
	v_rcp_f32_e32 v60, v60
	v_rcp_f32_e32 v62, v62
	v_rcp_f32_e32 v58, v58
	v_lshlrev_b32_e32 v79, 16, v192
	v_and_b32_e32 v64, 0xffff0000, v192
	v_lshlrev_b32_e32 v80, 16, v193
	v_and_b32_e32 v65, 0xffff0000, v193
	v_lshlrev_b32_e32 v81, 16, v194
	v_and_b32_e32 v66, 0xffff0000, v194
	v_lshlrev_b32_e32 v82, 16, v195
	v_and_b32_e32 v67, 0xffff0000, v195
	v_lshlrev_b32_e32 v84, 16, v187
	v_and_b32_e32 v69, 0xffff0000, v187
	v_lshlrev_b32_e32 v85, 16, v188
	v_and_b32_e32 v70, 0xffff0000, v188
	v_lshlrev_b32_e32 v86, 16, v189
	v_and_b32_e32 v71, 0xffff0000, v189
	v_fmac_f32_e32 v81, v56, v85
	v_fmac_f32_e32 v64, v61, v68
	v_fmac_f32_e32 v66, v57, v70
	v_fmac_f32_e32 v65, v63, v69
	v_fmac_f32_e32 v67, v59, v71
	v_lshl_add_u64 v[56:57], s[36:37], 0, v[72:73]
	v_fmac_f32_e32 v79, v60, v83
	v_fmac_f32_e32 v80, v62, v84
	v_fmac_f32_e32 v82, v58, v86
	v_cvt_pk_bf16_f32 v58, v79, v64
	v_cvt_pk_bf16_f32 v59, v80, v65
	v_cvt_pk_bf16_f32 v60, v81, v66
	v_cvt_pk_bf16_f32 v61, v82, v67
	v_mul_f32_e32 v52, v52, v190
	v_mul_f32_e32 v53, v53, v190
	v_mul_f32_e32 v48, v48, v190
	v_mul_f32_e32 v49, v49, v190
	v_mul_f32_e32 v54, v54, v190
	v_mul_f32_e32 v50, v50, v190
	v_mul_f32_e32 v55, v55, v190
	v_mul_f32_e32 v51, v51, v190
	v_mul_f32_e32 v52, 0xbfb8aa3b, v52
	v_mul_f32_e32 v53, 0xbfb8aa3b, v53
	v_mul_f32_e32 v48, 0xbfb8aa3b, v48
	v_mul_f32_e32 v49, 0xbfb8aa3b, v49
	v_mul_f32_e32 v54, 0xbfb8aa3b, v54
	v_mul_f32_e32 v50, 0xbfb8aa3b, v50
	v_mul_f32_e32 v55, 0xbfb8aa3b, v55
	v_mul_f32_e32 v51, 0xbfb8aa3b, v51
	v_exp_f32_e32 v52, v52
	v_exp_f32_e32 v53, v53
	v_exp_f32_e32 v48, v48
	v_exp_f32_e32 v49, v49
	v_exp_f32_e32 v54, v54
	v_exp_f32_e32 v50, v50
	v_exp_f32_e32 v55, v55
	v_exp_f32_e32 v51, v51
	v_add_f32_e32 v52, 1.0, v52
	v_add_f32_e32 v53, 1.0, v53
	v_add_u32_e32 v70, 0x90, v148
	v_add_f32_e32 v48, 1.0, v48
	v_add_f32_e32 v49, 1.0, v49
	v_add_f32_e32 v54, 1.0, v54
	v_add_f32_e32 v50, 1.0, v50
	v_add_f32_e32 v55, 1.0, v55
	v_add_f32_e32 v51, 1.0, v51
	v_rcp_f32_e32 v52, v52
	v_rcp_f32_e32 v53, v53
	v_ashrrev_i32_e32 v71, 31, v70
	v_rcp_f32_e32 v48, v48
	v_rcp_f32_e32 v49, v49
	v_rcp_f32_e32 v54, v54
	v_rcp_f32_e32 v50, v50
	v_rcp_f32_e32 v55, v55
	v_rcp_f32_e32 v51, v51
	v_lshlrev_b64 v[56:57], 11, v[70:71]
	v_lshl_add_u64 v[56:57], v[56:57], 0, v[150:151]
	global_store_dwordx4 v[74:75], v[58:61], off
	v_lshlrev_b64 v[56:57], 1, v[56:57]
	v_lshl_add_u64 v[72:73], s[40:41], 0, v[72:73]
	v_lshl_add_u64 v[76:77], s[34:35], 0, v[56:57]
	v_add_u32_e32 v240, 0xb0, v148
	v_ashrrev_i32_e32 v241, 31, v240
	v_lshlrev_b64 v[238:239], 11, v[240:241]
	v_lshl_add_u64 v[238:239], v[238:239], 0, v[150:151]
	v_lshlrev_b64 v[238:239], 1, v[238:239]
	v_lshl_add_u64 v[236:237], s[36:37], 0, v[238:239]
	global_load_dwordx4 v[186:189], v[236:237], off
	v_add_u32_e32 v238, 0xb0, v148
	v_ashrrev_i32_e32 v239, 31, v238
	v_lshl_add_u64 v[236:237], v[238:239], 2, s[26:27]
	global_load_dword v190, v[236:237], off
	v_add_u32_e32 v238, 0xb0, v148
	v_ashrrev_i32_e32 v239, 31, v238
	v_lshlrev_b64 v[236:237], 11, v[238:239]
	v_lshl_add_u64 v[236:237], v[236:237], 0, v[150:151]
	v_lshlrev_b64 v[236:237], 1, v[236:237]
	v_lshl_add_u64 v[240:241], s[34:35], 0, v[236:237]
	global_load_dwordx4 v[192:195], v[240:241], off
	s_waitcnt vmcnt(18)
	v_lshlrev_b32_e32 v58, 16, v196
	v_and_b32_e32 v59, 0xffff0000, v196
	v_lshlrev_b32_e32 v74, 16, v200
	v_and_b32_e32 v66, 0xffff0000, v200
	v_lshlrev_b32_e32 v60, 16, v197
	v_and_b32_e32 v61, 0xffff0000, v197
	v_lshlrev_b32_e32 v62, 16, v198
	v_and_b32_e32 v63, 0xffff0000, v198
	v_lshlrev_b32_e32 v64, 16, v199
	v_and_b32_e32 v65, 0xffff0000, v199
	v_lshlrev_b32_e32 v75, 16, v201
	v_and_b32_e32 v67, 0xffff0000, v201
	v_lshlrev_b32_e32 v78, 16, v202
	v_and_b32_e32 v68, 0xffff0000, v202
	v_lshlrev_b32_e32 v79, 16, v203
	v_and_b32_e32 v69, 0xffff0000, v203
	v_fmac_f32_e32 v58, v52, v74
	v_fmac_f32_e32 v59, v53, v66
	v_fmac_f32_e32 v62, v48, v78
	v_fmac_f32_e32 v63, v49, v68
	v_fmac_f32_e32 v60, v54, v75
	v_fmac_f32_e32 v64, v50, v79
	v_fmac_f32_e32 v61, v55, v67
	v_fmac_f32_e32 v65, v51, v69
	v_cvt_pk_bf16_f32 v48, v58, v59
	v_cvt_pk_bf16_f32 v49, v60, v61
	v_cvt_pk_bf16_f32 v50, v62, v63
	v_cvt_pk_bf16_f32 v51, v64, v65
	global_store_dwordx4 v[72:73], v[48:51], off
	v_lshl_add_u64 v[52:53], s[36:37], 0, v[56:57]
	v_lshl_add_u64 v[58:59], v[70:71], 2, s[26:27]
	s_nop 0
	v_lshl_add_u64 v[58:59], s[40:41], 0, v[56:57]
	v_or_b32_e32 v56, 0x100, v56
	v_lshl_add_u64 v[60:61], s[34:35], 0, v[56:57]
	v_add_u32_e32 v240, 0xb0, v148
	v_ashrrev_i32_e32 v241, 31, v240
	v_lshlrev_b64 v[236:237], 11, v[240:241]
	v_lshl_add_u64 v[236:237], v[236:237], 0, v[150:151]
	v_lshlrev_b64 v[236:237], 1, v[236:237]
	v_or_b32_e32 v236, 0x100, v236
	v_lshl_add_u64 v[238:239], s[34:35], 0, v[236:237]
	global_load_dwordx4 v[196:199], v[238:239], off
	v_add_u32_e32 v240, 0xb0, v148
	v_ashrrev_i32_e32 v241, 31, v240
	v_lshlrev_b64 v[238:239], 11, v[240:241]
	v_lshl_add_u64 v[238:239], v[238:239], 0, v[150:151]
	v_lshlrev_b64 v[238:239], 1, v[238:239]
	v_or_b32_e32 v238, 0x100, v238
	v_lshl_add_u64 v[236:237], s[36:37], 0, v[238:239]
	global_load_dwordx4 v[200:203], v[236:237], off
	s_waitcnt vmcnt(17)
; __device__ __forceinline__ f32x4 unpk4(uint2 u) { f32x4 r; r[0] = __uint_as_float(u.x << 16); r[1] = __uint_as_float(u.x & 0xffff0000u); r[2] = __uint_as_float(u.y << 16); r[3] = __uint_as_float(u.y & 0xffff0000u); return r; }
; __device__ __forceinline__ float sigm(float x) { return __builtin_amdgcn_rcpf(1.f + __expf(-x)); }
; __device__ __forceinline__ uint4 pk8(f32x4 a, f32x4 b) { return make_uint4(cvt_pk_bf16(a[0], a[1]), cvt_pk_bf16(a[2], a[3]), cvt_pk_bf16(b[0], b[1]), cvt_pk_bf16(b[2], b[3])); }
;     __device__ __forceinline__ void operator()(AccRef acc, const Unit& u, int wr, int wc, int fr, int fq) const {
;     ...
;         for (int ai = 0; ai < 2; ++ai)
; #pragma unroll
;             for (int m = 0; m < 4; ++m) {
;                 const int r = u.pm * 256 + ai * 128 + wr * 64 + m * 16 + fr;
;                 const float s = rinv[r];
;                 float ss = 0.f;
; #pragma unroll
;                 for (int bj = 0; bj < 2; ++bj) {
;                     const size_t o = (size_t)r * D + c0 + bj * 128;
;                     const uint4 h8 = *(const uint4*)(H2 + o);
;                     f32x4 v0 = unpk4(make_uint2(h8.x, h8.y)), v1 = unpk4(make_uint2(h8.z, h8.w));
;                     const uint4 pp8 = *(const uint4*)(PPb + o);
;                     const f32x4 p0 = unpk4(make_uint2(pp8.x, pp8.y)), p1 = unpk4(make_uint2(pp8.z, pp8.w));
; #pragma unroll
;                     for (int e = 0; e < 4; ++e) { v0[e] += sigm(acc[ai][bj][m][0][e] * s) * p0[e]; v1[e] += sigm(acc[ai][bj][m][1][e] * s) * p1[e]; }
;                     ss += v0[0] * v0[0] + v0[1] * v0[1] + v0[2] * v0[2] + v0[3] * v0[3] + v1[0] * v1[0] + v1[1] * v1[1] + v1[2] * v1[2] + v1[3] * v1[3];
;                     *(uint4*)(H3 + o) = pk8(v0, v1);
;                 }
	v_lshlrev_b32_e32 v67, 16, v204
	v_and_b32_e32 v52, 0xffff0000, v204
	v_mul_f32_e32 v40, v40, v191
	v_mul_f32_e32 v45, v45, v191
	v_mul_f32_e32 v41, v41, v191
	v_mul_f32_e32 v47, v47, v191
	v_mul_f32_e32 v43, v43, v191
	v_mul_f32_e32 v44, v44, v191
	v_mul_f32_e32 v46, v46, v191
	v_mul_f32_e32 v42, v42, v191
	v_mul_f32_e32 v40, 0xbfb8aa3b, v40
	v_mul_f32_e32 v45, 0xbfb8aa3b, v45
	v_mul_f32_e32 v41, 0xbfb8aa3b, v41
	v_mul_f32_e32 v47, 0xbfb8aa3b, v47
	v_mul_f32_e32 v43, 0xbfb8aa3b, v43
	v_mul_f32_e32 v44, 0xbfb8aa3b, v44
	v_mul_f32_e32 v46, 0xbfb8aa3b, v46
	v_mul_f32_e32 v42, 0xbfb8aa3b, v42
	v_exp_f32_e32 v40, v40
	v_exp_f32_e32 v45, v45
	v_exp_f32_e32 v41, v41
	v_exp_f32_e32 v47, v47
	v_exp_f32_e32 v43, v43
	v_exp_f32_e32 v44, v44
	v_exp_f32_e32 v46, v46
	v_exp_f32_e32 v42, v42
	v_add_f32_e32 v40, 1.0, v40
	v_add_f32_e32 v45, 1.0, v45
	v_add_f32_e32 v41, 1.0, v41
	v_add_f32_e32 v47, 1.0, v47
	v_add_f32_e32 v43, 1.0, v43
	v_add_f32_e32 v44, 1.0, v44
	v_add_f32_e32 v46, 1.0, v46
	v_add_f32_e32 v42, 1.0, v42
	v_rcp_f32_e32 v40, v40
	v_rcp_f32_e32 v45, v45
	v_rcp_f32_e32 v41, v41
	v_rcp_f32_e32 v47, v47
	v_rcp_f32_e32 v43, v43
	v_rcp_f32_e32 v44, v44
	v_rcp_f32_e32 v46, v46
	v_rcp_f32_e32 v42, v42
	v_lshlrev_b32_e32 v63, 16, v208
	v_and_b32_e32 v48, 0xffff0000, v208
	v_lshlrev_b32_e32 v64, 16, v209
	v_and_b32_e32 v49, 0xffff0000, v209
	v_lshlrev_b32_e32 v65, 16, v210
	v_and_b32_e32 v50, 0xffff0000, v210
	v_lshlrev_b32_e32 v66, 16, v211
	v_and_b32_e32 v51, 0xffff0000, v211
	v_lshlrev_b32_e32 v68, 16, v205
	v_and_b32_e32 v53, 0xffff0000, v205
	v_lshlrev_b32_e32 v69, 16, v206
	v_and_b32_e32 v54, 0xffff0000, v206
	v_lshlrev_b32_e32 v70, 16, v207
	v_and_b32_e32 v55, 0xffff0000, v207
	v_fmac_f32_e32 v65, v40, v69
	v_fmac_f32_e32 v48, v45, v52
	v_fmac_f32_e32 v50, v41, v54
	v_fmac_f32_e32 v49, v47, v53
	v_fmac_f32_e32 v51, v43, v55
	v_lshl_add_u64 v[40:41], s[36:37], 0, v[56:57]
	v_fmac_f32_e32 v63, v44, v67
	v_fmac_f32_e32 v64, v46, v68
	v_fmac_f32_e32 v66, v42, v70
	v_cvt_pk_bf16_f32 v42, v63, v48
	v_cvt_pk_bf16_f32 v43, v64, v49
	v_cvt_pk_bf16_f32 v44, v65, v50
	v_cvt_pk_bf16_f32 v45, v66, v51
	v_mul_f32_e32 v36, v36, v191
	v_mul_f32_e32 v37, v37, v191
	v_mul_f32_e32 v32, v32, v191
	v_mul_f32_e32 v33, v33, v191
	v_mul_f32_e32 v38, v38, v191
	v_mul_f32_e32 v34, v34, v191
	v_mul_f32_e32 v39, v39, v191
	v_mul_f32_e32 v35, v35, v191
	v_mul_f32_e32 v36, 0xbfb8aa3b, v36
	v_mul_f32_e32 v37, 0xbfb8aa3b, v37
	v_mul_f32_e32 v32, 0xbfb8aa3b, v32
	v_mul_f32_e32 v33, 0xbfb8aa3b, v33
	v_mul_f32_e32 v38, 0xbfb8aa3b, v38
	v_mul_f32_e32 v34, 0xbfb8aa3b, v34
	v_mul_f32_e32 v39, 0xbfb8aa3b, v39
	v_mul_f32_e32 v35, 0xbfb8aa3b, v35
	v_exp_f32_e32 v36, v36
	v_exp_f32_e32 v37, v37
	v_exp_f32_e32 v32, v32
	v_exp_f32_e32 v33, v33
	v_exp_f32_e32 v38, v38
	v_exp_f32_e32 v34, v34
	v_exp_f32_e32 v39, v39
	v_exp_f32_e32 v35, v35
	v_add_f32_e32 v36, 1.0, v36
	v_add_f32_e32 v37, 1.0, v37
	v_add_u32_e32 v54, 0xa0, v148
	v_add_f32_e32 v32, 1.0, v32
	v_add_f32_e32 v33, 1.0, v33
	v_add_f32_e32 v38, 1.0, v38
	v_add_f32_e32 v34, 1.0, v34
	v_add_f32_e32 v39, 1.0, v39
	v_add_f32_e32 v35, 1.0, v35
	v_rcp_f32_e32 v36, v36
	v_rcp_f32_e32 v37, v37
	v_ashrrev_i32_e32 v55, 31, v54
	v_rcp_f32_e32 v32, v32
	v_rcp_f32_e32 v33, v33
	v_rcp_f32_e32 v38, v38
	v_rcp_f32_e32 v34, v34
	v_rcp_f32_e32 v39, v39
	v_rcp_f32_e32 v35, v35
	v_lshlrev_b64 v[40:41], 11, v[54:55]
	v_lshl_add_u64 v[40:41], v[40:41], 0, v[150:151]
	global_store_dwordx4 v[58:59], v[42:45], off
	v_lshlrev_b64 v[40:41], 1, v[40:41]
	v_lshl_add_u64 v[56:57], s[40:41], 0, v[56:57]
	v_lshl_add_u64 v[60:61], s[34:35], 0, v[40:41]
	s_waitcnt vmcnt(15)
	v_lshlrev_b32_e32 v42, 16, v212
	v_and_b32_e32 v43, 0xffff0000, v212
	v_lshlrev_b32_e32 v58, 16, v216
	v_and_b32_e32 v50, 0xffff0000, v216
	v_lshlrev_b32_e32 v44, 16, v213
	v_and_b32_e32 v45, 0xffff0000, v213
	v_lshlrev_b32_e32 v46, 16, v214
	v_and_b32_e32 v47, 0xffff0000, v214
	v_lshlrev_b32_e32 v48, 16, v215
	v_and_b32_e32 v49, 0xffff0000, v215
	v_lshlrev_b32_e32 v59, 16, v217
	v_and_b32_e32 v51, 0xffff0000, v217
	v_lshlrev_b32_e32 v62, 16, v218
	v_and_b32_e32 v52, 0xffff0000, v218
	v_lshlrev_b32_e32 v63, 16, v219
	v_and_b32_e32 v53, 0xffff0000, v219
	v_fmac_f32_e32 v42, v36, v58
	v_fmac_f32_e32 v43, v37, v50
	v_fmac_f32_e32 v46, v32, v62
	v_fmac_f32_e32 v47, v33, v52
	v_fmac_f32_e32 v44, v38, v59
	v_fmac_f32_e32 v48, v34, v63
	v_fmac_f32_e32 v45, v39, v51
	v_fmac_f32_e32 v49, v35, v53
	v_cvt_pk_bf16_f32 v32, v42, v43
	v_cvt_pk_bf16_f32 v33, v44, v45
	v_cvt_pk_bf16_f32 v34, v46, v47
	v_cvt_pk_bf16_f32 v35, v48, v49
	global_store_dwordx4 v[56:57], v[32:35], off
	v_lshl_add_u64 v[36:37], s[36:37], 0, v[40:41]
	v_lshl_add_u64 v[42:43], v[54:55], 2, s[26:27]
	s_nop 0
	v_lshl_add_u64 v[42:43], s[40:41], 0, v[40:41]
	v_or_b32_e32 v40, 0x100, v40
	v_lshl_add_u64 v[44:45], s[34:35], 0, v[40:41]
	s_waitcnt vmcnt(12)
; __device__ __forceinline__ f32x4 unpk4(uint2 u) { f32x4 r; r[0] = __uint_as_float(u.x << 16); r[1] = __uint_as_float(u.x & 0xffff0000u); r[2] = __uint_as_float(u.y << 16); r[3] = __uint_as_float(u.y & 0xffff0000u); return r; }
; __device__ __forceinline__ float sigm(float x) { return __builtin_amdgcn_rcpf(1.f + __expf(-x)); }
; __device__ __forceinline__ uint4 pk8(f32x4 a, f32x4 b) { return make_uint4(cvt_pk_bf16(a[0], a[1]), cvt_pk_bf16(a[2], a[3]), cvt_pk_bf16(b[0], b[1]), cvt_pk_bf16(b[2], b[3])); }
;     __device__ __forceinline__ void operator()(AccRef acc, const Unit& u, int wr, int wc, int fr, int fq) const {
;     ...
;         for (int ai = 0; ai < 2; ++ai)
; #pragma unroll
;             for (int m = 0; m < 4; ++m) {
;                 const int r = u.pm * 256 + ai * 128 + wr * 64 + m * 16 + fr;
;                 const float s = rinv[r];
;                 float ss = 0.f;
; #pragma unroll
;                 for (int bj = 0; bj < 2; ++bj) {
;                     const size_t o = (size_t)r * D + c0 + bj * 128;
;                     const uint4 h8 = *(const uint4*)(H2 + o);
;                     f32x4 v0 = unpk4(make_uint2(h8.x, h8.y)), v1 = unpk4(make_uint2(h8.z, h8.w));
;                     const uint4 pp8 = *(const uint4*)(PPb + o);
;                     const f32x4 p0 = unpk4(make_uint2(pp8.x, pp8.y)), p1 = unpk4(make_uint2(pp8.z, pp8.w));
; #pragma unroll
;                     for (int e = 0; e < 4; ++e) { v0[e] += sigm(acc[ai][bj][m][0][e] * s) * p0[e]; v1[e] += sigm(acc[ai][bj][m][1][e] * s) * p1[e]; }
;                     ss += v0[0] * v0[0] + v0[1] * v0[1] + v0[2] * v0[2] + v0[3] * v0[3] + v1[0] * v1[0] + v1[1] * v1[1] + v1[2] * v1[2] + v1[3] * v1[3];
;                     *(uint4*)(H3 + o) = pk8(v0, v1);
;                 }
	v_lshlrev_b32_e32 v51, 16, v220
	v_and_b32_e32 v36, 0xffff0000, v220
	v_mul_f32_e32 v24, v24, v224
	v_mul_f32_e32 v29, v29, v224
	v_mul_f32_e32 v25, v25, v224
	v_mul_f32_e32 v31, v31, v224
	v_mul_f32_e32 v27, v27, v224
	v_mul_f32_e32 v28, v28, v224
	v_mul_f32_e32 v30, v30, v224
	v_mul_f32_e32 v26, v26, v224
	v_mul_f32_e32 v24, 0xbfb8aa3b, v24
	v_mul_f32_e32 v29, 0xbfb8aa3b, v29
	v_mul_f32_e32 v25, 0xbfb8aa3b, v25
	v_mul_f32_e32 v31, 0xbfb8aa3b, v31
	v_mul_f32_e32 v27, 0xbfb8aa3b, v27
	v_mul_f32_e32 v28, 0xbfb8aa3b, v28
	v_mul_f32_e32 v30, 0xbfb8aa3b, v30
	v_mul_f32_e32 v26, 0xbfb8aa3b, v26
	v_exp_f32_e32 v24, v24
	v_exp_f32_e32 v29, v29
	v_exp_f32_e32 v25, v25
	v_exp_f32_e32 v31, v31
	v_exp_f32_e32 v27, v27
	v_exp_f32_e32 v28, v28
	v_exp_f32_e32 v30, v30
	v_exp_f32_e32 v26, v26
	v_add_f32_e32 v24, 1.0, v24
	v_add_f32_e32 v29, 1.0, v29
	v_add_f32_e32 v25, 1.0, v25
	v_add_f32_e32 v31, 1.0, v31
	v_add_f32_e32 v27, 1.0, v27
	v_add_f32_e32 v28, 1.0, v28
	v_add_f32_e32 v30, 1.0, v30
	v_add_f32_e32 v26, 1.0, v26
	v_rcp_f32_e32 v24, v24
	v_rcp_f32_e32 v29, v29
	v_rcp_f32_e32 v25, v25
	v_rcp_f32_e32 v31, v31
	v_rcp_f32_e32 v27, v27
	v_rcp_f32_e32 v28, v28
	v_rcp_f32_e32 v30, v30
	v_rcp_f32_e32 v26, v26
	v_lshlrev_b32_e32 v47, 16, v226
	v_and_b32_e32 v32, 0xffff0000, v226
	v_lshlrev_b32_e32 v48, 16, v227
	v_and_b32_e32 v33, 0xffff0000, v227
	v_lshlrev_b32_e32 v49, 16, v228
	v_and_b32_e32 v34, 0xffff0000, v228
	v_lshlrev_b32_e32 v50, 16, v229
	v_and_b32_e32 v35, 0xffff0000, v229
	v_lshlrev_b32_e32 v52, 16, v221
	v_and_b32_e32 v37, 0xffff0000, v221
	v_lshlrev_b32_e32 v53, 16, v222
	v_and_b32_e32 v38, 0xffff0000, v222
	v_lshlrev_b32_e32 v54, 16, v223
	v_and_b32_e32 v39, 0xffff0000, v223
	v_fmac_f32_e32 v49, v24, v53
	v_fmac_f32_e32 v32, v29, v36
	v_fmac_f32_e32 v34, v25, v38
	v_fmac_f32_e32 v33, v31, v37
	v_fmac_f32_e32 v35, v27, v39
	v_lshl_add_u64 v[24:25], s[36:37], 0, v[40:41]
	v_fmac_f32_e32 v47, v28, v51
	v_fmac_f32_e32 v48, v30, v52
	v_fmac_f32_e32 v50, v26, v54
	v_cvt_pk_bf16_f32 v26, v47, v32
	v_cvt_pk_bf16_f32 v27, v48, v33
	v_cvt_pk_bf16_f32 v28, v49, v34
	v_cvt_pk_bf16_f32 v29, v50, v35
	v_mul_f32_e32 v20, v20, v224
	v_mul_f32_e32 v21, v21, v224
	v_mul_f32_e32 v16, v16, v224
	v_mul_f32_e32 v17, v17, v224
	v_mul_f32_e32 v22, v22, v224
	v_mul_f32_e32 v18, v18, v224
	v_mul_f32_e32 v23, v23, v224
	v_mul_f32_e32 v19, v19, v224
	v_mul_f32_e32 v20, 0xbfb8aa3b, v20
	v_mul_f32_e32 v21, 0xbfb8aa3b, v21
	v_mul_f32_e32 v16, 0xbfb8aa3b, v16
	v_mul_f32_e32 v17, 0xbfb8aa3b, v17
	v_mul_f32_e32 v22, 0xbfb8aa3b, v22
	v_mul_f32_e32 v18, 0xbfb8aa3b, v18
	v_mul_f32_e32 v23, 0xbfb8aa3b, v23
	v_mul_f32_e32 v19, 0xbfb8aa3b, v19
	v_exp_f32_e32 v20, v20
	v_exp_f32_e32 v21, v21
	v_exp_f32_e32 v16, v16
	v_exp_f32_e32 v17, v17
	v_exp_f32_e32 v22, v22
	v_exp_f32_e32 v18, v18
	v_exp_f32_e32 v23, v23
	v_exp_f32_e32 v19, v19
	v_add_f32_e32 v20, 1.0, v20
	v_add_f32_e32 v21, 1.0, v21
	v_add_u32_e32 v38, 0xb0, v148
	v_add_f32_e32 v16, 1.0, v16
	v_add_f32_e32 v17, 1.0, v17
	v_add_f32_e32 v22, 1.0, v22
	v_add_f32_e32 v18, 1.0, v18
	v_add_f32_e32 v23, 1.0, v23
	v_add_f32_e32 v19, 1.0, v19
	v_rcp_f32_e32 v20, v20
	v_rcp_f32_e32 v21, v21
	v_ashrrev_i32_e32 v39, 31, v38
	v_rcp_f32_e32 v16, v16
	v_rcp_f32_e32 v17, v17
	v_rcp_f32_e32 v22, v22
	v_rcp_f32_e32 v18, v18
	v_rcp_f32_e32 v23, v23
	v_rcp_f32_e32 v19, v19
	v_lshlrev_b64 v[24:25], 11, v[38:39]
	v_lshl_add_u64 v[24:25], v[24:25], 0, v[150:151]
	global_store_dwordx4 v[42:43], v[26:29], off
	v_lshlrev_b64 v[24:25], 1, v[24:25]
	v_lshl_add_u64 v[40:41], s[40:41], 0, v[40:41]
	v_lshl_add_u64 v[44:45], s[34:35], 0, v[24:25]
	s_waitcnt vmcnt(10)
	v_lshlrev_b32_e32 v26, 16, v178
	v_and_b32_e32 v27, 0xffff0000, v178
	v_lshlrev_b32_e32 v42, 16, v182
	v_and_b32_e32 v34, 0xffff0000, v182
	v_lshlrev_b32_e32 v28, 16, v179
	v_and_b32_e32 v29, 0xffff0000, v179
	v_lshlrev_b32_e32 v30, 16, v180
	v_and_b32_e32 v31, 0xffff0000, v180
	v_lshlrev_b32_e32 v32, 16, v181
	v_and_b32_e32 v33, 0xffff0000, v181
	v_lshlrev_b32_e32 v43, 16, v183
	v_and_b32_e32 v35, 0xffff0000, v183
	v_lshlrev_b32_e32 v46, 16, v184
	v_and_b32_e32 v36, 0xffff0000, v184
	v_lshlrev_b32_e32 v47, 16, v185
	v_and_b32_e32 v37, 0xffff0000, v185
	v_fmac_f32_e32 v26, v20, v42
	v_fmac_f32_e32 v27, v21, v34
	v_fmac_f32_e32 v30, v16, v46
	v_fmac_f32_e32 v31, v17, v36
	v_fmac_f32_e32 v28, v22, v43
	v_fmac_f32_e32 v32, v18, v47
	v_fmac_f32_e32 v29, v23, v35
	v_fmac_f32_e32 v33, v19, v37
	v_cvt_pk_bf16_f32 v16, v26, v27
	v_cvt_pk_bf16_f32 v17, v28, v29
	v_cvt_pk_bf16_f32 v18, v30, v31
	v_cvt_pk_bf16_f32 v19, v32, v33
	global_store_dwordx4 v[40:41], v[16:19], off
	v_lshl_add_u64 v[20:21], s[36:37], 0, v[24:25]
	v_lshl_add_u64 v[26:27], v[38:39], 2, s[26:27]
	s_nop 0
	v_lshl_add_u64 v[26:27], s[40:41], 0, v[24:25]
	v_or_b32_e32 v24, 0x100, v24
	v_lshl_add_u64 v[28:29], s[34:35], 0, v[24:25]
	s_waitcnt vmcnt(7)
; #define PG8_WAIT_V(n) asm volatile("s_waitcnt vmcnt(" #n ")" ::: "memory")
; #define PG8_BAR __builtin_amdgcn_s_barrier()
; __device__ __forceinline__ f32x4 unpk4(uint2 u) { f32x4 r; r[0] = __uint_as_float(u.x << 16); r[1] = __uint_as_float(u.x & 0xffff0000u); r[2] = __uint_as_float(u.y << 16); r[3] = __uint_as_float(u.y & 0xffff0000u); return r; }
; __device__ __forceinline__ float sigm(float x) { return __builtin_amdgcn_rcpf(1.f + __expf(-x)); }
; template <class Epi, class Sched>
; __device__ __forceinline__ void gemm_phase(PG8_LAS unsigned char* lds, const Gemm g, const Sched& S, const Epi& E) {
;     ...
;         if constexpr (!Epi::AFTER_DRAIN) { E(acc, cur, wr, wc, fr, fq); S.done(cur); }
;         if (!has_next) break;
; #pragma unroll
;         for (int a = 0; a < 2; ++a)
; #pragma unroll
;             for (int b = 0; b < 2; ++b)
; #pragma unroll
;                 for (int m = 0; m < 4; ++m)
; #pragma unroll
;                     for (int n = 0; n < 2; ++n) acc[a][b][m][n] = (f32x4){0.f, 0.f, 0.f, 0.f};
;         cur = nxt; cA = nA; cB = nB; ++ui;
;     }
;     PG8_WAIT_V(0);
;     if (wr == 0) PG8_BAR;
;     __device__ __forceinline__ void operator()(AccRef acc, const Unit& u, int wr, int wc, int fr, int fq) const {
;     ...
;                 const int r = u.pm * 256 + ai * 128 + wr * 64 + m * 16 + fr;
;                 const float s = rinv[r];
;                 float ss = 0.f;
; #pragma unroll
;                 for (int bj = 0; bj < 2; ++bj) {
;                     const size_t o = (size_t)r * D + c0 + bj * 128;
;                     const uint4 h8 = *(const uint4*)(H2 + o);
;                     f32x4 v0 = unpk4(make_uint2(h8.x, h8.y)), v1 = unpk4(make_uint2(h8.z, h8.w));
;                     const uint4 pp8 = *(const uint4*)(PPb + o);
;                     const f32x4 p0 = unpk4(make_uint2(pp8.x, pp8.y)), p1 = unpk4(make_uint2(pp8.z, pp8.w));
; #pragma unroll
;                     for (int e = 0; e < 4; ++e) { v0[e] += sigm(acc[ai][bj][m][0][e] * s) * p0[e]; v1[e] += sigm(acc[ai][bj][m][1][e] * s) * p1[e]; }
;                     ss += v0[0] * v0[0] + v0[1] * v0[1] + v0[2] * v0[2] + v0[3] * v0[3] + v1[0] * v1[0] + v1[1] * v1[1] + v1[2] * v1[2] + v1[3] * v1[3];
;                     *(uint4*)(H3 + o) = pk8(v0, v1);
	v_lshlrev_b32_e32 v35, 16, v186
	v_and_b32_e32 v20, 0xffff0000, v186
	v_mul_f32_e32 v13, v13, v190
	v_mul_f32_e32 v15, v15, v190
	v_mul_f32_e32 v12, v12, v190
	v_mul_f32_e32 v8, v8, v190
	v_mul_f32_e32 v9, v9, v190
	v_mul_f32_e32 v14, v14, v190
	v_mul_f32_e32 v11, v11, v190
	v_mul_f32_e32 v13, 0xbfb8aa3b, v13
	v_mul_f32_e32 v15, 0xbfb8aa3b, v15
	v_mul_f32_e32 v10, v10, v190
	v_mul_f32_e32 v12, 0xbfb8aa3b, v12
	v_mul_f32_e32 v8, 0xbfb8aa3b, v8
	v_mul_f32_e32 v9, 0xbfb8aa3b, v9
	v_mul_f32_e32 v14, 0xbfb8aa3b, v14
	v_mul_f32_e32 v11, 0xbfb8aa3b, v11
	v_exp_f32_e32 v13, v13
	v_exp_f32_e32 v15, v15
	v_mul_f32_e32 v10, 0xbfb8aa3b, v10
	v_exp_f32_e32 v12, v12
	v_exp_f32_e32 v8, v8
	v_exp_f32_e32 v9, v9
	v_exp_f32_e32 v14, v14
	v_exp_f32_e32 v11, v11
	v_exp_f32_e32 v10, v10
	v_add_f32_e32 v13, 1.0, v13
	v_add_f32_e32 v15, 1.0, v15
	v_add_f32_e32 v12, 1.0, v12
	v_add_f32_e32 v8, 1.0, v8
	v_add_f32_e32 v9, 1.0, v9
	v_add_f32_e32 v14, 1.0, v14
	v_add_f32_e32 v11, 1.0, v11
	v_rcp_f32_e32 v13, v13
	v_rcp_f32_e32 v15, v15
	v_add_f32_e32 v10, 1.0, v10
	v_rcp_f32_e32 v12, v12
	v_rcp_f32_e32 v8, v8
	v_rcp_f32_e32 v9, v9
	v_rcp_f32_e32 v14, v14
	v_rcp_f32_e32 v11, v11
	v_rcp_f32_e32 v10, v10
	v_lshlrev_b32_e32 v31, 16, v192
	v_and_b32_e32 v16, 0xffff0000, v192
	v_lshlrev_b32_e32 v32, 16, v193
	v_and_b32_e32 v17, 0xffff0000, v193
	v_lshlrev_b32_e32 v36, 16, v187
	v_and_b32_e32 v21, 0xffff0000, v187
	v_lshlrev_b32_e32 v33, 16, v194
	v_and_b32_e32 v18, 0xffff0000, v194
	v_lshlrev_b32_e32 v34, 16, v195
	v_and_b32_e32 v19, 0xffff0000, v195
	v_lshlrev_b32_e32 v37, 16, v188
	v_and_b32_e32 v22, 0xffff0000, v188
	v_lshlrev_b32_e32 v38, 16, v189
	v_and_b32_e32 v23, 0xffff0000, v189
	v_fmac_f32_e32 v16, v13, v20
	v_fmac_f32_e32 v17, v15, v21
	v_fmac_f32_e32 v31, v12, v35
	v_fmac_f32_e32 v33, v8, v37
	v_fmac_f32_e32 v18, v9, v22
	v_fmac_f32_e32 v32, v14, v36
	v_fmac_f32_e32 v19, v11, v23
	v_cvt_pk_bf16_f32 v8, v31, v16
	v_cvt_pk_bf16_f32 v9, v32, v17
	v_lshl_add_u64 v[16:17], s[36:37], 0, v[24:25]
	v_fmac_f32_e32 v34, v10, v38
	v_cvt_pk_bf16_f32 v10, v33, v18
	v_cvt_pk_bf16_f32 v11, v34, v19
	v_mul_f32_e32 v4, v4, v190
	v_mul_f32_e32 v0, v0, v190
	v_mul_f32_e32 v5, v5, v190
	v_mul_f32_e32 v1, v1, v190
	v_mul_f32_e32 v6, v6, v190
	v_mul_f32_e32 v2, v2, v190
	v_mul_f32_e32 v7, v7, v190
	v_mul_f32_e32 v3, v3, v190
	v_mul_f32_e32 v4, 0xbfb8aa3b, v4
	v_mul_f32_e32 v0, 0xbfb8aa3b, v0
	v_mul_f32_e32 v5, 0xbfb8aa3b, v5
	v_mul_f32_e32 v1, 0xbfb8aa3b, v1
	v_mul_f32_e32 v6, 0xbfb8aa3b, v6
	v_mul_f32_e32 v2, 0xbfb8aa3b, v2
	v_mul_f32_e32 v7, 0xbfb8aa3b, v7
	v_mul_f32_e32 v3, 0xbfb8aa3b, v3
	v_exp_f32_e32 v4, v4
	v_exp_f32_e32 v0, v0
	v_exp_f32_e32 v5, v5
	v_exp_f32_e32 v1, v1
	v_exp_f32_e32 v6, v6
	v_exp_f32_e32 v2, v2
	v_exp_f32_e32 v7, v7
	v_exp_f32_e32 v3, v3
	v_add_f32_e32 v4, 1.0, v4
	v_add_f32_e32 v0, 1.0, v0
	v_add_f32_e32 v5, 1.0, v5
	v_add_f32_e32 v1, 1.0, v1
	v_add_f32_e32 v6, 1.0, v6
	v_add_f32_e32 v2, 1.0, v2
	v_add_f32_e32 v7, 1.0, v7
	v_add_f32_e32 v3, 1.0, v3
	v_rcp_f32_e32 v4, v4
	v_rcp_f32_e32 v0, v0
	v_rcp_f32_e32 v5, v5
	v_rcp_f32_e32 v1, v1
	v_rcp_f32_e32 v6, v6
	v_rcp_f32_e32 v2, v2
	v_rcp_f32_e32 v7, v7
	v_rcp_f32_e32 v3, v3
	v_lshl_add_u64 v[20:21], s[40:41], 0, v[24:25]
	global_store_dwordx4 v[26:27], v[8:11], off
	s_waitcnt vmcnt(5)
	v_lshlrev_b32_e32 v22, 16, v200
	v_lshlrev_b32_e32 v8, 16, v196
	v_and_b32_e32 v9, 0xffff0000, v196
	v_lshlrev_b32_e32 v10, 16, v197
	v_and_b32_e32 v11, 0xffff0000, v197
	v_lshlrev_b32_e32 v12, 16, v198
	v_and_b32_e32 v13, 0xffff0000, v198
	v_lshlrev_b32_e32 v14, 16, v199
	v_and_b32_e32 v15, 0xffff0000, v199
	v_and_b32_e32 v16, 0xffff0000, v200
	v_lshlrev_b32_e32 v23, 16, v201
	v_and_b32_e32 v17, 0xffff0000, v201
	v_lshlrev_b32_e32 v24, 16, v202
	v_and_b32_e32 v18, 0xffff0000, v202
	v_lshlrev_b32_e32 v25, 16, v203
	v_and_b32_e32 v19, 0xffff0000, v203
	v_fmac_f32_e32 v8, v4, v22
	v_fmac_f32_e32 v12, v0, v24
	v_fmac_f32_e32 v9, v5, v16
	v_fmac_f32_e32 v13, v1, v18
	v_fmac_f32_e32 v10, v6, v23
	v_fmac_f32_e32 v14, v2, v25
	v_fmac_f32_e32 v11, v7, v17
	v_fmac_f32_e32 v15, v3, v19
	v_cvt_pk_bf16_f32 v0, v8, v9
	v_cvt_pk_bf16_f32 v1, v10, v11
	v_cvt_pk_bf16_f32 v2, v12, v13
	v_cvt_pk_bf16_f32 v3, v14, v15
	global_store_dwordx4 v[20:21], v[0:3], off
	s_cbranch_vccz .LBB0_1052
	s_waitcnt vmcnt(0)
	s_cmpk_gt_u32 s3, 0xff
	s_cbranch_scc1 .LBB0_1063
	s_barrier

; __device__ __forceinline__ f32x4 unpk4(uint2 u) { f32x4 r; r[0] = __uint_as_float(u.x << 16); r[1] = __uint_as_float(u.x & 0xffff0000u); r[2] = __uint_as_float(u.y << 16); r[3] = __uint_as_float(u.y & 0xffff0000u); return r; }
; __device__ void phase_final(const Params& P) {
;     const int lane = threadIdx.x & 63, wid = threadIdx.x >> 6;
;     const float* rowsq4 = (const float*)(P.ws + O_SMALL) + 3 * T;
;     const float* gf = P.in[I_NFIN];
;     const bf16_t* H3 = (const bf16_t*)(P.ws + O_R3);
;     (void)rowsq4;
;     for (int row = blockIdx.x * 8 + wid; row < T; row += gridDim.x * 8) {
;         float* rp = P.out + (size_t)row * D + lane * 8; const bf16_t* hp = H3 + (size_t)row * D + lane * 8;
;         f32x4 v0[4], v1[4]; float ss = 0.f;
; #pragma unroll
;         for (int j = 0; j < 4; ++j) {
;             const uint4 h8 = *(const uint4*)(hp + j * 512);
;             v0[j] = unpk4(make_uint2(h8.x, h8.y)); v1[j] = unpk4(make_uint2(h8.z, h8.w));
;             ss += v0[j][0] * v0[j][0] + v0[j][1] * v0[j][1] + v0[j][2] * v0[j][2] + v0[j][3] * v0[j][3] + v1[j][0] * v1[j][0] + v1[j][1] * v1[j][1] + v1[j][2] * v1[j][2] + v1[j][3] * v1[j][3];
;         }
;         ss = wave_sum(ss);
.LBB0_1118:
	s_setprio 0
	s_cmp_lt_i32 s92, 11
	s_cselect_b64 s[0:1], -1, 0
	s_cmp_gt_i32 s93, 10
	s_cselect_b64 s[4:5], -1, 0
	s_and_b64 s[0:1], s[0:1], s[4:5]
	s_andn2_b64 vcc, exec, s[0:1]
	s_cbranch_vccnz .LBB0_1122
	v_lshl_add_u32 v0, s2, 3, v146
	s_mov_b32 s0, 0x8000
	v_cmp_gt_i32_e32 vcc, s0, v0
	s_and_saveexec_b64 s[0:1], vcc
	s_cbranch_execz .LBB0_1122
	v_mbcnt_lo_u32_b32 v4, -1, 0
	v_mbcnt_hi_u32_b32 v4, -1, v4
	v_and_b32_e32 v5, 64, v4
	v_add_u32_e32 v5, 64, v5
	v_xor_b32_e32 v6, 32, v4
	v_cmp_lt_i32_e32 vcc, v6, v5
	v_lshlrev_b32_e32 v1, 3, v144
	v_and_b32_e32 v1, 0x1f8, v1
	v_cndmask_b32_e32 v6, v4, v6, vcc
	v_lshlrev_b32_e32 v12, 2, v6
	v_xor_b32_e32 v6, 16, v4
	v_cmp_lt_i32_e32 vcc, v6, v5
	v_lshlrev_b32_e32 v10, 1, v1
	v_mov_b32_e32 v11, 0
	v_cndmask_b32_e32 v6, v4, v6, vcc
	v_lshlrev_b32_e32 v13, 2, v6
	v_xor_b32_e32 v6, 8, v4
	v_cmp_lt_i32_e32 vcc, v6, v5
	v_lshl_add_u64 v[2:3], s[40:41], 0, v[10:11]
	v_lshlrev_b32_e32 v10, 2, v1
	v_cndmask_b32_e32 v6, v4, v6, vcc
	s_waitcnt lgkmcnt(0)
	v_lshlrev_b32_e32 v14, 2, v6
	v_xor_b32_e32 v6, 4, v4
	v_cmp_lt_i32_e32 vcc, v6, v5
	s_mov_b64 s[0:1], 0x1000
	s_lshl_b32 s2, s94, 3
	v_cndmask_b32_e32 v6, v4, v6, vcc
	v_lshlrev_b32_e32 v15, 2, v6
	v_xor_b32_e32 v6, 2, v4
	v_cmp_lt_i32_e32 vcc, v6, v5
	v_mov_b32_e32 v18, 0x358637bd
	s_mov_b32 s3, 0x800000
	v_cndmask_b32_e32 v6, v4, v6, vcc
	v_lshlrev_b32_e32 v16, 2, v6
	v_xor_b32_e32 v6, 1, v4
	v_cmp_lt_i32_e32 vcc, v6, v5
	s_movk_i32 s4, 0x1000
	s_movk_i32 s5, 0x7fff
	v_cndmask_b32_e32 v4, v4, v6, vcc
	v_lshlrev_b32_e32 v17, 2, v4
	v_lshl_add_u64 v[4:5], s[86:87], 0, v[10:11]
	v_lshl_add_u64 v[6:7], v[4:5], 0, s[0:1]
	s_mov_b64 s[0:1], 0x1800
	v_lshl_add_u64 v[8:9], v[4:5], 0, s[0:1]
	v_lshl_add_u64 v[10:11], s[88:89], 0, v[10:11]
	s_mov_b64 s[0:1], 0

; __global__ __launch_bounds__(512, 2) void mega(Params P) {
	.amdhsa_kernel _Z4mega6Params
		.amdhsa_group_segment_fixed_size 0
		.amdhsa_private_segment_fixed_size 0
		.amdhsa_kernarg_size 488
		.amdhsa_user_sgpr_count 2
		.amdhsa_user_sgpr_dispatch_ptr 0
		.amdhsa_user_sgpr_queue_ptr 0
		.amdhsa_user_sgpr_kernarg_segment_ptr 1
		.amdhsa_user_sgpr_dispatch_id 0
		.amdhsa_user_sgpr_kernarg_preload_length 0
		.amdhsa_user_sgpr_kernarg_preload_offset 0
		.amdhsa_user_sgpr_private_segment_size 0
		.amdhsa_uses_dynamic_stack 0
		.amdhsa_enable_private_segment 0
		.amdhsa_system_sgpr_workgroup_id_x 1
		.amdhsa_system_sgpr_workgroup_id_y 0
		.amdhsa_system_sgpr_workgroup_id_z 0
		.amdhsa_system_sgpr_workgroup_info 0
		.amdhsa_system_vgpr_workitem_id 2
		.amdhsa_next_free_vgpr 249
		.amdhsa_next_free_sgpr 102
		.amdhsa_accum_offset 252
		.amdhsa_reserve_vcc 1
		.amdhsa_float_round_mode_32 0
		.amdhsa_float_round_mode_16_64 0
		.amdhsa_float_denorm_mode_32 3
		.amdhsa_float_denorm_mode_16_64 3
		.amdhsa_dx10_clamp 1
		.amdhsa_ieee_mode 1
		.amdhsa_fp16_overflow 0
		.amdhsa_tg_split 0
		.amdhsa_exception_fp_ieee_invalid_op 0
		.amdhsa_exception_fp_denorm_src 0
		.amdhsa_exception_fp_ieee_div_zero 0
		.amdhsa_exception_fp_ieee_overflow 0
		.amdhsa_exception_fp_ieee_underflow 0
		.amdhsa_exception_fp_ieee_inexact 0
		.amdhsa_exception_int_div_zero 0
	.end_amdhsa_kernel

; __global__ __launch_bounds__(512, 2) void mega(Params P) {
amdhsa.kernels:
  - .agpr_count:     0
    .args:
      - .offset:         0
        .size:           232
        .value_kind:     by_value
      - .offset:         232
        .size:           4
        .value_kind:     hidden_block_count_x
      - .offset:         236
        .size:           4
        .value_kind:     hidden_block_count_y
      - .offset:         240
        .size:           4
        .value_kind:     hidden_block_count_z
      - .offset:         244
        .size:           2
        .value_kind:     hidden_group_size_x
      - .offset:         246
        .size:           2
        .value_kind:     hidden_group_size_y
      - .offset:         248
        .size:           2
        .value_kind:     hidden_group_size_z
      - .offset:         250
        .size:           2
        .value_kind:     hidden_remainder_x
      - .offset:         252
        .size:           2
        .value_kind:     hidden_remainder_y
      - .offset:         254
        .size:           2
        .value_kind:     hidden_remainder_z
      - .offset:         272
        .size:           8
        .value_kind:     hidden_global_offset_x
      - .offset:         280
        .size:           8
        .value_kind:     hidden_global_offset_y
      - .offset:         288
        .size:           8
        .value_kind:     hidden_global_offset_z
      - .offset:         296
        .size:           2
        .value_kind:     hidden_grid_dims
      - .offset:         320
        .size:           8
        .value_kind:     hidden_multigrid_sync_arg
      - .offset:         352
        .size:           4
        .value_kind:     hidden_dynamic_lds_size
    .group_segment_fixed_size: 0
    .kernarg_segment_align: 8
    .kernarg_segment_size: 488
    .language:       OpenCL C
    .language_version:
      - 2
      - 0
    .max_flat_workgroup_size: 512
    .name:           _Z4mega6Params
    .private_segment_fixed_size: 0
    .sgpr_count:     108
    .sgpr_spill_count: 38
    .symbol:         _Z4mega6Params.kd
    .uniform_work_group_size: 1
    .uses_dynamic_stack: false
    .vgpr_count:     249
    .vgpr_spill_count: 0
    .wavefront_size: 64
